# GEMM loops: LDS-DMA loads use SGPR base + 32-bit VGPR offset form, dropping the per-load 64-bit VALU address adds
# speedup vs baseline: 1.0226x; 1.0041x over previous
; #define PG8_STAGE(bufoff, gbase, voff) do { _Pragma("unroll") for (int _i = 0; _i < 2; ++_i) \
;         __builtin_amdgcn_global_load_lds((const unsigned*)((const char*)(gbase) + (voff)[_i]), (LAS unsigned*)(lds + (bufoff) + ldsw + _i * 8192), 16, 0, 0); } while (0)
; #define PG8_WAIT_V(n) asm volatile("s_waitcnt vmcnt(" #n ")" ::: "memory")
; #define PG8_BAR __builtin_amdgcn_s_barrier()
; template <class Epi>
; __device__ __forceinline__ void gemm_phase(LAS unsigned char* lds, const Gemm g, const StaticOrder S, const Epi E) {
;     ...
;     for (int i = 0; i < 2; ++i) { int R, C; stage_rc(tid * 16 + i * 8192, R, C); const int Rb = Epi::PERM ? ((R & ~31) + perm32(R & 31)) : R;
;         voffA[i] = (unsigned)(R * g.lda + C) * 2u; voffB[i] = (unsigned)(Rb * g.ldb + C) * 2u; }
;     const size_t kstep = (size_t)(BK * 2);
;     const size_t hstepA = (size_t)HALF * g.lda * 2, hstepB = (size_t)HALF * g.ldb * 2;
;     const size_t tstepA = 2 * hstepA, tstepB = 2 * hstepB;
;     const unsigned ldsw = (unsigned)wid * 1024u;
;     const int aoff = lds_byte(wr * 64 + fr, fq * 8), boff = lds_byte(wc * 32 + fr, fq * 8);
;     ...
;     PG8_STAGE(PG8_SB(1, 0), cB + ksc, voffB); PG8_STAGE(PG8_SA(1, 0), cA + ksc, voffA); PG8_STAGE(PG8_SB(1, 1), cB + hstepB + ksc, voffB);
;     PG8_WAIT_V(6); PG8_BAR;
.LBB0_115:
	s_lshl_b32 s9, s9, 5
	s_mov_b64 s[26:27], 0x80
	s_and_b32 s14, s9, 0x60
	s_add_i32 m0, s21, 0x18000
	v_lshl_add_u64 v[6:7], v[6:7], 0, s[26:27]
	s_lshl_b32 s10, s8, 13
	s_lshl_b32 s9, s14, 7
	s_waitcnt vmcnt(2)
	s_barrier
	global_load_lds_dwordx4 v[6:7], off
	v_lshl_add_u64 v[4:5], v[4:5], 0, s[26:27]
	s_add_i32 m0, s21, 0x1a000
	s_add_i32 s53, s21, 0x8000
	s_add_i32 s54, s21, 0xa000
	global_load_lds_dwordx4 v[4:5], off
	v_lshl_add_u64 v[0:1], v[0:1], 0, s[26:27]
	s_mov_b32 m0, s53
	s_add_u32 s12, s22, 0x80080
	global_load_lds_dwordx4 v[0:1], off
	v_lshl_add_u64 v[0:1], v[2:3], 0, s[26:27]
	s_mov_b32 m0, s54
	s_addc_u32 s13, s23, 0
	global_load_lds_dwordx4 v[0:1], off
	s_add_i32 m0, s21, 0x1c000
	s_nop 0
	global_load_lds_dwordx4 v132, s[12:13]
	s_add_i32 m0, s21, 0x1e000
	v_lshlrev_b32_e32 v2, 2, v224
	global_load_lds_dwordx4 v128, s[12:13]
	v_and_b32_e32 v0, 15, v224
	v_lshlrev_b32_e32 v1, 1, v8
	s_sext_i32_i16 s61, s0
	v_lshl_or_b32 v142, s8, 6, v0
	v_lshl_or_b32 v0, v0, 6, v1
	v_and_b32_e32 v2, 32, v2
	v_lshlrev_b32_e32 v3, 6, v224
	s_movk_i32 s0, 0x3c0
	s_waitcnt vmcnt(6)
	s_ashr_i32 s55, s78, 31
	v_bitop3_b32 v0, v0, s10, v2 bitop3:0xde
	v_and_or_b32 v1, v3, s0, v1
	s_cmpk_lt_u32 s1, 0x100
	v_bitop3_b32 v143, s9, v1, v2 bitop3:0xf6
	s_cselect_b64 s[8:9], -1, 0
	v_or_b32_e32 v144, s14, v8
	v_mov_b64_e32 v[136:137], 0xb00
	v_mov_b64_e32 v[138:139], 0xaff
	s_movk_i32 s56, 0xff80
	s_add_i32 s57, 0, 0x10000
	s_add_i32 s58, 0, 0x14000
	v_add_u32_e32 v145, 0, v0
	s_movk_i32 s59, 0x2c00
	v_mov_b32_e32 v146, 0x358637bd
	s_barrier
	s_branch .LBB0_118

; #define PG8_STAGE(bufoff, gbase, voff) do { _Pragma("unroll") for (int _i = 0; _i < 2; ++_i) \
;         __builtin_amdgcn_global_load_lds((const unsigned*)((const char*)(gbase) + (voff)[_i]), (LAS unsigned*)(lds + (bufoff) + ldsw + _i * 8192), 16, 0, 0); } while (0)
; #define PG8_LDA(dst, b, h) do { _Pragma("unroll") for (int m = 0; m < 4; ++m) _Pragma("unroll") for (int k = 0; k < 2; ++k) dst[m][k] = *(const LAS bf16x8*)(lds + PG8_SA(b, h) + aoff + m * 2048 + k * 1024); } while (0)
; #define PG8_LDB(dst, b, h) do { _Pragma("unroll") for (int n = 0; n < 2; ++n) _Pragma("unroll") for (int k = 0; k < 2; ++k) dst[n][k] = *(const LAS bf16x8*)(lds + PG8_SB(b, h) + boff + n * 2048 + k * 1024); } while (0)
; #define PG8_MMA(ai, bj, At, Bt) do { __builtin_amdgcn_s_setprio(1); _Pragma("unroll") for (int m = 0; m < 4; ++m) _Pragma("unroll") for (int n = 0; n < 2; ++n) _Pragma("unroll") for (int k = 0; k < 2; ++k) \
;         acc[ai][bj][m][n] = __builtin_amdgcn_mfma_f32_16x16x32_bf16(Bt[n][k], At[m][k], acc[ai][bj][m][n], 0, 0, 0); __builtin_amdgcn_s_setprio(0); } while (0)
; #define PG8_WAIT_V(n) asm volatile("s_waitcnt vmcnt(" #n ")" ::: "memory")
; #define PG8_WAIT_L(n) asm volatile("s_waitcnt lgkmcnt(" #n ")" ::: "memory")
; #define PG8_BAR __builtin_amdgcn_s_barrier()
; #define PG8_SCHED __builtin_amdgcn_sched_barrier(0)
; template <class Epi>
; __device__ __forceinline__ void gemm_phase(LAS unsigned char* lds, const Gemm g, const StaticOrder S, const Epi E) {
;     ...
;             PG8_LDB(B0, 0, 0); PG8_LDB(B1, 0, 1); PG8_SCHED; PG8_LDA(At, 0, 0); PG8_STAGE(PG8_SA(1, 1), a1 + hstepA, voffA);
;             PG8_WAIT_V(8); PG8_WAIT_L(0); PG8_BAR; PG8_MMA(0, 0, At, B0); PG8_MMA(0, 1, At, B1); PG8_BAR; PG8_SCHED;
;             PG8_LDA(At, 0, 1); PG8_STAGE(PG8_SB(0, 0), b2, voffB); PG8_STAGE(PG8_SB(0, 1), b2 + hstepB, voffB); PG8_STAGE(PG8_SA(0, 0), a2, voffA);
;             PG8_WAIT_V(8); PG8_WAIT_L(0); PG8_BAR; PG8_MMA(1, 0, At, B0); PG8_MMA(1, 1, At, B1); PG8_BAR; PG8_SCHED;
.LBB0_121:
	v_add_u32_e32 v140, s57, v143
	ds_read_b128 v[148:151], v140
	ds_read_b128 v[152:155], v140 offset:1024
	ds_read_b128 v[156:159], v140 offset:2048
	ds_read_b128 v[160:163], v140 offset:3072
	v_add_u32_e32 v140, s58, v143
	ds_read_b128 v[164:167], v140
	ds_read_b128 v[168:171], v140 offset:1024
	ds_read_b128 v[172:175], v140 offset:2048
	ds_read_b128 v[176:179], v140 offset:3072
	s_or_b32 s13, s62, 1
	s_mul_i32 s46, s27, s13
	s_mul_hi_u32 s47, s26, s13
	s_add_i32 s47, s47, s46
	s_mul_i32 s13, s26, s13
	s_add_u32 s13, s24, s13
	s_addc_u32 s63, s25, s47
	s_add_u32 s46, s44, s42
	s_addc_u32 s47, s45, s43
	s_add_u32 s64, s13, 0x80000
	s_addc_u32 s65, s63, 0
	s_add_i32 m0, s21, 0xc000
	ds_read_b128 v[180:183], v145
	ds_read_b128 v[184:187], v145 offset:1024
	ds_read_b128 v[188:191], v145 offset:2048
	ds_read_b128 v[192:195], v145 offset:3072
	ds_read_b128 v[196:199], v145 offset:4096
	ds_read_b128 v[200:203], v145 offset:5120
	ds_read_b128 v[204:207], v145 offset:6144
	ds_read_b128 v[208:211], v145 offset:7168
	global_load_lds_dwordx4 v134, s[64:65]
	s_add_i32 m0, s21, 0xe000
	s_nop 0
	global_load_lds_dwordx4 v130, s[64:65]
	s_waitcnt vmcnt(8)
	s_waitcnt lgkmcnt(0)
	s_barrier
	s_setprio 1
	s_waitcnt lgkmcnt(0)
	v_mfma_f32_16x16x32_bf16 v[116:119], v[148:151], v[180:183], v[116:119]
	v_mfma_f32_16x16x32_bf16 v[112:115], v[156:159], v[180:183], v[112:115]
	v_mfma_f32_16x16x32_bf16 v[108:111], v[148:151], v[188:191], v[108:111]
	v_mfma_f32_16x16x32_bf16 v[104:107], v[156:159], v[188:191], v[104:107]
	v_mfma_f32_16x16x32_bf16 v[92:95], v[148:151], v[196:199], v[92:95]
	v_mfma_f32_16x16x32_bf16 v[88:91], v[156:159], v[196:199], v[88:91]
	v_mfma_f32_16x16x32_bf16 v[76:79], v[148:151], v[204:207], v[76:79]
	v_mfma_f32_16x16x32_bf16 v[72:75], v[156:159], v[204:207], v[72:75]
	v_mfma_f32_16x16x32_bf16 v[116:119], v[152:155], v[184:187], v[116:119]
	v_mfma_f32_16x16x32_bf16 v[112:115], v[160:163], v[184:187], v[112:115]
	v_mfma_f32_16x16x32_bf16 v[108:111], v[152:155], v[192:195], v[108:111]
	v_mfma_f32_16x16x32_bf16 v[104:107], v[160:163], v[192:195], v[104:107]
	v_mfma_f32_16x16x32_bf16 v[92:95], v[152:155], v[200:203], v[92:95]
	v_mfma_f32_16x16x32_bf16 v[88:91], v[160:163], v[200:203], v[88:91]
	v_mfma_f32_16x16x32_bf16 v[76:79], v[152:155], v[208:211], v[76:79]
	v_mfma_f32_16x16x32_bf16 v[72:75], v[160:163], v[208:211], v[72:75]
	s_setprio 0
	s_setprio 1
	v_mfma_f32_16x16x32_bf16 v[124:127], v[164:167], v[180:183], v[124:127]
	v_mfma_f32_16x16x32_bf16 v[120:123], v[172:175], v[180:183], v[120:123]
	v_mfma_f32_16x16x32_bf16 v[100:103], v[164:167], v[188:191], v[100:103]
	v_mfma_f32_16x16x32_bf16 v[96:99], v[172:175], v[188:191], v[96:99]
	v_mfma_f32_16x16x32_bf16 v[84:87], v[164:167], v[196:199], v[84:87]
	v_mfma_f32_16x16x32_bf16 v[80:83], v[172:175], v[196:199], v[80:83]
	v_mfma_f32_16x16x32_bf16 v[68:71], v[164:167], v[204:207], v[68:71]
	v_mfma_f32_16x16x32_bf16 v[64:67], v[172:175], v[204:207], v[64:67]
	v_mfma_f32_16x16x32_bf16 v[124:127], v[168:171], v[184:187], v[124:127]
	v_mfma_f32_16x16x32_bf16 v[120:123], v[176:179], v[184:187], v[120:123]
	v_mfma_f32_16x16x32_bf16 v[100:103], v[168:171], v[192:195], v[100:103]
	v_mfma_f32_16x16x32_bf16 v[96:99], v[176:179], v[192:195], v[96:99]
	v_mfma_f32_16x16x32_bf16 v[84:87], v[168:171], v[200:203], v[84:87]
	v_mfma_f32_16x16x32_bf16 v[80:83], v[176:179], v[200:203], v[80:83]
	v_mfma_f32_16x16x32_bf16 v[68:71], v[168:171], v[208:211], v[68:71]
	v_mfma_f32_16x16x32_bf16 v[64:67], v[176:179], v[208:211], v[64:67]
	s_setprio 0
	s_barrier
	s_add_i32 s13, s57, s33
	s_mov_b32 m0, s13
	ds_read_b128 v[180:183], v145 offset:16384
	ds_read_b128 v[184:187], v145 offset:17408
	ds_read_b128 v[188:191], v145 offset:18432
	ds_read_b128 v[192:195], v145 offset:19456
	ds_read_b128 v[196:199], v145 offset:20480
	ds_read_b128 v[200:203], v145 offset:21504
	ds_read_b128 v[204:207], v145 offset:22528
	ds_read_b128 v[208:211], v145 offset:23552
	global_load_lds_dwordx4 v132, s[40:41]
	s_add_i32 m0, s13, 0x2000
	s_add_u32 s64, s40, 0x80000
	s_addc_u32 s65, s41, 0
	s_add_i32 s13, s58, s33
	global_load_lds_dwordx4 v128, s[40:41]
	s_mov_b32 m0, s13
	s_nop 0
	global_load_lds_dwordx4 v132, s[64:65]
	s_add_i32 m0, s13, 0x2000
	s_nop 0
	global_load_lds_dwordx4 v128, s[64:65]
	s_mov_b32 m0, s21
	s_nop 0
	global_load_lds_dwordx4 v134, s[44:45]
	s_mov_b32 m0, s50
	s_nop 0
	global_load_lds_dwordx4 v130, s[44:45]
	s_waitcnt vmcnt(8)
	s_waitcnt lgkmcnt(0)
	s_barrier
	s_setprio 1
	s_waitcnt lgkmcnt(0)
	v_mfma_f32_16x16x32_bf16 v[60:63], v[148:151], v[180:183], v[60:63]
	v_mfma_f32_16x16x32_bf16 v[56:59], v[156:159], v[180:183], v[56:59]
	v_mfma_f32_16x16x32_bf16 v[44:47], v[148:151], v[188:191], v[44:47]
	v_mfma_f32_16x16x32_bf16 v[40:43], v[156:159], v[188:191], v[40:43]
	v_mfma_f32_16x16x32_bf16 v[28:31], v[148:151], v[196:199], v[28:31]
	v_mfma_f32_16x16x32_bf16 v[24:27], v[156:159], v[196:199], v[24:27]
	v_mfma_f32_16x16x32_bf16 v[12:15], v[148:151], v[204:207], v[12:15]
	v_mfma_f32_16x16x32_bf16 v[8:11], v[156:159], v[204:207], v[8:11]
	v_mfma_f32_16x16x32_bf16 v[60:63], v[152:155], v[184:187], v[60:63]
	v_mfma_f32_16x16x32_bf16 v[56:59], v[160:163], v[184:187], v[56:59]
	v_mfma_f32_16x16x32_bf16 v[44:47], v[152:155], v[192:195], v[44:47]
	v_mfma_f32_16x16x32_bf16 v[40:43], v[160:163], v[192:195], v[40:43]
	v_mfma_f32_16x16x32_bf16 v[28:31], v[152:155], v[200:203], v[28:31]
	v_mfma_f32_16x16x32_bf16 v[24:27], v[160:163], v[200:203], v[24:27]
	v_mfma_f32_16x16x32_bf16 v[12:15], v[152:155], v[208:211], v[12:15]
	v_mfma_f32_16x16x32_bf16 v[8:11], v[160:163], v[208:211], v[8:11]
	s_setprio 0
	s_setprio 1
	v_mfma_f32_16x16x32_bf16 v[52:55], v[164:167], v[180:183], v[52:55]
	v_mfma_f32_16x16x32_bf16 v[48:51], v[172:175], v[180:183], v[48:51]
	v_mfma_f32_16x16x32_bf16 v[36:39], v[164:167], v[188:191], v[36:39]
	v_mfma_f32_16x16x32_bf16 v[32:35], v[172:175], v[188:191], v[32:35]
	v_mfma_f32_16x16x32_bf16 v[20:23], v[164:167], v[196:199], v[20:23]
	v_mfma_f32_16x16x32_bf16 v[16:19], v[172:175], v[196:199], v[16:19]
	v_mfma_f32_16x16x32_bf16 v[4:7], v[164:167], v[204:207], v[4:7]
	v_mfma_f32_16x16x32_bf16 v[0:3], v[172:175], v[204:207], v[0:3]
	v_mfma_f32_16x16x32_bf16 v[52:55], v[168:171], v[184:187], v[52:55]
	v_mfma_f32_16x16x32_bf16 v[48:51], v[176:179], v[184:187], v[48:51]
	v_mfma_f32_16x16x32_bf16 v[36:39], v[168:171], v[192:195], v[36:39]
	v_mfma_f32_16x16x32_bf16 v[32:35], v[176:179], v[192:195], v[32:35]
	v_mfma_f32_16x16x32_bf16 v[20:23], v[168:171], v[200:203], v[20:23]
	v_mfma_f32_16x16x32_bf16 v[16:19], v[176:179], v[200:203], v[16:19]
	v_mfma_f32_16x16x32_bf16 v[4:7], v[168:171], v[208:211], v[4:7]
	v_mfma_f32_16x16x32_bf16 v[0:3], v[176:179], v[208:211], v[0:3]
	s_setprio 0
	s_barrier
; #define PG8_STAGE(bufoff, gbase, voff) do { _Pragma("unroll") for (int _i = 0; _i < 2; ++_i) \
;         __builtin_amdgcn_global_load_lds((const unsigned*)((const char*)(gbase) + (voff)[_i]), (LAS unsigned*)(lds + (bufoff) + ldsw + _i * 8192), 16, 0, 0); } while (0)
; #define PG8_LDA(dst, b, h) do { _Pragma("unroll") for (int m = 0; m < 4; ++m) _Pragma("unroll") for (int k = 0; k < 2; ++k) dst[m][k] = *(const LAS bf16x8*)(lds + PG8_SA(b, h) + aoff + m * 2048 + k * 1024); } while (0)
; #define PG8_LDB(dst, b, h) do { _Pragma("unroll") for (int n = 0; n < 2; ++n) _Pragma("unroll") for (int k = 0; k < 2; ++k) dst[n][k] = *(const LAS bf16x8*)(lds + PG8_SB(b, h) + boff + n * 2048 + k * 1024); } while (0)
; #define PG8_MMA(ai, bj, At, Bt) do { __builtin_amdgcn_s_setprio(1); _Pragma("unroll") for (int m = 0; m < 4; ++m) _Pragma("unroll") for (int n = 0; n < 2; ++n) _Pragma("unroll") for (int k = 0; k < 2; ++k) \
;         acc[ai][bj][m][n] = __builtin_amdgcn_mfma_f32_16x16x32_bf16(Bt[n][k], At[m][k], acc[ai][bj][m][n], 0, 0, 0); __builtin_amdgcn_s_setprio(0); } while (0)
; #define PG8_WAIT_V(n) asm volatile("s_waitcnt vmcnt(" #n ")" ::: "memory")
; #define PG8_WAIT_L(n) asm volatile("s_waitcnt lgkmcnt(" #n ")" ::: "memory")
; #define PG8_BAR __builtin_amdgcn_s_barrier()
; #define PG8_SCHED __builtin_amdgcn_sched_barrier(0)
; template <class Epi>
; __device__ __forceinline__ void gemm_phase(LAS unsigned char* lds, const Gemm g, const StaticOrder S, const Epi E) {
;     ...
;             PG8_LDB(B0, 1, 0); PG8_LDB(B1, 1, 1); PG8_SCHED; PG8_LDA(At, 1, 0); PG8_STAGE(PG8_SA(0, 1), a2 + hstepA, voffA);
;             PG8_WAIT_V(8); PG8_WAIT_L(0); PG8_BAR; PG8_MMA(0, 0, At, B0); PG8_MMA(0, 1, At, B1); PG8_BAR; PG8_SCHED;
;             PG8_LDA(At, 1, 1); PG8_STAGE(PG8_SB(1, 0), b3, voffB); PG8_STAGE(PG8_SB(1, 1), b3 + hstepB, voffB); PG8_STAGE(PG8_SA(1, 0), a3, voffA);
;             PG8_WAIT_V(8); PG8_WAIT_L(0); PG8_BAR; PG8_MMA(1, 0, At, B0); PG8_MMA(1, 1, At, B1); PG8_BAR; PG8_SCHED;
;         }
	s_add_i32 s13, 0, 0x18000
	v_add_u32_e32 v140, s13, v143
	s_add_i32 s63, 0, 0x1c000
	ds_read_b128 v[148:151], v140
	ds_read_b128 v[152:155], v140 offset:1024
	ds_read_b128 v[156:159], v140 offset:2048
	ds_read_b128 v[160:163], v140 offset:3072
	v_add_u32_e32 v140, s63, v143
	ds_read_b128 v[164:167], v140
	ds_read_b128 v[168:171], v140 offset:1024
	ds_read_b128 v[172:175], v140 offset:2048
	ds_read_b128 v[176:179], v140 offset:3072
	s_add_u32 s44, s44, 0x80000
	s_addc_u32 s45, s45, 0
	s_mov_b32 m0, s51
	ds_read_b128 v[180:183], v145 offset:32768
	ds_read_b128 v[184:187], v145 offset:33792
	ds_read_b128 v[188:191], v145 offset:34816
	ds_read_b128 v[192:195], v145 offset:35840
	ds_read_b128 v[196:199], v145 offset:36864
	ds_read_b128 v[200:203], v145 offset:37888
	ds_read_b128 v[204:207], v145 offset:38912
	ds_read_b128 v[208:211], v145 offset:39936
	global_load_lds_dwordx4 v134, s[44:45]
	s_mov_b32 m0, s52
	s_nop 0
	global_load_lds_dwordx4 v130, s[44:45]
	s_waitcnt vmcnt(8)
	s_waitcnt lgkmcnt(0)
	s_barrier
	s_setprio 1
	s_waitcnt lgkmcnt(0)
	v_mfma_f32_16x16x32_bf16 v[116:119], v[148:151], v[180:183], v[116:119]
	v_mfma_f32_16x16x32_bf16 v[112:115], v[156:159], v[180:183], v[112:115]
	v_mfma_f32_16x16x32_bf16 v[108:111], v[148:151], v[188:191], v[108:111]
	v_mfma_f32_16x16x32_bf16 v[104:107], v[156:159], v[188:191], v[104:107]
	v_mfma_f32_16x16x32_bf16 v[92:95], v[148:151], v[196:199], v[92:95]
	v_mfma_f32_16x16x32_bf16 v[88:91], v[156:159], v[196:199], v[88:91]
	v_mfma_f32_16x16x32_bf16 v[76:79], v[148:151], v[204:207], v[76:79]
	v_mfma_f32_16x16x32_bf16 v[72:75], v[156:159], v[204:207], v[72:75]
	v_mfma_f32_16x16x32_bf16 v[116:119], v[152:155], v[184:187], v[116:119]
	v_mfma_f32_16x16x32_bf16 v[112:115], v[160:163], v[184:187], v[112:115]
	v_mfma_f32_16x16x32_bf16 v[108:111], v[152:155], v[192:195], v[108:111]
	v_mfma_f32_16x16x32_bf16 v[104:107], v[160:163], v[192:195], v[104:107]
	v_mfma_f32_16x16x32_bf16 v[92:95], v[152:155], v[200:203], v[92:95]
	v_mfma_f32_16x16x32_bf16 v[88:91], v[160:163], v[200:203], v[88:91]
	v_mfma_f32_16x16x32_bf16 v[76:79], v[152:155], v[208:211], v[76:79]
	v_mfma_f32_16x16x32_bf16 v[72:75], v[160:163], v[208:211], v[72:75]
	s_setprio 0
	s_setprio 1
	v_mfma_f32_16x16x32_bf16 v[124:127], v[164:167], v[180:183], v[124:127]
	v_mfma_f32_16x16x32_bf16 v[120:123], v[172:175], v[180:183], v[120:123]
	v_mfma_f32_16x16x32_bf16 v[100:103], v[164:167], v[188:191], v[100:103]
	v_mfma_f32_16x16x32_bf16 v[96:99], v[172:175], v[188:191], v[96:99]
	v_mfma_f32_16x16x32_bf16 v[84:87], v[164:167], v[196:199], v[84:87]
	v_mfma_f32_16x16x32_bf16 v[80:83], v[172:175], v[196:199], v[80:83]
	v_mfma_f32_16x16x32_bf16 v[68:71], v[164:167], v[204:207], v[68:71]
	v_mfma_f32_16x16x32_bf16 v[64:67], v[172:175], v[204:207], v[64:67]
	v_mfma_f32_16x16x32_bf16 v[124:127], v[168:171], v[184:187], v[124:127]
	v_mfma_f32_16x16x32_bf16 v[120:123], v[176:179], v[184:187], v[120:123]
	v_mfma_f32_16x16x32_bf16 v[100:103], v[168:171], v[192:195], v[100:103]
	v_mfma_f32_16x16x32_bf16 v[96:99], v[176:179], v[192:195], v[96:99]
	v_mfma_f32_16x16x32_bf16 v[84:87], v[168:171], v[200:203], v[84:87]
	v_mfma_f32_16x16x32_bf16 v[80:83], v[176:179], v[200:203], v[80:83]
	v_mfma_f32_16x16x32_bf16 v[68:71], v[168:171], v[208:211], v[68:71]
	v_mfma_f32_16x16x32_bf16 v[64:67], v[176:179], v[208:211], v[64:67]
	s_setprio 0
	s_barrier
	s_add_u32 s40, s40, s42
	s_addc_u32 s41, s41, s43
	s_add_i32 s13, s13, s33
	s_mov_b32 m0, s13
	ds_read_b128 v[180:183], v145 offset:49152
	ds_read_b128 v[184:187], v145 offset:50176
	ds_read_b128 v[188:191], v145 offset:51200
	ds_read_b128 v[192:195], v145 offset:52224
	ds_read_b128 v[196:199], v145 offset:53248
	ds_read_b128 v[200:203], v145 offset:54272
	ds_read_b128 v[204:207], v145 offset:55296
	ds_read_b128 v[208:211], v145 offset:56320
	global_load_lds_dwordx4 v132, s[40:41]
	s_add_i32 m0, s13, 0x2000
	v_lshl_add_u64 v[140:141], s[40:41], 0, v[128:129]
	s_add_u32 s40, s40, 0x80000
	s_addc_u32 s41, s41, 0
	s_add_i32 s13, s63, s33
	global_load_lds_dwordx4 v[140:141], off
	s_mov_b32 m0, s13
	s_nop 0
	global_load_lds_dwordx4 v132, s[40:41]
	s_add_i32 m0, s13, 0x2000
	s_nop 0
	global_load_lds_dwordx4 v128, s[40:41]
	s_mov_b32 m0, s53
	s_nop 0
	global_load_lds_dwordx4 v134, s[46:47]
	s_mov_b32 m0, s54
	s_nop 0
	global_load_lds_dwordx4 v130, s[46:47]
	s_waitcnt vmcnt(8)
	s_waitcnt lgkmcnt(0)
	s_barrier
	s_setprio 1
	s_waitcnt lgkmcnt(0)
	v_mfma_f32_16x16x32_bf16 v[60:63], v[148:151], v[180:183], v[60:63]
	v_mfma_f32_16x16x32_bf16 v[56:59], v[156:159], v[180:183], v[56:59]
	v_mfma_f32_16x16x32_bf16 v[44:47], v[148:151], v[188:191], v[44:47]
	v_mfma_f32_16x16x32_bf16 v[40:43], v[156:159], v[188:191], v[40:43]
	v_mfma_f32_16x16x32_bf16 v[28:31], v[148:151], v[196:199], v[28:31]
	v_mfma_f32_16x16x32_bf16 v[24:27], v[156:159], v[196:199], v[24:27]
	v_mfma_f32_16x16x32_bf16 v[12:15], v[148:151], v[204:207], v[12:15]
	v_mfma_f32_16x16x32_bf16 v[8:11], v[156:159], v[204:207], v[8:11]
	v_mfma_f32_16x16x32_bf16 v[60:63], v[152:155], v[184:187], v[60:63]
	v_mfma_f32_16x16x32_bf16 v[56:59], v[160:163], v[184:187], v[56:59]
	v_mfma_f32_16x16x32_bf16 v[44:47], v[152:155], v[192:195], v[44:47]
	v_mfma_f32_16x16x32_bf16 v[40:43], v[160:163], v[192:195], v[40:43]
	v_mfma_f32_16x16x32_bf16 v[28:31], v[152:155], v[200:203], v[28:31]
	v_mfma_f32_16x16x32_bf16 v[24:27], v[160:163], v[200:203], v[24:27]
	v_mfma_f32_16x16x32_bf16 v[12:15], v[152:155], v[208:211], v[12:15]
	v_mfma_f32_16x16x32_bf16 v[8:11], v[160:163], v[208:211], v[8:11]
	s_setprio 0
	s_setprio 1
	v_mfma_f32_16x16x32_bf16 v[52:55], v[164:167], v[180:183], v[52:55]
	v_mfma_f32_16x16x32_bf16 v[48:51], v[172:175], v[180:183], v[48:51]
	v_mfma_f32_16x16x32_bf16 v[36:39], v[164:167], v[188:191], v[36:39]
	v_mfma_f32_16x16x32_bf16 v[32:35], v[172:175], v[188:191], v[32:35]
	v_mfma_f32_16x16x32_bf16 v[20:23], v[164:167], v[196:199], v[20:23]
	v_mfma_f32_16x16x32_bf16 v[16:19], v[172:175], v[196:199], v[16:19]
	v_mfma_f32_16x16x32_bf16 v[4:7], v[164:167], v[204:207], v[4:7]
	v_mfma_f32_16x16x32_bf16 v[0:3], v[172:175], v[204:207], v[0:3]
	v_mfma_f32_16x16x32_bf16 v[52:55], v[168:171], v[184:187], v[52:55]
	v_mfma_f32_16x16x32_bf16 v[48:51], v[176:179], v[184:187], v[48:51]
	v_mfma_f32_16x16x32_bf16 v[36:39], v[168:171], v[192:195], v[36:39]
	v_mfma_f32_16x16x32_bf16 v[32:35], v[176:179], v[192:195], v[32:35]
	v_mfma_f32_16x16x32_bf16 v[20:23], v[168:171], v[200:203], v[20:23]
	v_mfma_f32_16x16x32_bf16 v[16:19], v[176:179], v[200:203], v[16:19]
	v_mfma_f32_16x16x32_bf16 v[4:7], v[168:171], v[208:211], v[4:7]
	v_mfma_f32_16x16x32_bf16 v[0:3], v[176:179], v[208:211], v[0:3]
	s_setprio 0
	s_barrier
	s_cmp_gt_u32 s62, 29
	s_mov_b32 s62, s11
	s_cbranch_scc1 .LBB0_126

; #define PG8_STAGE(bufoff, gbase, voff) do { _Pragma("unroll") for (int _i = 0; _i < 2; ++_i) \
;         __builtin_amdgcn_global_load_lds((const unsigned*)((const char*)(gbase) + (voff)[_i]), (LAS unsigned*)(lds + (bufoff) + ldsw + _i * 8192), 16, 0, 0); } while (0)
; #define PG8_WAIT_V(n) asm volatile("s_waitcnt vmcnt(" #n ")" ::: "memory")
; #define PG8_BAR __builtin_amdgcn_s_barrier()
; template <class Epi>
; __device__ __forceinline__ void gemm_phase(LAS unsigned char* lds, const Gemm g, const StaticOrder S, const Epi E) {
;     ...
;     for (int i = 0; i < 2; ++i) { int R, C; stage_rc(tid * 16 + i * 8192, R, C); const int Rb = Epi::PERM ? ((R & ~31) + perm32(R & 31)) : R;
;         voffA[i] = (unsigned)(R * g.lda + C) * 2u; voffB[i] = (unsigned)(Rb * g.ldb + C) * 2u; }
;     const size_t kstep = (size_t)(BK * 2);
;     const size_t hstepA = (size_t)HALF * g.lda * 2, hstepB = (size_t)HALF * g.ldb * 2;
;     const size_t tstepA = 2 * hstepA, tstepB = 2 * hstepB;
;     const unsigned ldsw = (unsigned)wid * 1024u;
;     const int aoff = lds_byte(wr * 64 + fr, fq * 8), boff = lds_byte(wc * 32 + fr, fq * 8);
;     ...
;     PG8_STAGE(PG8_SB(1, 0), cB + ksc, voffB); PG8_STAGE(PG8_SA(1, 0), cA + ksc, voffA); PG8_STAGE(PG8_SB(1, 1), cB + hstepB + ksc, voffB);
;     PG8_WAIT_V(6); PG8_BAR;
.LBB0_192:
	s_lshl_b32 s3, s3, 5
	s_and_b32 s3, s3, 0x60
	s_lshl_b32 s14, s0, 13
	s_lshl_b32 s15, s3, 7
	s_ashr_i32 s54, s79, 31
	s_add_u32 s12, s1, 0x2b00
	s_addc_u32 s13, s2, 0
	s_add_i32 m0, s50, 0x18000
	s_waitcnt vmcnt(2)
	s_barrier
	global_load_lds_dwordx4 v142, s[12:13]
	s_add_i32 m0, s50, 0x1a000
	v_lshl_add_u64 v[0:1], s[12:13], 0, v[146:147]
	s_add_u32 s12, s5, 0x2b00
	s_addc_u32 s13, s10, 0
	s_add_i32 s55, s50, 0x8000
	s_add_i32 s56, s50, 0xa000
	global_load_lds_dwordx4 v[0:1], off
	s_mov_b32 m0, s55
	s_add_u32 s10, s1, 0x162b00
	global_load_lds_dwordx4 v140, s[12:13]
	s_mov_b32 m0, s56
	s_addc_u32 s11, s2, 0
	global_load_lds_dwordx4 v144, s[12:13]
	s_add_i32 m0, s50, 0x1c000
	s_nop 0
	global_load_lds_dwordx4 v142, s[10:11]
	s_add_i32 m0, s50, 0x1e000
	v_and_b32_e32 v3, 32, v162
	global_load_lds_dwordx4 v146, s[10:11]
	v_and_b32_e32 v1, 3, v161
	v_and_b32_e32 v0, 15, v224
	v_lshlrev_b32_e32 v2, 4, v1
	v_lshl_or_b32 v163, s0, 6, v0
	v_lshl_or_b32 v0, v0, 6, v2
	s_ashr_i32 s57, s78, 31
	v_bitop3_b32 v0, v0, s14, v3 bitop3:0xde
	v_lshlrev_b32_e32 v4, 6, v224
	s_movk_i32 s0, 0x3c0
	s_waitcnt vmcnt(6)
	s_cmpk_lt_u32 s4, 0x100
	v_and_or_b32 v2, v4, s0, v2
	s_cselect_b64 s[10:11], -1, 0
	s_add_u32 s12, s82, 0x2a990000
	s_movk_i32 s34, 0xff80
	v_add_u32_e32 v166, 0, v0
	v_mbcnt_lo_u32_b32 v0, -1, 0
	v_bitop3_b32 v164, s15, v2, v3 bitop3:0xf6
	s_addc_u32 s13, s83, 0
	v_cmp_eq_u32_e64 s[0:1], 0, v1
	v_lshl_or_b32 v165, v1, 3, s3
	s_mov_b32 s35, -1
	v_mov_b64_e32 v[148:149], 0x200
	v_mov_b64_e32 v[150:151], 0x1ff
	s_movk_i32 s58, 0x80
	s_add_i32 s59, 0, 0x10000
	s_add_i32 s60, 0, 0x14000
	s_mov_b64 s[14:15], 0x80000
	s_mov_b32 s61, 0x80000
	s_mov_b64 s[16:17], 0x90000
	s_mov_b32 s62, 0x90000
	s_mov_b64 s[18:19], 0xa0000
	s_mov_b32 s63, 0xa0000
	s_mov_b64 s[20:21], 0xb0000
	s_mov_b32 s64, 0xb0000
	v_mbcnt_hi_u32_b32 v167, -1, v0
	s_barrier
	s_branch .LBB0_195

; #define PG8_STAGE(bufoff, gbase, voff) do { _Pragma("unroll") for (int _i = 0; _i < 2; ++_i) \
;         __builtin_amdgcn_global_load_lds((const unsigned*)((const char*)(gbase) + (voff)[_i]), (LAS unsigned*)(lds + (bufoff) + ldsw + _i * 8192), 16, 0, 0); } while (0)
; #define PG8_LDA(dst, b, h) do { _Pragma("unroll") for (int m = 0; m < 4; ++m) _Pragma("unroll") for (int k = 0; k < 2; ++k) dst[m][k] = *(const LAS bf16x8*)(lds + PG8_SA(b, h) + aoff + m * 2048 + k * 1024); } while (0)
; #define PG8_LDB(dst, b, h) do { _Pragma("unroll") for (int n = 0; n < 2; ++n) _Pragma("unroll") for (int k = 0; k < 2; ++k) dst[n][k] = *(const LAS bf16x8*)(lds + PG8_SB(b, h) + boff + n * 2048 + k * 1024); } while (0)
; #define PG8_MMA(ai, bj, At, Bt) do { __builtin_amdgcn_s_setprio(1); _Pragma("unroll") for (int m = 0; m < 4; ++m) _Pragma("unroll") for (int n = 0; n < 2; ++n) _Pragma("unroll") for (int k = 0; k < 2; ++k) \
;         acc[ai][bj][m][n] = __builtin_amdgcn_mfma_f32_16x16x32_bf16(Bt[n][k], At[m][k], acc[ai][bj][m][n], 0, 0, 0); __builtin_amdgcn_s_setprio(0); } while (0)
; #define PG8_WAIT_V(n) asm volatile("s_waitcnt vmcnt(" #n ")" ::: "memory")
; #define PG8_WAIT_L(n) asm volatile("s_waitcnt lgkmcnt(" #n ")" ::: "memory")
; #define PG8_BAR __builtin_amdgcn_s_barrier()
; #define PG8_SCHED __builtin_amdgcn_sched_barrier(0)
; template <class Epi>
; __device__ __forceinline__ void gemm_phase(LAS unsigned char* lds, const Gemm g, const StaticOrder S, const Epi E) {
;     ...
;             PG8_LDB(B0, 0, 0); PG8_LDB(B1, 0, 1); PG8_SCHED; PG8_LDA(At, 0, 0); PG8_STAGE(PG8_SA(1, 1), a1 + hstepA, voffA);
;             PG8_WAIT_V(8); PG8_WAIT_L(0); PG8_BAR; PG8_MMA(0, 0, At, B0); PG8_MMA(0, 1, At, B1); PG8_BAR; PG8_SCHED;
;             PG8_LDA(At, 0, 1); PG8_STAGE(PG8_SB(0, 0), b2, voffB); PG8_STAGE(PG8_SB(0, 1), b2 + hstepB, voffB); PG8_STAGE(PG8_SA(0, 0), a2, voffA);
;             PG8_WAIT_V(8); PG8_WAIT_L(0); PG8_BAR; PG8_MMA(1, 0, At, B0); PG8_MMA(1, 1, At, B1); PG8_BAR; PG8_SCHED;
.LBB0_206:
	v_add_u32_e32 v152, s59, v164
	v_add_u32_e32 v176, s60, v164
	ds_read_b128 v[128:131], v152
	ds_read_b128 v[132:135], v152 offset:1024
	ds_read_b128 v[136:139], v152 offset:2048
	ds_read_b128 v[152:155], v152 offset:3072
	ds_read_b128 v[156:159], v176
	ds_read_b128 v[168:171], v176 offset:1024
	ds_read_b128 v[172:175], v176 offset:2048
	ds_read_b128 v[176:179], v176 offset:3072
	s_or_b32 s48, s70, 1
	s_mul_i32 s49, s35, s48
	s_mul_hi_u32 s72, s34, s48
	s_add_i32 s72, s72, s49
	s_mul_i32 s48, s34, s48
	s_add_u32 s73, s30, s48
	s_addc_u32 s74, s31, s72
	s_add_u32 s48, s46, s44
	s_addc_u32 s49, s47, s45
	s_add_u32 s72, s73, 0x160000
	s_addc_u32 s73, s74, 0
	s_add_i32 m0, s50, 0xc000
	ds_read_b128 v[180:183], v166
	ds_read_b128 v[184:187], v166 offset:1024
	ds_read_b128 v[188:191], v166 offset:2048
	ds_read_b128 v[192:195], v166 offset:3072
	ds_read_b128 v[196:199], v166 offset:4096
	ds_read_b128 v[200:203], v166 offset:5120
	ds_read_b128 v[204:207], v166 offset:6144
	ds_read_b128 v[208:211], v166 offset:7168
	global_load_lds_dwordx4 v140, s[72:73]
	s_add_i32 m0, s50, 0xe000
	s_nop 0
	global_load_lds_dwordx4 v144, s[72:73]
	s_waitcnt vmcnt(8)
	s_waitcnt lgkmcnt(0)
	s_barrier
	s_setprio 1
	s_waitcnt lgkmcnt(0)
	v_mfma_f32_16x16x32_bf16 v[124:127], v[128:131], v[180:183], v[124:127]
	v_mfma_f32_16x16x32_bf16 v[120:123], v[136:139], v[180:183], v[120:123]
	v_mfma_f32_16x16x32_bf16 v[108:111], v[128:131], v[188:191], v[108:111]
	v_mfma_f32_16x16x32_bf16 v[104:107], v[136:139], v[188:191], v[104:107]
	v_mfma_f32_16x16x32_bf16 v[92:95], v[128:131], v[196:199], v[92:95]
	v_mfma_f32_16x16x32_bf16 v[88:91], v[136:139], v[196:199], v[88:91]
	v_mfma_f32_16x16x32_bf16 v[76:79], v[128:131], v[204:207], v[76:79]
	v_mfma_f32_16x16x32_bf16 v[72:75], v[136:139], v[204:207], v[72:75]
	v_mfma_f32_16x16x32_bf16 v[124:127], v[132:135], v[184:187], v[124:127]
	v_mfma_f32_16x16x32_bf16 v[120:123], v[152:155], v[184:187], v[120:123]
	v_mfma_f32_16x16x32_bf16 v[108:111], v[132:135], v[192:195], v[108:111]
	v_mfma_f32_16x16x32_bf16 v[104:107], v[152:155], v[192:195], v[104:107]
	v_mfma_f32_16x16x32_bf16 v[92:95], v[132:135], v[200:203], v[92:95]
	v_mfma_f32_16x16x32_bf16 v[88:91], v[152:155], v[200:203], v[88:91]
	v_mfma_f32_16x16x32_bf16 v[76:79], v[132:135], v[208:211], v[76:79]
	v_mfma_f32_16x16x32_bf16 v[72:75], v[152:155], v[208:211], v[72:75]
	s_setprio 0
	s_setprio 1
	v_mfma_f32_16x16x32_bf16 v[116:119], v[156:159], v[180:183], v[116:119]
	v_mfma_f32_16x16x32_bf16 v[112:115], v[172:175], v[180:183], v[112:115]
	v_mfma_f32_16x16x32_bf16 v[100:103], v[156:159], v[188:191], v[100:103]
	v_mfma_f32_16x16x32_bf16 v[96:99], v[172:175], v[188:191], v[96:99]
	v_mfma_f32_16x16x32_bf16 v[84:87], v[156:159], v[196:199], v[84:87]
	v_mfma_f32_16x16x32_bf16 v[80:83], v[172:175], v[196:199], v[80:83]
	v_mfma_f32_16x16x32_bf16 v[68:71], v[156:159], v[204:207], v[68:71]
	v_mfma_f32_16x16x32_bf16 v[64:67], v[172:175], v[204:207], v[64:67]
	v_mfma_f32_16x16x32_bf16 v[116:119], v[168:171], v[184:187], v[116:119]
	v_mfma_f32_16x16x32_bf16 v[112:115], v[176:179], v[184:187], v[112:115]
	v_mfma_f32_16x16x32_bf16 v[100:103], v[168:171], v[192:195], v[100:103]
	v_mfma_f32_16x16x32_bf16 v[96:99], v[176:179], v[192:195], v[96:99]
	v_mfma_f32_16x16x32_bf16 v[84:87], v[168:171], v[200:203], v[84:87]
	v_mfma_f32_16x16x32_bf16 v[80:83], v[176:179], v[200:203], v[80:83]
	v_mfma_f32_16x16x32_bf16 v[68:71], v[168:171], v[208:211], v[68:71]
	v_mfma_f32_16x16x32_bf16 v[64:67], v[176:179], v[208:211], v[64:67]
	s_setprio 0
	s_barrier
	s_add_i32 s72, s59, s33
	s_mov_b32 m0, s72
	ds_read_b128 v[180:183], v166 offset:16384
	ds_read_b128 v[184:187], v166 offset:17408
	ds_read_b128 v[188:191], v166 offset:18432
	ds_read_b128 v[192:195], v166 offset:19456
	ds_read_b128 v[196:199], v166 offset:20480
	ds_read_b128 v[200:203], v166 offset:21504
	ds_read_b128 v[204:207], v166 offset:22528
	ds_read_b128 v[208:211], v166 offset:23552
	global_load_lds_dwordx4 v142, s[42:43]
	s_add_i32 m0, s72, 0x2000
	s_add_u32 s72, s42, 0x160000
	s_addc_u32 s73, s43, 0
	s_add_i32 s74, s60, s33
	global_load_lds_dwordx4 v146, s[42:43]
	s_mov_b32 m0, s74
	s_nop 0
	global_load_lds_dwordx4 v142, s[72:73]
	s_add_i32 m0, s74, 0x2000
	s_nop 0
	global_load_lds_dwordx4 v146, s[72:73]
	s_mov_b32 m0, s50
	s_nop 0
	global_load_lds_dwordx4 v140, s[46:47]
	s_mov_b32 m0, s51
	s_nop 0
	global_load_lds_dwordx4 v144, s[46:47]
	s_waitcnt vmcnt(8)
	s_waitcnt lgkmcnt(0)
	s_barrier
	s_setprio 1
	s_waitcnt lgkmcnt(0)
	v_mfma_f32_16x16x32_bf16 v[60:63], v[128:131], v[180:183], v[60:63]
	v_mfma_f32_16x16x32_bf16 v[56:59], v[136:139], v[180:183], v[56:59]
	v_mfma_f32_16x16x32_bf16 v[44:47], v[128:131], v[188:191], v[44:47]
	v_mfma_f32_16x16x32_bf16 v[40:43], v[136:139], v[188:191], v[40:43]
	v_mfma_f32_16x16x32_bf16 v[28:31], v[128:131], v[196:199], v[28:31]
	v_mfma_f32_16x16x32_bf16 v[24:27], v[136:139], v[196:199], v[24:27]
	v_mfma_f32_16x16x32_bf16 v[12:15], v[128:131], v[204:207], v[12:15]
	v_mfma_f32_16x16x32_bf16 v[8:11], v[136:139], v[204:207], v[8:11]
	v_mfma_f32_16x16x32_bf16 v[60:63], v[132:135], v[184:187], v[60:63]
	v_mfma_f32_16x16x32_bf16 v[56:59], v[152:155], v[184:187], v[56:59]
	v_mfma_f32_16x16x32_bf16 v[44:47], v[132:135], v[192:195], v[44:47]
	v_mfma_f32_16x16x32_bf16 v[40:43], v[152:155], v[192:195], v[40:43]
	v_mfma_f32_16x16x32_bf16 v[28:31], v[132:135], v[200:203], v[28:31]
	v_mfma_f32_16x16x32_bf16 v[24:27], v[152:155], v[200:203], v[24:27]
	v_mfma_f32_16x16x32_bf16 v[12:15], v[132:135], v[208:211], v[12:15]
	v_mfma_f32_16x16x32_bf16 v[8:11], v[152:155], v[208:211], v[8:11]
	s_setprio 0
	s_setprio 1
	v_mfma_f32_16x16x32_bf16 v[52:55], v[156:159], v[180:183], v[52:55]
	v_mfma_f32_16x16x32_bf16 v[48:51], v[172:175], v[180:183], v[48:51]
	v_mfma_f32_16x16x32_bf16 v[36:39], v[156:159], v[188:191], v[36:39]
	v_mfma_f32_16x16x32_bf16 v[32:35], v[172:175], v[188:191], v[32:35]
	v_mfma_f32_16x16x32_bf16 v[20:23], v[156:159], v[196:199], v[20:23]
	v_mfma_f32_16x16x32_bf16 v[16:19], v[172:175], v[196:199], v[16:19]
	v_mfma_f32_16x16x32_bf16 v[4:7], v[156:159], v[204:207], v[4:7]
	v_mfma_f32_16x16x32_bf16 v[0:3], v[172:175], v[204:207], v[0:3]
	v_mfma_f32_16x16x32_bf16 v[52:55], v[168:171], v[184:187], v[52:55]
	v_mfma_f32_16x16x32_bf16 v[48:51], v[176:179], v[184:187], v[48:51]
	v_mfma_f32_16x16x32_bf16 v[36:39], v[168:171], v[192:195], v[36:39]
	v_mfma_f32_16x16x32_bf16 v[32:35], v[176:179], v[192:195], v[32:35]
	v_mfma_f32_16x16x32_bf16 v[20:23], v[168:171], v[200:203], v[20:23]
	v_mfma_f32_16x16x32_bf16 v[16:19], v[176:179], v[200:203], v[16:19]
	v_mfma_f32_16x16x32_bf16 v[4:7], v[168:171], v[208:211], v[4:7]
	v_mfma_f32_16x16x32_bf16 v[0:3], v[176:179], v[208:211], v[0:3]
	s_setprio 0
	s_barrier
; #define PG8_STAGE(bufoff, gbase, voff) do { _Pragma("unroll") for (int _i = 0; _i < 2; ++_i) \
;         __builtin_amdgcn_global_load_lds((const unsigned*)((const char*)(gbase) + (voff)[_i]), (LAS unsigned*)(lds + (bufoff) + ldsw + _i * 8192), 16, 0, 0); } while (0)
; #define PG8_LDA(dst, b, h) do { _Pragma("unroll") for (int m = 0; m < 4; ++m) _Pragma("unroll") for (int k = 0; k < 2; ++k) dst[m][k] = *(const LAS bf16x8*)(lds + PG8_SA(b, h) + aoff + m * 2048 + k * 1024); } while (0)
; #define PG8_LDB(dst, b, h) do { _Pragma("unroll") for (int n = 0; n < 2; ++n) _Pragma("unroll") for (int k = 0; k < 2; ++k) dst[n][k] = *(const LAS bf16x8*)(lds + PG8_SB(b, h) + boff + n * 2048 + k * 1024); } while (0)
; #define PG8_MMA(ai, bj, At, Bt) do { __builtin_amdgcn_s_setprio(1); _Pragma("unroll") for (int m = 0; m < 4; ++m) _Pragma("unroll") for (int n = 0; n < 2; ++n) _Pragma("unroll") for (int k = 0; k < 2; ++k) \
;         acc[ai][bj][m][n] = __builtin_amdgcn_mfma_f32_16x16x32_bf16(Bt[n][k], At[m][k], acc[ai][bj][m][n], 0, 0, 0); __builtin_amdgcn_s_setprio(0); } while (0)
; #define PG8_WAIT_V(n) asm volatile("s_waitcnt vmcnt(" #n ")" ::: "memory")
; #define PG8_WAIT_L(n) asm volatile("s_waitcnt lgkmcnt(" #n ")" ::: "memory")
; #define PG8_BAR __builtin_amdgcn_s_barrier()
; #define PG8_SCHED __builtin_amdgcn_sched_barrier(0)
; template <class Epi>
; __device__ __forceinline__ void gemm_phase(LAS unsigned char* lds, const Gemm g, const StaticOrder S, const Epi E) {
;     ...
;             PG8_LDB(B0, 1, 0); PG8_LDB(B1, 1, 1); PG8_SCHED; PG8_LDA(At, 1, 0); PG8_STAGE(PG8_SA(0, 1), a2 + hstepA, voffA);
;             PG8_WAIT_V(8); PG8_WAIT_L(0); PG8_BAR; PG8_MMA(0, 0, At, B0); PG8_MMA(0, 1, At, B1); PG8_BAR; PG8_SCHED;
;             PG8_LDA(At, 1, 1); PG8_STAGE(PG8_SB(1, 0), b3, voffB); PG8_STAGE(PG8_SB(1, 1), b3 + hstepB, voffB); PG8_STAGE(PG8_SA(1, 0), a3, voffA);
;             PG8_WAIT_V(8); PG8_WAIT_L(0); PG8_BAR; PG8_MMA(1, 0, At, B0); PG8_MMA(1, 1, At, B1); PG8_BAR; PG8_SCHED;
;         }
	s_add_i32 s72, 0, 0x18000
	s_add_i32 s73, 0, 0x1c000
	v_add_u32_e32 v152, s72, v164
	v_add_u32_e32 v176, s73, v164
	ds_read_b128 v[128:131], v152
	ds_read_b128 v[132:135], v152 offset:1024
	ds_read_b128 v[136:139], v152 offset:2048
	ds_read_b128 v[152:155], v152 offset:3072
	ds_read_b128 v[156:159], v176
	ds_read_b128 v[168:171], v176 offset:1024
	ds_read_b128 v[172:175], v176 offset:2048
	ds_read_b128 v[176:179], v176 offset:3072
	s_add_u32 s46, s46, 0x160000
	s_addc_u32 s47, s47, 0
	s_mov_b32 m0, s52
	ds_read_b128 v[180:183], v166 offset:32768
	ds_read_b128 v[184:187], v166 offset:33792
	ds_read_b128 v[188:191], v166 offset:34816
	ds_read_b128 v[192:195], v166 offset:35840
	ds_read_b128 v[196:199], v166 offset:36864
	ds_read_b128 v[200:203], v166 offset:37888
	ds_read_b128 v[204:207], v166 offset:38912
	ds_read_b128 v[208:211], v166 offset:39936
	global_load_lds_dwordx4 v140, s[46:47]
	s_mov_b32 m0, s53
	s_nop 0
	global_load_lds_dwordx4 v144, s[46:47]
	s_waitcnt vmcnt(8)
	s_waitcnt lgkmcnt(0)
	s_barrier
	s_setprio 1
	s_waitcnt lgkmcnt(0)
	v_mfma_f32_16x16x32_bf16 v[124:127], v[128:131], v[180:183], v[124:127]
	v_mfma_f32_16x16x32_bf16 v[120:123], v[136:139], v[180:183], v[120:123]
	v_mfma_f32_16x16x32_bf16 v[108:111], v[128:131], v[188:191], v[108:111]
	v_mfma_f32_16x16x32_bf16 v[104:107], v[136:139], v[188:191], v[104:107]
	v_mfma_f32_16x16x32_bf16 v[92:95], v[128:131], v[196:199], v[92:95]
	v_mfma_f32_16x16x32_bf16 v[88:91], v[136:139], v[196:199], v[88:91]
	v_mfma_f32_16x16x32_bf16 v[76:79], v[128:131], v[204:207], v[76:79]
	v_mfma_f32_16x16x32_bf16 v[72:75], v[136:139], v[204:207], v[72:75]
	v_mfma_f32_16x16x32_bf16 v[124:127], v[132:135], v[184:187], v[124:127]
	v_mfma_f32_16x16x32_bf16 v[120:123], v[152:155], v[184:187], v[120:123]
	v_mfma_f32_16x16x32_bf16 v[108:111], v[132:135], v[192:195], v[108:111]
	v_mfma_f32_16x16x32_bf16 v[104:107], v[152:155], v[192:195], v[104:107]
	v_mfma_f32_16x16x32_bf16 v[92:95], v[132:135], v[200:203], v[92:95]
	v_mfma_f32_16x16x32_bf16 v[88:91], v[152:155], v[200:203], v[88:91]
	v_mfma_f32_16x16x32_bf16 v[76:79], v[132:135], v[208:211], v[76:79]
	v_mfma_f32_16x16x32_bf16 v[72:75], v[152:155], v[208:211], v[72:75]
	s_setprio 0
	s_setprio 1
	v_mfma_f32_16x16x32_bf16 v[116:119], v[156:159], v[180:183], v[116:119]
	v_mfma_f32_16x16x32_bf16 v[112:115], v[172:175], v[180:183], v[112:115]
	v_mfma_f32_16x16x32_bf16 v[100:103], v[156:159], v[188:191], v[100:103]
	v_mfma_f32_16x16x32_bf16 v[96:99], v[172:175], v[188:191], v[96:99]
	v_mfma_f32_16x16x32_bf16 v[84:87], v[156:159], v[196:199], v[84:87]
	v_mfma_f32_16x16x32_bf16 v[80:83], v[172:175], v[196:199], v[80:83]
	v_mfma_f32_16x16x32_bf16 v[68:71], v[156:159], v[204:207], v[68:71]
	v_mfma_f32_16x16x32_bf16 v[64:67], v[172:175], v[204:207], v[64:67]
	v_mfma_f32_16x16x32_bf16 v[116:119], v[168:171], v[184:187], v[116:119]
	v_mfma_f32_16x16x32_bf16 v[112:115], v[176:179], v[184:187], v[112:115]
	v_mfma_f32_16x16x32_bf16 v[100:103], v[168:171], v[192:195], v[100:103]
	v_mfma_f32_16x16x32_bf16 v[96:99], v[176:179], v[192:195], v[96:99]
	v_mfma_f32_16x16x32_bf16 v[84:87], v[168:171], v[200:203], v[84:87]
	v_mfma_f32_16x16x32_bf16 v[80:83], v[176:179], v[200:203], v[80:83]
	v_mfma_f32_16x16x32_bf16 v[68:71], v[168:171], v[208:211], v[68:71]
	v_mfma_f32_16x16x32_bf16 v[64:67], v[176:179], v[208:211], v[64:67]
	s_setprio 0
	s_barrier
	s_add_u32 s42, s42, s44
	s_addc_u32 s43, s43, s45
	s_add_i32 s44, s72, s33
	s_mov_b32 m0, s44
	ds_read_b128 v[180:183], v166 offset:49152
	ds_read_b128 v[184:187], v166 offset:50176
	ds_read_b128 v[188:191], v166 offset:51200
	ds_read_b128 v[192:195], v166 offset:52224
	ds_read_b128 v[196:199], v166 offset:53248
	ds_read_b128 v[200:203], v166 offset:54272
	ds_read_b128 v[204:207], v166 offset:55296
	ds_read_b128 v[208:211], v166 offset:56320
	global_load_lds_dwordx4 v142, s[42:43]
	s_add_i32 m0, s44, 0x2000
	v_lshl_add_u64 v[212:213], s[42:43], 0, v[146:147]
	s_add_u32 s42, s42, 0x160000
	s_addc_u32 s43, s43, 0
	s_add_i32 s44, s73, s33
	global_load_lds_dwordx4 v[212:213], off
	s_mov_b32 m0, s44
	s_nop 0
	global_load_lds_dwordx4 v142, s[42:43]
	s_add_i32 m0, s44, 0x2000
	s_nop 0
	global_load_lds_dwordx4 v146, s[42:43]
	s_mov_b32 m0, s55
	s_nop 0
	global_load_lds_dwordx4 v140, s[48:49]
	s_mov_b32 m0, s56
	s_nop 0
	global_load_lds_dwordx4 v144, s[48:49]
	s_waitcnt vmcnt(8)
	s_waitcnt lgkmcnt(0)
	s_barrier
	s_setprio 1
	s_waitcnt lgkmcnt(0)
	v_mfma_f32_16x16x32_bf16 v[60:63], v[128:131], v[180:183], v[60:63]
	v_mfma_f32_16x16x32_bf16 v[56:59], v[136:139], v[180:183], v[56:59]
	v_mfma_f32_16x16x32_bf16 v[44:47], v[128:131], v[188:191], v[44:47]
	v_mfma_f32_16x16x32_bf16 v[40:43], v[136:139], v[188:191], v[40:43]
	v_mfma_f32_16x16x32_bf16 v[28:31], v[128:131], v[196:199], v[28:31]
	v_mfma_f32_16x16x32_bf16 v[24:27], v[136:139], v[196:199], v[24:27]
	v_mfma_f32_16x16x32_bf16 v[12:15], v[128:131], v[204:207], v[12:15]
	v_mfma_f32_16x16x32_bf16 v[8:11], v[136:139], v[204:207], v[8:11]
	v_mfma_f32_16x16x32_bf16 v[60:63], v[132:135], v[184:187], v[60:63]
	v_mfma_f32_16x16x32_bf16 v[56:59], v[152:155], v[184:187], v[56:59]
	v_mfma_f32_16x16x32_bf16 v[44:47], v[132:135], v[192:195], v[44:47]
	v_mfma_f32_16x16x32_bf16 v[40:43], v[152:155], v[192:195], v[40:43]
	v_mfma_f32_16x16x32_bf16 v[28:31], v[132:135], v[200:203], v[28:31]
	v_mfma_f32_16x16x32_bf16 v[24:27], v[152:155], v[200:203], v[24:27]
	v_mfma_f32_16x16x32_bf16 v[12:15], v[132:135], v[208:211], v[12:15]
	v_mfma_f32_16x16x32_bf16 v[8:11], v[152:155], v[208:211], v[8:11]
	s_setprio 0
	s_setprio 1
	v_mfma_f32_16x16x32_bf16 v[52:55], v[156:159], v[180:183], v[52:55]
	v_mfma_f32_16x16x32_bf16 v[48:51], v[172:175], v[180:183], v[48:51]
	v_mfma_f32_16x16x32_bf16 v[36:39], v[156:159], v[188:191], v[36:39]
	v_mfma_f32_16x16x32_bf16 v[32:35], v[172:175], v[188:191], v[32:35]
	v_mfma_f32_16x16x32_bf16 v[20:23], v[156:159], v[196:199], v[20:23]
	v_mfma_f32_16x16x32_bf16 v[16:19], v[172:175], v[196:199], v[16:19]
	v_mfma_f32_16x16x32_bf16 v[4:7], v[156:159], v[204:207], v[4:7]
	v_mfma_f32_16x16x32_bf16 v[0:3], v[172:175], v[204:207], v[0:3]
	v_mfma_f32_16x16x32_bf16 v[52:55], v[168:171], v[184:187], v[52:55]
	v_mfma_f32_16x16x32_bf16 v[48:51], v[176:179], v[184:187], v[48:51]
	v_mfma_f32_16x16x32_bf16 v[36:39], v[168:171], v[192:195], v[36:39]
	v_mfma_f32_16x16x32_bf16 v[32:35], v[176:179], v[192:195], v[32:35]
	v_mfma_f32_16x16x32_bf16 v[20:23], v[168:171], v[200:203], v[20:23]
	v_mfma_f32_16x16x32_bf16 v[16:19], v[176:179], v[200:203], v[16:19]
	v_mfma_f32_16x16x32_bf16 v[4:7], v[168:171], v[208:211], v[4:7]
	v_mfma_f32_16x16x32_bf16 v[0:3], v[176:179], v[208:211], v[0:3]
	s_setprio 0
	s_barrier
	s_cmpk_gt_u32 s70, 0x55
	s_mov_b32 s70, s71
	s_cbranch_scc1 .LBB0_211

; #define PG8_STAGE(bufoff, gbase, voff) do { _Pragma("unroll") for (int _i = 0; _i < 2; ++_i) \
;         __builtin_amdgcn_global_load_lds((const unsigned*)((const char*)(gbase) + (voff)[_i]), (LAS unsigned*)(lds + (bufoff) + ldsw + _i * 8192), 16, 0, 0); } while (0)
; #define PG8_WAIT_V(n) asm volatile("s_waitcnt vmcnt(" #n ")" ::: "memory")
; #define PG8_BAR __builtin_amdgcn_s_barrier()
; template <class Epi>
; __device__ __forceinline__ void gemm_phase(LAS unsigned char* lds, const Gemm g, const StaticOrder S, const Epi E) {
;     ...
;     for (int i = 0; i < 2; ++i) { int R, C; stage_rc(tid * 16 + i * 8192, R, C); const int Rb = Epi::PERM ? ((R & ~31) + perm32(R & 31)) : R;
;         voffA[i] = (unsigned)(R * g.lda + C) * 2u; voffB[i] = (unsigned)(Rb * g.ldb + C) * 2u; }
;     const size_t kstep = (size_t)(BK * 2);
;     const size_t hstepA = (size_t)HALF * g.lda * 2, hstepB = (size_t)HALF * g.ldb * 2;
;     const size_t tstepA = 2 * hstepA, tstepB = 2 * hstepB;
;     const unsigned ldsw = (unsigned)wid * 1024u;
;     const int aoff = lds_byte(wr * 64 + fr, fq * 8), boff = lds_byte(wc * 32 + fr, fq * 8);
;     ...
;     PG8_STAGE(PG8_SB(1, 0), cB + ksc, voffB); PG8_STAGE(PG8_SA(1, 0), cA + ksc, voffA); PG8_STAGE(PG8_SB(1, 1), cB + hstepB + ksc, voffB);
;     PG8_WAIT_V(6); PG8_BAR;
.LBB0_296:
	s_add_u32 s8, s82, 0x2a990000
	s_addc_u32 s9, s83, 0
	s_lshl_b32 s3, s3, 5
	s_mov_b64 s[44:45], 0x80
	s_and_b32 s3, s3, 0x60
	s_add_i32 m0, s31, 0x18000
	v_lshl_add_u64 v[6:7], v[6:7], 0, s[44:45]
	s_lshl_b32 s12, s1, 13
	s_lshl_b32 s13, s3, 7
	s_waitcnt vmcnt(2)
	s_barrier
	global_load_lds_dwordx4 v[6:7], off
	v_lshl_add_u64 v[4:5], v[4:5], 0, s[44:45]
	s_add_i32 m0, s31, 0x1a000
	s_add_i32 s58, s31, 0x8000
	s_add_i32 s59, s31, 0xa000
	global_load_lds_dwordx4 v[4:5], off
	v_lshl_add_u64 v[0:1], v[0:1], 0, s[44:45]
	s_mov_b32 m0, s58
	s_add_u32 s10, s34, 0x80080
	global_load_lds_dwordx4 v[0:1], off
	v_lshl_add_u64 v[0:1], v[2:3], 0, s[44:45]
	s_mov_b32 m0, s59
	s_addc_u32 s11, s35, 0
	global_load_lds_dwordx4 v[0:1], off
	s_add_i32 m0, s31, 0x1c000
	s_nop 0
	global_load_lds_dwordx4 v130, s[10:11]
	s_add_i32 m0, s31, 0x1e000
	v_lshlrev_b32_e32 v2, 2, v224
	global_load_lds_dwordx4 v134, s[10:11]
	v_and_b32_e32 v0, 15, v224
	v_lshlrev_b32_e32 v1, 1, v8
	s_sext_i32_i8 s69, s0
	v_lshl_or_b32 v142, s1, 6, v0
	v_lshl_or_b32 v0, v0, 6, v1
	v_and_b32_e32 v2, 32, v2
	v_lshlrev_b32_e32 v3, 6, v224
	s_movk_i32 s0, 0x3c0
	s_waitcnt vmcnt(6)
	s_ashr_i32 s60, s78, 31
	v_bitop3_b32 v0, v0, s12, v2 bitop3:0xde
	v_and_or_b32 v1, v3, s0, v1
	s_cmpk_lt_u32 s2, 0x100
	v_bitop3_b32 v143, s13, v1, v2 bitop3:0xf6
	s_cselect_b64 s[10:11], -1, 0
	v_or_b32_e32 v144, s3, v8
	v_mov_b64_e32 v[136:137], 0x400
	v_mov_b64_e32 v[138:139], 0x3ff
	s_movk_i32 s61, 0x80
	s_add_i32 s62, 0, 0x10000
	s_add_i32 s63, 0, 0x14000
	v_add_u32_e32 v145, 0, v0
	v_mov_b32_e32 v146, 0x358637bd
	s_mov_b64 s[12:13], 0x100000
	s_mov_b32 s64, 0x100000
	s_mov_b64 s[14:15], 0x120000
	s_mov_b32 s65, 0x120000
	s_mov_b64 s[16:17], 0x140000
	s_mov_b32 s66, 0x140000
	s_mov_b64 s[18:19], 0x160000
	s_mov_b32 s67, 0x160000
	s_barrier
	s_branch .LBB0_299

; #define PG8_STAGE(bufoff, gbase, voff) do { _Pragma("unroll") for (int _i = 0; _i < 2; ++_i) \
;         __builtin_amdgcn_global_load_lds((const unsigned*)((const char*)(gbase) + (voff)[_i]), (LAS unsigned*)(lds + (bufoff) + ldsw + _i * 8192), 16, 0, 0); } while (0)
; #define PG8_LDA(dst, b, h) do { _Pragma("unroll") for (int m = 0; m < 4; ++m) _Pragma("unroll") for (int k = 0; k < 2; ++k) dst[m][k] = *(const LAS bf16x8*)(lds + PG8_SA(b, h) + aoff + m * 2048 + k * 1024); } while (0)
; #define PG8_LDB(dst, b, h) do { _Pragma("unroll") for (int n = 0; n < 2; ++n) _Pragma("unroll") for (int k = 0; k < 2; ++k) dst[n][k] = *(const LAS bf16x8*)(lds + PG8_SB(b, h) + boff + n * 2048 + k * 1024); } while (0)
; #define PG8_MMA(ai, bj, At, Bt) do { __builtin_amdgcn_s_setprio(1); _Pragma("unroll") for (int m = 0; m < 4; ++m) _Pragma("unroll") for (int n = 0; n < 2; ++n) _Pragma("unroll") for (int k = 0; k < 2; ++k) \
;         acc[ai][bj][m][n] = __builtin_amdgcn_mfma_f32_16x16x32_bf16(Bt[n][k], At[m][k], acc[ai][bj][m][n], 0, 0, 0); __builtin_amdgcn_s_setprio(0); } while (0)
; #define PG8_WAIT_V(n) asm volatile("s_waitcnt vmcnt(" #n ")" ::: "memory")
; #define PG8_WAIT_L(n) asm volatile("s_waitcnt lgkmcnt(" #n ")" ::: "memory")
; #define PG8_BAR __builtin_amdgcn_s_barrier()
; #define PG8_SCHED __builtin_amdgcn_sched_barrier(0)
; template <class Epi>
; __device__ __forceinline__ void gemm_phase(LAS unsigned char* lds, const Gemm g, const StaticOrder S, const Epi E) {
;     ...
;             PG8_LDB(B0, 0, 0); PG8_LDB(B1, 0, 1); PG8_SCHED; PG8_LDA(At, 0, 0); PG8_STAGE(PG8_SA(1, 1), a1 + hstepA, voffA);
;             PG8_WAIT_V(8); PG8_WAIT_L(0); PG8_BAR; PG8_MMA(0, 0, At, B0); PG8_MMA(0, 1, At, B1); PG8_BAR; PG8_SCHED;
;             PG8_LDA(At, 0, 1); PG8_STAGE(PG8_SB(0, 0), b2, voffB); PG8_STAGE(PG8_SB(0, 1), b2 + hstepB, voffB); PG8_STAGE(PG8_SA(0, 0), a2, voffA);
;             PG8_WAIT_V(8); PG8_WAIT_L(0); PG8_BAR; PG8_MMA(1, 0, At, B0); PG8_MMA(1, 1, At, B1); PG8_BAR; PG8_SCHED;
.LBB0_310:
	v_add_u32_e32 v140, s62, v143
	ds_read_b128 v[148:151], v140
	ds_read_b128 v[152:155], v140 offset:1024
	ds_read_b128 v[156:159], v140 offset:2048
	ds_read_b128 v[160:163], v140 offset:3072
	v_add_u32_e32 v140, s63, v143
	ds_read_b128 v[164:167], v140
	ds_read_b128 v[168:171], v140 offset:1024
	ds_read_b128 v[172:175], v140 offset:2048
	ds_read_b128 v[176:179], v140 offset:3072
	s_or_b32 s52, s70, 1
	s_mul_i32 s53, s45, s52
	s_mul_hi_u32 s72, s44, s52
	s_add_i32 s73, s72, s53
	s_mul_i32 s72, s44, s52
	s_add_u32 s52, s50, s48
	s_addc_u32 s53, s51, s49
	s_add_u32 s72, s21, s72
	s_addc_u32 s73, s23, s73
	s_add_i32 m0, s31, 0xc000
	ds_read_b128 v[180:183], v145
	ds_read_b128 v[184:187], v145 offset:1024
	ds_read_b128 v[188:191], v145 offset:2048
	ds_read_b128 v[192:195], v145 offset:3072
	ds_read_b128 v[196:199], v145 offset:4096
	ds_read_b128 v[200:203], v145 offset:5120
	ds_read_b128 v[204:207], v145 offset:6144
	ds_read_b128 v[208:211], v145 offset:7168
	global_load_lds_dwordx4 v128, s[72:73]
	s_add_i32 m0, s31, 0xe000
	s_nop 0
	global_load_lds_dwordx4 v132, s[72:73]
	s_waitcnt vmcnt(8)
	s_waitcnt lgkmcnt(0)
	s_barrier
	s_setprio 1
	s_waitcnt lgkmcnt(0)
	v_mfma_f32_16x16x32_bf16 v[124:127], v[148:151], v[180:183], v[124:127]
	v_mfma_f32_16x16x32_bf16 v[120:123], v[156:159], v[180:183], v[120:123]
	v_mfma_f32_16x16x32_bf16 v[116:119], v[148:151], v[188:191], v[116:119]
	v_mfma_f32_16x16x32_bf16 v[112:115], v[156:159], v[188:191], v[112:115]
	v_mfma_f32_16x16x32_bf16 v[108:111], v[148:151], v[196:199], v[108:111]
	v_mfma_f32_16x16x32_bf16 v[100:103], v[156:159], v[196:199], v[100:103]
	v_mfma_f32_16x16x32_bf16 v[76:79], v[148:151], v[204:207], v[76:79]
	v_mfma_f32_16x16x32_bf16 v[72:75], v[156:159], v[204:207], v[72:75]
	v_mfma_f32_16x16x32_bf16 v[124:127], v[152:155], v[184:187], v[124:127]
	v_mfma_f32_16x16x32_bf16 v[120:123], v[160:163], v[184:187], v[120:123]
	v_mfma_f32_16x16x32_bf16 v[116:119], v[152:155], v[192:195], v[116:119]
	v_mfma_f32_16x16x32_bf16 v[112:115], v[160:163], v[192:195], v[112:115]
	v_mfma_f32_16x16x32_bf16 v[108:111], v[152:155], v[200:203], v[108:111]
	v_mfma_f32_16x16x32_bf16 v[100:103], v[160:163], v[200:203], v[100:103]
	v_mfma_f32_16x16x32_bf16 v[76:79], v[152:155], v[208:211], v[76:79]
	v_mfma_f32_16x16x32_bf16 v[72:75], v[160:163], v[208:211], v[72:75]
	s_setprio 0
	s_setprio 1
	v_mfma_f32_16x16x32_bf16 v[104:107], v[164:167], v[180:183], v[104:107]
	v_mfma_f32_16x16x32_bf16 v[96:99], v[172:175], v[180:183], v[96:99]
	v_mfma_f32_16x16x32_bf16 v[92:95], v[164:167], v[188:191], v[92:95]
	v_mfma_f32_16x16x32_bf16 v[88:91], v[172:175], v[188:191], v[88:91]
	v_mfma_f32_16x16x32_bf16 v[84:87], v[164:167], v[196:199], v[84:87]
	v_mfma_f32_16x16x32_bf16 v[80:83], v[172:175], v[196:199], v[80:83]
	v_mfma_f32_16x16x32_bf16 v[68:71], v[164:167], v[204:207], v[68:71]
	v_mfma_f32_16x16x32_bf16 v[64:67], v[172:175], v[204:207], v[64:67]
	v_mfma_f32_16x16x32_bf16 v[104:107], v[168:171], v[184:187], v[104:107]
	v_mfma_f32_16x16x32_bf16 v[96:99], v[176:179], v[184:187], v[96:99]
	v_mfma_f32_16x16x32_bf16 v[92:95], v[168:171], v[192:195], v[92:95]
	v_mfma_f32_16x16x32_bf16 v[88:91], v[176:179], v[192:195], v[88:91]
	v_mfma_f32_16x16x32_bf16 v[84:87], v[168:171], v[200:203], v[84:87]
	v_mfma_f32_16x16x32_bf16 v[80:83], v[176:179], v[200:203], v[80:83]
	v_mfma_f32_16x16x32_bf16 v[68:71], v[168:171], v[208:211], v[68:71]
	v_mfma_f32_16x16x32_bf16 v[64:67], v[176:179], v[208:211], v[64:67]
	s_setprio 0
	s_barrier
	s_add_i32 s72, s62, s54
	s_mov_b32 m0, s72
	ds_read_b128 v[180:183], v145 offset:16384
	ds_read_b128 v[184:187], v145 offset:17408
	ds_read_b128 v[188:191], v145 offset:18432
	ds_read_b128 v[192:195], v145 offset:19456
	ds_read_b128 v[196:199], v145 offset:20480
	ds_read_b128 v[200:203], v145 offset:21504
	ds_read_b128 v[204:207], v145 offset:22528
	ds_read_b128 v[208:211], v145 offset:23552
	global_load_lds_dwordx4 v130, s[46:47]
	s_add_i32 m0, s72, 0x2000
	s_add_u32 s72, s46, 0x80000
	s_addc_u32 s73, s47, 0
	s_add_i32 s74, s63, s54
	global_load_lds_dwordx4 v134, s[46:47]
	s_mov_b32 m0, s74
	s_nop 0
	global_load_lds_dwordx4 v130, s[72:73]
	s_add_i32 m0, s74, 0x2000
	s_nop 0
	global_load_lds_dwordx4 v134, s[72:73]
	s_mov_b32 m0, s31
	s_nop 0
	global_load_lds_dwordx4 v128, s[50:51]
	s_mov_b32 m0, s55
	s_nop 0
	global_load_lds_dwordx4 v132, s[50:51]
	s_waitcnt vmcnt(8)
	s_waitcnt lgkmcnt(0)
	s_barrier
	s_setprio 1
	s_waitcnt lgkmcnt(0)
	v_mfma_f32_16x16x32_bf16 v[60:63], v[148:151], v[180:183], v[60:63]
	v_mfma_f32_16x16x32_bf16 v[56:59], v[156:159], v[180:183], v[56:59]
	v_mfma_f32_16x16x32_bf16 v[48:51], v[148:151], v[188:191], v[48:51]
	v_mfma_f32_16x16x32_bf16 v[40:43], v[156:159], v[188:191], v[40:43]
	v_mfma_f32_16x16x32_bf16 v[32:35], v[148:151], v[196:199], v[32:35]
	v_mfma_f32_16x16x32_bf16 v[24:27], v[156:159], v[196:199], v[24:27]
	v_mfma_f32_16x16x32_bf16 v[16:19], v[148:151], v[204:207], v[16:19]
	v_mfma_f32_16x16x32_bf16 v[8:11], v[156:159], v[204:207], v[8:11]
	v_mfma_f32_16x16x32_bf16 v[60:63], v[152:155], v[184:187], v[60:63]
	v_mfma_f32_16x16x32_bf16 v[56:59], v[160:163], v[184:187], v[56:59]
	v_mfma_f32_16x16x32_bf16 v[48:51], v[152:155], v[192:195], v[48:51]
	v_mfma_f32_16x16x32_bf16 v[40:43], v[160:163], v[192:195], v[40:43]
	v_mfma_f32_16x16x32_bf16 v[32:35], v[152:155], v[200:203], v[32:35]
	v_mfma_f32_16x16x32_bf16 v[24:27], v[160:163], v[200:203], v[24:27]
	v_mfma_f32_16x16x32_bf16 v[16:19], v[152:155], v[208:211], v[16:19]
	v_mfma_f32_16x16x32_bf16 v[8:11], v[160:163], v[208:211], v[8:11]
	s_setprio 0
	s_setprio 1
	v_mfma_f32_16x16x32_bf16 v[52:55], v[164:167], v[180:183], v[52:55]
	v_mfma_f32_16x16x32_bf16 v[44:47], v[172:175], v[180:183], v[44:47]
	v_mfma_f32_16x16x32_bf16 v[36:39], v[164:167], v[188:191], v[36:39]
	v_mfma_f32_16x16x32_bf16 v[28:31], v[172:175], v[188:191], v[28:31]
	v_mfma_f32_16x16x32_bf16 v[20:23], v[164:167], v[196:199], v[20:23]
	v_mfma_f32_16x16x32_bf16 v[12:15], v[172:175], v[196:199], v[12:15]
	v_mfma_f32_16x16x32_bf16 v[4:7], v[164:167], v[204:207], v[4:7]
	v_mfma_f32_16x16x32_bf16 v[0:3], v[172:175], v[204:207], v[0:3]
	v_mfma_f32_16x16x32_bf16 v[52:55], v[168:171], v[184:187], v[52:55]
	v_mfma_f32_16x16x32_bf16 v[44:47], v[176:179], v[184:187], v[44:47]
	v_mfma_f32_16x16x32_bf16 v[36:39], v[168:171], v[192:195], v[36:39]
	v_mfma_f32_16x16x32_bf16 v[28:31], v[176:179], v[192:195], v[28:31]
	v_mfma_f32_16x16x32_bf16 v[20:23], v[168:171], v[200:203], v[20:23]
	v_mfma_f32_16x16x32_bf16 v[12:15], v[176:179], v[200:203], v[12:15]
	v_mfma_f32_16x16x32_bf16 v[4:7], v[168:171], v[208:211], v[4:7]
	v_mfma_f32_16x16x32_bf16 v[0:3], v[176:179], v[208:211], v[0:3]
	s_setprio 0
	s_barrier
; #define PG8_STAGE(bufoff, gbase, voff) do { _Pragma("unroll") for (int _i = 0; _i < 2; ++_i) \
;         __builtin_amdgcn_global_load_lds((const unsigned*)((const char*)(gbase) + (voff)[_i]), (LAS unsigned*)(lds + (bufoff) + ldsw + _i * 8192), 16, 0, 0); } while (0)
; #define PG8_LDA(dst, b, h) do { _Pragma("unroll") for (int m = 0; m < 4; ++m) _Pragma("unroll") for (int k = 0; k < 2; ++k) dst[m][k] = *(const LAS bf16x8*)(lds + PG8_SA(b, h) + aoff + m * 2048 + k * 1024); } while (0)
; #define PG8_LDB(dst, b, h) do { _Pragma("unroll") for (int n = 0; n < 2; ++n) _Pragma("unroll") for (int k = 0; k < 2; ++k) dst[n][k] = *(const LAS bf16x8*)(lds + PG8_SB(b, h) + boff + n * 2048 + k * 1024); } while (0)
; #define PG8_MMA(ai, bj, At, Bt) do { __builtin_amdgcn_s_setprio(1); _Pragma("unroll") for (int m = 0; m < 4; ++m) _Pragma("unroll") for (int n = 0; n < 2; ++n) _Pragma("unroll") for (int k = 0; k < 2; ++k) \
;         acc[ai][bj][m][n] = __builtin_amdgcn_mfma_f32_16x16x32_bf16(Bt[n][k], At[m][k], acc[ai][bj][m][n], 0, 0, 0); __builtin_amdgcn_s_setprio(0); } while (0)
; #define PG8_WAIT_V(n) asm volatile("s_waitcnt vmcnt(" #n ")" ::: "memory")
; #define PG8_WAIT_L(n) asm volatile("s_waitcnt lgkmcnt(" #n ")" ::: "memory")
; #define PG8_BAR __builtin_amdgcn_s_barrier()
; #define PG8_SCHED __builtin_amdgcn_sched_barrier(0)
; template <class Epi>
; __device__ __forceinline__ void gemm_phase(LAS unsigned char* lds, const Gemm g, const StaticOrder S, const Epi E) {
;     ...
;             PG8_LDB(B0, 1, 0); PG8_LDB(B1, 1, 1); PG8_SCHED; PG8_LDA(At, 1, 0); PG8_STAGE(PG8_SA(0, 1), a2 + hstepA, voffA);
;             PG8_WAIT_V(8); PG8_WAIT_L(0); PG8_BAR; PG8_MMA(0, 0, At, B0); PG8_MMA(0, 1, At, B1); PG8_BAR; PG8_SCHED;
;             PG8_LDA(At, 1, 1); PG8_STAGE(PG8_SB(1, 0), b3, voffB); PG8_STAGE(PG8_SB(1, 1), b3 + hstepB, voffB); PG8_STAGE(PG8_SA(1, 0), a3, voffA);
;             PG8_WAIT_V(8); PG8_WAIT_L(0); PG8_BAR; PG8_MMA(1, 0, At, B0); PG8_MMA(1, 1, At, B1); PG8_BAR; PG8_SCHED;
;         }
	s_add_i32 s72, 0, 0x18000
	v_add_u32_e32 v140, s72, v143
	s_add_i32 s73, 0, 0x1c000
	ds_read_b128 v[148:151], v140
	ds_read_b128 v[152:155], v140 offset:1024
	ds_read_b128 v[156:159], v140 offset:2048
	ds_read_b128 v[160:163], v140 offset:3072
	v_add_u32_e32 v140, s73, v143
	ds_read_b128 v[164:167], v140
	ds_read_b128 v[168:171], v140 offset:1024
	ds_read_b128 v[172:175], v140 offset:2048
	ds_read_b128 v[176:179], v140 offset:3072
	s_add_u32 s50, s50, 0x80000
	s_addc_u32 s51, s51, 0
	s_mov_b32 m0, s56
	ds_read_b128 v[180:183], v145 offset:32768
	ds_read_b128 v[184:187], v145 offset:33792
	ds_read_b128 v[188:191], v145 offset:34816
	ds_read_b128 v[192:195], v145 offset:35840
	ds_read_b128 v[196:199], v145 offset:36864
	ds_read_b128 v[200:203], v145 offset:37888
	ds_read_b128 v[204:207], v145 offset:38912
	ds_read_b128 v[208:211], v145 offset:39936
	global_load_lds_dwordx4 v128, s[50:51]
	s_mov_b32 m0, s57
	s_nop 0
	global_load_lds_dwordx4 v132, s[50:51]
	s_waitcnt vmcnt(8)
	s_waitcnt lgkmcnt(0)
	s_barrier
	s_setprio 1
	s_waitcnt lgkmcnt(0)
	v_mfma_f32_16x16x32_bf16 v[124:127], v[148:151], v[180:183], v[124:127]
	v_mfma_f32_16x16x32_bf16 v[120:123], v[156:159], v[180:183], v[120:123]
	v_mfma_f32_16x16x32_bf16 v[116:119], v[148:151], v[188:191], v[116:119]
	v_mfma_f32_16x16x32_bf16 v[112:115], v[156:159], v[188:191], v[112:115]
	v_mfma_f32_16x16x32_bf16 v[108:111], v[148:151], v[196:199], v[108:111]
	v_mfma_f32_16x16x32_bf16 v[100:103], v[156:159], v[196:199], v[100:103]
	v_mfma_f32_16x16x32_bf16 v[76:79], v[148:151], v[204:207], v[76:79]
	v_mfma_f32_16x16x32_bf16 v[72:75], v[156:159], v[204:207], v[72:75]
	v_mfma_f32_16x16x32_bf16 v[124:127], v[152:155], v[184:187], v[124:127]
	v_mfma_f32_16x16x32_bf16 v[120:123], v[160:163], v[184:187], v[120:123]
	v_mfma_f32_16x16x32_bf16 v[116:119], v[152:155], v[192:195], v[116:119]
	v_mfma_f32_16x16x32_bf16 v[112:115], v[160:163], v[192:195], v[112:115]
	v_mfma_f32_16x16x32_bf16 v[108:111], v[152:155], v[200:203], v[108:111]
	v_mfma_f32_16x16x32_bf16 v[100:103], v[160:163], v[200:203], v[100:103]
	v_mfma_f32_16x16x32_bf16 v[76:79], v[152:155], v[208:211], v[76:79]
	v_mfma_f32_16x16x32_bf16 v[72:75], v[160:163], v[208:211], v[72:75]
	s_setprio 0
	s_setprio 1
	v_mfma_f32_16x16x32_bf16 v[104:107], v[164:167], v[180:183], v[104:107]
	v_mfma_f32_16x16x32_bf16 v[96:99], v[172:175], v[180:183], v[96:99]
	v_mfma_f32_16x16x32_bf16 v[92:95], v[164:167], v[188:191], v[92:95]
	v_mfma_f32_16x16x32_bf16 v[88:91], v[172:175], v[188:191], v[88:91]
	v_mfma_f32_16x16x32_bf16 v[84:87], v[164:167], v[196:199], v[84:87]
	v_mfma_f32_16x16x32_bf16 v[80:83], v[172:175], v[196:199], v[80:83]
	v_mfma_f32_16x16x32_bf16 v[68:71], v[164:167], v[204:207], v[68:71]
	v_mfma_f32_16x16x32_bf16 v[64:67], v[172:175], v[204:207], v[64:67]
	v_mfma_f32_16x16x32_bf16 v[104:107], v[168:171], v[184:187], v[104:107]
	v_mfma_f32_16x16x32_bf16 v[96:99], v[176:179], v[184:187], v[96:99]
	v_mfma_f32_16x16x32_bf16 v[92:95], v[168:171], v[192:195], v[92:95]
	v_mfma_f32_16x16x32_bf16 v[88:91], v[176:179], v[192:195], v[88:91]
	v_mfma_f32_16x16x32_bf16 v[84:87], v[168:171], v[200:203], v[84:87]
	v_mfma_f32_16x16x32_bf16 v[80:83], v[176:179], v[200:203], v[80:83]
	v_mfma_f32_16x16x32_bf16 v[68:71], v[168:171], v[208:211], v[68:71]
	v_mfma_f32_16x16x32_bf16 v[64:67], v[176:179], v[208:211], v[64:67]
	s_setprio 0
	s_barrier
	s_add_u32 s46, s46, s48
	s_addc_u32 s47, s47, s49
	s_add_i32 s48, s72, s54
	s_mov_b32 m0, s48
	ds_read_b128 v[180:183], v145 offset:49152
	ds_read_b128 v[184:187], v145 offset:50176
	ds_read_b128 v[188:191], v145 offset:51200
	ds_read_b128 v[192:195], v145 offset:52224
	ds_read_b128 v[196:199], v145 offset:53248
	ds_read_b128 v[200:203], v145 offset:54272
	ds_read_b128 v[204:207], v145 offset:55296
	ds_read_b128 v[208:211], v145 offset:56320
	global_load_lds_dwordx4 v130, s[46:47]
	s_add_i32 m0, s48, 0x2000
	v_lshl_add_u64 v[140:141], s[46:47], 0, v[134:135]
	s_add_u32 s46, s46, 0x80000
	s_addc_u32 s47, s47, 0
	s_add_i32 s48, s73, s54
	global_load_lds_dwordx4 v[140:141], off
	s_mov_b32 m0, s48
	s_nop 0
	global_load_lds_dwordx4 v130, s[46:47]
	s_add_i32 m0, s48, 0x2000
	s_nop 0
	global_load_lds_dwordx4 v134, s[46:47]
	s_mov_b32 m0, s58
	s_nop 0
	global_load_lds_dwordx4 v128, s[52:53]
	s_mov_b32 m0, s59
	s_nop 0
	global_load_lds_dwordx4 v132, s[52:53]
	s_waitcnt vmcnt(8)
	s_waitcnt lgkmcnt(0)
	s_barrier
	s_setprio 1
	s_waitcnt lgkmcnt(0)
	v_mfma_f32_16x16x32_bf16 v[60:63], v[148:151], v[180:183], v[60:63]
	v_mfma_f32_16x16x32_bf16 v[56:59], v[156:159], v[180:183], v[56:59]
	v_mfma_f32_16x16x32_bf16 v[48:51], v[148:151], v[188:191], v[48:51]
	v_mfma_f32_16x16x32_bf16 v[40:43], v[156:159], v[188:191], v[40:43]
	v_mfma_f32_16x16x32_bf16 v[32:35], v[148:151], v[196:199], v[32:35]
	v_mfma_f32_16x16x32_bf16 v[24:27], v[156:159], v[196:199], v[24:27]
	v_mfma_f32_16x16x32_bf16 v[16:19], v[148:151], v[204:207], v[16:19]
	v_mfma_f32_16x16x32_bf16 v[8:11], v[156:159], v[204:207], v[8:11]
	v_mfma_f32_16x16x32_bf16 v[60:63], v[152:155], v[184:187], v[60:63]
	v_mfma_f32_16x16x32_bf16 v[56:59], v[160:163], v[184:187], v[56:59]
	v_mfma_f32_16x16x32_bf16 v[48:51], v[152:155], v[192:195], v[48:51]
	v_mfma_f32_16x16x32_bf16 v[40:43], v[160:163], v[192:195], v[40:43]
	v_mfma_f32_16x16x32_bf16 v[32:35], v[152:155], v[200:203], v[32:35]
	v_mfma_f32_16x16x32_bf16 v[24:27], v[160:163], v[200:203], v[24:27]
	v_mfma_f32_16x16x32_bf16 v[16:19], v[152:155], v[208:211], v[16:19]
	v_mfma_f32_16x16x32_bf16 v[8:11], v[160:163], v[208:211], v[8:11]
	s_setprio 0
	s_setprio 1
	v_mfma_f32_16x16x32_bf16 v[52:55], v[164:167], v[180:183], v[52:55]
	v_mfma_f32_16x16x32_bf16 v[44:47], v[172:175], v[180:183], v[44:47]
	v_mfma_f32_16x16x32_bf16 v[36:39], v[164:167], v[188:191], v[36:39]
	v_mfma_f32_16x16x32_bf16 v[28:31], v[172:175], v[188:191], v[28:31]
	v_mfma_f32_16x16x32_bf16 v[20:23], v[164:167], v[196:199], v[20:23]
	v_mfma_f32_16x16x32_bf16 v[12:15], v[172:175], v[196:199], v[12:15]
	v_mfma_f32_16x16x32_bf16 v[4:7], v[164:167], v[204:207], v[4:7]
	v_mfma_f32_16x16x32_bf16 v[0:3], v[172:175], v[204:207], v[0:3]
	v_mfma_f32_16x16x32_bf16 v[52:55], v[168:171], v[184:187], v[52:55]
	v_mfma_f32_16x16x32_bf16 v[44:47], v[176:179], v[184:187], v[44:47]
	v_mfma_f32_16x16x32_bf16 v[36:39], v[168:171], v[192:195], v[36:39]
	v_mfma_f32_16x16x32_bf16 v[28:31], v[176:179], v[192:195], v[28:31]
	v_mfma_f32_16x16x32_bf16 v[20:23], v[168:171], v[200:203], v[20:23]
	v_mfma_f32_16x16x32_bf16 v[12:15], v[176:179], v[200:203], v[12:15]
	v_mfma_f32_16x16x32_bf16 v[4:7], v[168:171], v[208:211], v[4:7]
	v_mfma_f32_16x16x32_bf16 v[0:3], v[176:179], v[208:211], v[0:3]
	s_setprio 0
	s_barrier
	s_cmp_gt_u32 s70, 29
	s_mov_b32 s70, s71
	s_cbranch_scc1 .LBB0_315

; #define PG8_STAGE(bufoff, gbase, voff) do { _Pragma("unroll") for (int _i = 0; _i < 2; ++_i) \
;         __builtin_amdgcn_global_load_lds((const unsigned*)((const char*)(gbase) + (voff)[_i]), (LAS unsigned*)(lds + (bufoff) + ldsw + _i * 8192), 16, 0, 0); } while (0)
; #define PG8_WAIT_V(n) asm volatile("s_waitcnt vmcnt(" #n ")" ::: "memory")
; #define PG8_BAR __builtin_amdgcn_s_barrier()
; template <class Epi>
; __device__ __forceinline__ void gemm_phase(LAS unsigned char* lds, const Gemm g, const StaticOrder S, const Epi E) {
;     ...
;     for (int i = 0; i < 2; ++i) { int R, C; stage_rc(tid * 16 + i * 8192, R, C); const int Rb = Epi::PERM ? ((R & ~31) + perm32(R & 31)) : R;
;         voffA[i] = (unsigned)(R * g.lda + C) * 2u; voffB[i] = (unsigned)(Rb * g.ldb + C) * 2u; }
;     const size_t kstep = (size_t)(BK * 2);
;     const size_t hstepA = (size_t)HALF * g.lda * 2, hstepB = (size_t)HALF * g.ldb * 2;
;     const size_t tstepA = 2 * hstepA, tstepB = 2 * hstepB;
;     const unsigned ldsw = (unsigned)wid * 1024u;
;     const int aoff = lds_byte(wr * 64 + fr, fq * 8), boff = lds_byte(wc * 32 + fr, fq * 8);
;     ...
;     PG8_STAGE(PG8_SB(1, 0), cB + ksc, voffB); PG8_STAGE(PG8_SA(1, 0), cA + ksc, voffA); PG8_STAGE(PG8_SB(1, 1), cB + hstepB + ksc, voffB);
;     PG8_WAIT_V(6); PG8_BAR;
.LBB0_467:
	s_add_u32 s10, s82, 0xa680800
	s_addc_u32 s11, s83, 0
	s_lshl_b32 s1, s1, 5
	s_mov_b64 s[48:49], 0x80
	s_and_b32 s1, s1, 0x60
	s_add_i32 m0, s45, 0x18000
	v_lshl_add_u64 v[6:7], v[6:7], 0, s[48:49]
	s_lshl_b32 s13, s0, 13
	s_lshl_b32 s14, s1, 7
	s_ashr_i32 s17, s79, 31
	s_waitcnt vmcnt(2)
	s_barrier
	global_load_lds_dwordx4 v[6:7], off
	v_lshl_add_u64 v[4:5], v[4:5], 0, s[48:49]
	s_add_i32 m0, s45, 0x1a000
	s_add_i32 s63, s45, 0x8000
	s_add_i32 s64, s45, 0xa000
	global_load_lds_dwordx4 v[4:5], off
	v_lshl_add_u64 v[0:1], v[0:1], 0, s[48:49]
	s_mov_b32 m0, s63
	s_add_u32 s2, s50, 0x10080
	global_load_lds_dwordx4 v[0:1], off
	v_lshl_add_u64 v[0:1], v[2:3], 0, s[48:49]
	s_mov_b32 m0, s64
	s_addc_u32 s3, s51, 0
	global_load_lds_dwordx4 v[0:1], off
	s_add_i32 m0, s45, 0x1c000
	s_nop 0
	global_load_lds_dwordx4 v146, s[2:3]
	s_add_i32 m0, s45, 0x1e000
	v_lshlrev_b32_e32 v2, 2, v224
	global_load_lds_dwordx4 v150, s[2:3]
	v_and_b32_e32 v0, 15, v224
	v_lshlrev_b32_e32 v1, 1, v8
	s_ashr_i32 s65, s78, 31
	v_lshl_or_b32 v160, s0, 6, v0
	v_lshl_or_b32 v0, v0, 6, v1
	v_and_b32_e32 v2, 32, v2
	v_lshlrev_b32_e32 v3, 6, v224
	s_movk_i32 s0, 0x3c0
	s_cmpk_lt_u32 s12, 0x100
	v_bitop3_b32 v0, v0, s13, v2 bitop3:0xde
	v_and_or_b32 v1, v3, s0, v1
	s_cselect_b64 s[12:13], -1, 0
	s_cmp_lg_u64 s[6:7], 0
	v_bitop3_b32 v161, s14, v1, v2 bitop3:0xf6
	s_waitcnt vmcnt(6)
	s_cselect_b64 s[14:15], -1, 0
	s_add_u32 s16, s79, s78
	s_addc_u32 s17, s17, s65
	s_add_i32 s66, 0, 0x10000
	s_add_i32 s67, 0, 0x14000
	v_or_b32_e32 v162, s1, v8
	v_mov_b64_e32 v[152:153], 0x100
	v_mov_b64_e32 v[154:155], 0xff
	v_add_u32_e32 v163, s66, v161
	v_add_u32_e32 v164, s67, v161
	v_add_u32_e32 v165, 0, v0
	s_mov_b64 s[18:19], 0x90000
	s_mov_b32 s68, 0x90000
	s_mov_b64 s[20:21], 0xa0000
	s_mov_b32 s69, 0xa0000
	s_mov_b64 s[22:23], 0xb0000
	s_mov_b32 s70, 0xb0000
	s_barrier
	s_branch .LBB0_470

; #define PG8_STAGE(bufoff, gbase, voff) do { _Pragma("unroll") for (int _i = 0; _i < 2; ++_i) \
;         __builtin_amdgcn_global_load_lds((const unsigned*)((const char*)(gbase) + (voff)[_i]), (LAS unsigned*)(lds + (bufoff) + ldsw + _i * 8192), 16, 0, 0); } while (0)
; #define PG8_LDA(dst, b, h) do { _Pragma("unroll") for (int m = 0; m < 4; ++m) _Pragma("unroll") for (int k = 0; k < 2; ++k) dst[m][k] = *(const LAS bf16x8*)(lds + PG8_SA(b, h) + aoff + m * 2048 + k * 1024); } while (0)
; #define PG8_LDB(dst, b, h) do { _Pragma("unroll") for (int n = 0; n < 2; ++n) _Pragma("unroll") for (int k = 0; k < 2; ++k) dst[n][k] = *(const LAS bf16x8*)(lds + PG8_SB(b, h) + boff + n * 2048 + k * 1024); } while (0)
; #define PG8_WAIT_V(n) asm volatile("s_waitcnt vmcnt(" #n ")" ::: "memory")
; #define PG8_WAIT_L(n) asm volatile("s_waitcnt lgkmcnt(" #n ")" ::: "memory")
; #define PG8_BAR __builtin_amdgcn_s_barrier()
; #define PG8_SCHED __builtin_amdgcn_sched_barrier(0)
; template <class Epi>
; __device__ __forceinline__ void gemm_phase(LAS unsigned char* lds, const Gemm g, const StaticOrder S, const Epi E) {
;     ...
;         ksn = has_next ? (nrev ? -(long)kstep : (long)kstep) : ksc;
;         const char* nA = has_next ? (const char*)g.A + (size_t)nxt.pm * tstepA + (size_t)nxt.pn * g.a_pn_off + (nrev ? klast : 0) : cA;
;         const char* nB = has_next ? (const char*)g.Bt + (size_t)nxt.pn * tstepB + (nrev ? klast : 0) : cB;
;         for (int t = 0; t < nt; t += 2) {
;             const bool last = (t == nt - 2);
;             const char* a1 = cA + (long)(t + 1) * ksc;
;             const char* a2 = last ? nA : cA + (long)(t + 2) * ksc; const char* b2 = last ? nB : cB + (long)(t + 2) * ksc;
;             const long ks3 = last ? ksn : ksc;
;             const char* a3 = a2 + ks3; const char* b3 = b2 + ks3;
;             PG8_LDB(B0, 0, 0); PG8_LDB(B1, 0, 1); PG8_SCHED; PG8_LDA(At, 0, 0); PG8_STAGE(PG8_SA(1, 1), a1 + hstepA, voffA);
;             PG8_WAIT_V(8); PG8_WAIT_L(0); PG8_BAR; PG8_MMA(0, 0, At, B0); PG8_MMA(0, 1, At, B1); PG8_BAR; PG8_SCHED;
;             PG8_LDA(At, 0, 1); PG8_STAGE(PG8_SB(0, 0), b2, voffB); PG8_STAGE(PG8_SB(0, 1), b2 + hstepB, voffB); PG8_STAGE(PG8_SA(0, 0), a2, voffA);
;             PG8_WAIT_V(8); PG8_WAIT_L(0); PG8_BAR; PG8_MMA(1, 0, At, B0); PG8_MMA(1, 1, At, B1); PG8_BAR; PG8_SCHED;
.LBB0_480:
	ds_read_b128 v[0:3], v163
	ds_read_b128 v[4:7], v163 offset:1024
	ds_read_b128 v[8:11], v163 offset:2048
	ds_read_b128 v[12:15], v163 offset:3072
	ds_read_b128 v[16:19], v164
	ds_read_b128 v[20:23], v164 offset:1024
	ds_read_b128 v[24:27], v164 offset:2048
	ds_read_b128 v[28:31], v164 offset:3072
	s_and_b64 s[34:35], s[34:35], exec
	s_movk_i32 s25, 0xff80
	s_cselect_b32 s35, -1, 0
	s_cselect_b32 s34, s25, 0x80
	s_and_b64 s[2:3], s[2:3], exec
	s_cselect_b32 s25, s35, s49
	s_cselect_b32 s27, s34, s48
	s_lshl_b64 s[2:3], s[48:49], 1
	s_add_u32 s58, s52, s2
	s_addc_u32 s59, s53, s3
	s_add_u32 s56, s50, s2
	s_addc_u32 s57, s51, s3
	s_add_u32 s54, s58, s48
	s_addc_u32 s55, s59, s49
	s_add_u32 s50, s52, s48
	s_addc_u32 s51, s53, s49
	s_add_u32 s50, s50, 0x40000
	s_addc_u32 s51, s51, 0
	s_add_i32 s74, s45, 0xc000
	s_mov_b32 m0, s74
	s_add_i32 s52, s45, 0xe000
	ds_read_b128 v[32:35], v165
	ds_read_b128 v[36:39], v165 offset:1024
	ds_read_b128 v[40:43], v165 offset:2048
	ds_read_b128 v[44:47], v165 offset:3072
	ds_read_b128 v[48:51], v165 offset:4096
	ds_read_b128 v[52:55], v165 offset:5120
	ds_read_b128 v[56:59], v165 offset:6144
	ds_read_b128 v[60:63], v165 offset:7168
	global_load_lds_dwordx4 v144, s[50:51]
	s_mov_b32 m0, s52
	s_nop 0
	global_load_lds_dwordx4 v148, s[50:51]
	s_waitcnt vmcnt(8)
	s_waitcnt lgkmcnt(0)
	s_barrier
	s_setprio 1
	s_waitcnt lgkmcnt(0)
	v_mfma_f32_16x16x32_bf16 v[64:67], v[0:3], v[32:35], 0
	v_mfma_f32_16x16x32_bf16 v[68:71], v[8:11], v[32:35], 0
	v_mfma_f32_16x16x32_bf16 v[72:75], v[0:3], v[40:43], 0
	v_mfma_f32_16x16x32_bf16 v[76:79], v[8:11], v[40:43], 0
	v_mfma_f32_16x16x32_bf16 v[80:83], v[0:3], v[48:51], 0
	v_mfma_f32_16x16x32_bf16 v[84:87], v[8:11], v[48:51], 0
	v_mfma_f32_16x16x32_bf16 v[88:91], v[0:3], v[56:59], 0
	v_mfma_f32_16x16x32_bf16 v[92:95], v[8:11], v[56:59], 0
	v_mfma_f32_16x16x32_bf16 v[64:67], v[4:7], v[36:39], v[64:67]
	v_mfma_f32_16x16x32_bf16 v[68:71], v[12:15], v[36:39], v[68:71]
	v_mfma_f32_16x16x32_bf16 v[72:75], v[4:7], v[44:47], v[72:75]
	v_mfma_f32_16x16x32_bf16 v[76:79], v[12:15], v[44:47], v[76:79]
	v_mfma_f32_16x16x32_bf16 v[80:83], v[4:7], v[52:55], v[80:83]
	v_mfma_f32_16x16x32_bf16 v[84:87], v[12:15], v[52:55], v[84:87]
	v_mfma_f32_16x16x32_bf16 v[88:91], v[4:7], v[60:63], v[88:91]
	v_mfma_f32_16x16x32_bf16 v[92:95], v[12:15], v[60:63], v[92:95]
	s_setprio 0
	s_setprio 1
	v_mfma_f32_16x16x32_bf16 v[96:99], v[16:19], v[32:35], 0
	v_mfma_f32_16x16x32_bf16 v[32:35], v[24:27], v[32:35], 0
	v_mfma_f32_16x16x32_bf16 v[96:99], v[20:23], v[36:39], v[96:99]
	v_mfma_f32_16x16x32_bf16 v[32:35], v[28:31], v[36:39], v[32:35]
	v_mfma_f32_16x16x32_bf16 v[36:39], v[16:19], v[40:43], 0
	v_mfma_f32_16x16x32_bf16 v[40:43], v[24:27], v[40:43], 0
	v_mfma_f32_16x16x32_bf16 v[36:39], v[20:23], v[44:47], v[36:39]
	v_mfma_f32_16x16x32_bf16 v[40:43], v[28:31], v[44:47], v[40:43]
	v_mfma_f32_16x16x32_bf16 v[44:47], v[16:19], v[48:51], 0
	v_mfma_f32_16x16x32_bf16 v[48:51], v[24:27], v[48:51], 0
	v_mfma_f32_16x16x32_bf16 v[44:47], v[20:23], v[52:55], v[44:47]
	v_mfma_f32_16x16x32_bf16 v[48:51], v[28:31], v[52:55], v[48:51]
	v_mfma_f32_16x16x32_bf16 v[52:55], v[16:19], v[56:59], 0
	v_mfma_f32_16x16x32_bf16 v[56:59], v[24:27], v[56:59], 0
	v_mfma_f32_16x16x32_bf16 v[52:55], v[20:23], v[60:63], v[52:55]
	v_mfma_f32_16x16x32_bf16 v[56:59], v[28:31], v[60:63], v[56:59]
	s_setprio 0
	s_barrier
	s_add_i32 s73, s66, s33
	s_add_i32 s53, s73, 0x2000
	s_mov_b32 m0, s73
	s_add_u32 s76, s56, 0x10000
	ds_read_b128 v[60:63], v165 offset:16384
	ds_read_b128 v[100:103], v165 offset:17408
	ds_read_b128 v[104:107], v165 offset:18432
	ds_read_b128 v[108:111], v165 offset:19456
	ds_read_b128 v[112:115], v165 offset:20480
	ds_read_b128 v[116:119], v165 offset:21504
	ds_read_b128 v[120:123], v165 offset:22528
	ds_read_b128 v[124:127], v165 offset:23552
	global_load_lds_dwordx4 v146, s[56:57]
	s_mov_b32 m0, s53
	s_addc_u32 s77, s57, 0
	s_add_i32 s71, s67, s33
	global_load_lds_dwordx4 v150, s[56:57]
	s_mov_b32 m0, s71
	s_add_i32 s72, s71, 0x2000
	global_load_lds_dwordx4 v146, s[76:77]
	s_mov_b32 m0, s72
	s_nop 0
	global_load_lds_dwordx4 v150, s[76:77]
	s_mov_b32 m0, s45
	s_nop 0
	global_load_lds_dwordx4 v144, s[58:59]
	s_mov_b32 m0, s47
	s_nop 0
	global_load_lds_dwordx4 v148, s[58:59]
	s_waitcnt vmcnt(8)
	s_waitcnt lgkmcnt(0)
	s_barrier
	s_setprio 1
	s_waitcnt lgkmcnt(0)
	v_mfma_f32_16x16x32_bf16 v[128:131], v[0:3], v[60:63], 0
	v_mfma_f32_16x16x32_bf16 v[136:139], v[0:3], v[104:107], 0
	v_mfma_f32_16x16x32_bf16 v[156:159], v[0:3], v[112:115], 0
	v_mfma_f32_16x16x32_bf16 v[0:3], v[0:3], v[120:123], 0
	v_mfma_f32_16x16x32_bf16 v[128:131], v[4:7], v[100:103], v[128:131]
	v_mfma_f32_16x16x32_bf16 v[132:135], v[8:11], v[60:63], 0
	v_mfma_f32_16x16x32_bf16 v[136:139], v[4:7], v[108:111], v[136:139]
	v_mfma_f32_16x16x32_bf16 v[140:143], v[8:11], v[104:107], 0
	v_mfma_f32_16x16x32_bf16 v[156:159], v[4:7], v[116:119], v[156:159]
	v_mfma_f32_16x16x32_bf16 v[0:3], v[4:7], v[124:127], v[0:3]
	v_mfma_f32_16x16x32_bf16 v[4:7], v[8:11], v[120:123], 0
	v_mfma_f32_16x16x32_bf16 v[132:135], v[12:15], v[100:103], v[132:135]
	v_mfma_f32_16x16x32_bf16 v[140:143], v[12:15], v[108:111], v[140:143]
	v_mfma_f32_16x16x32_bf16 v[166:169], v[8:11], v[112:115], 0
	v_mfma_f32_16x16x32_bf16 v[4:7], v[12:15], v[124:127], v[4:7]
	v_mfma_f32_16x16x32_bf16 v[166:169], v[12:15], v[116:119], v[166:169]
	s_setprio 0
	s_setprio 1
	v_mfma_f32_16x16x32_bf16 v[8:11], v[16:19], v[60:63], 0
	v_mfma_f32_16x16x32_bf16 v[12:15], v[24:27], v[60:63], 0
	v_mfma_f32_16x16x32_bf16 v[8:11], v[20:23], v[100:103], v[8:11]
	v_mfma_f32_16x16x32_bf16 v[12:15], v[28:31], v[100:103], v[12:15]
	v_mfma_f32_16x16x32_bf16 v[60:63], v[16:19], v[104:107], 0
	v_mfma_f32_16x16x32_bf16 v[100:103], v[24:27], v[104:107], 0
	v_mfma_f32_16x16x32_bf16 v[104:107], v[16:19], v[112:115], 0
	v_mfma_f32_16x16x32_bf16 v[16:19], v[16:19], v[120:123], 0
	v_mfma_f32_16x16x32_bf16 v[60:63], v[20:23], v[108:111], v[60:63]
	v_mfma_f32_16x16x32_bf16 v[100:103], v[28:31], v[108:111], v[100:103]
	v_mfma_f32_16x16x32_bf16 v[104:107], v[20:23], v[116:119], v[104:107]
	v_mfma_f32_16x16x32_bf16 v[108:111], v[24:27], v[112:115], 0
	v_mfma_f32_16x16x32_bf16 v[16:19], v[20:23], v[124:127], v[16:19]
	v_mfma_f32_16x16x32_bf16 v[20:23], v[24:27], v[120:123], 0
	v_mfma_f32_16x16x32_bf16 v[108:111], v[28:31], v[116:119], v[108:111]
	v_mfma_f32_16x16x32_bf16 v[20:23], v[28:31], v[124:127], v[20:23]
	s_setprio 0
	s_barrier
; #define PG8_STAGE(bufoff, gbase, voff) do { _Pragma("unroll") for (int _i = 0; _i < 2; ++_i) \
;         __builtin_amdgcn_global_load_lds((const unsigned*)((const char*)(gbase) + (voff)[_i]), (LAS unsigned*)(lds + (bufoff) + ldsw + _i * 8192), 16, 0, 0); } while (0)
; #define PG8_LDA(dst, b, h) do { _Pragma("unroll") for (int m = 0; m < 4; ++m) _Pragma("unroll") for (int k = 0; k < 2; ++k) dst[m][k] = *(const LAS bf16x8*)(lds + PG8_SA(b, h) + aoff + m * 2048 + k * 1024); } while (0)
; #define PG8_LDB(dst, b, h) do { _Pragma("unroll") for (int n = 0; n < 2; ++n) _Pragma("unroll") for (int k = 0; k < 2; ++k) dst[n][k] = *(const LAS bf16x8*)(lds + PG8_SB(b, h) + boff + n * 2048 + k * 1024); } while (0)
; #define PG8_MMA(ai, bj, At, Bt) do { __builtin_amdgcn_s_setprio(1); _Pragma("unroll") for (int m = 0; m < 4; ++m) _Pragma("unroll") for (int n = 0; n < 2; ++n) _Pragma("unroll") for (int k = 0; k < 2; ++k) \
;         acc[ai][bj][m][n] = __builtin_amdgcn_mfma_f32_16x16x32_bf16(Bt[n][k], At[m][k], acc[ai][bj][m][n], 0, 0, 0); __builtin_amdgcn_s_setprio(0); } while (0)
; #define PG8_WAIT_V(n) asm volatile("s_waitcnt vmcnt(" #n ")" ::: "memory")
; #define PG8_WAIT_L(n) asm volatile("s_waitcnt lgkmcnt(" #n ")" ::: "memory")
; #define PG8_BAR __builtin_amdgcn_s_barrier()
; #define PG8_SCHED __builtin_amdgcn_sched_barrier(0)
; template <class Epi>
; __device__ __forceinline__ void gemm_phase(LAS unsigned char* lds, const Gemm g, const StaticOrder S, const Epi E) {
;     ...
;             PG8_LDB(B0, 1, 0); PG8_LDB(B1, 1, 1); PG8_SCHED; PG8_LDA(At, 1, 0); PG8_STAGE(PG8_SA(0, 1), a2 + hstepA, voffA);
;             PG8_WAIT_V(8); PG8_WAIT_L(0); PG8_BAR; PG8_MMA(0, 0, At, B0); PG8_MMA(0, 1, At, B1); PG8_BAR; PG8_SCHED;
;             PG8_LDA(At, 1, 1); PG8_STAGE(PG8_SB(1, 0), b3, voffB); PG8_STAGE(PG8_SB(1, 1), b3 + hstepB, voffB); PG8_STAGE(PG8_SA(1, 0), a3, voffA);
;             PG8_WAIT_V(8); PG8_WAIT_L(0); PG8_BAR; PG8_MMA(1, 0, At, B0); PG8_MMA(1, 1, At, B1); PG8_BAR; PG8_SCHED;
	s_add_i32 s75, 0, 0x18000
	s_add_i32 s76, 0, 0x1c000
	v_add_u32_e32 v222, s75, v161
	v_add_u32_e32 v223, s76, v161
	ds_read_b128 v[24:27], v222
	ds_read_b128 v[28:31], v222 offset:1024
	ds_read_b128 v[112:115], v222 offset:2048
	ds_read_b128 v[116:119], v222 offset:3072
	ds_read_b128 v[120:123], v223
	ds_read_b128 v[124:127], v223 offset:1024
	ds_read_b128 v[170:173], v223 offset:2048
	ds_read_b128 v[174:177], v223 offset:3072
	s_add_u32 s58, s58, 0x40000
	s_addc_u32 s59, s59, 0
	s_mov_b32 m0, s60
	ds_read_b128 v[178:181], v165 offset:32768
	ds_read_b128 v[182:185], v165 offset:33792
	ds_read_b128 v[186:189], v165 offset:34816
	ds_read_b128 v[190:193], v165 offset:35840
	ds_read_b128 v[194:197], v165 offset:36864
	ds_read_b128 v[198:201], v165 offset:37888
	ds_read_b128 v[202:205], v165 offset:38912
	ds_read_b128 v[206:209], v165 offset:39936
	global_load_lds_dwordx4 v144, s[58:59]
	s_mov_b32 m0, s61
	s_nop 0
	global_load_lds_dwordx4 v148, s[58:59]
	s_waitcnt vmcnt(8)
	s_waitcnt lgkmcnt(0)
	s_barrier
	s_setprio 1
	s_waitcnt lgkmcnt(0)
	v_mfma_f32_16x16x32_bf16 v[64:67], v[24:27], v[178:181], v[64:67]
	v_mfma_f32_16x16x32_bf16 v[68:71], v[112:115], v[178:181], v[68:71]
	v_mfma_f32_16x16x32_bf16 v[72:75], v[24:27], v[186:189], v[72:75]
	v_mfma_f32_16x16x32_bf16 v[76:79], v[112:115], v[186:189], v[76:79]
	v_mfma_f32_16x16x32_bf16 v[80:83], v[24:27], v[194:197], v[80:83]
	v_mfma_f32_16x16x32_bf16 v[84:87], v[112:115], v[194:197], v[84:87]
	v_mfma_f32_16x16x32_bf16 v[88:91], v[24:27], v[202:205], v[88:91]
	v_mfma_f32_16x16x32_bf16 v[92:95], v[112:115], v[202:205], v[92:95]
	v_mfma_f32_16x16x32_bf16 v[64:67], v[28:31], v[182:185], v[64:67]
	v_mfma_f32_16x16x32_bf16 v[68:71], v[116:119], v[182:185], v[68:71]
	v_mfma_f32_16x16x32_bf16 v[72:75], v[28:31], v[190:193], v[72:75]
	v_mfma_f32_16x16x32_bf16 v[76:79], v[116:119], v[190:193], v[76:79]
	v_mfma_f32_16x16x32_bf16 v[80:83], v[28:31], v[198:201], v[80:83]
	v_mfma_f32_16x16x32_bf16 v[84:87], v[116:119], v[198:201], v[84:87]
	v_mfma_f32_16x16x32_bf16 v[88:91], v[28:31], v[206:209], v[88:91]
	v_mfma_f32_16x16x32_bf16 v[92:95], v[116:119], v[206:209], v[92:95]
	s_setprio 0
	s_setprio 1
	v_mfma_f32_16x16x32_bf16 v[96:99], v[120:123], v[178:181], v[96:99]
	v_mfma_f32_16x16x32_bf16 v[32:35], v[170:173], v[178:181], v[32:35]
	v_mfma_f32_16x16x32_bf16 v[36:39], v[120:123], v[186:189], v[36:39]
	v_mfma_f32_16x16x32_bf16 v[48:51], v[170:173], v[194:197], v[48:51]
	v_mfma_f32_16x16x32_bf16 v[52:55], v[120:123], v[202:205], v[52:55]
	v_mfma_f32_16x16x32_bf16 v[56:59], v[170:173], v[202:205], v[56:59]
	v_mfma_f32_16x16x32_bf16 v[96:99], v[124:127], v[182:185], v[96:99]
	v_mfma_f32_16x16x32_bf16 v[32:35], v[174:177], v[182:185], v[32:35]
	v_mfma_f32_16x16x32_bf16 v[36:39], v[124:127], v[190:193], v[36:39]
	v_mfma_f32_16x16x32_bf16 v[40:43], v[170:173], v[186:189], v[40:43]
	v_mfma_f32_16x16x32_bf16 v[44:47], v[120:123], v[194:197], v[44:47]
	v_mfma_f32_16x16x32_bf16 v[48:51], v[174:177], v[198:201], v[48:51]
	v_mfma_f32_16x16x32_bf16 v[52:55], v[124:127], v[206:209], v[52:55]
	v_mfma_f32_16x16x32_bf16 v[56:59], v[174:177], v[206:209], v[56:59]
	v_mfma_f32_16x16x32_bf16 v[40:43], v[174:177], v[190:193], v[40:43]
	v_mfma_f32_16x16x32_bf16 v[44:47], v[124:127], v[198:201], v[44:47]
	s_setprio 0
	s_barrier
	s_add_u32 s48, s56, s48
	s_addc_u32 s49, s57, s49
	s_add_i32 s59, s75, s33
	s_mov_b32 m0, s59
	s_add_i32 s56, s59, 0x2000
	ds_read_b128 v[178:181], v165 offset:49152
	ds_read_b128 v[182:185], v165 offset:50176
	ds_read_b128 v[186:189], v165 offset:51200
	ds_read_b128 v[190:193], v165 offset:52224
	ds_read_b128 v[194:197], v165 offset:53248
	ds_read_b128 v[198:201], v165 offset:54272
	ds_read_b128 v[202:205], v165 offset:55296
	ds_read_b128 v[206:209], v165 offset:56320
	global_load_lds_dwordx4 v146, s[48:49]
	v_lshl_add_u64 v[210:211], s[48:49], 0, v[150:151]
	s_add_u32 s48, s48, 0x10000
	s_mov_b32 m0, s56
	s_addc_u32 s49, s49, 0
	s_add_i32 s57, s76, s33
	global_load_lds_dwordx4 v[210:211], off
	s_mov_b32 m0, s57
	s_add_i32 s58, s57, 0x2000
	global_load_lds_dwordx4 v146, s[48:49]
	s_mov_b32 m0, s58
	s_nop 0
	global_load_lds_dwordx4 v150, s[48:49]
	s_mov_b32 m0, s63
	s_nop 0
	global_load_lds_dwordx4 v144, s[54:55]
	s_mov_b32 m0, s64
	s_nop 0
	global_load_lds_dwordx4 v148, s[54:55]
	s_waitcnt vmcnt(8)
	s_waitcnt lgkmcnt(0)
	s_barrier
	s_setprio 1
	s_waitcnt lgkmcnt(0)
	v_mfma_f32_16x16x32_bf16 v[128:131], v[24:27], v[178:181], v[128:131]
	v_mfma_f32_16x16x32_bf16 v[132:135], v[112:115], v[178:181], v[132:135]
	v_mfma_f32_16x16x32_bf16 v[136:139], v[24:27], v[186:189], v[136:139]
	v_mfma_f32_16x16x32_bf16 v[140:143], v[112:115], v[186:189], v[140:143]
	v_mfma_f32_16x16x32_bf16 v[0:3], v[24:27], v[202:205], v[0:3]
	v_mfma_f32_16x16x32_bf16 v[4:7], v[112:115], v[202:205], v[4:7]
	v_mfma_f32_16x16x32_bf16 v[128:131], v[28:31], v[182:185], v[128:131]
	v_mfma_f32_16x16x32_bf16 v[132:135], v[116:119], v[182:185], v[132:135]
	v_mfma_f32_16x16x32_bf16 v[136:139], v[28:31], v[190:193], v[136:139]
	v_mfma_f32_16x16x32_bf16 v[140:143], v[116:119], v[190:193], v[140:143]
	v_mfma_f32_16x16x32_bf16 v[156:159], v[24:27], v[194:197], v[156:159]
	v_mfma_f32_16x16x32_bf16 v[166:169], v[112:115], v[194:197], v[166:169]
	v_mfma_f32_16x16x32_bf16 v[0:3], v[28:31], v[206:209], v[0:3]
	v_mfma_f32_16x16x32_bf16 v[4:7], v[116:119], v[206:209], v[4:7]
	v_mfma_f32_16x16x32_bf16 v[156:159], v[28:31], v[198:201], v[156:159]
	v_mfma_f32_16x16x32_bf16 v[166:169], v[116:119], v[198:201], v[166:169]
	s_setprio 0
	s_setprio 1
	v_mfma_f32_16x16x32_bf16 v[8:11], v[120:123], v[178:181], v[8:11]
	v_mfma_f32_16x16x32_bf16 v[12:15], v[170:173], v[178:181], v[12:15]
	v_mfma_f32_16x16x32_bf16 v[24:27], v[120:123], v[186:189], v[60:63]
	v_mfma_f32_16x16x32_bf16 v[28:31], v[170:173], v[186:189], v[100:103]
	v_mfma_f32_16x16x32_bf16 v[60:63], v[120:123], v[194:197], v[104:107]
	v_mfma_f32_16x16x32_bf16 v[100:103], v[170:173], v[194:197], v[108:111]
	v_mfma_f32_16x16x32_bf16 v[20:23], v[170:173], v[202:205], v[20:23]
	v_mfma_f32_16x16x32_bf16 v[8:11], v[124:127], v[182:185], v[8:11]
	v_mfma_f32_16x16x32_bf16 v[12:15], v[174:177], v[182:185], v[12:15]
	v_mfma_f32_16x16x32_bf16 v[24:27], v[124:127], v[190:193], v[24:27]
	v_mfma_f32_16x16x32_bf16 v[60:63], v[124:127], v[198:201], v[60:63]
	v_mfma_f32_16x16x32_bf16 v[100:103], v[174:177], v[198:201], v[100:103]
	v_mfma_f32_16x16x32_bf16 v[16:19], v[120:123], v[202:205], v[16:19]
	v_mfma_f32_16x16x32_bf16 v[20:23], v[174:177], v[206:209], v[20:23]
	v_mfma_f32_16x16x32_bf16 v[28:31], v[174:177], v[190:193], v[28:31]
	v_mfma_f32_16x16x32_bf16 v[16:19], v[124:127], v[206:209], v[16:19]
	s_setprio 0
	s_barrier
; #define PG8_STAGE(bufoff, gbase, voff) do { _Pragma("unroll") for (int _i = 0; _i < 2; ++_i) \
;         __builtin_amdgcn_global_load_lds((const unsigned*)((const char*)(gbase) + (voff)[_i]), (LAS unsigned*)(lds + (bufoff) + ldsw + _i * 8192), 16, 0, 0); } while (0)
; #define PG8_LDA(dst, b, h) do { _Pragma("unroll") for (int m = 0; m < 4; ++m) _Pragma("unroll") for (int k = 0; k < 2; ++k) dst[m][k] = *(const LAS bf16x8*)(lds + PG8_SA(b, h) + aoff + m * 2048 + k * 1024); } while (0)
; #define PG8_LDB(dst, b, h) do { _Pragma("unroll") for (int n = 0; n < 2; ++n) _Pragma("unroll") for (int k = 0; k < 2; ++k) dst[n][k] = *(const LAS bf16x8*)(lds + PG8_SB(b, h) + boff + n * 2048 + k * 1024); } while (0)
; #define PG8_MMA(ai, bj, At, Bt) do { __builtin_amdgcn_s_setprio(1); _Pragma("unroll") for (int m = 0; m < 4; ++m) _Pragma("unroll") for (int n = 0; n < 2; ++n) _Pragma("unroll") for (int k = 0; k < 2; ++k) \
;         acc[ai][bj][m][n] = __builtin_amdgcn_mfma_f32_16x16x32_bf16(Bt[n][k], At[m][k], acc[ai][bj][m][n], 0, 0, 0); __builtin_amdgcn_s_setprio(0); } while (0)
; #define PG8_WAIT_V(n) asm volatile("s_waitcnt vmcnt(" #n ")" ::: "memory")
; #define PG8_WAIT_L(n) asm volatile("s_waitcnt lgkmcnt(" #n ")" ::: "memory")
; #define PG8_BAR __builtin_amdgcn_s_barrier()
; #define PG8_SCHED __builtin_amdgcn_sched_barrier(0)
; template <class Epi>
; __device__ __forceinline__ void gemm_phase(LAS unsigned char* lds, const Gemm g, const StaticOrder S, const Epi E) {
;     ...
;             const char* a1 = cA + (long)(t + 1) * ksc;
;             const char* a2 = last ? nA : cA + (long)(t + 2) * ksc; const char* b2 = last ? nB : cB + (long)(t + 2) * ksc;
;             const long ks3 = last ? ksn : ksc;
;             const char* a3 = a2 + ks3; const char* b3 = b2 + ks3;
;             PG8_LDB(B0, 0, 0); PG8_LDB(B1, 0, 1); PG8_SCHED; PG8_LDA(At, 0, 0); PG8_STAGE(PG8_SA(1, 1), a1 + hstepA, voffA);
;             PG8_WAIT_V(8); PG8_WAIT_L(0); PG8_BAR; PG8_MMA(0, 0, At, B0); PG8_MMA(0, 1, At, B1); PG8_BAR; PG8_SCHED;
;             PG8_LDA(At, 0, 1); PG8_STAGE(PG8_SB(0, 0), b2, voffB); PG8_STAGE(PG8_SB(0, 1), b2 + hstepB, voffB); PG8_STAGE(PG8_SA(0, 0), a2, voffA);
;             PG8_WAIT_V(8); PG8_WAIT_L(0); PG8_BAR; PG8_MMA(1, 0, At, B0); PG8_MMA(1, 1, At, B1); PG8_BAR; PG8_SCHED;
	ds_read_b128 v[104:107], v163
	ds_read_b128 v[108:111], v163 offset:1024
	ds_read_b128 v[112:115], v163 offset:2048
	ds_read_b128 v[116:119], v163 offset:3072
	ds_read_b128 v[120:123], v164
	ds_read_b128 v[124:127], v164 offset:1024
	ds_read_b128 v[170:173], v164 offset:2048
	ds_read_b128 v[174:177], v164 offset:3072
	s_add_u32 s48, s28, s27
	s_addc_u32 s49, s29, s25
	s_add_u32 s2, s50, s2
	s_addc_u32 s3, s51, s3
	s_mov_b32 m0, s74
	ds_read_b128 v[178:181], v165
	ds_read_b128 v[182:185], v165 offset:1024
	ds_read_b128 v[186:189], v165 offset:2048
	ds_read_b128 v[190:193], v165 offset:3072
	ds_read_b128 v[194:197], v165 offset:4096
	ds_read_b128 v[198:201], v165 offset:5120
	ds_read_b128 v[202:205], v165 offset:6144
	ds_read_b128 v[206:209], v165 offset:7168
	global_load_lds_dwordx4 v144, s[2:3]
	s_mov_b32 m0, s52
	s_nop 0
	global_load_lds_dwordx4 v148, s[2:3]
	s_waitcnt vmcnt(8)
	s_waitcnt lgkmcnt(0)
	s_barrier
	s_setprio 1
	s_waitcnt lgkmcnt(0)
	v_mfma_f32_16x16x32_bf16 v[64:67], v[104:107], v[178:181], v[64:67]
	v_mfma_f32_16x16x32_bf16 v[68:71], v[112:115], v[178:181], v[68:71]
	v_mfma_f32_16x16x32_bf16 v[72:75], v[104:107], v[186:189], v[72:75]
	v_mfma_f32_16x16x32_bf16 v[76:79], v[112:115], v[186:189], v[76:79]
	v_mfma_f32_16x16x32_bf16 v[80:83], v[104:107], v[194:197], v[80:83]
	v_mfma_f32_16x16x32_bf16 v[84:87], v[112:115], v[194:197], v[84:87]
	v_mfma_f32_16x16x32_bf16 v[88:91], v[104:107], v[202:205], v[88:91]
	v_mfma_f32_16x16x32_bf16 v[92:95], v[112:115], v[202:205], v[92:95]
	v_mfma_f32_16x16x32_bf16 v[64:67], v[108:111], v[182:185], v[64:67]
	v_mfma_f32_16x16x32_bf16 v[68:71], v[116:119], v[182:185], v[68:71]
	v_mfma_f32_16x16x32_bf16 v[72:75], v[108:111], v[190:193], v[72:75]
	v_mfma_f32_16x16x32_bf16 v[76:79], v[116:119], v[190:193], v[76:79]
	v_mfma_f32_16x16x32_bf16 v[80:83], v[108:111], v[198:201], v[80:83]
	v_mfma_f32_16x16x32_bf16 v[84:87], v[116:119], v[198:201], v[84:87]
	v_mfma_f32_16x16x32_bf16 v[88:91], v[108:111], v[206:209], v[88:91]
	v_mfma_f32_16x16x32_bf16 v[92:95], v[116:119], v[206:209], v[92:95]
	s_setprio 0
	s_setprio 1
	v_mfma_f32_16x16x32_bf16 v[96:99], v[120:123], v[178:181], v[96:99]
	v_mfma_f32_16x16x32_bf16 v[32:35], v[170:173], v[178:181], v[32:35]
	v_mfma_f32_16x16x32_bf16 v[36:39], v[120:123], v[186:189], v[36:39]
	v_mfma_f32_16x16x32_bf16 v[48:51], v[170:173], v[194:197], v[48:51]
	v_mfma_f32_16x16x32_bf16 v[52:55], v[120:123], v[202:205], v[52:55]
	v_mfma_f32_16x16x32_bf16 v[56:59], v[170:173], v[202:205], v[56:59]
	v_mfma_f32_16x16x32_bf16 v[96:99], v[124:127], v[182:185], v[96:99]
	v_mfma_f32_16x16x32_bf16 v[32:35], v[174:177], v[182:185], v[32:35]
	v_mfma_f32_16x16x32_bf16 v[36:39], v[124:127], v[190:193], v[36:39]
	v_mfma_f32_16x16x32_bf16 v[40:43], v[170:173], v[186:189], v[40:43]
	v_mfma_f32_16x16x32_bf16 v[44:47], v[120:123], v[194:197], v[44:47]
	v_mfma_f32_16x16x32_bf16 v[48:51], v[174:177], v[198:201], v[48:51]
	v_mfma_f32_16x16x32_bf16 v[52:55], v[124:127], v[206:209], v[52:55]
	v_mfma_f32_16x16x32_bf16 v[56:59], v[174:177], v[206:209], v[56:59]
	v_mfma_f32_16x16x32_bf16 v[40:43], v[174:177], v[190:193], v[40:43]
	v_mfma_f32_16x16x32_bf16 v[44:47], v[124:127], v[198:201], v[44:47]
	s_setprio 0
	s_barrier
	s_mov_b32 m0, s73
	s_add_u32 s2, s30, 0x10000
	ds_read_b128 v[178:181], v165 offset:16384
	ds_read_b128 v[182:185], v165 offset:17408
	ds_read_b128 v[186:189], v165 offset:18432
	ds_read_b128 v[190:193], v165 offset:19456
	ds_read_b128 v[194:197], v165 offset:20480
	ds_read_b128 v[198:201], v165 offset:21504
	ds_read_b128 v[202:205], v165 offset:22528
	ds_read_b128 v[206:209], v165 offset:23552
	global_load_lds_dwordx4 v146, s[30:31]
	s_mov_b32 m0, s53
	s_addc_u32 s3, s31, 0
	global_load_lds_dwordx4 v150, s[30:31]
	s_mov_b32 m0, s71
	s_nop 0
	global_load_lds_dwordx4 v146, s[2:3]
	s_mov_b32 m0, s72
	s_nop 0
	global_load_lds_dwordx4 v150, s[2:3]
	s_mov_b32 m0, s45
	s_nop 0
	global_load_lds_dwordx4 v144, s[28:29]
	s_mov_b32 m0, s47
	s_nop 0
	global_load_lds_dwordx4 v148, s[28:29]
	s_waitcnt vmcnt(8)
	s_waitcnt lgkmcnt(0)
	s_barrier
	s_setprio 1
	s_waitcnt lgkmcnt(0)
	v_mfma_f32_16x16x32_bf16 v[128:131], v[104:107], v[178:181], v[128:131]
	v_mfma_f32_16x16x32_bf16 v[210:213], v[108:111], v[182:185], v[128:131]
	v_mfma_f32_16x16x32_bf16 v[128:131], v[112:115], v[178:181], v[132:135]
	v_mfma_f32_16x16x32_bf16 v[214:217], v[116:119], v[182:185], v[128:131]
	v_mfma_f32_16x16x32_bf16 v[128:131], v[104:107], v[186:189], v[136:139]
	v_mfma_f32_16x16x32_bf16 v[218:221], v[108:111], v[190:193], v[128:131]
	v_mfma_f32_16x16x32_bf16 v[128:131], v[112:115], v[186:189], v[140:143]
	v_mfma_f32_16x16x32_bf16 v[226:229], v[116:119], v[190:193], v[128:131]
	v_mfma_f32_16x16x32_bf16 v[128:131], v[104:107], v[194:197], v[156:159]
	v_mfma_f32_16x16x32_bf16 v[0:3], v[104:107], v[202:205], v[0:3]
	v_mfma_f32_16x16x32_bf16 v[4:7], v[112:115], v[202:205], v[4:7]
	v_mfma_f32_16x16x32_bf16 v[156:159], v[108:111], v[198:201], v[128:131]
	v_mfma_f32_16x16x32_bf16 v[128:131], v[112:115], v[194:197], v[166:169]
	v_mfma_f32_16x16x32_bf16 v[0:3], v[108:111], v[206:209], v[0:3]
	v_mfma_f32_16x16x32_bf16 v[4:7], v[116:119], v[206:209], v[4:7]
	v_mfma_f32_16x16x32_bf16 v[166:169], v[116:119], v[198:201], v[128:131]
	s_setprio 0
	s_setprio 1
	v_mfma_f32_16x16x32_bf16 v[8:11], v[120:123], v[178:181], v[8:11]
	v_mfma_f32_16x16x32_bf16 v[230:233], v[124:127], v[182:185], v[8:11]
	v_mfma_f32_16x16x32_bf16 v[8:11], v[170:173], v[178:181], v[12:15]
	v_mfma_f32_16x16x32_bf16 v[178:181], v[174:177], v[182:185], v[8:11]
	v_mfma_f32_16x16x32_bf16 v[8:11], v[120:123], v[186:189], v[24:27]
	v_mfma_f32_16x16x32_bf16 v[24:27], v[124:127], v[190:193], v[8:11]
	v_mfma_f32_16x16x32_bf16 v[8:11], v[170:173], v[186:189], v[28:31]
	v_mfma_f32_16x16x32_bf16 v[28:31], v[174:177], v[190:193], v[8:11]
	v_mfma_f32_16x16x32_bf16 v[8:11], v[120:123], v[194:197], v[60:63]
	v_mfma_f32_16x16x32_bf16 v[182:185], v[124:127], v[198:201], v[8:11]
	v_mfma_f32_16x16x32_bf16 v[8:11], v[170:173], v[194:197], v[100:103]
	v_mfma_f32_16x16x32_bf16 v[186:189], v[174:177], v[198:201], v[8:11]
	v_mfma_f32_16x16x32_bf16 v[8:11], v[120:123], v[202:205], v[16:19]
	v_mfma_f32_16x16x32_bf16 v[16:19], v[124:127], v[206:209], v[8:11]
	v_mfma_f32_16x16x32_bf16 v[8:11], v[170:173], v[202:205], v[20:23]
	v_mfma_f32_16x16x32_bf16 v[170:173], v[174:177], v[206:209], v[8:11]
	s_setprio 0
	s_barrier
; #define PG8_STAGE(bufoff, gbase, voff) do { _Pragma("unroll") for (int _i = 0; _i < 2; ++_i) \
;         __builtin_amdgcn_global_load_lds((const unsigned*)((const char*)(gbase) + (voff)[_i]), (LAS unsigned*)(lds + (bufoff) + ldsw + _i * 8192), 16, 0, 0); } while (0)
; #define PG8_LDA(dst, b, h) do { _Pragma("unroll") for (int m = 0; m < 4; ++m) _Pragma("unroll") for (int k = 0; k < 2; ++k) dst[m][k] = *(const LAS bf16x8*)(lds + PG8_SA(b, h) + aoff + m * 2048 + k * 1024); } while (0)
; #define PG8_LDB(dst, b, h) do { _Pragma("unroll") for (int n = 0; n < 2; ++n) _Pragma("unroll") for (int k = 0; k < 2; ++k) dst[n][k] = *(const LAS bf16x8*)(lds + PG8_SB(b, h) + boff + n * 2048 + k * 1024); } while (0)
; #define PG8_MMA(ai, bj, At, Bt) do { __builtin_amdgcn_s_setprio(1); _Pragma("unroll") for (int m = 0; m < 4; ++m) _Pragma("unroll") for (int n = 0; n < 2; ++n) _Pragma("unroll") for (int k = 0; k < 2; ++k) \
;         acc[ai][bj][m][n] = __builtin_amdgcn_mfma_f32_16x16x32_bf16(Bt[n][k], At[m][k], acc[ai][bj][m][n], 0, 0, 0); __builtin_amdgcn_s_setprio(0); } while (0)
; #define PG8_WAIT_V(n) asm volatile("s_waitcnt vmcnt(" #n ")" ::: "memory")
; #define PG8_WAIT_L(n) asm volatile("s_waitcnt lgkmcnt(" #n ")" ::: "memory")
; #define PG8_BAR __builtin_amdgcn_s_barrier()
; #define PG8_SCHED __builtin_amdgcn_sched_barrier(0)
; template <class Epi>
; __device__ __forceinline__ void gemm_phase(LAS unsigned char* lds, const Gemm g, const StaticOrder S, const Epi E) {
;     ...
;             PG8_LDB(B0, 1, 0); PG8_LDB(B1, 1, 1); PG8_SCHED; PG8_LDA(At, 1, 0); PG8_STAGE(PG8_SA(0, 1), a2 + hstepA, voffA);
;             PG8_WAIT_V(8); PG8_WAIT_L(0); PG8_BAR; PG8_MMA(0, 0, At, B0); PG8_MMA(0, 1, At, B1); PG8_BAR; PG8_SCHED;
;             PG8_LDA(At, 1, 1); PG8_STAGE(PG8_SB(1, 0), b3, voffB); PG8_STAGE(PG8_SB(1, 1), b3 + hstepB, voffB); PG8_STAGE(PG8_SA(1, 0), a3, voffA);
;             PG8_WAIT_V(8); PG8_WAIT_L(0); PG8_BAR; PG8_MMA(1, 0, At, B0); PG8_MMA(1, 1, At, B1); PG8_BAR; PG8_SCHED;
;         }
;         if (wr == 0) PG8_BAR;
	s_nop 4
	ds_read_b128 v[8:11], v222
	ds_read_b128 v[12:15], v222 offset:1024
	ds_read_b128 v[20:23], v222 offset:2048
	ds_read_b128 v[174:177], v222 offset:3072
	ds_read_b128 v[190:193], v223
	ds_read_b128 v[194:197], v223 offset:1024
	ds_read_b128 v[198:201], v223 offset:2048
	ds_read_b128 v[202:205], v223 offset:3072
	s_add_u32 s2, s28, 0x40000
	s_addc_u32 s3, s29, 0
	s_mov_b32 m0, s60
	ds_read_b128 v[60:63], v165 offset:32768
	ds_read_b128 v[100:103], v165 offset:33792
	ds_read_b128 v[112:115], v165 offset:34816
	ds_read_b128 v[206:209], v165 offset:35840
	ds_read_b128 v[234:237], v165 offset:36864
	ds_read_b128 v[238:241], v165 offset:37888
	ds_read_b128 v[242:245], v165 offset:38912
	ds_read_b128 v[246:249], v165 offset:39936
	global_load_lds_dwordx4 v144, s[2:3]
	s_mov_b32 m0, s61
	s_nop 0
	global_load_lds_dwordx4 v148, s[2:3]
	s_waitcnt vmcnt(8)
	s_waitcnt lgkmcnt(0)
	s_barrier
	s_setprio 1
	s_waitcnt lgkmcnt(0)
	v_mfma_f32_16x16x32_bf16 v[64:67], v[8:11], v[60:63], v[64:67]
	v_mfma_f32_16x16x32_bf16 v[140:143], v[12:15], v[100:103], v[64:67]
	v_mfma_f32_16x16x32_bf16 v[64:67], v[20:23], v[60:63], v[68:71]
	v_mfma_f32_16x16x32_bf16 v[136:139], v[174:177], v[100:103], v[64:67]
	v_mfma_f32_16x16x32_bf16 v[64:67], v[8:11], v[112:115], v[72:75]
	v_mfma_f32_16x16x32_bf16 v[124:127], v[12:15], v[206:209], v[64:67]
	v_mfma_f32_16x16x32_bf16 v[64:67], v[20:23], v[112:115], v[76:79]
	v_mfma_f32_16x16x32_bf16 v[120:123], v[174:177], v[206:209], v[64:67]
	v_mfma_f32_16x16x32_bf16 v[64:67], v[8:11], v[234:237], v[80:83]
	v_mfma_f32_16x16x32_bf16 v[108:111], v[12:15], v[238:241], v[64:67]
	v_mfma_f32_16x16x32_bf16 v[64:67], v[20:23], v[234:237], v[84:87]
	v_mfma_f32_16x16x32_bf16 v[104:107], v[174:177], v[238:241], v[64:67]
	v_mfma_f32_16x16x32_bf16 v[64:67], v[8:11], v[242:245], v[88:91]
	v_mfma_f32_16x16x32_bf16 v[80:83], v[12:15], v[246:249], v[64:67]
	v_mfma_f32_16x16x32_bf16 v[64:67], v[20:23], v[242:245], v[92:95]
	v_mfma_f32_16x16x32_bf16 v[72:75], v[174:177], v[246:249], v[64:67]
	s_setprio 0
	s_setprio 1
	v_mfma_f32_16x16x32_bf16 v[32:35], v[198:201], v[60:63], v[32:35]
	v_mfma_f32_16x16x32_bf16 v[128:131], v[202:205], v[100:103], v[32:35]
	v_mfma_f32_16x16x32_bf16 v[32:35], v[190:193], v[112:115], v[36:39]
	v_mfma_f32_16x16x32_bf16 v[116:119], v[194:197], v[206:209], v[32:35]
	v_mfma_f32_16x16x32_bf16 v[32:35], v[198:201], v[112:115], v[40:43]
	v_mfma_f32_16x16x32_bf16 v[64:67], v[190:193], v[60:63], v[96:99]
	v_mfma_f32_16x16x32_bf16 v[112:115], v[202:205], v[206:209], v[32:35]
	v_mfma_f32_16x16x32_bf16 v[32:35], v[190:193], v[234:237], v[44:47]
	v_mfma_f32_16x16x32_bf16 v[132:135], v[194:197], v[100:103], v[64:67]
	v_mfma_f32_16x16x32_bf16 v[100:103], v[194:197], v[238:241], v[32:35]
	v_mfma_f32_16x16x32_bf16 v[32:35], v[198:201], v[234:237], v[48:51]
	v_mfma_f32_16x16x32_bf16 v[96:99], v[202:205], v[238:241], v[32:35]
	v_mfma_f32_16x16x32_bf16 v[32:35], v[190:193], v[242:245], v[52:55]
	v_mfma_f32_16x16x32_bf16 v[68:71], v[194:197], v[246:249], v[32:35]
	v_mfma_f32_16x16x32_bf16 v[32:35], v[198:201], v[242:245], v[56:59]
	v_mfma_f32_16x16x32_bf16 v[64:67], v[202:205], v[246:249], v[32:35]
	s_setprio 0
	s_barrier
	s_add_u32 s2, s30, s27
	s_addc_u32 s3, s31, s25
	s_mov_b32 m0, s59
	s_nop 1
	ds_read_b128 v[40:43], v165 offset:49152
	ds_read_b128 v[44:47], v165 offset:50176
	ds_read_b128 v[48:51], v165 offset:51200
	ds_read_b128 v[206:209], v165 offset:52224
	ds_read_b128 v[234:237], v165 offset:53248
	ds_read_b128 v[238:241], v165 offset:54272
	ds_read_b128 v[242:245], v165 offset:55296
	ds_read_b128 v[246:249], v165 offset:56320
	global_load_lds_dwordx4 v146, s[2:3]
	v_lshl_add_u64 v[32:33], s[2:3], 0, v[150:151]
	s_add_u32 s2, s2, 0x10000
	s_mov_b32 m0, s56
	s_addc_u32 s3, s3, 0
	global_load_lds_dwordx4 v[32:33], off
	s_mov_b32 m0, s57
	s_nop 0
	global_load_lds_dwordx4 v146, s[2:3]
	s_mov_b32 m0, s58
	s_nop 0
	global_load_lds_dwordx4 v150, s[2:3]
	s_mov_b32 m0, s63
	s_nop 0
	global_load_lds_dwordx4 v144, s[48:49]
	s_mov_b32 m0, s64
	s_nop 0
	global_load_lds_dwordx4 v148, s[48:49]
	s_waitcnt vmcnt(8)
	s_waitcnt lgkmcnt(0)
	s_barrier
	s_setprio 1
	s_waitcnt lgkmcnt(0)
	v_mfma_f32_16x16x32_bf16 v[32:35], v[8:11], v[40:43], v[210:213]
	v_mfma_f32_16x16x32_bf16 v[92:95], v[12:15], v[44:47], v[32:35]
	v_mfma_f32_16x16x32_bf16 v[32:35], v[20:23], v[40:43], v[214:217]
	v_mfma_f32_16x16x32_bf16 v[88:91], v[174:177], v[44:47], v[32:35]
	v_mfma_f32_16x16x32_bf16 v[32:35], v[8:11], v[48:51], v[218:221]
	v_mfma_f32_16x16x32_bf16 v[60:63], v[12:15], v[206:209], v[32:35]
	v_mfma_f32_16x16x32_bf16 v[32:35], v[20:23], v[48:51], v[226:229]
	v_mfma_f32_16x16x32_bf16 v[56:59], v[174:177], v[206:209], v[32:35]
	v_mfma_f32_16x16x32_bf16 v[32:35], v[8:11], v[234:237], v[156:159]
	v_mfma_f32_16x16x32_bf16 v[0:3], v[8:11], v[242:245], v[0:3]
	v_mfma_f32_16x16x32_bf16 v[36:39], v[12:15], v[238:241], v[32:35]
	v_mfma_f32_16x16x32_bf16 v[32:35], v[20:23], v[234:237], v[166:169]
	v_mfma_f32_16x16x32_bf16 v[12:15], v[12:15], v[246:249], v[0:3]
	v_mfma_f32_16x16x32_bf16 v[0:3], v[20:23], v[242:245], v[4:7]
	v_mfma_f32_16x16x32_bf16 v[32:35], v[174:177], v[238:241], v[32:35]
	v_mfma_f32_16x16x32_bf16 v[8:11], v[174:177], v[246:249], v[0:3]
	s_setprio 0
	s_setprio 1
	v_mfma_f32_16x16x32_bf16 v[0:3], v[190:193], v[40:43], v[230:233]
	v_mfma_f32_16x16x32_bf16 v[84:87], v[194:197], v[44:47], v[0:3]
	v_mfma_f32_16x16x32_bf16 v[0:3], v[198:201], v[40:43], v[178:181]
	v_mfma_f32_16x16x32_bf16 v[76:79], v[202:205], v[44:47], v[0:3]
	v_mfma_f32_16x16x32_bf16 v[0:3], v[190:193], v[48:51], v[24:27]
	v_mfma_f32_16x16x32_bf16 v[52:55], v[194:197], v[206:209], v[0:3]
	v_mfma_f32_16x16x32_bf16 v[0:3], v[198:201], v[48:51], v[28:31]
	v_mfma_f32_16x16x32_bf16 v[48:51], v[202:205], v[206:209], v[0:3]
	v_mfma_f32_16x16x32_bf16 v[0:3], v[190:193], v[234:237], v[182:185]
	v_mfma_f32_16x16x32_bf16 v[24:27], v[194:197], v[238:241], v[0:3]
	v_mfma_f32_16x16x32_bf16 v[0:3], v[198:201], v[234:237], v[186:189]
	v_mfma_f32_16x16x32_bf16 v[20:23], v[202:205], v[238:241], v[0:3]
	v_mfma_f32_16x16x32_bf16 v[0:3], v[190:193], v[242:245], v[16:19]
	v_mfma_f32_16x16x32_bf16 v[4:7], v[194:197], v[246:249], v[0:3]
	v_mfma_f32_16x16x32_bf16 v[0:3], v[198:201], v[242:245], v[170:173]
	v_mfma_f32_16x16x32_bf16 v[0:3], v[202:205], v[246:249], v[0:3]
	s_setprio 0
	s_barrier
	s_andn2_b64 vcc, exec, s[12:13]
	s_cbranch_vccnz .LBB0_482
	s_barrier

; #define PG8_STAGE(bufoff, gbase, voff) do { _Pragma("unroll") for (int _i = 0; _i < 2; ++_i) \
;         __builtin_amdgcn_global_load_lds((const unsigned*)((const char*)(gbase) + (voff)[_i]), (LAS unsigned*)(lds + (bufoff) + ldsw + _i * 8192), 16, 0, 0); } while (0)
; #define PG8_WAIT_V(n) asm volatile("s_waitcnt vmcnt(" #n ")" ::: "memory")
; #define PG8_BAR __builtin_amdgcn_s_barrier()
; template <class Epi>
; __device__ __forceinline__ void gemm_phase(LAS unsigned char* lds, const Gemm g, const StaticOrder S, const Epi E) {
;     ...
;     PG8_STAGE(PG8_SB(0, 0), cB, voffB); PG8_STAGE(PG8_SB(0, 1), cB + hstepB, voffB); PG8_STAGE(PG8_SA(0, 0), cA, voffA); PG8_STAGE(PG8_SA(0, 1), cA + hstepA, voffA);
;     if (wr == 1) PG8_BAR;
;     PG8_WAIT_V(2); PG8_BAR;
;     PG8_STAGE(PG8_SB(1, 0), cB + ksc, voffB); PG8_STAGE(PG8_SA(1, 0), cA + ksc, voffA); PG8_STAGE(PG8_SB(1, 1), cB + hstepB + ksc, voffB);
;     PG8_WAIT_V(6); PG8_BAR;
.LBB0_556:
	s_lshl_b32 s1, s1, 5
	s_mov_b64 s[44:45], 0x80
	s_and_b32 s12, s1, 0x60
	s_add_i32 m0, s31, 0x18000
	v_lshl_add_u64 v[6:7], v[6:7], 0, s[44:45]
	s_lshl_b32 s9, s0, 13
	s_lshl_b32 s1, s12, 7
	s_ashr_i32 s63, s79, 31
	s_waitcnt vmcnt(2)
	s_barrier
	global_load_lds_dwordx4 v[6:7], off
	v_lshl_add_u64 v[2:3], v[2:3], 0, s[44:45]
	s_add_i32 m0, s31, 0x1a000
	s_add_i32 s64, s31, 0x8000
	s_add_i32 s65, s31, 0xa000
	global_load_lds_dwordx4 v[2:3], off
	v_lshl_add_u64 v[0:1], v[0:1], 0, s[44:45]
	s_mov_b32 m0, s64
	s_add_u32 s2, s34, 0x80080
	global_load_lds_dwordx4 v[0:1], off
	v_lshl_add_u64 v[0:1], v[4:5], 0, s[44:45]
	s_mov_b32 m0, s65
	s_addc_u32 s3, s35, 0
	global_load_lds_dwordx4 v[0:1], off
	s_add_i32 m0, s31, 0x1c000
	s_nop 0
	global_load_lds_dwordx4 v142, s[2:3]
	s_add_i32 m0, s31, 0x1e000
	v_and_b32_e32 v3, 32, v162
	global_load_lds_dwordx4 v146, s[2:3]
	v_and_b32_e32 v1, 3, v161
	v_and_b32_e32 v0, 15, v224
	v_lshlrev_b32_e32 v2, 4, v1
	v_lshl_or_b32 v163, s0, 6, v0
	v_lshl_or_b32 v0, v0, 6, v2
	s_ashr_i32 s66, s78, 31
	v_bitop3_b32 v0, v0, s9, v3 bitop3:0xde
	v_lshlrev_b32_e32 v4, 6, v224
	s_movk_i32 s0, 0x3c0
	s_waitcnt vmcnt(6)
	s_cmpk_lt_u32 s8, 0x100
	v_and_or_b32 v2, v4, s0, v2
	s_cselect_b64 s[8:9], -1, 0
	s_add_u32 s10, s82, 0x2a9a0000
	v_add_u32_e32 v166, 0, v0
	v_mbcnt_lo_u32_b32 v0, -1, 0
	v_bitop3_b32 v164, s1, v2, v3 bitop3:0xf6
	s_addc_u32 s11, s83, 0
	v_cmp_eq_u32_e64 s[0:1], 0, v1
	v_lshl_or_b32 v165, v1, 3, s12
	v_mov_b64_e32 v[148:149], 0x200
	v_mov_b64_e32 v[150:151], 0x1ff
	s_add_i32 s67, 0, 0x10000
	s_add_i32 s68, 0, 0x14000
	s_mov_b32 s69, 0x80000
	s_mov_b64 s[12:13], 0x90000
	s_mov_b32 s70, 0x90000
	s_mov_b64 s[14:15], 0xa0000
	s_mov_b32 s71, 0xa0000
	s_mov_b64 s[16:17], 0xb0000
	s_mov_b32 s72, 0xb0000
	v_mbcnt_hi_u32_b32 v167, -1, v0
	s_barrier
	s_branch .LBB0_559

; #define PG8_STAGE(bufoff, gbase, voff) do { _Pragma("unroll") for (int _i = 0; _i < 2; ++_i) \
;         __builtin_amdgcn_global_load_lds((const unsigned*)((const char*)(gbase) + (voff)[_i]), (LAS unsigned*)(lds + (bufoff) + ldsw + _i * 8192), 16, 0, 0); } while (0)
; #define PG8_LDA(dst, b, h) do { _Pragma("unroll") for (int m = 0; m < 4; ++m) _Pragma("unroll") for (int k = 0; k < 2; ++k) dst[m][k] = *(const LAS bf16x8*)(lds + PG8_SA(b, h) + aoff + m * 2048 + k * 1024); } while (0)
; #define PG8_LDB(dst, b, h) do { _Pragma("unroll") for (int n = 0; n < 2; ++n) _Pragma("unroll") for (int k = 0; k < 2; ++k) dst[n][k] = *(const LAS bf16x8*)(lds + PG8_SB(b, h) + boff + n * 2048 + k * 1024); } while (0)
; #define PG8_MMA(ai, bj, At, Bt) do { __builtin_amdgcn_s_setprio(1); _Pragma("unroll") for (int m = 0; m < 4; ++m) _Pragma("unroll") for (int n = 0; n < 2; ++n) _Pragma("unroll") for (int k = 0; k < 2; ++k) \
;         acc[ai][bj][m][n] = __builtin_amdgcn_mfma_f32_16x16x32_bf16(Bt[n][k], At[m][k], acc[ai][bj][m][n], 0, 0, 0); __builtin_amdgcn_s_setprio(0); } while (0)
; #define PG8_WAIT_V(n) asm volatile("s_waitcnt vmcnt(" #n ")" ::: "memory")
; #define PG8_WAIT_L(n) asm volatile("s_waitcnt lgkmcnt(" #n ")" ::: "memory")
; #define PG8_BAR __builtin_amdgcn_s_barrier()
; #define PG8_SCHED __builtin_amdgcn_sched_barrier(0)
; template <class Epi>
; __device__ __forceinline__ void gemm_phase(LAS unsigned char* lds, const Gemm g, const StaticOrder S, const Epi E) {
;     ...
;             const char* a1 = cA + (long)(t + 1) * ksc;
;             const char* a2 = last ? nA : cA + (long)(t + 2) * ksc; const char* b2 = last ? nB : cB + (long)(t + 2) * ksc;
;             const long ks3 = last ? ksn : ksc;
;             const char* a3 = a2 + ks3; const char* b3 = b2 + ks3;
;             PG8_LDB(B0, 0, 0); PG8_LDB(B1, 0, 1); PG8_SCHED; PG8_LDA(At, 0, 0); PG8_STAGE(PG8_SA(1, 1), a1 + hstepA, voffA);
;             PG8_WAIT_V(8); PG8_WAIT_L(0); PG8_BAR; PG8_MMA(0, 0, At, B0); PG8_MMA(0, 1, At, B1); PG8_BAR; PG8_SCHED;
;             PG8_LDA(At, 0, 1); PG8_STAGE(PG8_SB(0, 0), b2, voffB); PG8_STAGE(PG8_SB(0, 1), b2 + hstepB, voffB); PG8_STAGE(PG8_SA(0, 0), a2, voffA);
;             PG8_WAIT_V(8); PG8_WAIT_L(0); PG8_BAR; PG8_MMA(1, 0, At, B0); PG8_MMA(1, 1, At, B1); PG8_BAR; PG8_SCHED;
.LBB0_566:
	v_add_u32_e32 v152, s67, v164
	v_add_u32_e32 v176, s68, v164
	ds_read_b128 v[128:131], v152
	ds_read_b128 v[132:135], v152 offset:1024
	ds_read_b128 v[136:139], v152 offset:2048
	ds_read_b128 v[152:155], v152 offset:3072
	ds_read_b128 v[156:159], v176
	ds_read_b128 v[168:171], v176 offset:1024
	ds_read_b128 v[172:175], v176 offset:2048
	ds_read_b128 v[176:179], v176 offset:3072
	s_or_b32 s21, s29, 1
	s_mul_i32 s58, s45, s21
	s_mul_hi_u32 s59, s44, s21
	s_add_i32 s59, s59, s58
	s_mul_i32 s21, s44, s21
	s_add_u32 s21, s42, s21
	s_addc_u32 s75, s43, s59
	s_add_u32 s58, s56, s54
	s_addc_u32 s59, s57, s55
	s_add_u32 s74, s21, 0x80000
	s_addc_u32 s75, s75, 0
	s_add_i32 m0, s31, 0xc000
	ds_read_b128 v[180:183], v166
	ds_read_b128 v[184:187], v166 offset:1024
	ds_read_b128 v[188:191], v166 offset:2048
	ds_read_b128 v[192:195], v166 offset:3072
	ds_read_b128 v[196:199], v166 offset:4096
	ds_read_b128 v[200:203], v166 offset:5120
	ds_read_b128 v[204:207], v166 offset:6144
	ds_read_b128 v[208:211], v166 offset:7168
	global_load_lds_dwordx4 v140, s[74:75]
	s_add_i32 m0, s31, 0xe000
	s_nop 0
	global_load_lds_dwordx4 v144, s[74:75]
	s_waitcnt vmcnt(8)
	s_waitcnt lgkmcnt(0)
	s_barrier
	s_setprio 1
	s_waitcnt lgkmcnt(0)
	v_mfma_f32_16x16x32_bf16 v[124:127], v[128:131], v[180:183], v[124:127]
	v_mfma_f32_16x16x32_bf16 v[120:123], v[136:139], v[180:183], v[120:123]
	v_mfma_f32_16x16x32_bf16 v[108:111], v[128:131], v[188:191], v[108:111]
	v_mfma_f32_16x16x32_bf16 v[104:107], v[136:139], v[188:191], v[104:107]
	v_mfma_f32_16x16x32_bf16 v[92:95], v[128:131], v[196:199], v[92:95]
	v_mfma_f32_16x16x32_bf16 v[88:91], v[136:139], v[196:199], v[88:91]
	v_mfma_f32_16x16x32_bf16 v[76:79], v[128:131], v[204:207], v[76:79]
	v_mfma_f32_16x16x32_bf16 v[72:75], v[136:139], v[204:207], v[72:75]
	v_mfma_f32_16x16x32_bf16 v[124:127], v[132:135], v[184:187], v[124:127]
	v_mfma_f32_16x16x32_bf16 v[120:123], v[152:155], v[184:187], v[120:123]
	v_mfma_f32_16x16x32_bf16 v[108:111], v[132:135], v[192:195], v[108:111]
	v_mfma_f32_16x16x32_bf16 v[104:107], v[152:155], v[192:195], v[104:107]
	v_mfma_f32_16x16x32_bf16 v[92:95], v[132:135], v[200:203], v[92:95]
	v_mfma_f32_16x16x32_bf16 v[88:91], v[152:155], v[200:203], v[88:91]
	v_mfma_f32_16x16x32_bf16 v[76:79], v[132:135], v[208:211], v[76:79]
	v_mfma_f32_16x16x32_bf16 v[72:75], v[152:155], v[208:211], v[72:75]
	s_setprio 0
	s_setprio 1
	v_mfma_f32_16x16x32_bf16 v[116:119], v[156:159], v[180:183], v[116:119]
	v_mfma_f32_16x16x32_bf16 v[112:115], v[172:175], v[180:183], v[112:115]
	v_mfma_f32_16x16x32_bf16 v[100:103], v[156:159], v[188:191], v[100:103]
	v_mfma_f32_16x16x32_bf16 v[96:99], v[172:175], v[188:191], v[96:99]
	v_mfma_f32_16x16x32_bf16 v[84:87], v[156:159], v[196:199], v[84:87]
	v_mfma_f32_16x16x32_bf16 v[80:83], v[172:175], v[196:199], v[80:83]
	v_mfma_f32_16x16x32_bf16 v[68:71], v[156:159], v[204:207], v[68:71]
	v_mfma_f32_16x16x32_bf16 v[64:67], v[172:175], v[204:207], v[64:67]
	v_mfma_f32_16x16x32_bf16 v[116:119], v[168:171], v[184:187], v[116:119]
	v_mfma_f32_16x16x32_bf16 v[112:115], v[176:179], v[184:187], v[112:115]
	v_mfma_f32_16x16x32_bf16 v[100:103], v[168:171], v[192:195], v[100:103]
	v_mfma_f32_16x16x32_bf16 v[96:99], v[176:179], v[192:195], v[96:99]
	v_mfma_f32_16x16x32_bf16 v[84:87], v[168:171], v[200:203], v[84:87]
	v_mfma_f32_16x16x32_bf16 v[80:83], v[176:179], v[200:203], v[80:83]
	v_mfma_f32_16x16x32_bf16 v[68:71], v[168:171], v[208:211], v[68:71]
	v_mfma_f32_16x16x32_bf16 v[64:67], v[176:179], v[208:211], v[64:67]
	s_setprio 0
	s_barrier
	s_add_i32 s21, s67, s33
	s_mov_b32 m0, s21
	ds_read_b128 v[180:183], v166 offset:16384
	ds_read_b128 v[184:187], v166 offset:17408
	ds_read_b128 v[188:191], v166 offset:18432
	ds_read_b128 v[192:195], v166 offset:19456
	ds_read_b128 v[196:199], v166 offset:20480
	ds_read_b128 v[200:203], v166 offset:21504
	ds_read_b128 v[204:207], v166 offset:22528
	ds_read_b128 v[208:211], v166 offset:23552
	global_load_lds_dwordx4 v142, s[52:53]
	s_add_i32 m0, s21, 0x2000
	s_add_u32 s74, s52, 0x80000
	s_addc_u32 s75, s53, 0
	s_add_i32 s21, s68, s33
	global_load_lds_dwordx4 v146, s[52:53]
	s_mov_b32 m0, s21
	s_nop 0
	global_load_lds_dwordx4 v142, s[74:75]
	s_add_i32 m0, s21, 0x2000
	s_nop 0
	global_load_lds_dwordx4 v146, s[74:75]
	s_mov_b32 m0, s31
	s_nop 0
	global_load_lds_dwordx4 v140, s[56:57]
	s_mov_b32 m0, s60
	s_nop 0
	global_load_lds_dwordx4 v144, s[56:57]
	s_waitcnt vmcnt(8)
	s_waitcnt lgkmcnt(0)
	s_barrier
	s_setprio 1
	s_waitcnt lgkmcnt(0)
	v_mfma_f32_16x16x32_bf16 v[60:63], v[128:131], v[180:183], v[60:63]
	v_mfma_f32_16x16x32_bf16 v[56:59], v[136:139], v[180:183], v[56:59]
	v_mfma_f32_16x16x32_bf16 v[44:47], v[128:131], v[188:191], v[44:47]
	v_mfma_f32_16x16x32_bf16 v[40:43], v[136:139], v[188:191], v[40:43]
	v_mfma_f32_16x16x32_bf16 v[28:31], v[128:131], v[196:199], v[28:31]
	v_mfma_f32_16x16x32_bf16 v[24:27], v[136:139], v[196:199], v[24:27]
	v_mfma_f32_16x16x32_bf16 v[12:15], v[128:131], v[204:207], v[12:15]
	v_mfma_f32_16x16x32_bf16 v[8:11], v[136:139], v[204:207], v[8:11]
	v_mfma_f32_16x16x32_bf16 v[60:63], v[132:135], v[184:187], v[60:63]
	v_mfma_f32_16x16x32_bf16 v[56:59], v[152:155], v[184:187], v[56:59]
	v_mfma_f32_16x16x32_bf16 v[44:47], v[132:135], v[192:195], v[44:47]
	v_mfma_f32_16x16x32_bf16 v[40:43], v[152:155], v[192:195], v[40:43]
	v_mfma_f32_16x16x32_bf16 v[28:31], v[132:135], v[200:203], v[28:31]
	v_mfma_f32_16x16x32_bf16 v[24:27], v[152:155], v[200:203], v[24:27]
	v_mfma_f32_16x16x32_bf16 v[12:15], v[132:135], v[208:211], v[12:15]
	v_mfma_f32_16x16x32_bf16 v[8:11], v[152:155], v[208:211], v[8:11]
	s_setprio 0
	s_setprio 1
	v_mfma_f32_16x16x32_bf16 v[52:55], v[156:159], v[180:183], v[52:55]
	v_mfma_f32_16x16x32_bf16 v[48:51], v[172:175], v[180:183], v[48:51]
	v_mfma_f32_16x16x32_bf16 v[36:39], v[156:159], v[188:191], v[36:39]
	v_mfma_f32_16x16x32_bf16 v[32:35], v[172:175], v[188:191], v[32:35]
	v_mfma_f32_16x16x32_bf16 v[20:23], v[156:159], v[196:199], v[20:23]
	v_mfma_f32_16x16x32_bf16 v[16:19], v[172:175], v[196:199], v[16:19]
	v_mfma_f32_16x16x32_bf16 v[4:7], v[156:159], v[204:207], v[4:7]
	v_mfma_f32_16x16x32_bf16 v[0:3], v[172:175], v[204:207], v[0:3]
	v_mfma_f32_16x16x32_bf16 v[52:55], v[168:171], v[184:187], v[52:55]
	v_mfma_f32_16x16x32_bf16 v[48:51], v[176:179], v[184:187], v[48:51]
	v_mfma_f32_16x16x32_bf16 v[36:39], v[168:171], v[192:195], v[36:39]
	v_mfma_f32_16x16x32_bf16 v[32:35], v[176:179], v[192:195], v[32:35]
	v_mfma_f32_16x16x32_bf16 v[20:23], v[168:171], v[200:203], v[20:23]
	v_mfma_f32_16x16x32_bf16 v[16:19], v[176:179], v[200:203], v[16:19]
	v_mfma_f32_16x16x32_bf16 v[4:7], v[168:171], v[208:211], v[4:7]
	v_mfma_f32_16x16x32_bf16 v[0:3], v[176:179], v[208:211], v[0:3]
	s_setprio 0
	s_barrier
; #define PG8_STAGE(bufoff, gbase, voff) do { _Pragma("unroll") for (int _i = 0; _i < 2; ++_i) \
;         __builtin_amdgcn_global_load_lds((const unsigned*)((const char*)(gbase) + (voff)[_i]), (LAS unsigned*)(lds + (bufoff) + ldsw + _i * 8192), 16, 0, 0); } while (0)
; #define PG8_LDA(dst, b, h) do { _Pragma("unroll") for (int m = 0; m < 4; ++m) _Pragma("unroll") for (int k = 0; k < 2; ++k) dst[m][k] = *(const LAS bf16x8*)(lds + PG8_SA(b, h) + aoff + m * 2048 + k * 1024); } while (0)
; #define PG8_LDB(dst, b, h) do { _Pragma("unroll") for (int n = 0; n < 2; ++n) _Pragma("unroll") for (int k = 0; k < 2; ++k) dst[n][k] = *(const LAS bf16x8*)(lds + PG8_SB(b, h) + boff + n * 2048 + k * 1024); } while (0)
; #define PG8_MMA(ai, bj, At, Bt) do { __builtin_amdgcn_s_setprio(1); _Pragma("unroll") for (int m = 0; m < 4; ++m) _Pragma("unroll") for (int n = 0; n < 2; ++n) _Pragma("unroll") for (int k = 0; k < 2; ++k) \
;         acc[ai][bj][m][n] = __builtin_amdgcn_mfma_f32_16x16x32_bf16(Bt[n][k], At[m][k], acc[ai][bj][m][n], 0, 0, 0); __builtin_amdgcn_s_setprio(0); } while (0)
; #define PG8_WAIT_V(n) asm volatile("s_waitcnt vmcnt(" #n ")" ::: "memory")
; #define PG8_WAIT_L(n) asm volatile("s_waitcnt lgkmcnt(" #n ")" ::: "memory")
; #define PG8_BAR __builtin_amdgcn_s_barrier()
; #define PG8_SCHED __builtin_amdgcn_sched_barrier(0)
; template <class Epi>
; __device__ __forceinline__ void gemm_phase(LAS unsigned char* lds, const Gemm g, const StaticOrder S, const Epi E) {
;     ...
;             PG8_LDB(B0, 1, 0); PG8_LDB(B1, 1, 1); PG8_SCHED; PG8_LDA(At, 1, 0); PG8_STAGE(PG8_SA(0, 1), a2 + hstepA, voffA);
;             PG8_WAIT_V(8); PG8_WAIT_L(0); PG8_BAR; PG8_MMA(0, 0, At, B0); PG8_MMA(0, 1, At, B1); PG8_BAR; PG8_SCHED;
;             PG8_LDA(At, 1, 1); PG8_STAGE(PG8_SB(1, 0), b3, voffB); PG8_STAGE(PG8_SB(1, 1), b3 + hstepB, voffB); PG8_STAGE(PG8_SA(1, 0), a3, voffA);
;             PG8_WAIT_V(8); PG8_WAIT_L(0); PG8_BAR; PG8_MMA(1, 0, At, B0); PG8_MMA(1, 1, At, B1); PG8_BAR; PG8_SCHED;
;         }
	s_add_i32 s21, 0, 0x18000
	s_add_i32 s74, 0, 0x1c000
	v_add_u32_e32 v152, s21, v164
	v_add_u32_e32 v176, s74, v164
	ds_read_b128 v[128:131], v152
	ds_read_b128 v[132:135], v152 offset:1024
	ds_read_b128 v[136:139], v152 offset:2048
	ds_read_b128 v[152:155], v152 offset:3072
	ds_read_b128 v[156:159], v176
	ds_read_b128 v[168:171], v176 offset:1024
	ds_read_b128 v[172:175], v176 offset:2048
	ds_read_b128 v[176:179], v176 offset:3072
	s_add_u32 s56, s56, 0x80000
	s_addc_u32 s57, s57, 0
	s_mov_b32 m0, s61
	ds_read_b128 v[180:183], v166 offset:32768
	ds_read_b128 v[184:187], v166 offset:33792
	ds_read_b128 v[188:191], v166 offset:34816
	ds_read_b128 v[192:195], v166 offset:35840
	ds_read_b128 v[196:199], v166 offset:36864
	ds_read_b128 v[200:203], v166 offset:37888
	ds_read_b128 v[204:207], v166 offset:38912
	ds_read_b128 v[208:211], v166 offset:39936
	global_load_lds_dwordx4 v140, s[56:57]
	s_mov_b32 m0, s62
	s_nop 0
	global_load_lds_dwordx4 v144, s[56:57]
	s_waitcnt vmcnt(8)
	s_waitcnt lgkmcnt(0)
	s_barrier
	s_setprio 1
	s_waitcnt lgkmcnt(0)
	v_mfma_f32_16x16x32_bf16 v[124:127], v[128:131], v[180:183], v[124:127]
	v_mfma_f32_16x16x32_bf16 v[120:123], v[136:139], v[180:183], v[120:123]
	v_mfma_f32_16x16x32_bf16 v[108:111], v[128:131], v[188:191], v[108:111]
	v_mfma_f32_16x16x32_bf16 v[104:107], v[136:139], v[188:191], v[104:107]
	v_mfma_f32_16x16x32_bf16 v[92:95], v[128:131], v[196:199], v[92:95]
	v_mfma_f32_16x16x32_bf16 v[88:91], v[136:139], v[196:199], v[88:91]
	v_mfma_f32_16x16x32_bf16 v[76:79], v[128:131], v[204:207], v[76:79]
	v_mfma_f32_16x16x32_bf16 v[72:75], v[136:139], v[204:207], v[72:75]
	v_mfma_f32_16x16x32_bf16 v[124:127], v[132:135], v[184:187], v[124:127]
	v_mfma_f32_16x16x32_bf16 v[120:123], v[152:155], v[184:187], v[120:123]
	v_mfma_f32_16x16x32_bf16 v[108:111], v[132:135], v[192:195], v[108:111]
	v_mfma_f32_16x16x32_bf16 v[104:107], v[152:155], v[192:195], v[104:107]
	v_mfma_f32_16x16x32_bf16 v[92:95], v[132:135], v[200:203], v[92:95]
	v_mfma_f32_16x16x32_bf16 v[88:91], v[152:155], v[200:203], v[88:91]
	v_mfma_f32_16x16x32_bf16 v[76:79], v[132:135], v[208:211], v[76:79]
	v_mfma_f32_16x16x32_bf16 v[72:75], v[152:155], v[208:211], v[72:75]
	s_setprio 0
	s_setprio 1
	v_mfma_f32_16x16x32_bf16 v[116:119], v[156:159], v[180:183], v[116:119]
	v_mfma_f32_16x16x32_bf16 v[112:115], v[172:175], v[180:183], v[112:115]
	v_mfma_f32_16x16x32_bf16 v[100:103], v[156:159], v[188:191], v[100:103]
	v_mfma_f32_16x16x32_bf16 v[96:99], v[172:175], v[188:191], v[96:99]
	v_mfma_f32_16x16x32_bf16 v[84:87], v[156:159], v[196:199], v[84:87]
	v_mfma_f32_16x16x32_bf16 v[80:83], v[172:175], v[196:199], v[80:83]
	v_mfma_f32_16x16x32_bf16 v[68:71], v[156:159], v[204:207], v[68:71]
	v_mfma_f32_16x16x32_bf16 v[64:67], v[172:175], v[204:207], v[64:67]
	v_mfma_f32_16x16x32_bf16 v[116:119], v[168:171], v[184:187], v[116:119]
	v_mfma_f32_16x16x32_bf16 v[112:115], v[176:179], v[184:187], v[112:115]
	v_mfma_f32_16x16x32_bf16 v[100:103], v[168:171], v[192:195], v[100:103]
	v_mfma_f32_16x16x32_bf16 v[96:99], v[176:179], v[192:195], v[96:99]
	v_mfma_f32_16x16x32_bf16 v[84:87], v[168:171], v[200:203], v[84:87]
	v_mfma_f32_16x16x32_bf16 v[80:83], v[176:179], v[200:203], v[80:83]
	v_mfma_f32_16x16x32_bf16 v[68:71], v[168:171], v[208:211], v[68:71]
	v_mfma_f32_16x16x32_bf16 v[64:67], v[176:179], v[208:211], v[64:67]
	s_setprio 0
	s_barrier
	s_add_u32 s52, s52, s54
	s_addc_u32 s53, s53, s55
	s_add_i32 s21, s21, s33
	s_mov_b32 m0, s21
	ds_read_b128 v[180:183], v166 offset:49152
	ds_read_b128 v[184:187], v166 offset:50176
	ds_read_b128 v[188:191], v166 offset:51200
	ds_read_b128 v[192:195], v166 offset:52224
	ds_read_b128 v[196:199], v166 offset:53248
	ds_read_b128 v[200:203], v166 offset:54272
	ds_read_b128 v[204:207], v166 offset:55296
	ds_read_b128 v[208:211], v166 offset:56320
	global_load_lds_dwordx4 v142, s[52:53]
	s_add_i32 m0, s21, 0x2000
	v_lshl_add_u64 v[212:213], s[52:53], 0, v[146:147]
	s_add_u32 s52, s52, 0x80000
	s_addc_u32 s53, s53, 0
	s_add_i32 s21, s74, s33
	global_load_lds_dwordx4 v[212:213], off
	s_mov_b32 m0, s21
	s_nop 0
	global_load_lds_dwordx4 v142, s[52:53]
	s_add_i32 m0, s21, 0x2000
	s_nop 0
	global_load_lds_dwordx4 v146, s[52:53]
	s_mov_b32 m0, s64
	s_nop 0
	global_load_lds_dwordx4 v140, s[58:59]
	s_mov_b32 m0, s65
	s_nop 0
	global_load_lds_dwordx4 v144, s[58:59]
	s_waitcnt vmcnt(8)
	s_waitcnt lgkmcnt(0)
	s_barrier
	s_setprio 1
	s_waitcnt lgkmcnt(0)
	v_mfma_f32_16x16x32_bf16 v[60:63], v[128:131], v[180:183], v[60:63]
	v_mfma_f32_16x16x32_bf16 v[56:59], v[136:139], v[180:183], v[56:59]
	v_mfma_f32_16x16x32_bf16 v[44:47], v[128:131], v[188:191], v[44:47]
	v_mfma_f32_16x16x32_bf16 v[40:43], v[136:139], v[188:191], v[40:43]
	v_mfma_f32_16x16x32_bf16 v[28:31], v[128:131], v[196:199], v[28:31]
	v_mfma_f32_16x16x32_bf16 v[24:27], v[136:139], v[196:199], v[24:27]
	v_mfma_f32_16x16x32_bf16 v[12:15], v[128:131], v[204:207], v[12:15]
	v_mfma_f32_16x16x32_bf16 v[8:11], v[136:139], v[204:207], v[8:11]
	v_mfma_f32_16x16x32_bf16 v[60:63], v[132:135], v[184:187], v[60:63]
	v_mfma_f32_16x16x32_bf16 v[56:59], v[152:155], v[184:187], v[56:59]
	v_mfma_f32_16x16x32_bf16 v[44:47], v[132:135], v[192:195], v[44:47]
	v_mfma_f32_16x16x32_bf16 v[40:43], v[152:155], v[192:195], v[40:43]
	v_mfma_f32_16x16x32_bf16 v[28:31], v[132:135], v[200:203], v[28:31]
	v_mfma_f32_16x16x32_bf16 v[24:27], v[152:155], v[200:203], v[24:27]
	v_mfma_f32_16x16x32_bf16 v[12:15], v[132:135], v[208:211], v[12:15]
	v_mfma_f32_16x16x32_bf16 v[8:11], v[152:155], v[208:211], v[8:11]
	s_setprio 0
	s_setprio 1
	v_mfma_f32_16x16x32_bf16 v[52:55], v[156:159], v[180:183], v[52:55]
	v_mfma_f32_16x16x32_bf16 v[48:51], v[172:175], v[180:183], v[48:51]
	v_mfma_f32_16x16x32_bf16 v[36:39], v[156:159], v[188:191], v[36:39]
	v_mfma_f32_16x16x32_bf16 v[32:35], v[172:175], v[188:191], v[32:35]
	v_mfma_f32_16x16x32_bf16 v[20:23], v[156:159], v[196:199], v[20:23]
	v_mfma_f32_16x16x32_bf16 v[16:19], v[172:175], v[196:199], v[16:19]
	v_mfma_f32_16x16x32_bf16 v[4:7], v[156:159], v[204:207], v[4:7]
	v_mfma_f32_16x16x32_bf16 v[0:3], v[172:175], v[204:207], v[0:3]
	v_mfma_f32_16x16x32_bf16 v[52:55], v[168:171], v[184:187], v[52:55]
	v_mfma_f32_16x16x32_bf16 v[48:51], v[176:179], v[184:187], v[48:51]
	v_mfma_f32_16x16x32_bf16 v[36:39], v[168:171], v[192:195], v[36:39]
	v_mfma_f32_16x16x32_bf16 v[32:35], v[176:179], v[192:195], v[32:35]
	v_mfma_f32_16x16x32_bf16 v[20:23], v[168:171], v[200:203], v[20:23]
	v_mfma_f32_16x16x32_bf16 v[16:19], v[176:179], v[200:203], v[16:19]
	v_mfma_f32_16x16x32_bf16 v[4:7], v[168:171], v[208:211], v[4:7]
	v_mfma_f32_16x16x32_bf16 v[0:3], v[176:179], v[208:211], v[0:3]
	s_setprio 0
	s_barrier
	s_cmp_gt_u32 s29, 29
	s_mov_b32 s29, s19
	s_cbranch_scc1 .LBB0_571

; #define PG8_STAGE(bufoff, gbase, voff) do { _Pragma("unroll") for (int _i = 0; _i < 2; ++_i) \
;         __builtin_amdgcn_global_load_lds((const unsigned*)((const char*)(gbase) + (voff)[_i]), (LAS unsigned*)(lds + (bufoff) + ldsw + _i * 8192), 16, 0, 0); } while (0)
; #define PG8_WAIT_V(n) asm volatile("s_waitcnt vmcnt(" #n ")" ::: "memory")
; #define PG8_BAR __builtin_amdgcn_s_barrier()
; template <class Epi>
; __device__ __forceinline__ void gemm_phase(LAS unsigned char* lds, const Gemm g, const StaticOrder S, const Epi E) {
;     ...
;     PG8_STAGE(PG8_SB(0, 0), cB, voffB); PG8_STAGE(PG8_SB(0, 1), cB + hstepB, voffB); PG8_STAGE(PG8_SA(0, 0), cA, voffA); PG8_STAGE(PG8_SA(0, 1), cA + hstepA, voffA);
;     if (wr == 1) PG8_BAR;
;     PG8_WAIT_V(2); PG8_BAR;
;     PG8_STAGE(PG8_SB(1, 0), cB + ksc, voffB); PG8_STAGE(PG8_SA(1, 0), cA + ksc, voffA); PG8_STAGE(PG8_SB(1, 1), cB + hstepB + ksc, voffB);
;     PG8_WAIT_V(6); PG8_BAR;
.LBB0_660:
	s_add_u32 s6, s82, 0x2a9a0000
	s_addc_u32 s7, s83, 0
	s_lshl_b32 s9, s9, 5
	s_mov_b64 s[26:27], 0x80
	s_and_b32 s14, s9, 0x60
	s_add_i32 m0, s21, 0x18000
	v_lshl_add_u64 v[6:7], v[6:7], 0, s[26:27]
	s_lshl_b32 s10, s8, 13
	s_lshl_b32 s9, s14, 7
	s_waitcnt vmcnt(2)
	s_barrier
	global_load_lds_dwordx4 v[6:7], off
	v_lshl_add_u64 v[4:5], v[4:5], 0, s[26:27]
	s_add_i32 m0, s21, 0x1a000
	s_add_i32 s57, s21, 0x8000
	s_add_i32 s58, s21, 0xa000
	global_load_lds_dwordx4 v[4:5], off
	v_lshl_add_u64 v[0:1], v[0:1], 0, s[26:27]
	s_mov_b32 m0, s57
	s_add_u32 s12, s22, 0x80080
	global_load_lds_dwordx4 v[0:1], off
	v_lshl_add_u64 v[0:1], v[2:3], 0, s[26:27]
	s_mov_b32 m0, s58
	s_addc_u32 s13, s23, 0
	global_load_lds_dwordx4 v[0:1], off
	s_add_i32 m0, s21, 0x1c000
	s_nop 0
	global_load_lds_dwordx4 v132, s[12:13]
	s_add_i32 m0, s21, 0x1e000
	v_lshlrev_b32_e32 v2, 2, v224
	global_load_lds_dwordx4 v128, s[12:13]
	v_and_b32_e32 v0, 15, v224
	v_lshlrev_b32_e32 v1, 1, v8
	s_sext_i32_i16 s65, s0
	v_lshl_or_b32 v142, s8, 6, v0
	v_lshl_or_b32 v0, v0, 6, v1
	v_and_b32_e32 v2, 32, v2
	v_lshlrev_b32_e32 v3, 6, v224
	s_movk_i32 s0, 0x3c0
	s_waitcnt vmcnt(6)
	s_ashr_i32 s59, s78, 31
	v_bitop3_b32 v0, v0, s10, v2 bitop3:0xde
	v_and_or_b32 v1, v3, s0, v1
	s_cmpk_lt_u32 s1, 0x100
	v_bitop3_b32 v143, s9, v1, v2 bitop3:0xf6
	s_cselect_b64 s[8:9], -1, 0
	v_or_b32_e32 v144, s14, v8
	v_mov_b64_e32 v[136:137], 0xb00
	v_mov_b64_e32 v[138:139], 0xaff
	s_movk_i32 s60, 0xff80
	s_add_i32 s61, 0, 0x10000
	s_add_i32 s62, 0, 0x14000
	v_add_u32_e32 v145, 0, v0
	s_movk_i32 s63, 0x2c00
	v_mov_b32_e32 v146, 0x358637bd
	s_barrier
	s_branch .LBB0_663

; #define PG8_STAGE(bufoff, gbase, voff) do { _Pragma("unroll") for (int _i = 0; _i < 2; ++_i) \
;         __builtin_amdgcn_global_load_lds((const unsigned*)((const char*)(gbase) + (voff)[_i]), (LAS unsigned*)(lds + (bufoff) + ldsw + _i * 8192), 16, 0, 0); } while (0)
; #define PG8_LDA(dst, b, h) do { _Pragma("unroll") for (int m = 0; m < 4; ++m) _Pragma("unroll") for (int k = 0; k < 2; ++k) dst[m][k] = *(const LAS bf16x8*)(lds + PG8_SA(b, h) + aoff + m * 2048 + k * 1024); } while (0)
; #define PG8_LDB(dst, b, h) do { _Pragma("unroll") for (int n = 0; n < 2; ++n) _Pragma("unroll") for (int k = 0; k < 2; ++k) dst[n][k] = *(const LAS bf16x8*)(lds + PG8_SB(b, h) + boff + n * 2048 + k * 1024); } while (0)
; #define PG8_MMA(ai, bj, At, Bt) do { __builtin_amdgcn_s_setprio(1); _Pragma("unroll") for (int m = 0; m < 4; ++m) _Pragma("unroll") for (int n = 0; n < 2; ++n) _Pragma("unroll") for (int k = 0; k < 2; ++k) \
;         acc[ai][bj][m][n] = __builtin_amdgcn_mfma_f32_16x16x32_bf16(Bt[n][k], At[m][k], acc[ai][bj][m][n], 0, 0, 0); __builtin_amdgcn_s_setprio(0); } while (0)
; #define PG8_WAIT_V(n) asm volatile("s_waitcnt vmcnt(" #n ")" ::: "memory")
; #define PG8_WAIT_L(n) asm volatile("s_waitcnt lgkmcnt(" #n ")" ::: "memory")
; #define PG8_BAR __builtin_amdgcn_s_barrier()
; #define PG8_SCHED __builtin_amdgcn_sched_barrier(0)
; template <class Epi>
; __device__ __forceinline__ void gemm_phase(LAS unsigned char* lds, const Gemm g, const StaticOrder S, const Epi E) {
;     ...
;             const char* a1 = cA + (long)(t + 1) * ksc;
;             const char* a2 = last ? nA : cA + (long)(t + 2) * ksc; const char* b2 = last ? nB : cB + (long)(t + 2) * ksc;
;             const long ks3 = last ? ksn : ksc;
;             const char* a3 = a2 + ks3; const char* b3 = b2 + ks3;
;             PG8_LDB(B0, 0, 0); PG8_LDB(B1, 0, 1); PG8_SCHED; PG8_LDA(At, 0, 0); PG8_STAGE(PG8_SA(1, 1), a1 + hstepA, voffA);
;             PG8_WAIT_V(8); PG8_WAIT_L(0); PG8_BAR; PG8_MMA(0, 0, At, B0); PG8_MMA(0, 1, At, B1); PG8_BAR; PG8_SCHED;
;             PG8_LDA(At, 0, 1); PG8_STAGE(PG8_SB(0, 0), b2, voffB); PG8_STAGE(PG8_SB(0, 1), b2 + hstepB, voffB); PG8_STAGE(PG8_SA(0, 0), a2, voffA);
;             PG8_WAIT_V(8); PG8_WAIT_L(0); PG8_BAR; PG8_MMA(1, 0, At, B0); PG8_MMA(1, 1, At, B1); PG8_BAR; PG8_SCHED;
.LBB0_666:
	v_add_u32_e32 v140, s61, v143
	ds_read_b128 v[148:151], v140
	ds_read_b128 v[152:155], v140 offset:1024
	ds_read_b128 v[156:159], v140 offset:2048
	ds_read_b128 v[160:163], v140 offset:3072
	v_add_u32_e32 v140, s62, v143
	ds_read_b128 v[164:167], v140
	ds_read_b128 v[168:171], v140 offset:1024
	ds_read_b128 v[172:175], v140 offset:2048
	ds_read_b128 v[176:179], v140 offset:3072
	s_or_b32 s13, s66, 1
	s_mul_i32 s48, s27, s13
	s_mul_hi_u32 s49, s26, s13
	s_add_i32 s49, s49, s48
	s_mul_i32 s13, s26, s13
	s_add_u32 s13, s24, s13
	s_addc_u32 s67, s25, s49
	s_add_u32 s48, s46, s44
	s_addc_u32 s49, s47, s45
	s_add_u32 s68, s13, 0x80000
	s_addc_u32 s69, s67, 0
	s_add_i32 m0, s21, 0xc000
	ds_read_b128 v[180:183], v145
	ds_read_b128 v[184:187], v145 offset:1024
	ds_read_b128 v[188:191], v145 offset:2048
	ds_read_b128 v[192:195], v145 offset:3072
	ds_read_b128 v[196:199], v145 offset:4096
	ds_read_b128 v[200:203], v145 offset:5120
	ds_read_b128 v[204:207], v145 offset:6144
	ds_read_b128 v[208:211], v145 offset:7168
	global_load_lds_dwordx4 v134, s[68:69]
	s_add_i32 m0, s21, 0xe000
	s_nop 0
	global_load_lds_dwordx4 v130, s[68:69]
	s_waitcnt vmcnt(8)
	s_waitcnt lgkmcnt(0)
	s_barrier
	s_setprio 1
	s_waitcnt lgkmcnt(0)
	v_mfma_f32_16x16x32_bf16 v[116:119], v[148:151], v[180:183], v[116:119]
	v_mfma_f32_16x16x32_bf16 v[112:115], v[156:159], v[180:183], v[112:115]
	v_mfma_f32_16x16x32_bf16 v[108:111], v[148:151], v[188:191], v[108:111]
	v_mfma_f32_16x16x32_bf16 v[104:107], v[156:159], v[188:191], v[104:107]
	v_mfma_f32_16x16x32_bf16 v[92:95], v[148:151], v[196:199], v[92:95]
	v_mfma_f32_16x16x32_bf16 v[88:91], v[156:159], v[196:199], v[88:91]
	v_mfma_f32_16x16x32_bf16 v[76:79], v[148:151], v[204:207], v[76:79]
	v_mfma_f32_16x16x32_bf16 v[72:75], v[156:159], v[204:207], v[72:75]
	v_mfma_f32_16x16x32_bf16 v[116:119], v[152:155], v[184:187], v[116:119]
	v_mfma_f32_16x16x32_bf16 v[112:115], v[160:163], v[184:187], v[112:115]
	v_mfma_f32_16x16x32_bf16 v[108:111], v[152:155], v[192:195], v[108:111]
	v_mfma_f32_16x16x32_bf16 v[104:107], v[160:163], v[192:195], v[104:107]
	v_mfma_f32_16x16x32_bf16 v[92:95], v[152:155], v[200:203], v[92:95]
	v_mfma_f32_16x16x32_bf16 v[88:91], v[160:163], v[200:203], v[88:91]
	v_mfma_f32_16x16x32_bf16 v[76:79], v[152:155], v[208:211], v[76:79]
	v_mfma_f32_16x16x32_bf16 v[72:75], v[160:163], v[208:211], v[72:75]
	s_setprio 0
	s_setprio 1
	v_mfma_f32_16x16x32_bf16 v[124:127], v[164:167], v[180:183], v[124:127]
	v_mfma_f32_16x16x32_bf16 v[120:123], v[172:175], v[180:183], v[120:123]
	v_mfma_f32_16x16x32_bf16 v[100:103], v[164:167], v[188:191], v[100:103]
	v_mfma_f32_16x16x32_bf16 v[96:99], v[172:175], v[188:191], v[96:99]
	v_mfma_f32_16x16x32_bf16 v[84:87], v[164:167], v[196:199], v[84:87]
	v_mfma_f32_16x16x32_bf16 v[80:83], v[172:175], v[196:199], v[80:83]
	v_mfma_f32_16x16x32_bf16 v[68:71], v[164:167], v[204:207], v[68:71]
	v_mfma_f32_16x16x32_bf16 v[64:67], v[172:175], v[204:207], v[64:67]
	v_mfma_f32_16x16x32_bf16 v[124:127], v[168:171], v[184:187], v[124:127]
	v_mfma_f32_16x16x32_bf16 v[120:123], v[176:179], v[184:187], v[120:123]
	v_mfma_f32_16x16x32_bf16 v[100:103], v[168:171], v[192:195], v[100:103]
	v_mfma_f32_16x16x32_bf16 v[96:99], v[176:179], v[192:195], v[96:99]
	v_mfma_f32_16x16x32_bf16 v[84:87], v[168:171], v[200:203], v[84:87]
	v_mfma_f32_16x16x32_bf16 v[80:83], v[176:179], v[200:203], v[80:83]
	v_mfma_f32_16x16x32_bf16 v[68:71], v[168:171], v[208:211], v[68:71]
	v_mfma_f32_16x16x32_bf16 v[64:67], v[176:179], v[208:211], v[64:67]
	s_setprio 0
	s_barrier
	s_add_i32 s13, s61, s51
	s_mov_b32 m0, s13
	ds_read_b128 v[180:183], v145 offset:16384
	ds_read_b128 v[184:187], v145 offset:17408
	ds_read_b128 v[188:191], v145 offset:18432
	ds_read_b128 v[192:195], v145 offset:19456
	ds_read_b128 v[196:199], v145 offset:20480
	ds_read_b128 v[200:203], v145 offset:21504
	ds_read_b128 v[204:207], v145 offset:22528
	ds_read_b128 v[208:211], v145 offset:23552
	global_load_lds_dwordx4 v132, s[42:43]
	s_add_i32 m0, s13, 0x2000
	s_add_u32 s68, s42, 0x80000
	s_addc_u32 s69, s43, 0
	s_add_i32 s13, s62, s51
	global_load_lds_dwordx4 v128, s[42:43]
	s_mov_b32 m0, s13
	s_nop 0
	global_load_lds_dwordx4 v132, s[68:69]
	s_add_i32 m0, s13, 0x2000
	s_nop 0
	global_load_lds_dwordx4 v128, s[68:69]
	s_mov_b32 m0, s21
	s_nop 0
	global_load_lds_dwordx4 v134, s[46:47]
	s_mov_b32 m0, s54
	s_nop 0
	global_load_lds_dwordx4 v130, s[46:47]
	s_waitcnt vmcnt(8)
	s_waitcnt lgkmcnt(0)
	s_barrier
	s_setprio 1
	s_waitcnt lgkmcnt(0)
	v_mfma_f32_16x16x32_bf16 v[60:63], v[148:151], v[180:183], v[60:63]
	v_mfma_f32_16x16x32_bf16 v[56:59], v[156:159], v[180:183], v[56:59]
	v_mfma_f32_16x16x32_bf16 v[44:47], v[148:151], v[188:191], v[44:47]
	v_mfma_f32_16x16x32_bf16 v[40:43], v[156:159], v[188:191], v[40:43]
	v_mfma_f32_16x16x32_bf16 v[28:31], v[148:151], v[196:199], v[28:31]
	v_mfma_f32_16x16x32_bf16 v[24:27], v[156:159], v[196:199], v[24:27]
	v_mfma_f32_16x16x32_bf16 v[12:15], v[148:151], v[204:207], v[12:15]
	v_mfma_f32_16x16x32_bf16 v[8:11], v[156:159], v[204:207], v[8:11]
	v_mfma_f32_16x16x32_bf16 v[60:63], v[152:155], v[184:187], v[60:63]
	v_mfma_f32_16x16x32_bf16 v[56:59], v[160:163], v[184:187], v[56:59]
	v_mfma_f32_16x16x32_bf16 v[44:47], v[152:155], v[192:195], v[44:47]
	v_mfma_f32_16x16x32_bf16 v[40:43], v[160:163], v[192:195], v[40:43]
	v_mfma_f32_16x16x32_bf16 v[28:31], v[152:155], v[200:203], v[28:31]
	v_mfma_f32_16x16x32_bf16 v[24:27], v[160:163], v[200:203], v[24:27]
	v_mfma_f32_16x16x32_bf16 v[12:15], v[152:155], v[208:211], v[12:15]
	v_mfma_f32_16x16x32_bf16 v[8:11], v[160:163], v[208:211], v[8:11]
	s_setprio 0
	s_setprio 1
	v_mfma_f32_16x16x32_bf16 v[52:55], v[164:167], v[180:183], v[52:55]
	v_mfma_f32_16x16x32_bf16 v[48:51], v[172:175], v[180:183], v[48:51]
	v_mfma_f32_16x16x32_bf16 v[36:39], v[164:167], v[188:191], v[36:39]
	v_mfma_f32_16x16x32_bf16 v[32:35], v[172:175], v[188:191], v[32:35]
	v_mfma_f32_16x16x32_bf16 v[20:23], v[164:167], v[196:199], v[20:23]
	v_mfma_f32_16x16x32_bf16 v[16:19], v[172:175], v[196:199], v[16:19]
	v_mfma_f32_16x16x32_bf16 v[4:7], v[164:167], v[204:207], v[4:7]
	v_mfma_f32_16x16x32_bf16 v[0:3], v[172:175], v[204:207], v[0:3]
	v_mfma_f32_16x16x32_bf16 v[52:55], v[168:171], v[184:187], v[52:55]
	v_mfma_f32_16x16x32_bf16 v[48:51], v[176:179], v[184:187], v[48:51]
	v_mfma_f32_16x16x32_bf16 v[36:39], v[168:171], v[192:195], v[36:39]
	v_mfma_f32_16x16x32_bf16 v[32:35], v[176:179], v[192:195], v[32:35]
	v_mfma_f32_16x16x32_bf16 v[20:23], v[168:171], v[200:203], v[20:23]
	v_mfma_f32_16x16x32_bf16 v[16:19], v[176:179], v[200:203], v[16:19]
	v_mfma_f32_16x16x32_bf16 v[4:7], v[168:171], v[208:211], v[4:7]
	v_mfma_f32_16x16x32_bf16 v[0:3], v[176:179], v[208:211], v[0:3]
	s_setprio 0
	s_barrier
; #define PG8_STAGE(bufoff, gbase, voff) do { _Pragma("unroll") for (int _i = 0; _i < 2; ++_i) \
;         __builtin_amdgcn_global_load_lds((const unsigned*)((const char*)(gbase) + (voff)[_i]), (LAS unsigned*)(lds + (bufoff) + ldsw + _i * 8192), 16, 0, 0); } while (0)
; #define PG8_LDA(dst, b, h) do { _Pragma("unroll") for (int m = 0; m < 4; ++m) _Pragma("unroll") for (int k = 0; k < 2; ++k) dst[m][k] = *(const LAS bf16x8*)(lds + PG8_SA(b, h) + aoff + m * 2048 + k * 1024); } while (0)
; #define PG8_LDB(dst, b, h) do { _Pragma("unroll") for (int n = 0; n < 2; ++n) _Pragma("unroll") for (int k = 0; k < 2; ++k) dst[n][k] = *(const LAS bf16x8*)(lds + PG8_SB(b, h) + boff + n * 2048 + k * 1024); } while (0)
; #define PG8_MMA(ai, bj, At, Bt) do { __builtin_amdgcn_s_setprio(1); _Pragma("unroll") for (int m = 0; m < 4; ++m) _Pragma("unroll") for (int n = 0; n < 2; ++n) _Pragma("unroll") for (int k = 0; k < 2; ++k) \
;         acc[ai][bj][m][n] = __builtin_amdgcn_mfma_f32_16x16x32_bf16(Bt[n][k], At[m][k], acc[ai][bj][m][n], 0, 0, 0); __builtin_amdgcn_s_setprio(0); } while (0)
; #define PG8_WAIT_V(n) asm volatile("s_waitcnt vmcnt(" #n ")" ::: "memory")
; #define PG8_WAIT_L(n) asm volatile("s_waitcnt lgkmcnt(" #n ")" ::: "memory")
; #define PG8_BAR __builtin_amdgcn_s_barrier()
; #define PG8_SCHED __builtin_amdgcn_sched_barrier(0)
; template <class Epi>
; __device__ __forceinline__ void gemm_phase(LAS unsigned char* lds, const Gemm g, const StaticOrder S, const Epi E) {
;     ...
;             PG8_LDB(B0, 1, 0); PG8_LDB(B1, 1, 1); PG8_SCHED; PG8_LDA(At, 1, 0); PG8_STAGE(PG8_SA(0, 1), a2 + hstepA, voffA);
;             PG8_WAIT_V(8); PG8_WAIT_L(0); PG8_BAR; PG8_MMA(0, 0, At, B0); PG8_MMA(0, 1, At, B1); PG8_BAR; PG8_SCHED;
;             PG8_LDA(At, 1, 1); PG8_STAGE(PG8_SB(1, 0), b3, voffB); PG8_STAGE(PG8_SB(1, 1), b3 + hstepB, voffB); PG8_STAGE(PG8_SA(1, 0), a3, voffA);
;             PG8_WAIT_V(8); PG8_WAIT_L(0); PG8_BAR; PG8_MMA(1, 0, At, B0); PG8_MMA(1, 1, At, B1); PG8_BAR; PG8_SCHED;
;         }
	s_add_i32 s13, 0, 0x18000
	v_add_u32_e32 v140, s13, v143
	s_add_i32 s67, 0, 0x1c000
	ds_read_b128 v[148:151], v140
	ds_read_b128 v[152:155], v140 offset:1024
	ds_read_b128 v[156:159], v140 offset:2048
	ds_read_b128 v[160:163], v140 offset:3072
	v_add_u32_e32 v140, s67, v143
	ds_read_b128 v[164:167], v140
	ds_read_b128 v[168:171], v140 offset:1024
	ds_read_b128 v[172:175], v140 offset:2048
	ds_read_b128 v[176:179], v140 offset:3072
	s_add_u32 s46, s46, 0x80000
	s_addc_u32 s47, s47, 0
	s_mov_b32 m0, s55
	ds_read_b128 v[180:183], v145 offset:32768
	ds_read_b128 v[184:187], v145 offset:33792
	ds_read_b128 v[188:191], v145 offset:34816
	ds_read_b128 v[192:195], v145 offset:35840
	ds_read_b128 v[196:199], v145 offset:36864
	ds_read_b128 v[200:203], v145 offset:37888
	ds_read_b128 v[204:207], v145 offset:38912
	ds_read_b128 v[208:211], v145 offset:39936
	global_load_lds_dwordx4 v134, s[46:47]
	s_mov_b32 m0, s56
	s_nop 0
	global_load_lds_dwordx4 v130, s[46:47]
	s_waitcnt vmcnt(8)
	s_waitcnt lgkmcnt(0)
	s_barrier
	s_setprio 1
	s_waitcnt lgkmcnt(0)
	v_mfma_f32_16x16x32_bf16 v[116:119], v[148:151], v[180:183], v[116:119]
	v_mfma_f32_16x16x32_bf16 v[112:115], v[156:159], v[180:183], v[112:115]
	v_mfma_f32_16x16x32_bf16 v[108:111], v[148:151], v[188:191], v[108:111]
	v_mfma_f32_16x16x32_bf16 v[104:107], v[156:159], v[188:191], v[104:107]
	v_mfma_f32_16x16x32_bf16 v[92:95], v[148:151], v[196:199], v[92:95]
	v_mfma_f32_16x16x32_bf16 v[88:91], v[156:159], v[196:199], v[88:91]
	v_mfma_f32_16x16x32_bf16 v[76:79], v[148:151], v[204:207], v[76:79]
	v_mfma_f32_16x16x32_bf16 v[72:75], v[156:159], v[204:207], v[72:75]
	v_mfma_f32_16x16x32_bf16 v[116:119], v[152:155], v[184:187], v[116:119]
	v_mfma_f32_16x16x32_bf16 v[112:115], v[160:163], v[184:187], v[112:115]
	v_mfma_f32_16x16x32_bf16 v[108:111], v[152:155], v[192:195], v[108:111]
	v_mfma_f32_16x16x32_bf16 v[104:107], v[160:163], v[192:195], v[104:107]
	v_mfma_f32_16x16x32_bf16 v[92:95], v[152:155], v[200:203], v[92:95]
	v_mfma_f32_16x16x32_bf16 v[88:91], v[160:163], v[200:203], v[88:91]
	v_mfma_f32_16x16x32_bf16 v[76:79], v[152:155], v[208:211], v[76:79]
	v_mfma_f32_16x16x32_bf16 v[72:75], v[160:163], v[208:211], v[72:75]
	s_setprio 0
	s_setprio 1
	v_mfma_f32_16x16x32_bf16 v[124:127], v[164:167], v[180:183], v[124:127]
	v_mfma_f32_16x16x32_bf16 v[120:123], v[172:175], v[180:183], v[120:123]
	v_mfma_f32_16x16x32_bf16 v[100:103], v[164:167], v[188:191], v[100:103]
	v_mfma_f32_16x16x32_bf16 v[96:99], v[172:175], v[188:191], v[96:99]
	v_mfma_f32_16x16x32_bf16 v[84:87], v[164:167], v[196:199], v[84:87]
	v_mfma_f32_16x16x32_bf16 v[80:83], v[172:175], v[196:199], v[80:83]
	v_mfma_f32_16x16x32_bf16 v[68:71], v[164:167], v[204:207], v[68:71]
	v_mfma_f32_16x16x32_bf16 v[64:67], v[172:175], v[204:207], v[64:67]
	v_mfma_f32_16x16x32_bf16 v[124:127], v[168:171], v[184:187], v[124:127]
	v_mfma_f32_16x16x32_bf16 v[120:123], v[176:179], v[184:187], v[120:123]
	v_mfma_f32_16x16x32_bf16 v[100:103], v[168:171], v[192:195], v[100:103]
	v_mfma_f32_16x16x32_bf16 v[96:99], v[176:179], v[192:195], v[96:99]
	v_mfma_f32_16x16x32_bf16 v[84:87], v[168:171], v[200:203], v[84:87]
	v_mfma_f32_16x16x32_bf16 v[80:83], v[176:179], v[200:203], v[80:83]
	v_mfma_f32_16x16x32_bf16 v[68:71], v[168:171], v[208:211], v[68:71]
	v_mfma_f32_16x16x32_bf16 v[64:67], v[176:179], v[208:211], v[64:67]
	s_setprio 0
	s_barrier
	s_add_u32 s42, s42, s44
	s_addc_u32 s43, s43, s45
	s_add_i32 s13, s13, s51
	s_mov_b32 m0, s13
	ds_read_b128 v[180:183], v145 offset:49152
	ds_read_b128 v[184:187], v145 offset:50176
	ds_read_b128 v[188:191], v145 offset:51200
	ds_read_b128 v[192:195], v145 offset:52224
	ds_read_b128 v[196:199], v145 offset:53248
	ds_read_b128 v[200:203], v145 offset:54272
	ds_read_b128 v[204:207], v145 offset:55296
	ds_read_b128 v[208:211], v145 offset:56320
	global_load_lds_dwordx4 v132, s[42:43]
	s_add_i32 m0, s13, 0x2000
	v_lshl_add_u64 v[140:141], s[42:43], 0, v[128:129]
	s_add_u32 s42, s42, 0x80000
	s_addc_u32 s43, s43, 0
	s_add_i32 s13, s67, s51
	global_load_lds_dwordx4 v[140:141], off
	s_mov_b32 m0, s13
	s_nop 0
	global_load_lds_dwordx4 v132, s[42:43]
	s_add_i32 m0, s13, 0x2000
	s_nop 0
	global_load_lds_dwordx4 v128, s[42:43]
	s_mov_b32 m0, s57
	s_nop 0
	global_load_lds_dwordx4 v134, s[48:49]
	s_mov_b32 m0, s58
	s_nop 0
	global_load_lds_dwordx4 v130, s[48:49]
	s_waitcnt vmcnt(8)
	s_waitcnt lgkmcnt(0)
	s_barrier
	s_setprio 1
	s_waitcnt lgkmcnt(0)
	v_mfma_f32_16x16x32_bf16 v[60:63], v[148:151], v[180:183], v[60:63]
	v_mfma_f32_16x16x32_bf16 v[56:59], v[156:159], v[180:183], v[56:59]
	v_mfma_f32_16x16x32_bf16 v[44:47], v[148:151], v[188:191], v[44:47]
	v_mfma_f32_16x16x32_bf16 v[40:43], v[156:159], v[188:191], v[40:43]
	v_mfma_f32_16x16x32_bf16 v[28:31], v[148:151], v[196:199], v[28:31]
	v_mfma_f32_16x16x32_bf16 v[24:27], v[156:159], v[196:199], v[24:27]
	v_mfma_f32_16x16x32_bf16 v[12:15], v[148:151], v[204:207], v[12:15]
	v_mfma_f32_16x16x32_bf16 v[8:11], v[156:159], v[204:207], v[8:11]
	v_mfma_f32_16x16x32_bf16 v[60:63], v[152:155], v[184:187], v[60:63]
	v_mfma_f32_16x16x32_bf16 v[56:59], v[160:163], v[184:187], v[56:59]
	v_mfma_f32_16x16x32_bf16 v[44:47], v[152:155], v[192:195], v[44:47]
	v_mfma_f32_16x16x32_bf16 v[40:43], v[160:163], v[192:195], v[40:43]
	v_mfma_f32_16x16x32_bf16 v[28:31], v[152:155], v[200:203], v[28:31]
	v_mfma_f32_16x16x32_bf16 v[24:27], v[160:163], v[200:203], v[24:27]
	v_mfma_f32_16x16x32_bf16 v[12:15], v[152:155], v[208:211], v[12:15]
	v_mfma_f32_16x16x32_bf16 v[8:11], v[160:163], v[208:211], v[8:11]
	s_setprio 0
	s_setprio 1
	v_mfma_f32_16x16x32_bf16 v[52:55], v[164:167], v[180:183], v[52:55]
	v_mfma_f32_16x16x32_bf16 v[48:51], v[172:175], v[180:183], v[48:51]
	v_mfma_f32_16x16x32_bf16 v[36:39], v[164:167], v[188:191], v[36:39]
	v_mfma_f32_16x16x32_bf16 v[32:35], v[172:175], v[188:191], v[32:35]
	v_mfma_f32_16x16x32_bf16 v[20:23], v[164:167], v[196:199], v[20:23]
	v_mfma_f32_16x16x32_bf16 v[16:19], v[172:175], v[196:199], v[16:19]
	v_mfma_f32_16x16x32_bf16 v[4:7], v[164:167], v[204:207], v[4:7]
	v_mfma_f32_16x16x32_bf16 v[0:3], v[172:175], v[204:207], v[0:3]
	v_mfma_f32_16x16x32_bf16 v[52:55], v[168:171], v[184:187], v[52:55]
	v_mfma_f32_16x16x32_bf16 v[48:51], v[176:179], v[184:187], v[48:51]
	v_mfma_f32_16x16x32_bf16 v[36:39], v[168:171], v[192:195], v[36:39]
	v_mfma_f32_16x16x32_bf16 v[32:35], v[176:179], v[192:195], v[32:35]
	v_mfma_f32_16x16x32_bf16 v[20:23], v[168:171], v[200:203], v[20:23]
	v_mfma_f32_16x16x32_bf16 v[16:19], v[176:179], v[200:203], v[16:19]
	v_mfma_f32_16x16x32_bf16 v[4:7], v[168:171], v[208:211], v[4:7]
	v_mfma_f32_16x16x32_bf16 v[0:3], v[176:179], v[208:211], v[0:3]
	s_setprio 0
	s_barrier
	s_cmp_gt_u32 s66, 29
	s_mov_b32 s66, s11
	s_cbranch_scc1 .LBB0_671

; #define PG8_STAGE(bufoff, gbase, voff) do { _Pragma("unroll") for (int _i = 0; _i < 2; ++_i) \
;         __builtin_amdgcn_global_load_lds((const unsigned*)((const char*)(gbase) + (voff)[_i]), (LAS unsigned*)(lds + (bufoff) + ldsw + _i * 8192), 16, 0, 0); } while (0)
; #define PG8_WAIT_V(n) asm volatile("s_waitcnt vmcnt(" #n ")" ::: "memory")
; #define PG8_BAR __builtin_amdgcn_s_barrier()
; template <class Epi>
; __device__ __forceinline__ void gemm_phase(LAS unsigned char* lds, const Gemm g, const StaticOrder S, const Epi E) {
;     ...
;     PG8_STAGE(PG8_SB(0, 0), cB, voffB); PG8_STAGE(PG8_SB(0, 1), cB + hstepB, voffB); PG8_STAGE(PG8_SA(0, 0), cA, voffA); PG8_STAGE(PG8_SA(0, 1), cA + hstepA, voffA);
;     if (wr == 1) PG8_BAR;
;     PG8_WAIT_V(2); PG8_BAR;
;     PG8_STAGE(PG8_SB(1, 0), cB + ksc, voffB); PG8_STAGE(PG8_SA(1, 0), cA + ksc, voffA); PG8_STAGE(PG8_SB(1, 1), cB + hstepB + ksc, voffB);
;     PG8_WAIT_V(6); PG8_BAR;
.LBB0_739:
	s_lshl_b32 s3, s3, 5
	s_and_b32 s3, s3, 0x60
	s_lshl_b32 s14, s0, 13
	s_lshl_b32 s15, s3, 7
	s_ashr_i32 s56, s79, 31
	s_add_u32 s12, s1, 0x2b00
	s_addc_u32 s13, s2, 0
	s_add_i32 m0, s52, 0x18000
	s_waitcnt vmcnt(2)
	s_barrier
	global_load_lds_dwordx4 v142, s[12:13]
	s_add_i32 m0, s52, 0x1a000
	v_lshl_add_u64 v[0:1], s[12:13], 0, v[146:147]
	s_add_u32 s12, s5, 0x2b00
	s_addc_u32 s13, s10, 0
	s_add_i32 s57, s52, 0x8000
	s_add_i32 s58, s52, 0xa000
	global_load_lds_dwordx4 v[0:1], off
	s_mov_b32 m0, s57
	s_add_u32 s10, s1, 0x162b00
	global_load_lds_dwordx4 v140, s[12:13]
	s_mov_b32 m0, s58
	s_addc_u32 s11, s2, 0
	global_load_lds_dwordx4 v144, s[12:13]
	s_add_i32 m0, s52, 0x1c000
	s_nop 0
	global_load_lds_dwordx4 v142, s[10:11]
	s_add_i32 m0, s52, 0x1e000
	v_and_b32_e32 v3, 32, v162
	global_load_lds_dwordx4 v146, s[10:11]
	v_and_b32_e32 v1, 3, v161
	v_and_b32_e32 v0, 15, v224
	v_lshlrev_b32_e32 v2, 4, v1
	v_lshl_or_b32 v163, s0, 6, v0
	v_lshl_or_b32 v0, v0, 6, v2
	s_ashr_i32 s59, s78, 31
	v_bitop3_b32 v0, v0, s14, v3 bitop3:0xde
	v_lshlrev_b32_e32 v4, 6, v224
	s_movk_i32 s0, 0x3c0
	s_waitcnt vmcnt(6)
	s_cmpk_lt_u32 s4, 0x100
	v_and_or_b32 v2, v4, s0, v2
	s_cselect_b64 s[10:11], -1, 0
	s_add_u32 s12, s82, 0x2a9b0000
	s_movk_i32 s34, 0xff80
	v_add_u32_e32 v166, 0, v0
	v_mbcnt_lo_u32_b32 v0, -1, 0
	v_bitop3_b32 v164, s15, v2, v3 bitop3:0xf6
	s_addc_u32 s13, s83, 0
	v_cmp_eq_u32_e64 s[0:1], 0, v1
	v_lshl_or_b32 v165, v1, 3, s3
	s_mov_b32 s35, -1
	v_mov_b64_e32 v[148:149], 0x200
	v_mov_b64_e32 v[150:151], 0x1ff
	s_add_i32 s60, 0, 0x10000
	s_add_i32 s61, 0, 0x14000
	s_mov_b64 s[14:15], 0x80000
	s_mov_b32 s62, 0x80000
	s_mov_b64 s[16:17], 0x90000
	s_mov_b32 s63, 0x90000
	s_mov_b64 s[18:19], 0xa0000
	s_mov_b32 s64, 0xa0000
	s_mov_b64 s[20:21], 0xb0000
	s_mov_b32 s65, 0xb0000
	v_mbcnt_hi_u32_b32 v167, -1, v0
	s_barrier
	s_branch .LBB0_742

; #define PG8_STAGE(bufoff, gbase, voff) do { _Pragma("unroll") for (int _i = 0; _i < 2; ++_i) \
;         __builtin_amdgcn_global_load_lds((const unsigned*)((const char*)(gbase) + (voff)[_i]), (LAS unsigned*)(lds + (bufoff) + ldsw + _i * 8192), 16, 0, 0); } while (0)
; #define PG8_LDA(dst, b, h) do { _Pragma("unroll") for (int m = 0; m < 4; ++m) _Pragma("unroll") for (int k = 0; k < 2; ++k) dst[m][k] = *(const LAS bf16x8*)(lds + PG8_SA(b, h) + aoff + m * 2048 + k * 1024); } while (0)
; #define PG8_LDB(dst, b, h) do { _Pragma("unroll") for (int n = 0; n < 2; ++n) _Pragma("unroll") for (int k = 0; k < 2; ++k) dst[n][k] = *(const LAS bf16x8*)(lds + PG8_SB(b, h) + boff + n * 2048 + k * 1024); } while (0)
; #define PG8_MMA(ai, bj, At, Bt) do { __builtin_amdgcn_s_setprio(1); _Pragma("unroll") for (int m = 0; m < 4; ++m) _Pragma("unroll") for (int n = 0; n < 2; ++n) _Pragma("unroll") for (int k = 0; k < 2; ++k) \
;         acc[ai][bj][m][n] = __builtin_amdgcn_mfma_f32_16x16x32_bf16(Bt[n][k], At[m][k], acc[ai][bj][m][n], 0, 0, 0); __builtin_amdgcn_s_setprio(0); } while (0)
; #define PG8_WAIT_V(n) asm volatile("s_waitcnt vmcnt(" #n ")" ::: "memory")
; #define PG8_WAIT_L(n) asm volatile("s_waitcnt lgkmcnt(" #n ")" ::: "memory")
; #define PG8_BAR __builtin_amdgcn_s_barrier()
; #define PG8_SCHED __builtin_amdgcn_sched_barrier(0)
; template <class Epi>
; __device__ __forceinline__ void gemm_phase(LAS unsigned char* lds, const Gemm g, const StaticOrder S, const Epi E) {
;     ...
;             const char* a1 = cA + (long)(t + 1) * ksc;
;             const char* a2 = last ? nA : cA + (long)(t + 2) * ksc; const char* b2 = last ? nB : cB + (long)(t + 2) * ksc;
;             const long ks3 = last ? ksn : ksc;
;             const char* a3 = a2 + ks3; const char* b3 = b2 + ks3;
;             PG8_LDB(B0, 0, 0); PG8_LDB(B1, 0, 1); PG8_SCHED; PG8_LDA(At, 0, 0); PG8_STAGE(PG8_SA(1, 1), a1 + hstepA, voffA);
;             PG8_WAIT_V(8); PG8_WAIT_L(0); PG8_BAR; PG8_MMA(0, 0, At, B0); PG8_MMA(0, 1, At, B1); PG8_BAR; PG8_SCHED;
;             PG8_LDA(At, 0, 1); PG8_STAGE(PG8_SB(0, 0), b2, voffB); PG8_STAGE(PG8_SB(0, 1), b2 + hstepB, voffB); PG8_STAGE(PG8_SA(0, 0), a2, voffA);
;             PG8_WAIT_V(8); PG8_WAIT_L(0); PG8_BAR; PG8_MMA(1, 0, At, B0); PG8_MMA(1, 1, At, B1); PG8_BAR; PG8_SCHED;
.LBB0_753:
	v_add_u32_e32 v152, s60, v164
	v_add_u32_e32 v176, s61, v164
	ds_read_b128 v[128:131], v152
	ds_read_b128 v[132:135], v152 offset:1024
	ds_read_b128 v[136:139], v152 offset:2048
	ds_read_b128 v[152:155], v152 offset:3072
	ds_read_b128 v[156:159], v176
	ds_read_b128 v[168:171], v176 offset:1024
	ds_read_b128 v[172:175], v176 offset:2048
	ds_read_b128 v[176:179], v176 offset:3072
	s_or_b32 s48, s71, 1
	s_mul_i32 s49, s35, s48
	s_mul_hi_u32 s73, s34, s48
	s_add_i32 s73, s73, s49
	s_mul_i32 s48, s34, s48
	s_add_u32 s74, s30, s48
	s_addc_u32 s73, s31, s73
	s_add_u32 s48, s46, s44
	s_addc_u32 s49, s47, s45
	s_add_u32 s74, s74, 0x160000
	s_addc_u32 s75, s73, 0
	s_add_i32 m0, s52, 0xc000
	ds_read_b128 v[180:183], v166
	ds_read_b128 v[184:187], v166 offset:1024
	ds_read_b128 v[188:191], v166 offset:2048
	ds_read_b128 v[192:195], v166 offset:3072
	ds_read_b128 v[196:199], v166 offset:4096
	ds_read_b128 v[200:203], v166 offset:5120
	ds_read_b128 v[204:207], v166 offset:6144
	ds_read_b128 v[208:211], v166 offset:7168
	global_load_lds_dwordx4 v140, s[74:75]
	s_add_i32 m0, s52, 0xe000
	s_nop 0
	global_load_lds_dwordx4 v144, s[74:75]
	s_waitcnt vmcnt(8)
	s_waitcnt lgkmcnt(0)
	s_barrier
	s_setprio 1
	s_waitcnt lgkmcnt(0)
	v_mfma_f32_16x16x32_bf16 v[124:127], v[128:131], v[180:183], v[124:127]
	v_mfma_f32_16x16x32_bf16 v[120:123], v[136:139], v[180:183], v[120:123]
	v_mfma_f32_16x16x32_bf16 v[108:111], v[128:131], v[188:191], v[108:111]
	v_mfma_f32_16x16x32_bf16 v[104:107], v[136:139], v[188:191], v[104:107]
	v_mfma_f32_16x16x32_bf16 v[92:95], v[128:131], v[196:199], v[92:95]
	v_mfma_f32_16x16x32_bf16 v[88:91], v[136:139], v[196:199], v[88:91]
	v_mfma_f32_16x16x32_bf16 v[76:79], v[128:131], v[204:207], v[76:79]
	v_mfma_f32_16x16x32_bf16 v[72:75], v[136:139], v[204:207], v[72:75]
	v_mfma_f32_16x16x32_bf16 v[124:127], v[132:135], v[184:187], v[124:127]
	v_mfma_f32_16x16x32_bf16 v[120:123], v[152:155], v[184:187], v[120:123]
	v_mfma_f32_16x16x32_bf16 v[108:111], v[132:135], v[192:195], v[108:111]
	v_mfma_f32_16x16x32_bf16 v[104:107], v[152:155], v[192:195], v[104:107]
	v_mfma_f32_16x16x32_bf16 v[92:95], v[132:135], v[200:203], v[92:95]
	v_mfma_f32_16x16x32_bf16 v[88:91], v[152:155], v[200:203], v[88:91]
	v_mfma_f32_16x16x32_bf16 v[76:79], v[132:135], v[208:211], v[76:79]
	v_mfma_f32_16x16x32_bf16 v[72:75], v[152:155], v[208:211], v[72:75]
	s_setprio 0
	s_setprio 1
	v_mfma_f32_16x16x32_bf16 v[116:119], v[156:159], v[180:183], v[116:119]
	v_mfma_f32_16x16x32_bf16 v[112:115], v[172:175], v[180:183], v[112:115]
	v_mfma_f32_16x16x32_bf16 v[100:103], v[156:159], v[188:191], v[100:103]
	v_mfma_f32_16x16x32_bf16 v[96:99], v[172:175], v[188:191], v[96:99]
	v_mfma_f32_16x16x32_bf16 v[84:87], v[156:159], v[196:199], v[84:87]
	v_mfma_f32_16x16x32_bf16 v[80:83], v[172:175], v[196:199], v[80:83]
	v_mfma_f32_16x16x32_bf16 v[68:71], v[156:159], v[204:207], v[68:71]
	v_mfma_f32_16x16x32_bf16 v[64:67], v[172:175], v[204:207], v[64:67]
	v_mfma_f32_16x16x32_bf16 v[116:119], v[168:171], v[184:187], v[116:119]
	v_mfma_f32_16x16x32_bf16 v[112:115], v[176:179], v[184:187], v[112:115]
	v_mfma_f32_16x16x32_bf16 v[100:103], v[168:171], v[192:195], v[100:103]
	v_mfma_f32_16x16x32_bf16 v[96:99], v[176:179], v[192:195], v[96:99]
	v_mfma_f32_16x16x32_bf16 v[84:87], v[168:171], v[200:203], v[84:87]
	v_mfma_f32_16x16x32_bf16 v[80:83], v[176:179], v[200:203], v[80:83]
	v_mfma_f32_16x16x32_bf16 v[68:71], v[168:171], v[208:211], v[68:71]
	v_mfma_f32_16x16x32_bf16 v[64:67], v[176:179], v[208:211], v[64:67]
	s_setprio 0
	s_barrier
	s_add_i32 s73, s60, s51
	s_mov_b32 m0, s73
	ds_read_b128 v[180:183], v166 offset:16384
	ds_read_b128 v[184:187], v166 offset:17408
	ds_read_b128 v[188:191], v166 offset:18432
	ds_read_b128 v[192:195], v166 offset:19456
	ds_read_b128 v[196:199], v166 offset:20480
	ds_read_b128 v[200:203], v166 offset:21504
	ds_read_b128 v[204:207], v166 offset:22528
	ds_read_b128 v[208:211], v166 offset:23552
	global_load_lds_dwordx4 v142, s[42:43]
	s_add_i32 m0, s73, 0x2000
	s_add_u32 s74, s42, 0x160000
	s_addc_u32 s75, s43, 0
	s_add_i32 s73, s61, s51
	global_load_lds_dwordx4 v146, s[42:43]
	s_mov_b32 m0, s73
	s_nop 0
	global_load_lds_dwordx4 v142, s[74:75]
	s_add_i32 m0, s73, 0x2000
	s_nop 0
	global_load_lds_dwordx4 v146, s[74:75]
	s_mov_b32 m0, s52
	s_nop 0
	global_load_lds_dwordx4 v140, s[46:47]
	s_mov_b32 m0, s53
	s_nop 0
	global_load_lds_dwordx4 v144, s[46:47]
	s_waitcnt vmcnt(8)
	s_waitcnt lgkmcnt(0)
	s_barrier
	s_setprio 1
	s_waitcnt lgkmcnt(0)
	v_mfma_f32_16x16x32_bf16 v[60:63], v[128:131], v[180:183], v[60:63]
	v_mfma_f32_16x16x32_bf16 v[56:59], v[136:139], v[180:183], v[56:59]
	v_mfma_f32_16x16x32_bf16 v[44:47], v[128:131], v[188:191], v[44:47]
	v_mfma_f32_16x16x32_bf16 v[40:43], v[136:139], v[188:191], v[40:43]
	v_mfma_f32_16x16x32_bf16 v[28:31], v[128:131], v[196:199], v[28:31]
	v_mfma_f32_16x16x32_bf16 v[24:27], v[136:139], v[196:199], v[24:27]
	v_mfma_f32_16x16x32_bf16 v[12:15], v[128:131], v[204:207], v[12:15]
	v_mfma_f32_16x16x32_bf16 v[8:11], v[136:139], v[204:207], v[8:11]
	v_mfma_f32_16x16x32_bf16 v[60:63], v[132:135], v[184:187], v[60:63]
	v_mfma_f32_16x16x32_bf16 v[56:59], v[152:155], v[184:187], v[56:59]
	v_mfma_f32_16x16x32_bf16 v[44:47], v[132:135], v[192:195], v[44:47]
	v_mfma_f32_16x16x32_bf16 v[40:43], v[152:155], v[192:195], v[40:43]
	v_mfma_f32_16x16x32_bf16 v[28:31], v[132:135], v[200:203], v[28:31]
	v_mfma_f32_16x16x32_bf16 v[24:27], v[152:155], v[200:203], v[24:27]
	v_mfma_f32_16x16x32_bf16 v[12:15], v[132:135], v[208:211], v[12:15]
	v_mfma_f32_16x16x32_bf16 v[8:11], v[152:155], v[208:211], v[8:11]
	s_setprio 0
	s_setprio 1
	v_mfma_f32_16x16x32_bf16 v[52:55], v[156:159], v[180:183], v[52:55]
	v_mfma_f32_16x16x32_bf16 v[48:51], v[172:175], v[180:183], v[48:51]
	v_mfma_f32_16x16x32_bf16 v[36:39], v[156:159], v[188:191], v[36:39]
	v_mfma_f32_16x16x32_bf16 v[32:35], v[172:175], v[188:191], v[32:35]
	v_mfma_f32_16x16x32_bf16 v[20:23], v[156:159], v[196:199], v[20:23]
	v_mfma_f32_16x16x32_bf16 v[16:19], v[172:175], v[196:199], v[16:19]
	v_mfma_f32_16x16x32_bf16 v[4:7], v[156:159], v[204:207], v[4:7]
	v_mfma_f32_16x16x32_bf16 v[0:3], v[172:175], v[204:207], v[0:3]
	v_mfma_f32_16x16x32_bf16 v[52:55], v[168:171], v[184:187], v[52:55]
	v_mfma_f32_16x16x32_bf16 v[48:51], v[176:179], v[184:187], v[48:51]
	v_mfma_f32_16x16x32_bf16 v[36:39], v[168:171], v[192:195], v[36:39]
	v_mfma_f32_16x16x32_bf16 v[32:35], v[176:179], v[192:195], v[32:35]
	v_mfma_f32_16x16x32_bf16 v[20:23], v[168:171], v[200:203], v[20:23]
	v_mfma_f32_16x16x32_bf16 v[16:19], v[176:179], v[200:203], v[16:19]
	v_mfma_f32_16x16x32_bf16 v[4:7], v[168:171], v[208:211], v[4:7]
	v_mfma_f32_16x16x32_bf16 v[0:3], v[176:179], v[208:211], v[0:3]
	s_setprio 0
	s_barrier
; #define PG8_STAGE(bufoff, gbase, voff) do { _Pragma("unroll") for (int _i = 0; _i < 2; ++_i) \
;         __builtin_amdgcn_global_load_lds((const unsigned*)((const char*)(gbase) + (voff)[_i]), (LAS unsigned*)(lds + (bufoff) + ldsw + _i * 8192), 16, 0, 0); } while (0)
; #define PG8_LDA(dst, b, h) do { _Pragma("unroll") for (int m = 0; m < 4; ++m) _Pragma("unroll") for (int k = 0; k < 2; ++k) dst[m][k] = *(const LAS bf16x8*)(lds + PG8_SA(b, h) + aoff + m * 2048 + k * 1024); } while (0)
; #define PG8_LDB(dst, b, h) do { _Pragma("unroll") for (int n = 0; n < 2; ++n) _Pragma("unroll") for (int k = 0; k < 2; ++k) dst[n][k] = *(const LAS bf16x8*)(lds + PG8_SB(b, h) + boff + n * 2048 + k * 1024); } while (0)
; #define PG8_MMA(ai, bj, At, Bt) do { __builtin_amdgcn_s_setprio(1); _Pragma("unroll") for (int m = 0; m < 4; ++m) _Pragma("unroll") for (int n = 0; n < 2; ++n) _Pragma("unroll") for (int k = 0; k < 2; ++k) \
;         acc[ai][bj][m][n] = __builtin_amdgcn_mfma_f32_16x16x32_bf16(Bt[n][k], At[m][k], acc[ai][bj][m][n], 0, 0, 0); __builtin_amdgcn_s_setprio(0); } while (0)
; #define PG8_WAIT_V(n) asm volatile("s_waitcnt vmcnt(" #n ")" ::: "memory")
; #define PG8_WAIT_L(n) asm volatile("s_waitcnt lgkmcnt(" #n ")" ::: "memory")
; #define PG8_BAR __builtin_amdgcn_s_barrier()
; #define PG8_SCHED __builtin_amdgcn_sched_barrier(0)
; template <class Epi>
; __device__ __forceinline__ void gemm_phase(LAS unsigned char* lds, const Gemm g, const StaticOrder S, const Epi E) {
;     ...
;             PG8_LDB(B0, 1, 0); PG8_LDB(B1, 1, 1); PG8_SCHED; PG8_LDA(At, 1, 0); PG8_STAGE(PG8_SA(0, 1), a2 + hstepA, voffA);
;             PG8_WAIT_V(8); PG8_WAIT_L(0); PG8_BAR; PG8_MMA(0, 0, At, B0); PG8_MMA(0, 1, At, B1); PG8_BAR; PG8_SCHED;
;             PG8_LDA(At, 1, 1); PG8_STAGE(PG8_SB(1, 0), b3, voffB); PG8_STAGE(PG8_SB(1, 1), b3 + hstepB, voffB); PG8_STAGE(PG8_SA(1, 0), a3, voffA);
;             PG8_WAIT_V(8); PG8_WAIT_L(0); PG8_BAR; PG8_MMA(1, 0, At, B0); PG8_MMA(1, 1, At, B1); PG8_BAR; PG8_SCHED;
;         }
	s_add_i32 s73, 0, 0x18000
	s_add_i32 s74, 0, 0x1c000
	v_add_u32_e32 v152, s73, v164
	v_add_u32_e32 v176, s74, v164
	ds_read_b128 v[128:131], v152
	ds_read_b128 v[132:135], v152 offset:1024
	ds_read_b128 v[136:139], v152 offset:2048
	ds_read_b128 v[152:155], v152 offset:3072
	ds_read_b128 v[156:159], v176
	ds_read_b128 v[168:171], v176 offset:1024
	ds_read_b128 v[172:175], v176 offset:2048
	ds_read_b128 v[176:179], v176 offset:3072
	s_add_u32 s46, s46, 0x160000
	s_addc_u32 s47, s47, 0
	s_mov_b32 m0, s54
	ds_read_b128 v[180:183], v166 offset:32768
	ds_read_b128 v[184:187], v166 offset:33792
	ds_read_b128 v[188:191], v166 offset:34816
	ds_read_b128 v[192:195], v166 offset:35840
	ds_read_b128 v[196:199], v166 offset:36864
	ds_read_b128 v[200:203], v166 offset:37888
	ds_read_b128 v[204:207], v166 offset:38912
	ds_read_b128 v[208:211], v166 offset:39936
	global_load_lds_dwordx4 v140, s[46:47]
	s_mov_b32 m0, s55
	s_nop 0
	global_load_lds_dwordx4 v144, s[46:47]
	s_waitcnt vmcnt(8)
	s_waitcnt lgkmcnt(0)
	s_barrier
	s_setprio 1
	s_waitcnt lgkmcnt(0)
	v_mfma_f32_16x16x32_bf16 v[124:127], v[128:131], v[180:183], v[124:127]
	v_mfma_f32_16x16x32_bf16 v[120:123], v[136:139], v[180:183], v[120:123]
	v_mfma_f32_16x16x32_bf16 v[108:111], v[128:131], v[188:191], v[108:111]
	v_mfma_f32_16x16x32_bf16 v[104:107], v[136:139], v[188:191], v[104:107]
	v_mfma_f32_16x16x32_bf16 v[92:95], v[128:131], v[196:199], v[92:95]
	v_mfma_f32_16x16x32_bf16 v[88:91], v[136:139], v[196:199], v[88:91]
	v_mfma_f32_16x16x32_bf16 v[76:79], v[128:131], v[204:207], v[76:79]
	v_mfma_f32_16x16x32_bf16 v[72:75], v[136:139], v[204:207], v[72:75]
	v_mfma_f32_16x16x32_bf16 v[124:127], v[132:135], v[184:187], v[124:127]
	v_mfma_f32_16x16x32_bf16 v[120:123], v[152:155], v[184:187], v[120:123]
	v_mfma_f32_16x16x32_bf16 v[108:111], v[132:135], v[192:195], v[108:111]
	v_mfma_f32_16x16x32_bf16 v[104:107], v[152:155], v[192:195], v[104:107]
	v_mfma_f32_16x16x32_bf16 v[92:95], v[132:135], v[200:203], v[92:95]
	v_mfma_f32_16x16x32_bf16 v[88:91], v[152:155], v[200:203], v[88:91]
	v_mfma_f32_16x16x32_bf16 v[76:79], v[132:135], v[208:211], v[76:79]
	v_mfma_f32_16x16x32_bf16 v[72:75], v[152:155], v[208:211], v[72:75]
	s_setprio 0
	s_setprio 1
	v_mfma_f32_16x16x32_bf16 v[116:119], v[156:159], v[180:183], v[116:119]
	v_mfma_f32_16x16x32_bf16 v[112:115], v[172:175], v[180:183], v[112:115]
	v_mfma_f32_16x16x32_bf16 v[100:103], v[156:159], v[188:191], v[100:103]
	v_mfma_f32_16x16x32_bf16 v[96:99], v[172:175], v[188:191], v[96:99]
	v_mfma_f32_16x16x32_bf16 v[84:87], v[156:159], v[196:199], v[84:87]
	v_mfma_f32_16x16x32_bf16 v[80:83], v[172:175], v[196:199], v[80:83]
	v_mfma_f32_16x16x32_bf16 v[68:71], v[156:159], v[204:207], v[68:71]
	v_mfma_f32_16x16x32_bf16 v[64:67], v[172:175], v[204:207], v[64:67]
	v_mfma_f32_16x16x32_bf16 v[116:119], v[168:171], v[184:187], v[116:119]
	v_mfma_f32_16x16x32_bf16 v[112:115], v[176:179], v[184:187], v[112:115]
	v_mfma_f32_16x16x32_bf16 v[100:103], v[168:171], v[192:195], v[100:103]
	v_mfma_f32_16x16x32_bf16 v[96:99], v[176:179], v[192:195], v[96:99]
	v_mfma_f32_16x16x32_bf16 v[84:87], v[168:171], v[200:203], v[84:87]
	v_mfma_f32_16x16x32_bf16 v[80:83], v[176:179], v[200:203], v[80:83]
	v_mfma_f32_16x16x32_bf16 v[68:71], v[168:171], v[208:211], v[68:71]
	v_mfma_f32_16x16x32_bf16 v[64:67], v[176:179], v[208:211], v[64:67]
	s_setprio 0
	s_barrier
	s_add_u32 s42, s42, s44
	s_addc_u32 s43, s43, s45
	s_add_i32 s44, s73, s51
	s_mov_b32 m0, s44
	ds_read_b128 v[180:183], v166 offset:49152
	ds_read_b128 v[184:187], v166 offset:50176
	ds_read_b128 v[188:191], v166 offset:51200
	ds_read_b128 v[192:195], v166 offset:52224
	ds_read_b128 v[196:199], v166 offset:53248
	ds_read_b128 v[200:203], v166 offset:54272
	ds_read_b128 v[204:207], v166 offset:55296
	ds_read_b128 v[208:211], v166 offset:56320
	global_load_lds_dwordx4 v142, s[42:43]
	s_add_i32 m0, s44, 0x2000
	v_lshl_add_u64 v[212:213], s[42:43], 0, v[146:147]
	s_add_u32 s42, s42, 0x160000
	s_addc_u32 s43, s43, 0
	s_add_i32 s44, s74, s51
	global_load_lds_dwordx4 v[212:213], off
	s_mov_b32 m0, s44
	s_nop 0
	global_load_lds_dwordx4 v142, s[42:43]
	s_add_i32 m0, s44, 0x2000
	s_nop 0
	global_load_lds_dwordx4 v146, s[42:43]
	s_mov_b32 m0, s57
	s_nop 0
	global_load_lds_dwordx4 v140, s[48:49]
	s_mov_b32 m0, s58
	s_nop 0
	global_load_lds_dwordx4 v144, s[48:49]
	s_waitcnt vmcnt(8)
	s_waitcnt lgkmcnt(0)
	s_barrier
	s_setprio 1
	s_waitcnt lgkmcnt(0)
	v_mfma_f32_16x16x32_bf16 v[60:63], v[128:131], v[180:183], v[60:63]
	v_mfma_f32_16x16x32_bf16 v[56:59], v[136:139], v[180:183], v[56:59]
	v_mfma_f32_16x16x32_bf16 v[44:47], v[128:131], v[188:191], v[44:47]
	v_mfma_f32_16x16x32_bf16 v[40:43], v[136:139], v[188:191], v[40:43]
	v_mfma_f32_16x16x32_bf16 v[28:31], v[128:131], v[196:199], v[28:31]
	v_mfma_f32_16x16x32_bf16 v[24:27], v[136:139], v[196:199], v[24:27]
	v_mfma_f32_16x16x32_bf16 v[12:15], v[128:131], v[204:207], v[12:15]
	v_mfma_f32_16x16x32_bf16 v[8:11], v[136:139], v[204:207], v[8:11]
	v_mfma_f32_16x16x32_bf16 v[60:63], v[132:135], v[184:187], v[60:63]
	v_mfma_f32_16x16x32_bf16 v[56:59], v[152:155], v[184:187], v[56:59]
	v_mfma_f32_16x16x32_bf16 v[44:47], v[132:135], v[192:195], v[44:47]
	v_mfma_f32_16x16x32_bf16 v[40:43], v[152:155], v[192:195], v[40:43]
	v_mfma_f32_16x16x32_bf16 v[28:31], v[132:135], v[200:203], v[28:31]
	v_mfma_f32_16x16x32_bf16 v[24:27], v[152:155], v[200:203], v[24:27]
	v_mfma_f32_16x16x32_bf16 v[12:15], v[132:135], v[208:211], v[12:15]
	v_mfma_f32_16x16x32_bf16 v[8:11], v[152:155], v[208:211], v[8:11]
	s_setprio 0
	s_setprio 1
	v_mfma_f32_16x16x32_bf16 v[52:55], v[156:159], v[180:183], v[52:55]
	v_mfma_f32_16x16x32_bf16 v[48:51], v[172:175], v[180:183], v[48:51]
	v_mfma_f32_16x16x32_bf16 v[36:39], v[156:159], v[188:191], v[36:39]
	v_mfma_f32_16x16x32_bf16 v[32:35], v[172:175], v[188:191], v[32:35]
	v_mfma_f32_16x16x32_bf16 v[20:23], v[156:159], v[196:199], v[20:23]
	v_mfma_f32_16x16x32_bf16 v[16:19], v[172:175], v[196:199], v[16:19]
	v_mfma_f32_16x16x32_bf16 v[4:7], v[156:159], v[204:207], v[4:7]
	v_mfma_f32_16x16x32_bf16 v[0:3], v[172:175], v[204:207], v[0:3]
	v_mfma_f32_16x16x32_bf16 v[52:55], v[168:171], v[184:187], v[52:55]
	v_mfma_f32_16x16x32_bf16 v[48:51], v[176:179], v[184:187], v[48:51]
	v_mfma_f32_16x16x32_bf16 v[36:39], v[168:171], v[192:195], v[36:39]
	v_mfma_f32_16x16x32_bf16 v[32:35], v[176:179], v[192:195], v[32:35]
	v_mfma_f32_16x16x32_bf16 v[20:23], v[168:171], v[200:203], v[20:23]
	v_mfma_f32_16x16x32_bf16 v[16:19], v[176:179], v[200:203], v[16:19]
	v_mfma_f32_16x16x32_bf16 v[4:7], v[168:171], v[208:211], v[4:7]
	v_mfma_f32_16x16x32_bf16 v[0:3], v[176:179], v[208:211], v[0:3]
	s_setprio 0
	s_barrier
	s_cmpk_gt_u32 s71, 0x55
	s_mov_b32 s71, s72
	s_cbranch_scc1 .LBB0_758

; #define PG8_STAGE(bufoff, gbase, voff) do { _Pragma("unroll") for (int _i = 0; _i < 2; ++_i) \
;         __builtin_amdgcn_global_load_lds((const unsigned*)((const char*)(gbase) + (voff)[_i]), (LAS unsigned*)(lds + (bufoff) + ldsw + _i * 8192), 16, 0, 0); } while (0)
; #define PG8_WAIT_V(n) asm volatile("s_waitcnt vmcnt(" #n ")" ::: "memory")
; #define PG8_BAR __builtin_amdgcn_s_barrier()
; template <class Epi>
; __device__ __forceinline__ void gemm_phase(LAS unsigned char* lds, const Gemm g, const StaticOrder S, const Epi E) {
;     ...
;     PG8_STAGE(PG8_SB(0, 0), cB, voffB); PG8_STAGE(PG8_SB(0, 1), cB + hstepB, voffB); PG8_STAGE(PG8_SA(0, 0), cA, voffA); PG8_STAGE(PG8_SA(0, 1), cA + hstepA, voffA);
;     if (wr == 1) PG8_BAR;
;     PG8_WAIT_V(2); PG8_BAR;
;     PG8_STAGE(PG8_SB(1, 0), cB + ksc, voffB); PG8_STAGE(PG8_SA(1, 0), cA + ksc, voffA); PG8_STAGE(PG8_SB(1, 1), cB + hstepB + ksc, voffB);
;     PG8_WAIT_V(6); PG8_BAR;
.LBB0_847:
	s_add_u32 s6, s82, 0x2a9b0000
	s_addc_u32 s7, s83, 0
	s_lshl_b32 s9, s9, 5
	s_mov_b64 s[26:27], 0x80
	s_and_b32 s14, s9, 0x60
	s_add_i32 m0, s21, 0x18000
	v_lshl_add_u64 v[6:7], v[6:7], 0, s[26:27]
	s_lshl_b32 s10, s8, 13
	s_lshl_b32 s9, s14, 7
	s_waitcnt vmcnt(2)
	s_barrier
	global_load_lds_dwordx4 v[6:7], off
	v_lshl_add_u64 v[4:5], v[4:5], 0, s[26:27]
	s_add_i32 m0, s21, 0x1a000
	s_add_i32 s55, s21, 0x8000
	s_add_i32 s56, s21, 0xa000
	global_load_lds_dwordx4 v[4:5], off
	v_lshl_add_u64 v[0:1], v[0:1], 0, s[26:27]
	s_mov_b32 m0, s55
	s_add_u32 s12, s22, 0x80080
	global_load_lds_dwordx4 v[0:1], off
	v_lshl_add_u64 v[0:1], v[2:3], 0, s[26:27]
	s_mov_b32 m0, s56
	s_addc_u32 s13, s23, 0
	global_load_lds_dwordx4 v[0:1], off
	s_add_i32 m0, s21, 0x1c000
	s_nop 0
	global_load_lds_dwordx4 v132, s[12:13]
	s_add_i32 m0, s21, 0x1e000
	v_lshlrev_b32_e32 v2, 2, v224
	global_load_lds_dwordx4 v128, s[12:13]
	v_and_b32_e32 v0, 15, v224
	v_lshlrev_b32_e32 v1, 1, v8
	s_sext_i32_i16 s63, s0
	v_lshl_or_b32 v142, s8, 6, v0
	v_lshl_or_b32 v0, v0, 6, v1
	v_and_b32_e32 v2, 32, v2
	v_lshlrev_b32_e32 v3, 6, v224
	s_movk_i32 s0, 0x3c0
	s_waitcnt vmcnt(6)
	s_ashr_i32 s57, s78, 31
	v_bitop3_b32 v0, v0, s10, v2 bitop3:0xde
	v_and_or_b32 v1, v3, s0, v1
	s_cmpk_lt_u32 s1, 0x100
	v_bitop3_b32 v143, s9, v1, v2 bitop3:0xf6
	s_cselect_b64 s[8:9], -1, 0
	v_or_b32_e32 v144, s14, v8
	v_mov_b64_e32 v[136:137], 0xb00
	v_mov_b64_e32 v[138:139], 0xaff
	s_movk_i32 s58, 0xff80
	s_add_i32 s59, 0, 0x10000
	s_add_i32 s60, 0, 0x14000
	v_add_u32_e32 v145, 0, v0
	s_movk_i32 s61, 0x2c00
	v_mov_b32_e32 v146, 0x358637bd
	s_barrier
	s_branch .LBB0_850

; #define PG8_STAGE(bufoff, gbase, voff) do { _Pragma("unroll") for (int _i = 0; _i < 2; ++_i) \
;         __builtin_amdgcn_global_load_lds((const unsigned*)((const char*)(gbase) + (voff)[_i]), (LAS unsigned*)(lds + (bufoff) + ldsw + _i * 8192), 16, 0, 0); } while (0)
; #define PG8_LDA(dst, b, h) do { _Pragma("unroll") for (int m = 0; m < 4; ++m) _Pragma("unroll") for (int k = 0; k < 2; ++k) dst[m][k] = *(const LAS bf16x8*)(lds + PG8_SA(b, h) + aoff + m * 2048 + k * 1024); } while (0)
; #define PG8_LDB(dst, b, h) do { _Pragma("unroll") for (int n = 0; n < 2; ++n) _Pragma("unroll") for (int k = 0; k < 2; ++k) dst[n][k] = *(const LAS bf16x8*)(lds + PG8_SB(b, h) + boff + n * 2048 + k * 1024); } while (0)
; #define PG8_MMA(ai, bj, At, Bt) do { __builtin_amdgcn_s_setprio(1); _Pragma("unroll") for (int m = 0; m < 4; ++m) _Pragma("unroll") for (int n = 0; n < 2; ++n) _Pragma("unroll") for (int k = 0; k < 2; ++k) \
;         acc[ai][bj][m][n] = __builtin_amdgcn_mfma_f32_16x16x32_bf16(Bt[n][k], At[m][k], acc[ai][bj][m][n], 0, 0, 0); __builtin_amdgcn_s_setprio(0); } while (0)
; #define PG8_WAIT_V(n) asm volatile("s_waitcnt vmcnt(" #n ")" ::: "memory")
; #define PG8_WAIT_L(n) asm volatile("s_waitcnt lgkmcnt(" #n ")" ::: "memory")
; #define PG8_BAR __builtin_amdgcn_s_barrier()
; #define PG8_SCHED __builtin_amdgcn_sched_barrier(0)
; template <class Epi>
; __device__ __forceinline__ void gemm_phase(LAS unsigned char* lds, const Gemm g, const StaticOrder S, const Epi E) {
;     ...
;             const char* a1 = cA + (long)(t + 1) * ksc;
;             const char* a2 = last ? nA : cA + (long)(t + 2) * ksc; const char* b2 = last ? nB : cB + (long)(t + 2) * ksc;
;             const long ks3 = last ? ksn : ksc;
;             const char* a3 = a2 + ks3; const char* b3 = b2 + ks3;
;             PG8_LDB(B0, 0, 0); PG8_LDB(B1, 0, 1); PG8_SCHED; PG8_LDA(At, 0, 0); PG8_STAGE(PG8_SA(1, 1), a1 + hstepA, voffA);
;             PG8_WAIT_V(8); PG8_WAIT_L(0); PG8_BAR; PG8_MMA(0, 0, At, B0); PG8_MMA(0, 1, At, B1); PG8_BAR; PG8_SCHED;
;             PG8_LDA(At, 0, 1); PG8_STAGE(PG8_SB(0, 0), b2, voffB); PG8_STAGE(PG8_SB(0, 1), b2 + hstepB, voffB); PG8_STAGE(PG8_SA(0, 0), a2, voffA);
;             PG8_WAIT_V(8); PG8_WAIT_L(0); PG8_BAR; PG8_MMA(1, 0, At, B0); PG8_MMA(1, 1, At, B1); PG8_BAR; PG8_SCHED;
.LBB0_853:
	v_add_u32_e32 v140, s59, v143
	ds_read_b128 v[148:151], v140
	ds_read_b128 v[152:155], v140 offset:1024
	ds_read_b128 v[156:159], v140 offset:2048
	ds_read_b128 v[160:163], v140 offset:3072
	v_add_u32_e32 v140, s60, v143
	ds_read_b128 v[164:167], v140
	ds_read_b128 v[168:171], v140 offset:1024
	ds_read_b128 v[172:175], v140 offset:2048
	ds_read_b128 v[176:179], v140 offset:3072
	s_or_b32 s13, s64, 1
	s_mul_i32 s48, s27, s13
	s_mul_hi_u32 s49, s26, s13
	s_add_i32 s49, s49, s48
	s_mul_i32 s13, s26, s13
	s_add_u32 s13, s24, s13
	s_addc_u32 s65, s25, s49
	s_add_u32 s48, s46, s44
	s_addc_u32 s49, s47, s45
	s_add_u32 s66, s13, 0x80000
	s_addc_u32 s67, s65, 0
	s_add_i32 m0, s21, 0xc000
	ds_read_b128 v[180:183], v145
	ds_read_b128 v[184:187], v145 offset:1024
	ds_read_b128 v[188:191], v145 offset:2048
	ds_read_b128 v[192:195], v145 offset:3072
	ds_read_b128 v[196:199], v145 offset:4096
	ds_read_b128 v[200:203], v145 offset:5120
	ds_read_b128 v[204:207], v145 offset:6144
	ds_read_b128 v[208:211], v145 offset:7168
	global_load_lds_dwordx4 v134, s[66:67]
	s_add_i32 m0, s21, 0xe000
	s_nop 0
	global_load_lds_dwordx4 v130, s[66:67]
	s_waitcnt vmcnt(8)
	s_waitcnt lgkmcnt(0)
	s_barrier
	s_setprio 1
	s_waitcnt lgkmcnt(0)
	v_mfma_f32_16x16x32_bf16 v[116:119], v[148:151], v[180:183], v[116:119]
	v_mfma_f32_16x16x32_bf16 v[112:115], v[156:159], v[180:183], v[112:115]
	v_mfma_f32_16x16x32_bf16 v[108:111], v[148:151], v[188:191], v[108:111]
	v_mfma_f32_16x16x32_bf16 v[104:107], v[156:159], v[188:191], v[104:107]
	v_mfma_f32_16x16x32_bf16 v[92:95], v[148:151], v[196:199], v[92:95]
	v_mfma_f32_16x16x32_bf16 v[88:91], v[156:159], v[196:199], v[88:91]
	v_mfma_f32_16x16x32_bf16 v[76:79], v[148:151], v[204:207], v[76:79]
	v_mfma_f32_16x16x32_bf16 v[72:75], v[156:159], v[204:207], v[72:75]
	v_mfma_f32_16x16x32_bf16 v[116:119], v[152:155], v[184:187], v[116:119]
	v_mfma_f32_16x16x32_bf16 v[112:115], v[160:163], v[184:187], v[112:115]
	v_mfma_f32_16x16x32_bf16 v[108:111], v[152:155], v[192:195], v[108:111]
	v_mfma_f32_16x16x32_bf16 v[104:107], v[160:163], v[192:195], v[104:107]
	v_mfma_f32_16x16x32_bf16 v[92:95], v[152:155], v[200:203], v[92:95]
	v_mfma_f32_16x16x32_bf16 v[88:91], v[160:163], v[200:203], v[88:91]
	v_mfma_f32_16x16x32_bf16 v[76:79], v[152:155], v[208:211], v[76:79]
	v_mfma_f32_16x16x32_bf16 v[72:75], v[160:163], v[208:211], v[72:75]
	s_setprio 0
	s_setprio 1
	v_mfma_f32_16x16x32_bf16 v[124:127], v[164:167], v[180:183], v[124:127]
	v_mfma_f32_16x16x32_bf16 v[120:123], v[172:175], v[180:183], v[120:123]
	v_mfma_f32_16x16x32_bf16 v[100:103], v[164:167], v[188:191], v[100:103]
	v_mfma_f32_16x16x32_bf16 v[96:99], v[172:175], v[188:191], v[96:99]
	v_mfma_f32_16x16x32_bf16 v[84:87], v[164:167], v[196:199], v[84:87]
	v_mfma_f32_16x16x32_bf16 v[80:83], v[172:175], v[196:199], v[80:83]
	v_mfma_f32_16x16x32_bf16 v[68:71], v[164:167], v[204:207], v[68:71]
	v_mfma_f32_16x16x32_bf16 v[64:67], v[172:175], v[204:207], v[64:67]
	v_mfma_f32_16x16x32_bf16 v[124:127], v[168:171], v[184:187], v[124:127]
	v_mfma_f32_16x16x32_bf16 v[120:123], v[176:179], v[184:187], v[120:123]
	v_mfma_f32_16x16x32_bf16 v[100:103], v[168:171], v[192:195], v[100:103]
	v_mfma_f32_16x16x32_bf16 v[96:99], v[176:179], v[192:195], v[96:99]
	v_mfma_f32_16x16x32_bf16 v[84:87], v[168:171], v[200:203], v[84:87]
	v_mfma_f32_16x16x32_bf16 v[80:83], v[176:179], v[200:203], v[80:83]
	v_mfma_f32_16x16x32_bf16 v[68:71], v[168:171], v[208:211], v[68:71]
	v_mfma_f32_16x16x32_bf16 v[64:67], v[176:179], v[208:211], v[64:67]
	s_setprio 0
	s_barrier
	s_add_i32 s13, s59, s33
	s_mov_b32 m0, s13
	ds_read_b128 v[180:183], v145 offset:16384
	ds_read_b128 v[184:187], v145 offset:17408
	ds_read_b128 v[188:191], v145 offset:18432
	ds_read_b128 v[192:195], v145 offset:19456
	ds_read_b128 v[196:199], v145 offset:20480
	ds_read_b128 v[200:203], v145 offset:21504
	ds_read_b128 v[204:207], v145 offset:22528
	ds_read_b128 v[208:211], v145 offset:23552
	global_load_lds_dwordx4 v132, s[42:43]
	s_add_i32 m0, s13, 0x2000
	s_add_u32 s66, s42, 0x80000
	s_addc_u32 s67, s43, 0
	s_add_i32 s13, s60, s33
	global_load_lds_dwordx4 v128, s[42:43]
	s_mov_b32 m0, s13
	s_nop 0
	global_load_lds_dwordx4 v132, s[66:67]
	s_add_i32 m0, s13, 0x2000
	s_nop 0
	global_load_lds_dwordx4 v128, s[66:67]
	s_mov_b32 m0, s21
	s_nop 0
	global_load_lds_dwordx4 v134, s[46:47]
	s_mov_b32 m0, s52
	s_nop 0
	global_load_lds_dwordx4 v130, s[46:47]
	s_waitcnt vmcnt(8)
	s_waitcnt lgkmcnt(0)
	s_barrier
	s_setprio 1
	s_waitcnt lgkmcnt(0)
	v_mfma_f32_16x16x32_bf16 v[60:63], v[148:151], v[180:183], v[60:63]
	v_mfma_f32_16x16x32_bf16 v[56:59], v[156:159], v[180:183], v[56:59]
	v_mfma_f32_16x16x32_bf16 v[44:47], v[148:151], v[188:191], v[44:47]
	v_mfma_f32_16x16x32_bf16 v[40:43], v[156:159], v[188:191], v[40:43]
	v_mfma_f32_16x16x32_bf16 v[28:31], v[148:151], v[196:199], v[28:31]
	v_mfma_f32_16x16x32_bf16 v[24:27], v[156:159], v[196:199], v[24:27]
	v_mfma_f32_16x16x32_bf16 v[12:15], v[148:151], v[204:207], v[12:15]
	v_mfma_f32_16x16x32_bf16 v[8:11], v[156:159], v[204:207], v[8:11]
	v_mfma_f32_16x16x32_bf16 v[60:63], v[152:155], v[184:187], v[60:63]
	v_mfma_f32_16x16x32_bf16 v[56:59], v[160:163], v[184:187], v[56:59]
	v_mfma_f32_16x16x32_bf16 v[44:47], v[152:155], v[192:195], v[44:47]
	v_mfma_f32_16x16x32_bf16 v[40:43], v[160:163], v[192:195], v[40:43]
	v_mfma_f32_16x16x32_bf16 v[28:31], v[152:155], v[200:203], v[28:31]
	v_mfma_f32_16x16x32_bf16 v[24:27], v[160:163], v[200:203], v[24:27]
	v_mfma_f32_16x16x32_bf16 v[12:15], v[152:155], v[208:211], v[12:15]
	v_mfma_f32_16x16x32_bf16 v[8:11], v[160:163], v[208:211], v[8:11]
	s_setprio 0
	s_setprio 1
	v_mfma_f32_16x16x32_bf16 v[52:55], v[164:167], v[180:183], v[52:55]
	v_mfma_f32_16x16x32_bf16 v[48:51], v[172:175], v[180:183], v[48:51]
	v_mfma_f32_16x16x32_bf16 v[36:39], v[164:167], v[188:191], v[36:39]
	v_mfma_f32_16x16x32_bf16 v[32:35], v[172:175], v[188:191], v[32:35]
	v_mfma_f32_16x16x32_bf16 v[20:23], v[164:167], v[196:199], v[20:23]
	v_mfma_f32_16x16x32_bf16 v[16:19], v[172:175], v[196:199], v[16:19]
	v_mfma_f32_16x16x32_bf16 v[4:7], v[164:167], v[204:207], v[4:7]
	v_mfma_f32_16x16x32_bf16 v[0:3], v[172:175], v[204:207], v[0:3]
	v_mfma_f32_16x16x32_bf16 v[52:55], v[168:171], v[184:187], v[52:55]
	v_mfma_f32_16x16x32_bf16 v[48:51], v[176:179], v[184:187], v[48:51]
	v_mfma_f32_16x16x32_bf16 v[36:39], v[168:171], v[192:195], v[36:39]
	v_mfma_f32_16x16x32_bf16 v[32:35], v[176:179], v[192:195], v[32:35]
	v_mfma_f32_16x16x32_bf16 v[20:23], v[168:171], v[200:203], v[20:23]
	v_mfma_f32_16x16x32_bf16 v[16:19], v[176:179], v[200:203], v[16:19]
	v_mfma_f32_16x16x32_bf16 v[4:7], v[168:171], v[208:211], v[4:7]
	v_mfma_f32_16x16x32_bf16 v[0:3], v[176:179], v[208:211], v[0:3]
	s_setprio 0
	s_barrier
; #define PG8_STAGE(bufoff, gbase, voff) do { _Pragma("unroll") for (int _i = 0; _i < 2; ++_i) \
;         __builtin_amdgcn_global_load_lds((const unsigned*)((const char*)(gbase) + (voff)[_i]), (LAS unsigned*)(lds + (bufoff) + ldsw + _i * 8192), 16, 0, 0); } while (0)
; #define PG8_LDA(dst, b, h) do { _Pragma("unroll") for (int m = 0; m < 4; ++m) _Pragma("unroll") for (int k = 0; k < 2; ++k) dst[m][k] = *(const LAS bf16x8*)(lds + PG8_SA(b, h) + aoff + m * 2048 + k * 1024); } while (0)
; #define PG8_LDB(dst, b, h) do { _Pragma("unroll") for (int n = 0; n < 2; ++n) _Pragma("unroll") for (int k = 0; k < 2; ++k) dst[n][k] = *(const LAS bf16x8*)(lds + PG8_SB(b, h) + boff + n * 2048 + k * 1024); } while (0)
; #define PG8_MMA(ai, bj, At, Bt) do { __builtin_amdgcn_s_setprio(1); _Pragma("unroll") for (int m = 0; m < 4; ++m) _Pragma("unroll") for (int n = 0; n < 2; ++n) _Pragma("unroll") for (int k = 0; k < 2; ++k) \
;         acc[ai][bj][m][n] = __builtin_amdgcn_mfma_f32_16x16x32_bf16(Bt[n][k], At[m][k], acc[ai][bj][m][n], 0, 0, 0); __builtin_amdgcn_s_setprio(0); } while (0)
; #define PG8_WAIT_V(n) asm volatile("s_waitcnt vmcnt(" #n ")" ::: "memory")
; #define PG8_WAIT_L(n) asm volatile("s_waitcnt lgkmcnt(" #n ")" ::: "memory")
; #define PG8_BAR __builtin_amdgcn_s_barrier()
; #define PG8_SCHED __builtin_amdgcn_sched_barrier(0)
; template <class Epi>
; __device__ __forceinline__ void gemm_phase(LAS unsigned char* lds, const Gemm g, const StaticOrder S, const Epi E) {
;     ...
;             PG8_LDB(B0, 1, 0); PG8_LDB(B1, 1, 1); PG8_SCHED; PG8_LDA(At, 1, 0); PG8_STAGE(PG8_SA(0, 1), a2 + hstepA, voffA);
;             PG8_WAIT_V(8); PG8_WAIT_L(0); PG8_BAR; PG8_MMA(0, 0, At, B0); PG8_MMA(0, 1, At, B1); PG8_BAR; PG8_SCHED;
;             PG8_LDA(At, 1, 1); PG8_STAGE(PG8_SB(1, 0), b3, voffB); PG8_STAGE(PG8_SB(1, 1), b3 + hstepB, voffB); PG8_STAGE(PG8_SA(1, 0), a3, voffA);
;             PG8_WAIT_V(8); PG8_WAIT_L(0); PG8_BAR; PG8_MMA(1, 0, At, B0); PG8_MMA(1, 1, At, B1); PG8_BAR; PG8_SCHED;
;         }
	s_add_i32 s13, 0, 0x18000
	v_add_u32_e32 v140, s13, v143
	s_add_i32 s65, 0, 0x1c000
	ds_read_b128 v[148:151], v140
	ds_read_b128 v[152:155], v140 offset:1024
	ds_read_b128 v[156:159], v140 offset:2048
	ds_read_b128 v[160:163], v140 offset:3072
	v_add_u32_e32 v140, s65, v143
	ds_read_b128 v[164:167], v140
	ds_read_b128 v[168:171], v140 offset:1024
	ds_read_b128 v[172:175], v140 offset:2048
	ds_read_b128 v[176:179], v140 offset:3072
	s_add_u32 s46, s46, 0x80000
	s_addc_u32 s47, s47, 0
	s_mov_b32 m0, s53
	ds_read_b128 v[180:183], v145 offset:32768
	ds_read_b128 v[184:187], v145 offset:33792
	ds_read_b128 v[188:191], v145 offset:34816
	ds_read_b128 v[192:195], v145 offset:35840
	ds_read_b128 v[196:199], v145 offset:36864
	ds_read_b128 v[200:203], v145 offset:37888
	ds_read_b128 v[204:207], v145 offset:38912
	ds_read_b128 v[208:211], v145 offset:39936
	global_load_lds_dwordx4 v134, s[46:47]
	s_mov_b32 m0, s54
	s_nop 0
	global_load_lds_dwordx4 v130, s[46:47]
	s_waitcnt vmcnt(8)
	s_waitcnt lgkmcnt(0)
	s_barrier
	s_setprio 1
	s_waitcnt lgkmcnt(0)
	v_mfma_f32_16x16x32_bf16 v[116:119], v[148:151], v[180:183], v[116:119]
	v_mfma_f32_16x16x32_bf16 v[112:115], v[156:159], v[180:183], v[112:115]
	v_mfma_f32_16x16x32_bf16 v[108:111], v[148:151], v[188:191], v[108:111]
	v_mfma_f32_16x16x32_bf16 v[104:107], v[156:159], v[188:191], v[104:107]
	v_mfma_f32_16x16x32_bf16 v[92:95], v[148:151], v[196:199], v[92:95]
	v_mfma_f32_16x16x32_bf16 v[88:91], v[156:159], v[196:199], v[88:91]
	v_mfma_f32_16x16x32_bf16 v[76:79], v[148:151], v[204:207], v[76:79]
	v_mfma_f32_16x16x32_bf16 v[72:75], v[156:159], v[204:207], v[72:75]
	v_mfma_f32_16x16x32_bf16 v[116:119], v[152:155], v[184:187], v[116:119]
	v_mfma_f32_16x16x32_bf16 v[112:115], v[160:163], v[184:187], v[112:115]
	v_mfma_f32_16x16x32_bf16 v[108:111], v[152:155], v[192:195], v[108:111]
	v_mfma_f32_16x16x32_bf16 v[104:107], v[160:163], v[192:195], v[104:107]
	v_mfma_f32_16x16x32_bf16 v[92:95], v[152:155], v[200:203], v[92:95]
	v_mfma_f32_16x16x32_bf16 v[88:91], v[160:163], v[200:203], v[88:91]
	v_mfma_f32_16x16x32_bf16 v[76:79], v[152:155], v[208:211], v[76:79]
	v_mfma_f32_16x16x32_bf16 v[72:75], v[160:163], v[208:211], v[72:75]
	s_setprio 0
	s_setprio 1
	v_mfma_f32_16x16x32_bf16 v[124:127], v[164:167], v[180:183], v[124:127]
	v_mfma_f32_16x16x32_bf16 v[120:123], v[172:175], v[180:183], v[120:123]
	v_mfma_f32_16x16x32_bf16 v[100:103], v[164:167], v[188:191], v[100:103]
	v_mfma_f32_16x16x32_bf16 v[96:99], v[172:175], v[188:191], v[96:99]
	v_mfma_f32_16x16x32_bf16 v[84:87], v[164:167], v[196:199], v[84:87]
	v_mfma_f32_16x16x32_bf16 v[80:83], v[172:175], v[196:199], v[80:83]
	v_mfma_f32_16x16x32_bf16 v[68:71], v[164:167], v[204:207], v[68:71]
	v_mfma_f32_16x16x32_bf16 v[64:67], v[172:175], v[204:207], v[64:67]
	v_mfma_f32_16x16x32_bf16 v[124:127], v[168:171], v[184:187], v[124:127]
	v_mfma_f32_16x16x32_bf16 v[120:123], v[176:179], v[184:187], v[120:123]
	v_mfma_f32_16x16x32_bf16 v[100:103], v[168:171], v[192:195], v[100:103]
	v_mfma_f32_16x16x32_bf16 v[96:99], v[176:179], v[192:195], v[96:99]
	v_mfma_f32_16x16x32_bf16 v[84:87], v[168:171], v[200:203], v[84:87]
	v_mfma_f32_16x16x32_bf16 v[80:83], v[176:179], v[200:203], v[80:83]
	v_mfma_f32_16x16x32_bf16 v[68:71], v[168:171], v[208:211], v[68:71]
	v_mfma_f32_16x16x32_bf16 v[64:67], v[176:179], v[208:211], v[64:67]
	s_setprio 0
	s_barrier
	s_add_u32 s42, s42, s44
	s_addc_u32 s43, s43, s45
	s_add_i32 s13, s13, s33
	s_mov_b32 m0, s13
	ds_read_b128 v[180:183], v145 offset:49152
	ds_read_b128 v[184:187], v145 offset:50176
	ds_read_b128 v[188:191], v145 offset:51200
	ds_read_b128 v[192:195], v145 offset:52224
	ds_read_b128 v[196:199], v145 offset:53248
	ds_read_b128 v[200:203], v145 offset:54272
	ds_read_b128 v[204:207], v145 offset:55296
	ds_read_b128 v[208:211], v145 offset:56320
	global_load_lds_dwordx4 v132, s[42:43]
	s_add_i32 m0, s13, 0x2000
	v_lshl_add_u64 v[140:141], s[42:43], 0, v[128:129]
	s_add_u32 s42, s42, 0x80000
	s_addc_u32 s43, s43, 0
	s_add_i32 s13, s65, s33
	global_load_lds_dwordx4 v[140:141], off
	s_mov_b32 m0, s13
	s_nop 0
	global_load_lds_dwordx4 v132, s[42:43]
	s_add_i32 m0, s13, 0x2000
	s_nop 0
	global_load_lds_dwordx4 v128, s[42:43]
	s_mov_b32 m0, s55
	s_nop 0
	global_load_lds_dwordx4 v134, s[48:49]
	s_mov_b32 m0, s56
	s_nop 0
	global_load_lds_dwordx4 v130, s[48:49]
	s_waitcnt vmcnt(8)
	s_waitcnt lgkmcnt(0)
	s_barrier
	s_setprio 1
	s_waitcnt lgkmcnt(0)
	v_mfma_f32_16x16x32_bf16 v[60:63], v[148:151], v[180:183], v[60:63]
	v_mfma_f32_16x16x32_bf16 v[56:59], v[156:159], v[180:183], v[56:59]
	v_mfma_f32_16x16x32_bf16 v[44:47], v[148:151], v[188:191], v[44:47]
	v_mfma_f32_16x16x32_bf16 v[40:43], v[156:159], v[188:191], v[40:43]
	v_mfma_f32_16x16x32_bf16 v[28:31], v[148:151], v[196:199], v[28:31]
	v_mfma_f32_16x16x32_bf16 v[24:27], v[156:159], v[196:199], v[24:27]
	v_mfma_f32_16x16x32_bf16 v[12:15], v[148:151], v[204:207], v[12:15]
	v_mfma_f32_16x16x32_bf16 v[8:11], v[156:159], v[204:207], v[8:11]
	v_mfma_f32_16x16x32_bf16 v[60:63], v[152:155], v[184:187], v[60:63]
	v_mfma_f32_16x16x32_bf16 v[56:59], v[160:163], v[184:187], v[56:59]
	v_mfma_f32_16x16x32_bf16 v[44:47], v[152:155], v[192:195], v[44:47]
	v_mfma_f32_16x16x32_bf16 v[40:43], v[160:163], v[192:195], v[40:43]
	v_mfma_f32_16x16x32_bf16 v[28:31], v[152:155], v[200:203], v[28:31]
	v_mfma_f32_16x16x32_bf16 v[24:27], v[160:163], v[200:203], v[24:27]
	v_mfma_f32_16x16x32_bf16 v[12:15], v[152:155], v[208:211], v[12:15]
	v_mfma_f32_16x16x32_bf16 v[8:11], v[160:163], v[208:211], v[8:11]
	s_setprio 0
	s_setprio 1
	v_mfma_f32_16x16x32_bf16 v[52:55], v[164:167], v[180:183], v[52:55]
	v_mfma_f32_16x16x32_bf16 v[48:51], v[172:175], v[180:183], v[48:51]
	v_mfma_f32_16x16x32_bf16 v[36:39], v[164:167], v[188:191], v[36:39]
	v_mfma_f32_16x16x32_bf16 v[32:35], v[172:175], v[188:191], v[32:35]
	v_mfma_f32_16x16x32_bf16 v[20:23], v[164:167], v[196:199], v[20:23]
	v_mfma_f32_16x16x32_bf16 v[16:19], v[172:175], v[196:199], v[16:19]
	v_mfma_f32_16x16x32_bf16 v[4:7], v[164:167], v[204:207], v[4:7]
	v_mfma_f32_16x16x32_bf16 v[0:3], v[172:175], v[204:207], v[0:3]
	v_mfma_f32_16x16x32_bf16 v[52:55], v[168:171], v[184:187], v[52:55]
	v_mfma_f32_16x16x32_bf16 v[48:51], v[176:179], v[184:187], v[48:51]
	v_mfma_f32_16x16x32_bf16 v[36:39], v[168:171], v[192:195], v[36:39]
	v_mfma_f32_16x16x32_bf16 v[32:35], v[176:179], v[192:195], v[32:35]
	v_mfma_f32_16x16x32_bf16 v[20:23], v[168:171], v[200:203], v[20:23]
	v_mfma_f32_16x16x32_bf16 v[16:19], v[176:179], v[200:203], v[16:19]
	v_mfma_f32_16x16x32_bf16 v[4:7], v[168:171], v[208:211], v[4:7]
	v_mfma_f32_16x16x32_bf16 v[0:3], v[176:179], v[208:211], v[0:3]
	s_setprio 0
	s_barrier
	s_cmp_gt_u32 s64, 29
	s_mov_b32 s64, s11
	s_cbranch_scc1 .LBB0_858

; #define PG8_STAGE(bufoff, gbase, voff) do { _Pragma("unroll") for (int _i = 0; _i < 2; ++_i) \
;         __builtin_amdgcn_global_load_lds((const unsigned*)((const char*)(gbase) + (voff)[_i]), (LAS unsigned*)(lds + (bufoff) + ldsw + _i * 8192), 16, 0, 0); } while (0)
; #define PG8_WAIT_V(n) asm volatile("s_waitcnt vmcnt(" #n ")" ::: "memory")
; #define PG8_BAR __builtin_amdgcn_s_barrier()
; template <class Epi>
; __device__ __forceinline__ void gemm_phase(LAS unsigned char* lds, const Gemm g, const StaticOrder S, const Epi E) {
;     ...
;     PG8_STAGE(PG8_SB(0, 0), cB, voffB); PG8_STAGE(PG8_SB(0, 1), cB + hstepB, voffB); PG8_STAGE(PG8_SA(0, 0), cA, voffA); PG8_STAGE(PG8_SA(0, 1), cA + hstepA, voffA);
;     if (wr == 1) PG8_BAR;
;     PG8_WAIT_V(2); PG8_BAR;
;     PG8_STAGE(PG8_SB(1, 0), cB + ksc, voffB); PG8_STAGE(PG8_SA(1, 0), cA + ksc, voffA); PG8_STAGE(PG8_SB(1, 1), cB + hstepB + ksc, voffB);
;     PG8_WAIT_V(6); PG8_BAR;
.LBB0_924:
	s_lshl_b32 s3, s3, 5
	s_and_b32 s3, s3, 0x60
	s_lshl_b32 s14, s0, 13
	s_lshl_b32 s15, s3, 7
	s_ashr_i32 s54, s79, 31
	s_add_u32 s12, s1, 0x2b00
	s_addc_u32 s13, s2, 0
	s_add_i32 m0, s50, 0x18000
	s_waitcnt vmcnt(2)
	s_barrier
	global_load_lds_dwordx4 v142, s[12:13]
	s_add_i32 m0, s50, 0x1a000
	v_lshl_add_u64 v[0:1], s[12:13], 0, v[146:147]
	s_add_u32 s12, s5, 0x2b00
	s_addc_u32 s13, s10, 0
	s_add_i32 s55, s50, 0x8000
	s_add_i32 s56, s50, 0xa000
	global_load_lds_dwordx4 v[0:1], off
	s_mov_b32 m0, s55
	s_add_u32 s10, s1, 0x162b00
	global_load_lds_dwordx4 v140, s[12:13]
	s_mov_b32 m0, s56
	s_addc_u32 s11, s2, 0
	global_load_lds_dwordx4 v144, s[12:13]
	s_add_i32 m0, s50, 0x1c000
	s_nop 0
	global_load_lds_dwordx4 v142, s[10:11]
	s_add_i32 m0, s50, 0x1e000
	v_and_b32_e32 v3, 32, v164
	global_load_lds_dwordx4 v146, s[10:11]
	v_and_b32_e32 v1, 3, v161
	v_and_b32_e32 v0, 15, v224
	v_lshlrev_b32_e32 v2, 4, v1
	v_lshl_or_b32 v165, s0, 6, v0
	v_lshl_or_b32 v0, v0, 6, v2
	s_ashr_i32 s57, s78, 31
	v_bitop3_b32 v0, v0, s14, v3 bitop3:0xde
	v_lshlrev_b32_e32 v4, 6, v224
	s_movk_i32 s0, 0x3c0
	s_waitcnt vmcnt(6)
	s_cmpk_lt_u32 s4, 0x100
	v_and_or_b32 v2, v4, s0, v2
	s_cselect_b64 s[10:11], -1, 0
	s_add_u32 s12, s82, 0x2a9c0000
	s_movk_i32 s34, 0xff80
	v_add_u32_e32 v168, 0, v0
	v_mbcnt_lo_u32_b32 v0, -1, 0
	v_bitop3_b32 v166, s15, v2, v3 bitop3:0xf6
	s_addc_u32 s13, s83, 0
	v_cmp_eq_u32_e64 s[0:1], 0, v1
	v_lshl_or_b32 v167, v1, 3, s3
	s_mov_b32 s35, -1
	v_mov_b64_e32 v[148:149], 0x200
	v_mov_b64_e32 v[150:151], 0x1ff
	s_movk_i32 s58, 0x80
	s_add_i32 s59, 0, 0x10000
	s_add_i32 s60, 0, 0x14000
	s_mov_b64 s[14:15], 0x80000
	s_mov_b32 s61, 0x80000
	s_mov_b64 s[16:17], 0x90000
	s_mov_b32 s62, 0x90000
	s_mov_b64 s[18:19], 0xa0000
	s_mov_b32 s63, 0xa0000
	s_mov_b64 s[20:21], 0xb0000
	s_mov_b32 s64, 0xb0000
	v_mbcnt_hi_u32_b32 v169, -1, v0
	s_barrier
	s_branch .LBB0_927

; #define PG8_STAGE(bufoff, gbase, voff) do { _Pragma("unroll") for (int _i = 0; _i < 2; ++_i) \
;         __builtin_amdgcn_global_load_lds((const unsigned*)((const char*)(gbase) + (voff)[_i]), (LAS unsigned*)(lds + (bufoff) + ldsw + _i * 8192), 16, 0, 0); } while (0)
; #define PG8_LDA(dst, b, h) do { _Pragma("unroll") for (int m = 0; m < 4; ++m) _Pragma("unroll") for (int k = 0; k < 2; ++k) dst[m][k] = *(const LAS bf16x8*)(lds + PG8_SA(b, h) + aoff + m * 2048 + k * 1024); } while (0)
; #define PG8_LDB(dst, b, h) do { _Pragma("unroll") for (int n = 0; n < 2; ++n) _Pragma("unroll") for (int k = 0; k < 2; ++k) dst[n][k] = *(const LAS bf16x8*)(lds + PG8_SB(b, h) + boff + n * 2048 + k * 1024); } while (0)
; #define PG8_MMA(ai, bj, At, Bt) do { __builtin_amdgcn_s_setprio(1); _Pragma("unroll") for (int m = 0; m < 4; ++m) _Pragma("unroll") for (int n = 0; n < 2; ++n) _Pragma("unroll") for (int k = 0; k < 2; ++k) \
;         acc[ai][bj][m][n] = __builtin_amdgcn_mfma_f32_16x16x32_bf16(Bt[n][k], At[m][k], acc[ai][bj][m][n], 0, 0, 0); __builtin_amdgcn_s_setprio(0); } while (0)
; #define PG8_WAIT_V(n) asm volatile("s_waitcnt vmcnt(" #n ")" ::: "memory")
; #define PG8_WAIT_L(n) asm volatile("s_waitcnt lgkmcnt(" #n ")" ::: "memory")
; #define PG8_BAR __builtin_amdgcn_s_barrier()
; #define PG8_SCHED __builtin_amdgcn_sched_barrier(0)
; template <class Epi>
; __device__ __forceinline__ void gemm_phase(LAS unsigned char* lds, const Gemm g, const StaticOrder S, const Epi E) {
;     ...
;             const char* a1 = cA + (long)(t + 1) * ksc;
;             const char* a2 = last ? nA : cA + (long)(t + 2) * ksc; const char* b2 = last ? nB : cB + (long)(t + 2) * ksc;
;             const long ks3 = last ? ksn : ksc;
;             const char* a3 = a2 + ks3; const char* b3 = b2 + ks3;
;             PG8_LDB(B0, 0, 0); PG8_LDB(B1, 0, 1); PG8_SCHED; PG8_LDA(At, 0, 0); PG8_STAGE(PG8_SA(1, 1), a1 + hstepA, voffA);
;             PG8_WAIT_V(8); PG8_WAIT_L(0); PG8_BAR; PG8_MMA(0, 0, At, B0); PG8_MMA(0, 1, At, B1); PG8_BAR; PG8_SCHED;
;             PG8_LDA(At, 0, 1); PG8_STAGE(PG8_SB(0, 0), b2, voffB); PG8_STAGE(PG8_SB(0, 1), b2 + hstepB, voffB); PG8_STAGE(PG8_SA(0, 0), a2, voffA);
;             PG8_WAIT_V(8); PG8_WAIT_L(0); PG8_BAR; PG8_MMA(1, 0, At, B0); PG8_MMA(1, 1, At, B1); PG8_BAR; PG8_SCHED;
.LBB0_938:
	v_add_u32_e32 v152, s59, v166
	v_add_u32_e32 v178, s60, v166
	ds_read_b128 v[128:131], v152
	ds_read_b128 v[132:135], v152 offset:1024
	ds_read_b128 v[136:139], v152 offset:2048
	ds_read_b128 v[152:155], v152 offset:3072
	ds_read_b128 v[156:159], v178
	ds_read_b128 v[170:173], v178 offset:1024
	ds_read_b128 v[174:177], v178 offset:2048
	ds_read_b128 v[178:181], v178 offset:3072
	s_or_b32 s48, s70, 1
	s_mul_i32 s49, s35, s48
	s_mul_hi_u32 s72, s34, s48
	s_add_i32 s72, s72, s49
	s_mul_i32 s48, s34, s48
	s_add_u32 s73, s30, s48
	s_addc_u32 s74, s31, s72
	s_add_u32 s48, s46, s44
	s_addc_u32 s49, s47, s45
	s_add_u32 s72, s73, 0x160000
	s_addc_u32 s73, s74, 0
	s_add_i32 m0, s50, 0xc000
	ds_read_b128 v[182:185], v168
	ds_read_b128 v[186:189], v168 offset:1024
	ds_read_b128 v[190:193], v168 offset:2048
	ds_read_b128 v[194:197], v168 offset:3072
	ds_read_b128 v[198:201], v168 offset:4096
	ds_read_b128 v[202:205], v168 offset:5120
	ds_read_b128 v[206:209], v168 offset:6144
	ds_read_b128 v[210:213], v168 offset:7168
	global_load_lds_dwordx4 v140, s[72:73]
	s_add_i32 m0, s50, 0xe000
	s_nop 0
	global_load_lds_dwordx4 v144, s[72:73]
	s_waitcnt vmcnt(8)
	s_waitcnt lgkmcnt(0)
	s_barrier
	s_setprio 1
	s_waitcnt lgkmcnt(0)
	v_mfma_f32_16x16x32_bf16 v[124:127], v[128:131], v[182:185], v[124:127]
	v_mfma_f32_16x16x32_bf16 v[120:123], v[136:139], v[182:185], v[120:123]
	v_mfma_f32_16x16x32_bf16 v[108:111], v[128:131], v[190:193], v[108:111]
	v_mfma_f32_16x16x32_bf16 v[104:107], v[136:139], v[190:193], v[104:107]
	v_mfma_f32_16x16x32_bf16 v[92:95], v[128:131], v[198:201], v[92:95]
	v_mfma_f32_16x16x32_bf16 v[88:91], v[136:139], v[198:201], v[88:91]
	v_mfma_f32_16x16x32_bf16 v[76:79], v[128:131], v[206:209], v[76:79]
	v_mfma_f32_16x16x32_bf16 v[72:75], v[136:139], v[206:209], v[72:75]
	v_mfma_f32_16x16x32_bf16 v[124:127], v[132:135], v[186:189], v[124:127]
	v_mfma_f32_16x16x32_bf16 v[120:123], v[152:155], v[186:189], v[120:123]
	v_mfma_f32_16x16x32_bf16 v[108:111], v[132:135], v[194:197], v[108:111]
	v_mfma_f32_16x16x32_bf16 v[104:107], v[152:155], v[194:197], v[104:107]
	v_mfma_f32_16x16x32_bf16 v[92:95], v[132:135], v[202:205], v[92:95]
	v_mfma_f32_16x16x32_bf16 v[88:91], v[152:155], v[202:205], v[88:91]
	v_mfma_f32_16x16x32_bf16 v[76:79], v[132:135], v[210:213], v[76:79]
	v_mfma_f32_16x16x32_bf16 v[72:75], v[152:155], v[210:213], v[72:75]
	s_setprio 0
	s_setprio 1
	v_mfma_f32_16x16x32_bf16 v[116:119], v[156:159], v[182:185], v[116:119]
	v_mfma_f32_16x16x32_bf16 v[112:115], v[174:177], v[182:185], v[112:115]
	v_mfma_f32_16x16x32_bf16 v[100:103], v[156:159], v[190:193], v[100:103]
	v_mfma_f32_16x16x32_bf16 v[96:99], v[174:177], v[190:193], v[96:99]
	v_mfma_f32_16x16x32_bf16 v[84:87], v[156:159], v[198:201], v[84:87]
	v_mfma_f32_16x16x32_bf16 v[80:83], v[174:177], v[198:201], v[80:83]
	v_mfma_f32_16x16x32_bf16 v[68:71], v[156:159], v[206:209], v[68:71]
	v_mfma_f32_16x16x32_bf16 v[64:67], v[174:177], v[206:209], v[64:67]
	v_mfma_f32_16x16x32_bf16 v[116:119], v[170:173], v[186:189], v[116:119]
	v_mfma_f32_16x16x32_bf16 v[112:115], v[178:181], v[186:189], v[112:115]
	v_mfma_f32_16x16x32_bf16 v[100:103], v[170:173], v[194:197], v[100:103]
	v_mfma_f32_16x16x32_bf16 v[96:99], v[178:181], v[194:197], v[96:99]
	v_mfma_f32_16x16x32_bf16 v[84:87], v[170:173], v[202:205], v[84:87]
	v_mfma_f32_16x16x32_bf16 v[80:83], v[178:181], v[202:205], v[80:83]
	v_mfma_f32_16x16x32_bf16 v[68:71], v[170:173], v[210:213], v[68:71]
	v_mfma_f32_16x16x32_bf16 v[64:67], v[178:181], v[210:213], v[64:67]
	s_setprio 0
	s_barrier
	s_add_i32 s72, s59, s33
	s_mov_b32 m0, s72
	ds_read_b128 v[182:185], v168 offset:16384
	ds_read_b128 v[186:189], v168 offset:17408
	ds_read_b128 v[190:193], v168 offset:18432
	ds_read_b128 v[194:197], v168 offset:19456
	ds_read_b128 v[198:201], v168 offset:20480
	ds_read_b128 v[202:205], v168 offset:21504
	ds_read_b128 v[206:209], v168 offset:22528
	ds_read_b128 v[210:213], v168 offset:23552
	global_load_lds_dwordx4 v142, s[42:43]
	s_add_i32 m0, s72, 0x2000
	s_add_u32 s72, s42, 0x160000
	s_addc_u32 s73, s43, 0
	s_add_i32 s74, s60, s33
	global_load_lds_dwordx4 v146, s[42:43]
	s_mov_b32 m0, s74
	s_nop 0
	global_load_lds_dwordx4 v142, s[72:73]
	s_add_i32 m0, s74, 0x2000
	s_nop 0
	global_load_lds_dwordx4 v146, s[72:73]
	s_mov_b32 m0, s50
	s_nop 0
	global_load_lds_dwordx4 v140, s[46:47]
	s_mov_b32 m0, s51
	s_nop 0
	global_load_lds_dwordx4 v144, s[46:47]
	s_waitcnt vmcnt(8)
	s_waitcnt lgkmcnt(0)
	s_barrier
	s_setprio 1
	s_waitcnt lgkmcnt(0)
	v_mfma_f32_16x16x32_bf16 v[60:63], v[128:131], v[182:185], v[60:63]
	v_mfma_f32_16x16x32_bf16 v[56:59], v[136:139], v[182:185], v[56:59]
	v_mfma_f32_16x16x32_bf16 v[44:47], v[128:131], v[190:193], v[44:47]
	v_mfma_f32_16x16x32_bf16 v[40:43], v[136:139], v[190:193], v[40:43]
	v_mfma_f32_16x16x32_bf16 v[28:31], v[128:131], v[198:201], v[28:31]
	v_mfma_f32_16x16x32_bf16 v[24:27], v[136:139], v[198:201], v[24:27]
	v_mfma_f32_16x16x32_bf16 v[12:15], v[128:131], v[206:209], v[12:15]
	v_mfma_f32_16x16x32_bf16 v[8:11], v[136:139], v[206:209], v[8:11]
	v_mfma_f32_16x16x32_bf16 v[60:63], v[132:135], v[186:189], v[60:63]
	v_mfma_f32_16x16x32_bf16 v[56:59], v[152:155], v[186:189], v[56:59]
	v_mfma_f32_16x16x32_bf16 v[44:47], v[132:135], v[194:197], v[44:47]
	v_mfma_f32_16x16x32_bf16 v[40:43], v[152:155], v[194:197], v[40:43]
	v_mfma_f32_16x16x32_bf16 v[28:31], v[132:135], v[202:205], v[28:31]
	v_mfma_f32_16x16x32_bf16 v[24:27], v[152:155], v[202:205], v[24:27]
	v_mfma_f32_16x16x32_bf16 v[12:15], v[132:135], v[210:213], v[12:15]
	v_mfma_f32_16x16x32_bf16 v[8:11], v[152:155], v[210:213], v[8:11]
	s_setprio 0
	s_setprio 1
	v_mfma_f32_16x16x32_bf16 v[52:55], v[156:159], v[182:185], v[52:55]
	v_mfma_f32_16x16x32_bf16 v[48:51], v[174:177], v[182:185], v[48:51]
	v_mfma_f32_16x16x32_bf16 v[36:39], v[156:159], v[190:193], v[36:39]
	v_mfma_f32_16x16x32_bf16 v[32:35], v[174:177], v[190:193], v[32:35]
	v_mfma_f32_16x16x32_bf16 v[20:23], v[156:159], v[198:201], v[20:23]
	v_mfma_f32_16x16x32_bf16 v[16:19], v[174:177], v[198:201], v[16:19]
	v_mfma_f32_16x16x32_bf16 v[4:7], v[156:159], v[206:209], v[4:7]
	v_mfma_f32_16x16x32_bf16 v[0:3], v[174:177], v[206:209], v[0:3]
	v_mfma_f32_16x16x32_bf16 v[52:55], v[170:173], v[186:189], v[52:55]
	v_mfma_f32_16x16x32_bf16 v[48:51], v[178:181], v[186:189], v[48:51]
	v_mfma_f32_16x16x32_bf16 v[36:39], v[170:173], v[194:197], v[36:39]
	v_mfma_f32_16x16x32_bf16 v[32:35], v[178:181], v[194:197], v[32:35]
	v_mfma_f32_16x16x32_bf16 v[20:23], v[170:173], v[202:205], v[20:23]
	v_mfma_f32_16x16x32_bf16 v[16:19], v[178:181], v[202:205], v[16:19]
	v_mfma_f32_16x16x32_bf16 v[4:7], v[170:173], v[210:213], v[4:7]
	v_mfma_f32_16x16x32_bf16 v[0:3], v[178:181], v[210:213], v[0:3]
	s_setprio 0
	s_barrier
; #define PG8_STAGE(bufoff, gbase, voff) do { _Pragma("unroll") for (int _i = 0; _i < 2; ++_i) \
;         __builtin_amdgcn_global_load_lds((const unsigned*)((const char*)(gbase) + (voff)[_i]), (LAS unsigned*)(lds + (bufoff) + ldsw + _i * 8192), 16, 0, 0); } while (0)
; #define PG8_LDA(dst, b, h) do { _Pragma("unroll") for (int m = 0; m < 4; ++m) _Pragma("unroll") for (int k = 0; k < 2; ++k) dst[m][k] = *(const LAS bf16x8*)(lds + PG8_SA(b, h) + aoff + m * 2048 + k * 1024); } while (0)
; #define PG8_LDB(dst, b, h) do { _Pragma("unroll") for (int n = 0; n < 2; ++n) _Pragma("unroll") for (int k = 0; k < 2; ++k) dst[n][k] = *(const LAS bf16x8*)(lds + PG8_SB(b, h) + boff + n * 2048 + k * 1024); } while (0)
; #define PG8_MMA(ai, bj, At, Bt) do { __builtin_amdgcn_s_setprio(1); _Pragma("unroll") for (int m = 0; m < 4; ++m) _Pragma("unroll") for (int n = 0; n < 2; ++n) _Pragma("unroll") for (int k = 0; k < 2; ++k) \
;         acc[ai][bj][m][n] = __builtin_amdgcn_mfma_f32_16x16x32_bf16(Bt[n][k], At[m][k], acc[ai][bj][m][n], 0, 0, 0); __builtin_amdgcn_s_setprio(0); } while (0)
; #define PG8_WAIT_V(n) asm volatile("s_waitcnt vmcnt(" #n ")" ::: "memory")
; #define PG8_WAIT_L(n) asm volatile("s_waitcnt lgkmcnt(" #n ")" ::: "memory")
; #define PG8_BAR __builtin_amdgcn_s_barrier()
; #define PG8_SCHED __builtin_amdgcn_sched_barrier(0)
; template <class Epi>
; __device__ __forceinline__ void gemm_phase(LAS unsigned char* lds, const Gemm g, const StaticOrder S, const Epi E) {
;     ...
;             PG8_LDB(B0, 1, 0); PG8_LDB(B1, 1, 1); PG8_SCHED; PG8_LDA(At, 1, 0); PG8_STAGE(PG8_SA(0, 1), a2 + hstepA, voffA);
;             PG8_WAIT_V(8); PG8_WAIT_L(0); PG8_BAR; PG8_MMA(0, 0, At, B0); PG8_MMA(0, 1, At, B1); PG8_BAR; PG8_SCHED;
;             PG8_LDA(At, 1, 1); PG8_STAGE(PG8_SB(1, 0), b3, voffB); PG8_STAGE(PG8_SB(1, 1), b3 + hstepB, voffB); PG8_STAGE(PG8_SA(1, 0), a3, voffA);
;             PG8_WAIT_V(8); PG8_WAIT_L(0); PG8_BAR; PG8_MMA(1, 0, At, B0); PG8_MMA(1, 1, At, B1); PG8_BAR; PG8_SCHED;
;         }
	s_add_i32 s72, 0, 0x18000
	s_add_i32 s73, 0, 0x1c000
	v_add_u32_e32 v152, s72, v166
	v_add_u32_e32 v178, s73, v166
	ds_read_b128 v[128:131], v152
	ds_read_b128 v[132:135], v152 offset:1024
	ds_read_b128 v[136:139], v152 offset:2048
	ds_read_b128 v[152:155], v152 offset:3072
	ds_read_b128 v[156:159], v178
	ds_read_b128 v[170:173], v178 offset:1024
	ds_read_b128 v[174:177], v178 offset:2048
	ds_read_b128 v[178:181], v178 offset:3072
	s_add_u32 s46, s46, 0x160000
	s_addc_u32 s47, s47, 0
	s_mov_b32 m0, s52
	ds_read_b128 v[182:185], v168 offset:32768
	ds_read_b128 v[186:189], v168 offset:33792
	ds_read_b128 v[190:193], v168 offset:34816
	ds_read_b128 v[194:197], v168 offset:35840
	ds_read_b128 v[198:201], v168 offset:36864
	ds_read_b128 v[202:205], v168 offset:37888
	ds_read_b128 v[206:209], v168 offset:38912
	ds_read_b128 v[210:213], v168 offset:39936
	global_load_lds_dwordx4 v140, s[46:47]
	s_mov_b32 m0, s53
	s_nop 0
	global_load_lds_dwordx4 v144, s[46:47]
	s_waitcnt vmcnt(8)
	s_waitcnt lgkmcnt(0)
	s_barrier
	s_setprio 1
	s_waitcnt lgkmcnt(0)
	v_mfma_f32_16x16x32_bf16 v[124:127], v[128:131], v[182:185], v[124:127]
	v_mfma_f32_16x16x32_bf16 v[120:123], v[136:139], v[182:185], v[120:123]
	v_mfma_f32_16x16x32_bf16 v[108:111], v[128:131], v[190:193], v[108:111]
	v_mfma_f32_16x16x32_bf16 v[104:107], v[136:139], v[190:193], v[104:107]
	v_mfma_f32_16x16x32_bf16 v[92:95], v[128:131], v[198:201], v[92:95]
	v_mfma_f32_16x16x32_bf16 v[88:91], v[136:139], v[198:201], v[88:91]
	v_mfma_f32_16x16x32_bf16 v[76:79], v[128:131], v[206:209], v[76:79]
	v_mfma_f32_16x16x32_bf16 v[72:75], v[136:139], v[206:209], v[72:75]
	v_mfma_f32_16x16x32_bf16 v[124:127], v[132:135], v[186:189], v[124:127]
	v_mfma_f32_16x16x32_bf16 v[120:123], v[152:155], v[186:189], v[120:123]
	v_mfma_f32_16x16x32_bf16 v[108:111], v[132:135], v[194:197], v[108:111]
	v_mfma_f32_16x16x32_bf16 v[104:107], v[152:155], v[194:197], v[104:107]
	v_mfma_f32_16x16x32_bf16 v[92:95], v[132:135], v[202:205], v[92:95]
	v_mfma_f32_16x16x32_bf16 v[88:91], v[152:155], v[202:205], v[88:91]
	v_mfma_f32_16x16x32_bf16 v[76:79], v[132:135], v[210:213], v[76:79]
	v_mfma_f32_16x16x32_bf16 v[72:75], v[152:155], v[210:213], v[72:75]
	s_setprio 0
	s_setprio 1
	v_mfma_f32_16x16x32_bf16 v[116:119], v[156:159], v[182:185], v[116:119]
	v_mfma_f32_16x16x32_bf16 v[112:115], v[174:177], v[182:185], v[112:115]
	v_mfma_f32_16x16x32_bf16 v[100:103], v[156:159], v[190:193], v[100:103]
	v_mfma_f32_16x16x32_bf16 v[96:99], v[174:177], v[190:193], v[96:99]
	v_mfma_f32_16x16x32_bf16 v[84:87], v[156:159], v[198:201], v[84:87]
	v_mfma_f32_16x16x32_bf16 v[80:83], v[174:177], v[198:201], v[80:83]
	v_mfma_f32_16x16x32_bf16 v[68:71], v[156:159], v[206:209], v[68:71]
	v_mfma_f32_16x16x32_bf16 v[64:67], v[174:177], v[206:209], v[64:67]
	v_mfma_f32_16x16x32_bf16 v[116:119], v[170:173], v[186:189], v[116:119]
	v_mfma_f32_16x16x32_bf16 v[112:115], v[178:181], v[186:189], v[112:115]
	v_mfma_f32_16x16x32_bf16 v[100:103], v[170:173], v[194:197], v[100:103]
	v_mfma_f32_16x16x32_bf16 v[96:99], v[178:181], v[194:197], v[96:99]
	v_mfma_f32_16x16x32_bf16 v[84:87], v[170:173], v[202:205], v[84:87]
	v_mfma_f32_16x16x32_bf16 v[80:83], v[178:181], v[202:205], v[80:83]
	v_mfma_f32_16x16x32_bf16 v[68:71], v[170:173], v[210:213], v[68:71]
	v_mfma_f32_16x16x32_bf16 v[64:67], v[178:181], v[210:213], v[64:67]
	s_setprio 0
	s_barrier
	s_add_u32 s42, s42, s44
	s_addc_u32 s43, s43, s45
	s_add_i32 s44, s72, s33
	s_mov_b32 m0, s44
	ds_read_b128 v[182:185], v168 offset:49152
	ds_read_b128 v[186:189], v168 offset:50176
	ds_read_b128 v[190:193], v168 offset:51200
	ds_read_b128 v[194:197], v168 offset:52224
	ds_read_b128 v[198:201], v168 offset:53248
	ds_read_b128 v[202:205], v168 offset:54272
	ds_read_b128 v[206:209], v168 offset:55296
	ds_read_b128 v[210:213], v168 offset:56320
	global_load_lds_dwordx4 v142, s[42:43]
	s_add_i32 m0, s44, 0x2000
	v_lshl_add_u64 v[214:215], s[42:43], 0, v[146:147]
	s_add_u32 s42, s42, 0x160000
	s_addc_u32 s43, s43, 0
	s_add_i32 s44, s73, s33
	global_load_lds_dwordx4 v[214:215], off
	s_mov_b32 m0, s44
	s_nop 0
	global_load_lds_dwordx4 v142, s[42:43]
	s_add_i32 m0, s44, 0x2000
	s_nop 0
	global_load_lds_dwordx4 v146, s[42:43]
	s_mov_b32 m0, s55
	s_nop 0
	global_load_lds_dwordx4 v140, s[48:49]
	s_mov_b32 m0, s56
	s_nop 0
	global_load_lds_dwordx4 v144, s[48:49]
	s_waitcnt vmcnt(8)
	s_waitcnt lgkmcnt(0)
	s_barrier
	s_setprio 1
	s_waitcnt lgkmcnt(0)
	v_mfma_f32_16x16x32_bf16 v[60:63], v[128:131], v[182:185], v[60:63]
	v_mfma_f32_16x16x32_bf16 v[56:59], v[136:139], v[182:185], v[56:59]
	v_mfma_f32_16x16x32_bf16 v[44:47], v[128:131], v[190:193], v[44:47]
	v_mfma_f32_16x16x32_bf16 v[40:43], v[136:139], v[190:193], v[40:43]
	v_mfma_f32_16x16x32_bf16 v[28:31], v[128:131], v[198:201], v[28:31]
	v_mfma_f32_16x16x32_bf16 v[24:27], v[136:139], v[198:201], v[24:27]
	v_mfma_f32_16x16x32_bf16 v[12:15], v[128:131], v[206:209], v[12:15]
	v_mfma_f32_16x16x32_bf16 v[8:11], v[136:139], v[206:209], v[8:11]
	v_mfma_f32_16x16x32_bf16 v[60:63], v[132:135], v[186:189], v[60:63]
	v_mfma_f32_16x16x32_bf16 v[56:59], v[152:155], v[186:189], v[56:59]
	v_mfma_f32_16x16x32_bf16 v[44:47], v[132:135], v[194:197], v[44:47]
	v_mfma_f32_16x16x32_bf16 v[40:43], v[152:155], v[194:197], v[40:43]
	v_mfma_f32_16x16x32_bf16 v[28:31], v[132:135], v[202:205], v[28:31]
	v_mfma_f32_16x16x32_bf16 v[24:27], v[152:155], v[202:205], v[24:27]
	v_mfma_f32_16x16x32_bf16 v[12:15], v[132:135], v[210:213], v[12:15]
	v_mfma_f32_16x16x32_bf16 v[8:11], v[152:155], v[210:213], v[8:11]
	s_setprio 0
	s_setprio 1
	v_mfma_f32_16x16x32_bf16 v[52:55], v[156:159], v[182:185], v[52:55]
	v_mfma_f32_16x16x32_bf16 v[48:51], v[174:177], v[182:185], v[48:51]
	v_mfma_f32_16x16x32_bf16 v[36:39], v[156:159], v[190:193], v[36:39]
	v_mfma_f32_16x16x32_bf16 v[32:35], v[174:177], v[190:193], v[32:35]
	v_mfma_f32_16x16x32_bf16 v[20:23], v[156:159], v[198:201], v[20:23]
	v_mfma_f32_16x16x32_bf16 v[16:19], v[174:177], v[198:201], v[16:19]
	v_mfma_f32_16x16x32_bf16 v[4:7], v[156:159], v[206:209], v[4:7]
	v_mfma_f32_16x16x32_bf16 v[0:3], v[174:177], v[206:209], v[0:3]
	v_mfma_f32_16x16x32_bf16 v[52:55], v[170:173], v[186:189], v[52:55]
	v_mfma_f32_16x16x32_bf16 v[48:51], v[178:181], v[186:189], v[48:51]
	v_mfma_f32_16x16x32_bf16 v[36:39], v[170:173], v[194:197], v[36:39]
	v_mfma_f32_16x16x32_bf16 v[32:35], v[178:181], v[194:197], v[32:35]
	v_mfma_f32_16x16x32_bf16 v[20:23], v[170:173], v[202:205], v[20:23]
	v_mfma_f32_16x16x32_bf16 v[16:19], v[178:181], v[202:205], v[16:19]
	v_mfma_f32_16x16x32_bf16 v[4:7], v[170:173], v[210:213], v[4:7]
	v_mfma_f32_16x16x32_bf16 v[0:3], v[178:181], v[210:213], v[0:3]
	s_setprio 0
	s_barrier
	s_cmpk_gt_u32 s70, 0x55
	s_mov_b32 s70, s71
	s_cbranch_scc1 .LBB0_943

; #define PG8_STAGE(bufoff, gbase, voff) do { _Pragma("unroll") for (int _i = 0; _i < 2; ++_i) \
;         __builtin_amdgcn_global_load_lds((const unsigned*)((const char*)(gbase) + (voff)[_i]), (LAS unsigned*)(lds + (bufoff) + ldsw + _i * 8192), 16, 0, 0); } while (0)
; #define PG8_WAIT_V(n) asm volatile("s_waitcnt vmcnt(" #n ")" ::: "memory")
; #define PG8_BAR __builtin_amdgcn_s_barrier()
; template <class Epi>
; __device__ __forceinline__ void gemm_phase(LAS unsigned char* lds, const Gemm g, const StaticOrder S, const Epi E) {
;     ...
;     PG8_STAGE(PG8_SB(0, 0), cB, voffB); PG8_STAGE(PG8_SB(0, 1), cB + hstepB, voffB); PG8_STAGE(PG8_SA(0, 0), cA, voffA); PG8_STAGE(PG8_SA(0, 1), cA + hstepA, voffA);
;     if (wr == 1) PG8_BAR;
;     PG8_WAIT_V(2); PG8_BAR;
;     PG8_STAGE(PG8_SB(1, 0), cB + ksc, voffB); PG8_STAGE(PG8_SA(1, 0), cA + ksc, voffA); PG8_STAGE(PG8_SB(1, 1), cB + hstepB + ksc, voffB);
;     PG8_WAIT_V(6); PG8_BAR;
.LBB0_1026:
	s_add_u32 s8, s82, 0x2a9c0000
	s_mov_b64 s[30:31], 0x80
	s_addc_u32 s9, s83, 0
	s_and_b32 s1, s1, 3
	s_add_i32 m0, s25, 0x18000
	v_lshl_add_u64 v[6:7], v[6:7], 0, s[30:31]
	s_lshl_b32 s11, s0, 13
	s_lshl_b32 s14, s1, 12
	s_ashr_i32 s53, s79, 31
	s_waitcnt vmcnt(2)
	s_barrier
	global_load_lds_dwordx4 v[6:7], off
	v_lshl_add_u64 v[4:5], v[4:5], 0, s[30:31]
	s_add_i32 m0, s25, 0x1a000
	s_add_i32 s54, s25, 0x8000
	s_add_i32 s55, s25, 0xa000
	global_load_lds_dwordx4 v[4:5], off
	v_lshl_add_u64 v[0:1], v[0:1], 0, s[30:31]
	s_mov_b32 m0, s54
	s_add_u32 s12, s26, 0x80080
	global_load_lds_dwordx4 v[0:1], off
	v_lshl_add_u64 v[0:1], v[2:3], 0, s[30:31]
	s_mov_b32 m0, s55
	s_addc_u32 s13, s27, 0
	global_load_lds_dwordx4 v[0:1], off
	s_add_i32 m0, s25, 0x1c000
	s_nop 0
	global_load_lds_dwordx4 v194, s[12:13]
	s_add_i32 m0, s25, 0x1e000
	v_lshlrev_b32_e32 v3, 2, v224
	global_load_lds_dwordx4 v198, s[12:13]
	v_bfe_u32 v0, v224, 4, 2
	v_and_b32_e32 v1, 15, v224
	v_lshlrev_b32_e32 v2, 3, v0
	v_lshlrev_b32_e32 v0, 4, v0
	v_lshl_or_b32 v226, s0, 6, v1
	v_lshl_or_b32 v1, v1, 6, v0
	v_and_b32_e32 v3, 32, v3
	v_bitop3_b32 v4, v1, s11, v3 bitop3:0xde
	v_lshlrev_b32_e32 v1, 6, v224
	s_movk_i32 s0, 0x3c0
	s_ashr_i32 s56, s78, 31
	v_and_or_b32 v1, v1, s0, v0
	s_waitcnt vmcnt(6)
	s_cmpk_lt_u32 s10, 0x100
	v_bitop3_b32 v227, s14, v1, v3 bitop3:0xf6
	s_cselect_b64 s[10:11], -1, 0
	s_cmp_eq_u32 s1, 0
	v_mov_b32_e32 v1, v195
	v_lshl_or_b32 v228, s1, 5, v2
	s_cselect_b64 s[12:13], -1, 0
	v_lshl_add_u64 v[200:201], s[36:37], 0, v[0:1]
	v_mov_b64_e32 v[202:203], 0x600
	v_mov_b64_e32 v[204:205], 0x5ff
	s_movk_i32 s57, 0xc1
	s_movk_i32 s58, 0xff80
	s_add_i32 s59, 0, 0x10000
	s_add_i32 s60, 0, 0x14000
	v_add_u32_e32 v229, 0, v4
	s_movk_i32 s61, 0x3000
	v_mov_b32_e32 v230, 0x358637bd
	s_barrier
	s_branch .LBB0_1029

; #define PG8_STAGE(bufoff, gbase, voff) do { _Pragma("unroll") for (int _i = 0; _i < 2; ++_i) \
;         __builtin_amdgcn_global_load_lds((const unsigned*)((const char*)(gbase) + (voff)[_i]), (LAS unsigned*)(lds + (bufoff) + ldsw + _i * 8192), 16, 0, 0); } while (0)
; #define PG8_LDA(dst, b, h) do { _Pragma("unroll") for (int m = 0; m < 4; ++m) _Pragma("unroll") for (int k = 0; k < 2; ++k) dst[m][k] = *(const LAS bf16x8*)(lds + PG8_SA(b, h) + aoff + m * 2048 + k * 1024); } while (0)
; #define PG8_LDB(dst, b, h) do { _Pragma("unroll") for (int n = 0; n < 2; ++n) _Pragma("unroll") for (int k = 0; k < 2; ++k) dst[n][k] = *(const LAS bf16x8*)(lds + PG8_SB(b, h) + boff + n * 2048 + k * 1024); } while (0)
; #define PG8_MMA(ai, bj, At, Bt) do { __builtin_amdgcn_s_setprio(1); _Pragma("unroll") for (int m = 0; m < 4; ++m) _Pragma("unroll") for (int n = 0; n < 2; ++n) _Pragma("unroll") for (int k = 0; k < 2; ++k) \
;         acc[ai][bj][m][n] = __builtin_amdgcn_mfma_f32_16x16x32_bf16(Bt[n][k], At[m][k], acc[ai][bj][m][n], 0, 0, 0); __builtin_amdgcn_s_setprio(0); } while (0)
; #define PG8_WAIT_V(n) asm volatile("s_waitcnt vmcnt(" #n ")" ::: "memory")
; #define PG8_WAIT_L(n) asm volatile("s_waitcnt lgkmcnt(" #n ")" ::: "memory")
; #define PG8_BAR __builtin_amdgcn_s_barrier()
; #define PG8_SCHED __builtin_amdgcn_sched_barrier(0)
; template <class Epi>
; __device__ __forceinline__ void gemm_phase(LAS unsigned char* lds, const Gemm g, const StaticOrder S, const Epi E) {
;     ...
;             const char* a1 = cA + (long)(t + 1) * ksc;
;             const char* a2 = last ? nA : cA + (long)(t + 2) * ksc; const char* b2 = last ? nB : cB + (long)(t + 2) * ksc;
;             const long ks3 = last ? ksn : ksc;
;             const char* a3 = a2 + ks3; const char* b3 = b2 + ks3;
;             PG8_LDB(B0, 0, 0); PG8_LDB(B1, 0, 1); PG8_SCHED; PG8_LDA(At, 0, 0); PG8_STAGE(PG8_SA(1, 1), a1 + hstepA, voffA);
;             PG8_WAIT_V(8); PG8_WAIT_L(0); PG8_BAR; PG8_MMA(0, 0, At, B0); PG8_MMA(0, 1, At, B1); PG8_BAR; PG8_SCHED;
;             PG8_LDA(At, 0, 1); PG8_STAGE(PG8_SB(0, 0), b2, voffB); PG8_STAGE(PG8_SB(0, 1), b2 + hstepB, voffB); PG8_STAGE(PG8_SA(0, 0), a2, voffA);
;             PG8_WAIT_V(8); PG8_WAIT_L(0); PG8_BAR; PG8_MMA(1, 0, At, B0); PG8_MMA(1, 1, At, B1); PG8_BAR; PG8_SCHED;
.LBB0_1032:
	v_add_u32_e32 v140, s59, v227
	v_add_u32_e32 v156, s60, v227
	ds_read_b128 v[128:131], v140
	ds_read_b128 v[132:135], v140 offset:1024
	ds_read_b128 v[136:139], v140 offset:2048
	ds_read_b128 v[140:143], v140 offset:3072
	ds_read_b128 v[144:147], v156
	ds_read_b128 v[148:151], v156 offset:1024
	ds_read_b128 v[152:155], v156 offset:2048
	ds_read_b128 v[156:159], v156 offset:3072
	s_or_b32 s17, s3, 1
	s_mul_i32 s48, s31, s17
	s_mul_hi_u32 s49, s30, s17
	s_add_i32 s49, s49, s48
	s_mul_i32 s17, s30, s17
	s_add_u32 s17, s28, s17
	s_addc_u32 s63, s29, s49
	s_add_u32 s48, s46, s44
	s_addc_u32 s49, s47, s45
	s_add_u32 s64, s17, 0x80000
	s_addc_u32 s65, s63, 0
	s_add_i32 m0, s25, 0xc000
	ds_read_b128 v[160:163], v229
	ds_read_b128 v[164:167], v229 offset:1024
	ds_read_b128 v[168:171], v229 offset:2048
	ds_read_b128 v[172:175], v229 offset:3072
	ds_read_b128 v[176:179], v229 offset:4096
	ds_read_b128 v[180:183], v229 offset:5120
	ds_read_b128 v[184:187], v229 offset:6144
	ds_read_b128 v[188:191], v229 offset:7168
	global_load_lds_dwordx4 v192, s[64:65]
	s_add_i32 m0, s25, 0xe000
	s_nop 0
	global_load_lds_dwordx4 v196, s[64:65]
	s_waitcnt vmcnt(8)
	s_waitcnt lgkmcnt(0)
	s_barrier
	s_setprio 1
	s_waitcnt lgkmcnt(0)
	v_mfma_f32_16x16x32_bf16 v[124:127], v[128:131], v[160:163], v[124:127]
	v_mfma_f32_16x16x32_bf16 v[120:123], v[136:139], v[160:163], v[120:123]
	v_mfma_f32_16x16x32_bf16 v[108:111], v[128:131], v[168:171], v[108:111]
	v_mfma_f32_16x16x32_bf16 v[104:107], v[136:139], v[168:171], v[104:107]
	v_mfma_f32_16x16x32_bf16 v[92:95], v[128:131], v[176:179], v[92:95]
	v_mfma_f32_16x16x32_bf16 v[88:91], v[136:139], v[176:179], v[88:91]
	v_mfma_f32_16x16x32_bf16 v[76:79], v[128:131], v[184:187], v[76:79]
	v_mfma_f32_16x16x32_bf16 v[72:75], v[136:139], v[184:187], v[72:75]
	v_mfma_f32_16x16x32_bf16 v[124:127], v[132:135], v[164:167], v[124:127]
	v_mfma_f32_16x16x32_bf16 v[120:123], v[140:143], v[164:167], v[120:123]
	v_mfma_f32_16x16x32_bf16 v[108:111], v[132:135], v[172:175], v[108:111]
	v_mfma_f32_16x16x32_bf16 v[104:107], v[140:143], v[172:175], v[104:107]
	v_mfma_f32_16x16x32_bf16 v[92:95], v[132:135], v[180:183], v[92:95]
	v_mfma_f32_16x16x32_bf16 v[88:91], v[140:143], v[180:183], v[88:91]
	v_mfma_f32_16x16x32_bf16 v[76:79], v[132:135], v[188:191], v[76:79]
	v_mfma_f32_16x16x32_bf16 v[72:75], v[140:143], v[188:191], v[72:75]
	s_setprio 0
	s_setprio 1
	v_mfma_f32_16x16x32_bf16 v[116:119], v[144:147], v[160:163], v[116:119]
	v_mfma_f32_16x16x32_bf16 v[112:115], v[152:155], v[160:163], v[112:115]
	v_mfma_f32_16x16x32_bf16 v[100:103], v[144:147], v[168:171], v[100:103]
	v_mfma_f32_16x16x32_bf16 v[96:99], v[152:155], v[168:171], v[96:99]
	v_mfma_f32_16x16x32_bf16 v[84:87], v[144:147], v[176:179], v[84:87]
	v_mfma_f32_16x16x32_bf16 v[80:83], v[152:155], v[176:179], v[80:83]
	v_mfma_f32_16x16x32_bf16 v[68:71], v[144:147], v[184:187], v[68:71]
	v_mfma_f32_16x16x32_bf16 v[64:67], v[152:155], v[184:187], v[64:67]
	v_mfma_f32_16x16x32_bf16 v[116:119], v[148:151], v[164:167], v[116:119]
	v_mfma_f32_16x16x32_bf16 v[112:115], v[156:159], v[164:167], v[112:115]
	v_mfma_f32_16x16x32_bf16 v[100:103], v[148:151], v[172:175], v[100:103]
	v_mfma_f32_16x16x32_bf16 v[96:99], v[156:159], v[172:175], v[96:99]
	v_mfma_f32_16x16x32_bf16 v[84:87], v[148:151], v[180:183], v[84:87]
	v_mfma_f32_16x16x32_bf16 v[80:83], v[156:159], v[180:183], v[80:83]
	v_mfma_f32_16x16x32_bf16 v[68:71], v[148:151], v[188:191], v[68:71]
	v_mfma_f32_16x16x32_bf16 v[64:67], v[156:159], v[188:191], v[64:67]
	s_setprio 0
	s_barrier
	s_add_i32 s17, s59, s33
	s_mov_b32 m0, s17
	ds_read_b128 v[160:163], v229 offset:16384
	ds_read_b128 v[164:167], v229 offset:17408
	ds_read_b128 v[168:171], v229 offset:18432
	ds_read_b128 v[172:175], v229 offset:19456
	ds_read_b128 v[176:179], v229 offset:20480
	ds_read_b128 v[180:183], v229 offset:21504
	ds_read_b128 v[184:187], v229 offset:22528
	ds_read_b128 v[188:191], v229 offset:23552
	global_load_lds_dwordx4 v194, s[42:43]
	s_add_i32 m0, s17, 0x2000
	s_add_u32 s64, s42, 0x80000
	s_addc_u32 s65, s43, 0
	s_add_i32 s17, s60, s33
	global_load_lds_dwordx4 v198, s[42:43]
	s_mov_b32 m0, s17
	s_nop 0
	global_load_lds_dwordx4 v194, s[64:65]
	s_add_i32 m0, s17, 0x2000
	s_nop 0
	global_load_lds_dwordx4 v198, s[64:65]
	s_mov_b32 m0, s25
	s_nop 0
	global_load_lds_dwordx4 v192, s[46:47]
	s_mov_b32 m0, s50
	s_nop 0
	global_load_lds_dwordx4 v196, s[46:47]
	s_waitcnt vmcnt(8)
	s_waitcnt lgkmcnt(0)
	s_barrier
	s_setprio 1
	s_waitcnt lgkmcnt(0)
	v_mfma_f32_16x16x32_bf16 v[60:63], v[128:131], v[160:163], v[60:63]
	v_mfma_f32_16x16x32_bf16 v[56:59], v[136:139], v[160:163], v[56:59]
	v_mfma_f32_16x16x32_bf16 v[44:47], v[128:131], v[168:171], v[44:47]
	v_mfma_f32_16x16x32_bf16 v[40:43], v[136:139], v[168:171], v[40:43]
	v_mfma_f32_16x16x32_bf16 v[28:31], v[128:131], v[176:179], v[28:31]
	v_mfma_f32_16x16x32_bf16 v[24:27], v[136:139], v[176:179], v[24:27]
	v_mfma_f32_16x16x32_bf16 v[12:15], v[128:131], v[184:187], v[12:15]
	v_mfma_f32_16x16x32_bf16 v[8:11], v[136:139], v[184:187], v[8:11]
	v_mfma_f32_16x16x32_bf16 v[60:63], v[132:135], v[164:167], v[60:63]
	v_mfma_f32_16x16x32_bf16 v[56:59], v[140:143], v[164:167], v[56:59]
	v_mfma_f32_16x16x32_bf16 v[44:47], v[132:135], v[172:175], v[44:47]
	v_mfma_f32_16x16x32_bf16 v[40:43], v[140:143], v[172:175], v[40:43]
	v_mfma_f32_16x16x32_bf16 v[28:31], v[132:135], v[180:183], v[28:31]
	v_mfma_f32_16x16x32_bf16 v[24:27], v[140:143], v[180:183], v[24:27]
	v_mfma_f32_16x16x32_bf16 v[12:15], v[132:135], v[188:191], v[12:15]
	v_mfma_f32_16x16x32_bf16 v[8:11], v[140:143], v[188:191], v[8:11]
	s_setprio 0
	s_setprio 1
	v_mfma_f32_16x16x32_bf16 v[52:55], v[144:147], v[160:163], v[52:55]
	v_mfma_f32_16x16x32_bf16 v[48:51], v[152:155], v[160:163], v[48:51]
	v_mfma_f32_16x16x32_bf16 v[36:39], v[144:147], v[168:171], v[36:39]
	v_mfma_f32_16x16x32_bf16 v[32:35], v[152:155], v[168:171], v[32:35]
	v_mfma_f32_16x16x32_bf16 v[20:23], v[144:147], v[176:179], v[20:23]
	v_mfma_f32_16x16x32_bf16 v[16:19], v[152:155], v[176:179], v[16:19]
	v_mfma_f32_16x16x32_bf16 v[4:7], v[144:147], v[184:187], v[4:7]
	v_mfma_f32_16x16x32_bf16 v[0:3], v[152:155], v[184:187], v[0:3]
	v_mfma_f32_16x16x32_bf16 v[52:55], v[148:151], v[164:167], v[52:55]
	v_mfma_f32_16x16x32_bf16 v[48:51], v[156:159], v[164:167], v[48:51]
	v_mfma_f32_16x16x32_bf16 v[36:39], v[148:151], v[172:175], v[36:39]
	v_mfma_f32_16x16x32_bf16 v[32:35], v[156:159], v[172:175], v[32:35]
	v_mfma_f32_16x16x32_bf16 v[20:23], v[148:151], v[180:183], v[20:23]
	v_mfma_f32_16x16x32_bf16 v[16:19], v[156:159], v[180:183], v[16:19]
	v_mfma_f32_16x16x32_bf16 v[4:7], v[148:151], v[188:191], v[4:7]
	v_mfma_f32_16x16x32_bf16 v[0:3], v[156:159], v[188:191], v[0:3]
	s_setprio 0
	s_barrier
; #define PG8_STAGE(bufoff, gbase, voff) do { _Pragma("unroll") for (int _i = 0; _i < 2; ++_i) \
;         __builtin_amdgcn_global_load_lds((const unsigned*)((const char*)(gbase) + (voff)[_i]), (LAS unsigned*)(lds + (bufoff) + ldsw + _i * 8192), 16, 0, 0); } while (0)
; #define PG8_LDA(dst, b, h) do { _Pragma("unroll") for (int m = 0; m < 4; ++m) _Pragma("unroll") for (int k = 0; k < 2; ++k) dst[m][k] = *(const LAS bf16x8*)(lds + PG8_SA(b, h) + aoff + m * 2048 + k * 1024); } while (0)
; #define PG8_LDB(dst, b, h) do { _Pragma("unroll") for (int n = 0; n < 2; ++n) _Pragma("unroll") for (int k = 0; k < 2; ++k) dst[n][k] = *(const LAS bf16x8*)(lds + PG8_SB(b, h) + boff + n * 2048 + k * 1024); } while (0)
; #define PG8_MMA(ai, bj, At, Bt) do { __builtin_amdgcn_s_setprio(1); _Pragma("unroll") for (int m = 0; m < 4; ++m) _Pragma("unroll") for (int n = 0; n < 2; ++n) _Pragma("unroll") for (int k = 0; k < 2; ++k) \
;         acc[ai][bj][m][n] = __builtin_amdgcn_mfma_f32_16x16x32_bf16(Bt[n][k], At[m][k], acc[ai][bj][m][n], 0, 0, 0); __builtin_amdgcn_s_setprio(0); } while (0)
; #define PG8_WAIT_V(n) asm volatile("s_waitcnt vmcnt(" #n ")" ::: "memory")
; #define PG8_WAIT_L(n) asm volatile("s_waitcnt lgkmcnt(" #n ")" ::: "memory")
; #define PG8_BAR __builtin_amdgcn_s_barrier()
; #define PG8_SCHED __builtin_amdgcn_sched_barrier(0)
; template <class Epi>
; __device__ __forceinline__ void gemm_phase(LAS unsigned char* lds, const Gemm g, const StaticOrder S, const Epi E) {
;     ...
;             PG8_LDB(B0, 1, 0); PG8_LDB(B1, 1, 1); PG8_SCHED; PG8_LDA(At, 1, 0); PG8_STAGE(PG8_SA(0, 1), a2 + hstepA, voffA);
;             PG8_WAIT_V(8); PG8_WAIT_L(0); PG8_BAR; PG8_MMA(0, 0, At, B0); PG8_MMA(0, 1, At, B1); PG8_BAR; PG8_SCHED;
;             PG8_LDA(At, 1, 1); PG8_STAGE(PG8_SB(1, 0), b3, voffB); PG8_STAGE(PG8_SB(1, 1), b3 + hstepB, voffB); PG8_STAGE(PG8_SA(1, 0), a3, voffA);
;             PG8_WAIT_V(8); PG8_WAIT_L(0); PG8_BAR; PG8_MMA(1, 0, At, B0); PG8_MMA(1, 1, At, B1); PG8_BAR; PG8_SCHED;
	s_add_i32 s17, 0, 0x18000
	s_add_i32 s63, 0, 0x1c000
	v_add_u32_e32 v140, s17, v227
	v_add_u32_e32 v156, s63, v227
	ds_read_b128 v[128:131], v140
	ds_read_b128 v[132:135], v140 offset:1024
	ds_read_b128 v[136:139], v140 offset:2048
	ds_read_b128 v[140:143], v140 offset:3072
	ds_read_b128 v[144:147], v156
	ds_read_b128 v[148:151], v156 offset:1024
	ds_read_b128 v[152:155], v156 offset:2048
	ds_read_b128 v[156:159], v156 offset:3072
	s_add_u32 s46, s46, 0x80000
	s_addc_u32 s47, s47, 0
	s_mov_b32 m0, s51
	ds_read_b128 v[160:163], v229 offset:32768
	ds_read_b128 v[164:167], v229 offset:33792
	ds_read_b128 v[168:171], v229 offset:34816
	ds_read_b128 v[172:175], v229 offset:35840
	ds_read_b128 v[176:179], v229 offset:36864
	ds_read_b128 v[180:183], v229 offset:37888
	ds_read_b128 v[184:187], v229 offset:38912
	ds_read_b128 v[188:191], v229 offset:39936
	global_load_lds_dwordx4 v192, s[46:47]
	s_mov_b32 m0, s52
	s_nop 0
	global_load_lds_dwordx4 v196, s[46:47]
	s_waitcnt vmcnt(8)
	s_waitcnt lgkmcnt(0)
	s_barrier
	s_setprio 1
	s_waitcnt lgkmcnt(0)
	v_mfma_f32_16x16x32_bf16 v[124:127], v[128:131], v[160:163], v[124:127]
	v_mfma_f32_16x16x32_bf16 v[120:123], v[136:139], v[160:163], v[120:123]
	v_mfma_f32_16x16x32_bf16 v[108:111], v[128:131], v[168:171], v[108:111]
	v_mfma_f32_16x16x32_bf16 v[104:107], v[136:139], v[168:171], v[104:107]
	v_mfma_f32_16x16x32_bf16 v[92:95], v[128:131], v[176:179], v[92:95]
	v_mfma_f32_16x16x32_bf16 v[88:91], v[136:139], v[176:179], v[88:91]
	v_mfma_f32_16x16x32_bf16 v[76:79], v[128:131], v[184:187], v[76:79]
	v_mfma_f32_16x16x32_bf16 v[72:75], v[136:139], v[184:187], v[72:75]
	v_mfma_f32_16x16x32_bf16 v[124:127], v[132:135], v[164:167], v[124:127]
	v_mfma_f32_16x16x32_bf16 v[120:123], v[140:143], v[164:167], v[120:123]
	v_mfma_f32_16x16x32_bf16 v[108:111], v[132:135], v[172:175], v[108:111]
	v_mfma_f32_16x16x32_bf16 v[104:107], v[140:143], v[172:175], v[104:107]
	v_mfma_f32_16x16x32_bf16 v[92:95], v[132:135], v[180:183], v[92:95]
	v_mfma_f32_16x16x32_bf16 v[88:91], v[140:143], v[180:183], v[88:91]
	v_mfma_f32_16x16x32_bf16 v[76:79], v[132:135], v[188:191], v[76:79]
	v_mfma_f32_16x16x32_bf16 v[72:75], v[140:143], v[188:191], v[72:75]
	s_setprio 0
	s_setprio 1
	v_mfma_f32_16x16x32_bf16 v[116:119], v[144:147], v[160:163], v[116:119]
	v_mfma_f32_16x16x32_bf16 v[112:115], v[152:155], v[160:163], v[112:115]
	v_mfma_f32_16x16x32_bf16 v[100:103], v[144:147], v[168:171], v[100:103]
	v_mfma_f32_16x16x32_bf16 v[96:99], v[152:155], v[168:171], v[96:99]
	v_mfma_f32_16x16x32_bf16 v[84:87], v[144:147], v[176:179], v[84:87]
	v_mfma_f32_16x16x32_bf16 v[80:83], v[152:155], v[176:179], v[80:83]
	v_mfma_f32_16x16x32_bf16 v[68:71], v[144:147], v[184:187], v[68:71]
	v_mfma_f32_16x16x32_bf16 v[64:67], v[152:155], v[184:187], v[64:67]
	v_mfma_f32_16x16x32_bf16 v[116:119], v[148:151], v[164:167], v[116:119]
	v_mfma_f32_16x16x32_bf16 v[112:115], v[156:159], v[164:167], v[112:115]
	v_mfma_f32_16x16x32_bf16 v[100:103], v[148:151], v[172:175], v[100:103]
	v_mfma_f32_16x16x32_bf16 v[96:99], v[156:159], v[172:175], v[96:99]
	v_mfma_f32_16x16x32_bf16 v[84:87], v[148:151], v[180:183], v[84:87]
	v_mfma_f32_16x16x32_bf16 v[80:83], v[156:159], v[180:183], v[80:83]
	v_mfma_f32_16x16x32_bf16 v[68:71], v[148:151], v[188:191], v[68:71]
	v_mfma_f32_16x16x32_bf16 v[64:67], v[156:159], v[188:191], v[64:67]
	s_setprio 0
	s_barrier
	s_add_u32 s42, s42, s44
	s_addc_u32 s43, s43, s45
	s_add_i32 s17, s17, s33
	s_mov_b32 m0, s17
	ds_read_b128 v[160:163], v229 offset:49152
	ds_read_b128 v[164:167], v229 offset:50176
	ds_read_b128 v[168:171], v229 offset:51200
	ds_read_b128 v[172:175], v229 offset:52224
	ds_read_b128 v[176:179], v229 offset:53248
	ds_read_b128 v[180:183], v229 offset:54272
	ds_read_b128 v[184:187], v229 offset:55296
	ds_read_b128 v[188:191], v229 offset:56320
	global_load_lds_dwordx4 v194, s[42:43]
	s_add_i32 m0, s17, 0x2000
	v_lshl_add_u64 v[206:207], s[42:43], 0, v[198:199]
	s_add_u32 s42, s42, 0x80000
	s_addc_u32 s43, s43, 0
	s_add_i32 s17, s63, s33
	global_load_lds_dwordx4 v[206:207], off
	s_mov_b32 m0, s17
	s_nop 0
	global_load_lds_dwordx4 v194, s[42:43]
	s_add_i32 m0, s17, 0x2000
	s_nop 0
	global_load_lds_dwordx4 v198, s[42:43]
	s_mov_b32 m0, s54
	s_nop 0
	global_load_lds_dwordx4 v192, s[48:49]
	s_mov_b32 m0, s55
	s_nop 0
	global_load_lds_dwordx4 v196, s[48:49]
	s_waitcnt vmcnt(8)
	s_waitcnt lgkmcnt(0)
	s_barrier
	s_setprio 1
	s_waitcnt lgkmcnt(0)
	v_mfma_f32_16x16x32_bf16 v[60:63], v[128:131], v[160:163], v[60:63]
	v_mfma_f32_16x16x32_bf16 v[56:59], v[136:139], v[160:163], v[56:59]
	v_mfma_f32_16x16x32_bf16 v[44:47], v[128:131], v[168:171], v[44:47]
	v_mfma_f32_16x16x32_bf16 v[40:43], v[136:139], v[168:171], v[40:43]
	v_mfma_f32_16x16x32_bf16 v[28:31], v[128:131], v[176:179], v[28:31]
	v_mfma_f32_16x16x32_bf16 v[24:27], v[136:139], v[176:179], v[24:27]
	v_mfma_f32_16x16x32_bf16 v[12:15], v[128:131], v[184:187], v[12:15]
	v_mfma_f32_16x16x32_bf16 v[8:11], v[136:139], v[184:187], v[8:11]
	v_mfma_f32_16x16x32_bf16 v[60:63], v[132:135], v[164:167], v[60:63]
	v_mfma_f32_16x16x32_bf16 v[56:59], v[140:143], v[164:167], v[56:59]
	v_mfma_f32_16x16x32_bf16 v[44:47], v[132:135], v[172:175], v[44:47]
	v_mfma_f32_16x16x32_bf16 v[40:43], v[140:143], v[172:175], v[40:43]
	v_mfma_f32_16x16x32_bf16 v[28:31], v[132:135], v[180:183], v[28:31]
	v_mfma_f32_16x16x32_bf16 v[24:27], v[140:143], v[180:183], v[24:27]
	v_mfma_f32_16x16x32_bf16 v[12:15], v[132:135], v[188:191], v[12:15]
	v_mfma_f32_16x16x32_bf16 v[8:11], v[140:143], v[188:191], v[8:11]
	s_setprio 0
	s_setprio 1
	v_mfma_f32_16x16x32_bf16 v[52:55], v[144:147], v[160:163], v[52:55]
	v_mfma_f32_16x16x32_bf16 v[48:51], v[152:155], v[160:163], v[48:51]
	v_mfma_f32_16x16x32_bf16 v[36:39], v[144:147], v[168:171], v[36:39]
	v_mfma_f32_16x16x32_bf16 v[32:35], v[152:155], v[168:171], v[32:35]
	v_mfma_f32_16x16x32_bf16 v[20:23], v[144:147], v[176:179], v[20:23]
	v_mfma_f32_16x16x32_bf16 v[16:19], v[152:155], v[176:179], v[16:19]
	v_mfma_f32_16x16x32_bf16 v[4:7], v[144:147], v[184:187], v[4:7]
	v_mfma_f32_16x16x32_bf16 v[0:3], v[152:155], v[184:187], v[0:3]
	v_mfma_f32_16x16x32_bf16 v[52:55], v[148:151], v[164:167], v[52:55]
	v_mfma_f32_16x16x32_bf16 v[48:51], v[156:159], v[164:167], v[48:51]
	v_mfma_f32_16x16x32_bf16 v[36:39], v[148:151], v[172:175], v[36:39]
	v_mfma_f32_16x16x32_bf16 v[32:35], v[156:159], v[172:175], v[32:35]
	v_mfma_f32_16x16x32_bf16 v[20:23], v[148:151], v[180:183], v[20:23]
	v_mfma_f32_16x16x32_bf16 v[16:19], v[156:159], v[180:183], v[16:19]
	v_mfma_f32_16x16x32_bf16 v[4:7], v[148:151], v[188:191], v[4:7]
	v_mfma_f32_16x16x32_bf16 v[0:3], v[156:159], v[188:191], v[0:3]
	s_setprio 0
	s_barrier
	s_cmp_gt_u32 s3, 29
	s_mov_b32 s3, s15
	s_cbranch_scc1 .LBB0_1037

; #define PG8_STAGE(bufoff, gbase, voff) do { _Pragma("unroll") for (int _i = 0; _i < 2; ++_i) \
;         __builtin_amdgcn_global_load_lds((const unsigned*)((const char*)(gbase) + (voff)[_i]), (LAS unsigned*)(lds + (bufoff) + ldsw + _i * 8192), 16, 0, 0); } while (0)
; #define PG8_WAIT_V(n) asm volatile("s_waitcnt vmcnt(" #n ")" ::: "memory")
; #define PG8_BAR __builtin_amdgcn_s_barrier()
; template <class Epi>
; __device__ __forceinline__ void gemm_phase(LAS unsigned char* lds, const Gemm g, const StaticOrder S, const Epi E) {
;     ...
;     const int aoff = lds_byte(wr * 64 + fr, fq * 8), boff = lds_byte(wc * 32 + fr, fq * 8);
;     ...
;     PG8_STAGE(PG8_SB(0, 0), cB, voffB); PG8_STAGE(PG8_SB(0, 1), cB + hstepB, voffB); PG8_STAGE(PG8_SA(0, 0), cA, voffA); PG8_STAGE(PG8_SA(0, 1), cA + hstepA, voffA);
;     if (wr == 1) PG8_BAR;
;     PG8_WAIT_V(2); PG8_BAR;
;     PG8_STAGE(PG8_SB(1, 0), cB + ksc, voffB); PG8_STAGE(PG8_SA(1, 0), cA + ksc, voffA); PG8_STAGE(PG8_SB(1, 1), cB + hstepB + ksc, voffB);
;     PG8_WAIT_V(6); PG8_BAR;
.LBB0_1363:
	s_lshl_b32 s1, s1, 5
	s_mov_b64 s[40:41], 0x80
	s_and_b32 s14, s1, 0x60
	s_add_i32 m0, s35, 0x18000
	v_lshl_add_u64 v[6:7], v[6:7], 0, s[40:41]
	s_lshl_b32 s11, s0, 13
	s_lshl_b32 s1, s14, 7
	s_ashr_i32 s59, s79, 31
	s_waitcnt vmcnt(2)
	s_barrier
	global_load_lds_dwordx4 v[6:7], off
	v_lshl_add_u64 v[2:3], v[2:3], 0, s[40:41]
	s_add_i32 m0, s35, 0x1a000
	s_add_i32 s60, s35, 0x8000
	s_add_i32 s61, s35, 0xa000
	global_load_lds_dwordx4 v[2:3], off
	v_lshl_add_u64 v[0:1], v[0:1], 0, s[40:41]
	s_mov_b32 m0, s60
	s_add_u32 s2, s36, 0x80080
	global_load_lds_dwordx4 v[0:1], off
	v_lshl_add_u64 v[0:1], v[4:5], 0, s[40:41]
	s_mov_b32 m0, s61
	s_addc_u32 s3, s37, 0
	global_load_lds_dwordx4 v[0:1], off
	s_add_i32 m0, s35, 0x1c000
	s_nop 0
	global_load_lds_dwordx4 v142, s[2:3]
	s_add_i32 m0, s35, 0x1e000
	v_and_b32_e32 v3, 32, v162
	global_load_lds_dwordx4 v146, s[2:3]
	v_and_b32_e32 v1, 3, v161
	v_and_b32_e32 v0, 15, v224
	v_lshlrev_b32_e32 v2, 4, v1
	v_lshl_or_b32 v163, s0, 6, v0
	v_lshl_or_b32 v0, v0, 6, v2
	s_ashr_i32 s62, s78, 31
	v_bitop3_b32 v0, v0, s11, v3 bitop3:0xde
	v_lshlrev_b32_e32 v4, 6, v224
	s_movk_i32 s0, 0x3c0
	s_waitcnt vmcnt(6)
	s_cmpk_lt_u32 s10, 0x100
	v_and_or_b32 v2, v4, s0, v2
	s_cselect_b64 s[10:11], -1, 0
	s_add_u32 s12, s82, 0x2a9d0000
	v_add_u32_e32 v166, 0, v0
	v_mbcnt_lo_u32_b32 v0, -1, 0
	v_bitop3_b32 v164, s1, v2, v3 bitop3:0xf6
	s_addc_u32 s13, s83, 0
	v_cmp_eq_u32_e64 s[0:1], 0, v1
	v_lshl_or_b32 v165, v1, 3, s14
	v_mov_b64_e32 v[148:149], 0x200
	v_mov_b64_e32 v[150:151], 0x1ff
	s_movk_i32 s63, 0xff80
	s_add_i32 s64, 0, 0x10000
	s_add_i32 s65, 0, 0x14000
	s_mov_b32 s66, 0x80000
	s_mov_b64 s[14:15], 0x90000
	s_mov_b32 s67, 0x90000
	s_mov_b64 s[16:17], 0xa0000
	s_mov_b32 s68, 0xa0000
	s_mov_b64 s[18:19], 0xb0000
	s_mov_b32 s69, 0xb0000
	v_mbcnt_hi_u32_b32 v167, -1, v0
	s_barrier
	s_branch .LBB0_1366

; #define PG8_STAGE(bufoff, gbase, voff) do { _Pragma("unroll") for (int _i = 0; _i < 2; ++_i) \
;         __builtin_amdgcn_global_load_lds((const unsigned*)((const char*)(gbase) + (voff)[_i]), (LAS unsigned*)(lds + (bufoff) + ldsw + _i * 8192), 16, 0, 0); } while (0)
; #define PG8_LDA(dst, b, h) do { _Pragma("unroll") for (int m = 0; m < 4; ++m) _Pragma("unroll") for (int k = 0; k < 2; ++k) dst[m][k] = *(const LAS bf16x8*)(lds + PG8_SA(b, h) + aoff + m * 2048 + k * 1024); } while (0)
; #define PG8_LDB(dst, b, h) do { _Pragma("unroll") for (int n = 0; n < 2; ++n) _Pragma("unroll") for (int k = 0; k < 2; ++k) dst[n][k] = *(const LAS bf16x8*)(lds + PG8_SB(b, h) + boff + n * 2048 + k * 1024); } while (0)
; #define PG8_MMA(ai, bj, At, Bt) do { __builtin_amdgcn_s_setprio(1); _Pragma("unroll") for (int m = 0; m < 4; ++m) _Pragma("unroll") for (int n = 0; n < 2; ++n) _Pragma("unroll") for (int k = 0; k < 2; ++k) \
;         acc[ai][bj][m][n] = __builtin_amdgcn_mfma_f32_16x16x32_bf16(Bt[n][k], At[m][k], acc[ai][bj][m][n], 0, 0, 0); __builtin_amdgcn_s_setprio(0); } while (0)
; #define PG8_WAIT_V(n) asm volatile("s_waitcnt vmcnt(" #n ")" ::: "memory")
; #define PG8_WAIT_L(n) asm volatile("s_waitcnt lgkmcnt(" #n ")" ::: "memory")
; #define PG8_BAR __builtin_amdgcn_s_barrier()
; #define PG8_SCHED __builtin_amdgcn_sched_barrier(0)
; template <class Epi>
; __device__ __forceinline__ void gemm_phase(LAS unsigned char* lds, const Gemm g, const StaticOrder S, const Epi E) {
;     ...
;             const char* a1 = cA + (long)(t + 1) * ksc;
;             const char* a2 = last ? nA : cA + (long)(t + 2) * ksc; const char* b2 = last ? nB : cB + (long)(t + 2) * ksc;
;             const long ks3 = last ? ksn : ksc;
;             const char* a3 = a2 + ks3; const char* b3 = b2 + ks3;
;             PG8_LDB(B0, 0, 0); PG8_LDB(B1, 0, 1); PG8_SCHED; PG8_LDA(At, 0, 0); PG8_STAGE(PG8_SA(1, 1), a1 + hstepA, voffA);
;             PG8_WAIT_V(8); PG8_WAIT_L(0); PG8_BAR; PG8_MMA(0, 0, At, B0); PG8_MMA(0, 1, At, B1); PG8_BAR; PG8_SCHED;
;             PG8_LDA(At, 0, 1); PG8_STAGE(PG8_SB(0, 0), b2, voffB); PG8_STAGE(PG8_SB(0, 1), b2 + hstepB, voffB); PG8_STAGE(PG8_SA(0, 0), a2, voffA);
;             PG8_WAIT_V(8); PG8_WAIT_L(0); PG8_BAR; PG8_MMA(1, 0, At, B0); PG8_MMA(1, 1, At, B1); PG8_BAR; PG8_SCHED;
.LBB0_1373:
	v_add_u32_e32 v152, s64, v164
	v_add_u32_e32 v176, s65, v164
	ds_read_b128 v[128:131], v152
	ds_read_b128 v[132:135], v152 offset:1024
	ds_read_b128 v[136:139], v152 offset:2048
	ds_read_b128 v[152:155], v152 offset:3072
	ds_read_b128 v[156:159], v176
	ds_read_b128 v[168:171], v176 offset:1024
	ds_read_b128 v[172:175], v176 offset:2048
	ds_read_b128 v[176:179], v176 offset:3072
	s_or_b32 s23, s31, 1
	s_mul_i32 s54, s41, s23
	s_mul_hi_u32 s55, s40, s23
	s_add_i32 s55, s55, s54
	s_mul_i32 s23, s40, s23
	s_add_u32 s23, s38, s23
	s_addc_u32 s71, s39, s55
	s_add_u32 s54, s52, s50
	s_addc_u32 s55, s53, s51
	s_add_u32 s72, s23, 0x80000
	s_addc_u32 s73, s71, 0
	s_add_i32 m0, s35, 0xc000
	ds_read_b128 v[180:183], v166
	ds_read_b128 v[184:187], v166 offset:1024
	ds_read_b128 v[188:191], v166 offset:2048
	ds_read_b128 v[192:195], v166 offset:3072
	ds_read_b128 v[196:199], v166 offset:4096
	ds_read_b128 v[200:203], v166 offset:5120
	ds_read_b128 v[204:207], v166 offset:6144
	ds_read_b128 v[208:211], v166 offset:7168
	global_load_lds_dwordx4 v140, s[72:73]
	s_add_i32 m0, s35, 0xe000
	s_nop 0
	global_load_lds_dwordx4 v144, s[72:73]
	s_waitcnt vmcnt(8)
	s_waitcnt lgkmcnt(0)
	s_barrier
	s_setprio 1
	s_waitcnt lgkmcnt(0)
	v_mfma_f32_16x16x32_bf16 v[124:127], v[128:131], v[180:183], v[124:127]
	v_mfma_f32_16x16x32_bf16 v[120:123], v[136:139], v[180:183], v[120:123]
	v_mfma_f32_16x16x32_bf16 v[108:111], v[128:131], v[188:191], v[108:111]
	v_mfma_f32_16x16x32_bf16 v[104:107], v[136:139], v[188:191], v[104:107]
	v_mfma_f32_16x16x32_bf16 v[92:95], v[128:131], v[196:199], v[92:95]
	v_mfma_f32_16x16x32_bf16 v[88:91], v[136:139], v[196:199], v[88:91]
	v_mfma_f32_16x16x32_bf16 v[76:79], v[128:131], v[204:207], v[76:79]
	v_mfma_f32_16x16x32_bf16 v[72:75], v[136:139], v[204:207], v[72:75]
	v_mfma_f32_16x16x32_bf16 v[124:127], v[132:135], v[184:187], v[124:127]
	v_mfma_f32_16x16x32_bf16 v[120:123], v[152:155], v[184:187], v[120:123]
	v_mfma_f32_16x16x32_bf16 v[108:111], v[132:135], v[192:195], v[108:111]
	v_mfma_f32_16x16x32_bf16 v[104:107], v[152:155], v[192:195], v[104:107]
	v_mfma_f32_16x16x32_bf16 v[92:95], v[132:135], v[200:203], v[92:95]
	v_mfma_f32_16x16x32_bf16 v[88:91], v[152:155], v[200:203], v[88:91]
	v_mfma_f32_16x16x32_bf16 v[76:79], v[132:135], v[208:211], v[76:79]
	v_mfma_f32_16x16x32_bf16 v[72:75], v[152:155], v[208:211], v[72:75]
	s_setprio 0
	s_setprio 1
	v_mfma_f32_16x16x32_bf16 v[116:119], v[156:159], v[180:183], v[116:119]
	v_mfma_f32_16x16x32_bf16 v[112:115], v[172:175], v[180:183], v[112:115]
	v_mfma_f32_16x16x32_bf16 v[100:103], v[156:159], v[188:191], v[100:103]
	v_mfma_f32_16x16x32_bf16 v[96:99], v[172:175], v[188:191], v[96:99]
	v_mfma_f32_16x16x32_bf16 v[84:87], v[156:159], v[196:199], v[84:87]
	v_mfma_f32_16x16x32_bf16 v[80:83], v[172:175], v[196:199], v[80:83]
	v_mfma_f32_16x16x32_bf16 v[68:71], v[156:159], v[204:207], v[68:71]
	v_mfma_f32_16x16x32_bf16 v[64:67], v[172:175], v[204:207], v[64:67]
	v_mfma_f32_16x16x32_bf16 v[116:119], v[168:171], v[184:187], v[116:119]
	v_mfma_f32_16x16x32_bf16 v[112:115], v[176:179], v[184:187], v[112:115]
	v_mfma_f32_16x16x32_bf16 v[100:103], v[168:171], v[192:195], v[100:103]
	v_mfma_f32_16x16x32_bf16 v[96:99], v[176:179], v[192:195], v[96:99]
	v_mfma_f32_16x16x32_bf16 v[84:87], v[168:171], v[200:203], v[84:87]
	v_mfma_f32_16x16x32_bf16 v[80:83], v[176:179], v[200:203], v[80:83]
	v_mfma_f32_16x16x32_bf16 v[68:71], v[168:171], v[208:211], v[68:71]
	v_mfma_f32_16x16x32_bf16 v[64:67], v[176:179], v[208:211], v[64:67]
	s_setprio 0
	s_barrier
	s_add_i32 s23, s64, s33
	s_mov_b32 m0, s23
	ds_read_b128 v[180:183], v166 offset:16384
	ds_read_b128 v[184:187], v166 offset:17408
	ds_read_b128 v[188:191], v166 offset:18432
	ds_read_b128 v[192:195], v166 offset:19456
	ds_read_b128 v[196:199], v166 offset:20480
	ds_read_b128 v[200:203], v166 offset:21504
	ds_read_b128 v[204:207], v166 offset:22528
	ds_read_b128 v[208:211], v166 offset:23552
	global_load_lds_dwordx4 v142, s[48:49]
	s_add_i32 m0, s23, 0x2000
	s_add_u32 s72, s48, 0x80000
	s_addc_u32 s73, s49, 0
	s_add_i32 s23, s65, s33
	global_load_lds_dwordx4 v146, s[48:49]
	s_mov_b32 m0, s23
	s_nop 0
	global_load_lds_dwordx4 v142, s[72:73]
	s_add_i32 m0, s23, 0x2000
	s_nop 0
	global_load_lds_dwordx4 v146, s[72:73]
	s_mov_b32 m0, s35
	s_nop 0
	global_load_lds_dwordx4 v140, s[52:53]
	s_mov_b32 m0, s56
	s_nop 0
	global_load_lds_dwordx4 v144, s[52:53]
	s_waitcnt vmcnt(8)
	s_waitcnt lgkmcnt(0)
	s_barrier
	s_setprio 1
	s_waitcnt lgkmcnt(0)
	v_mfma_f32_16x16x32_bf16 v[60:63], v[128:131], v[180:183], v[60:63]
	v_mfma_f32_16x16x32_bf16 v[56:59], v[136:139], v[180:183], v[56:59]
	v_mfma_f32_16x16x32_bf16 v[44:47], v[128:131], v[188:191], v[44:47]
	v_mfma_f32_16x16x32_bf16 v[40:43], v[136:139], v[188:191], v[40:43]
	v_mfma_f32_16x16x32_bf16 v[28:31], v[128:131], v[196:199], v[28:31]
	v_mfma_f32_16x16x32_bf16 v[24:27], v[136:139], v[196:199], v[24:27]
	v_mfma_f32_16x16x32_bf16 v[12:15], v[128:131], v[204:207], v[12:15]
	v_mfma_f32_16x16x32_bf16 v[8:11], v[136:139], v[204:207], v[8:11]
	v_mfma_f32_16x16x32_bf16 v[60:63], v[132:135], v[184:187], v[60:63]
	v_mfma_f32_16x16x32_bf16 v[56:59], v[152:155], v[184:187], v[56:59]
	v_mfma_f32_16x16x32_bf16 v[44:47], v[132:135], v[192:195], v[44:47]
	v_mfma_f32_16x16x32_bf16 v[40:43], v[152:155], v[192:195], v[40:43]
	v_mfma_f32_16x16x32_bf16 v[28:31], v[132:135], v[200:203], v[28:31]
	v_mfma_f32_16x16x32_bf16 v[24:27], v[152:155], v[200:203], v[24:27]
	v_mfma_f32_16x16x32_bf16 v[12:15], v[132:135], v[208:211], v[12:15]
	v_mfma_f32_16x16x32_bf16 v[8:11], v[152:155], v[208:211], v[8:11]
	s_setprio 0
	s_setprio 1
	v_mfma_f32_16x16x32_bf16 v[52:55], v[156:159], v[180:183], v[52:55]
	v_mfma_f32_16x16x32_bf16 v[48:51], v[172:175], v[180:183], v[48:51]
	v_mfma_f32_16x16x32_bf16 v[36:39], v[156:159], v[188:191], v[36:39]
	v_mfma_f32_16x16x32_bf16 v[32:35], v[172:175], v[188:191], v[32:35]
	v_mfma_f32_16x16x32_bf16 v[20:23], v[156:159], v[196:199], v[20:23]
	v_mfma_f32_16x16x32_bf16 v[16:19], v[172:175], v[196:199], v[16:19]
	v_mfma_f32_16x16x32_bf16 v[4:7], v[156:159], v[204:207], v[4:7]
	v_mfma_f32_16x16x32_bf16 v[0:3], v[172:175], v[204:207], v[0:3]
	v_mfma_f32_16x16x32_bf16 v[52:55], v[168:171], v[184:187], v[52:55]
	v_mfma_f32_16x16x32_bf16 v[48:51], v[176:179], v[184:187], v[48:51]
	v_mfma_f32_16x16x32_bf16 v[36:39], v[168:171], v[192:195], v[36:39]
	v_mfma_f32_16x16x32_bf16 v[32:35], v[176:179], v[192:195], v[32:35]
	v_mfma_f32_16x16x32_bf16 v[20:23], v[168:171], v[200:203], v[20:23]
	v_mfma_f32_16x16x32_bf16 v[16:19], v[176:179], v[200:203], v[16:19]
	v_mfma_f32_16x16x32_bf16 v[4:7], v[168:171], v[208:211], v[4:7]
	v_mfma_f32_16x16x32_bf16 v[0:3], v[176:179], v[208:211], v[0:3]
	s_setprio 0
	s_barrier
; #define PG8_STAGE(bufoff, gbase, voff) do { _Pragma("unroll") for (int _i = 0; _i < 2; ++_i) \
;         __builtin_amdgcn_global_load_lds((const unsigned*)((const char*)(gbase) + (voff)[_i]), (LAS unsigned*)(lds + (bufoff) + ldsw + _i * 8192), 16, 0, 0); } while (0)
; #define PG8_LDA(dst, b, h) do { _Pragma("unroll") for (int m = 0; m < 4; ++m) _Pragma("unroll") for (int k = 0; k < 2; ++k) dst[m][k] = *(const LAS bf16x8*)(lds + PG8_SA(b, h) + aoff + m * 2048 + k * 1024); } while (0)
; #define PG8_LDB(dst, b, h) do { _Pragma("unroll") for (int n = 0; n < 2; ++n) _Pragma("unroll") for (int k = 0; k < 2; ++k) dst[n][k] = *(const LAS bf16x8*)(lds + PG8_SB(b, h) + boff + n * 2048 + k * 1024); } while (0)
; #define PG8_MMA(ai, bj, At, Bt) do { __builtin_amdgcn_s_setprio(1); _Pragma("unroll") for (int m = 0; m < 4; ++m) _Pragma("unroll") for (int n = 0; n < 2; ++n) _Pragma("unroll") for (int k = 0; k < 2; ++k) \
;         acc[ai][bj][m][n] = __builtin_amdgcn_mfma_f32_16x16x32_bf16(Bt[n][k], At[m][k], acc[ai][bj][m][n], 0, 0, 0); __builtin_amdgcn_s_setprio(0); } while (0)
; #define PG8_WAIT_V(n) asm volatile("s_waitcnt vmcnt(" #n ")" ::: "memory")
; #define PG8_WAIT_L(n) asm volatile("s_waitcnt lgkmcnt(" #n ")" ::: "memory")
; #define PG8_BAR __builtin_amdgcn_s_barrier()
; #define PG8_SCHED __builtin_amdgcn_sched_barrier(0)
; template <class Epi>
; __device__ __forceinline__ void gemm_phase(LAS unsigned char* lds, const Gemm g, const StaticOrder S, const Epi E) {
;     ...
;             PG8_LDB(B0, 1, 0); PG8_LDB(B1, 1, 1); PG8_SCHED; PG8_LDA(At, 1, 0); PG8_STAGE(PG8_SA(0, 1), a2 + hstepA, voffA);
;             PG8_WAIT_V(8); PG8_WAIT_L(0); PG8_BAR; PG8_MMA(0, 0, At, B0); PG8_MMA(0, 1, At, B1); PG8_BAR; PG8_SCHED;
;             PG8_LDA(At, 1, 1); PG8_STAGE(PG8_SB(1, 0), b3, voffB); PG8_STAGE(PG8_SB(1, 1), b3 + hstepB, voffB); PG8_STAGE(PG8_SA(1, 0), a3, voffA);
;             PG8_WAIT_V(8); PG8_WAIT_L(0); PG8_BAR; PG8_MMA(1, 0, At, B0); PG8_MMA(1, 1, At, B1); PG8_BAR; PG8_SCHED;
	s_add_i32 s23, 0, 0x18000
	s_add_i32 s71, 0, 0x1c000
	v_add_u32_e32 v152, s23, v164
	v_add_u32_e32 v176, s71, v164
	ds_read_b128 v[128:131], v152
	ds_read_b128 v[132:135], v152 offset:1024
	ds_read_b128 v[136:139], v152 offset:2048
	ds_read_b128 v[152:155], v152 offset:3072
	ds_read_b128 v[156:159], v176
	ds_read_b128 v[168:171], v176 offset:1024
	ds_read_b128 v[172:175], v176 offset:2048
	ds_read_b128 v[176:179], v176 offset:3072
	s_add_u32 s52, s52, 0x80000
	s_addc_u32 s53, s53, 0
	s_mov_b32 m0, s57
	ds_read_b128 v[180:183], v166 offset:32768
	ds_read_b128 v[184:187], v166 offset:33792
	ds_read_b128 v[188:191], v166 offset:34816
	ds_read_b128 v[192:195], v166 offset:35840
	ds_read_b128 v[196:199], v166 offset:36864
	ds_read_b128 v[200:203], v166 offset:37888
	ds_read_b128 v[204:207], v166 offset:38912
	ds_read_b128 v[208:211], v166 offset:39936
	global_load_lds_dwordx4 v140, s[52:53]
	s_mov_b32 m0, s58
	s_nop 0
	global_load_lds_dwordx4 v144, s[52:53]
	s_waitcnt vmcnt(8)
	s_waitcnt lgkmcnt(0)
	s_barrier
	s_setprio 1
	s_waitcnt lgkmcnt(0)
	v_mfma_f32_16x16x32_bf16 v[124:127], v[128:131], v[180:183], v[124:127]
	v_mfma_f32_16x16x32_bf16 v[120:123], v[136:139], v[180:183], v[120:123]
	v_mfma_f32_16x16x32_bf16 v[108:111], v[128:131], v[188:191], v[108:111]
	v_mfma_f32_16x16x32_bf16 v[104:107], v[136:139], v[188:191], v[104:107]
	v_mfma_f32_16x16x32_bf16 v[92:95], v[128:131], v[196:199], v[92:95]
	v_mfma_f32_16x16x32_bf16 v[88:91], v[136:139], v[196:199], v[88:91]
	v_mfma_f32_16x16x32_bf16 v[76:79], v[128:131], v[204:207], v[76:79]
	v_mfma_f32_16x16x32_bf16 v[72:75], v[136:139], v[204:207], v[72:75]
	v_mfma_f32_16x16x32_bf16 v[124:127], v[132:135], v[184:187], v[124:127]
	v_mfma_f32_16x16x32_bf16 v[120:123], v[152:155], v[184:187], v[120:123]
	v_mfma_f32_16x16x32_bf16 v[108:111], v[132:135], v[192:195], v[108:111]
	v_mfma_f32_16x16x32_bf16 v[104:107], v[152:155], v[192:195], v[104:107]
	v_mfma_f32_16x16x32_bf16 v[92:95], v[132:135], v[200:203], v[92:95]
	v_mfma_f32_16x16x32_bf16 v[88:91], v[152:155], v[200:203], v[88:91]
	v_mfma_f32_16x16x32_bf16 v[76:79], v[132:135], v[208:211], v[76:79]
	v_mfma_f32_16x16x32_bf16 v[72:75], v[152:155], v[208:211], v[72:75]
	s_setprio 0
	s_setprio 1
	v_mfma_f32_16x16x32_bf16 v[116:119], v[156:159], v[180:183], v[116:119]
	v_mfma_f32_16x16x32_bf16 v[112:115], v[172:175], v[180:183], v[112:115]
	v_mfma_f32_16x16x32_bf16 v[100:103], v[156:159], v[188:191], v[100:103]
	v_mfma_f32_16x16x32_bf16 v[96:99], v[172:175], v[188:191], v[96:99]
	v_mfma_f32_16x16x32_bf16 v[84:87], v[156:159], v[196:199], v[84:87]
	v_mfma_f32_16x16x32_bf16 v[80:83], v[172:175], v[196:199], v[80:83]
	v_mfma_f32_16x16x32_bf16 v[68:71], v[156:159], v[204:207], v[68:71]
	v_mfma_f32_16x16x32_bf16 v[64:67], v[172:175], v[204:207], v[64:67]
	v_mfma_f32_16x16x32_bf16 v[116:119], v[168:171], v[184:187], v[116:119]
	v_mfma_f32_16x16x32_bf16 v[112:115], v[176:179], v[184:187], v[112:115]
	v_mfma_f32_16x16x32_bf16 v[100:103], v[168:171], v[192:195], v[100:103]
	v_mfma_f32_16x16x32_bf16 v[96:99], v[176:179], v[192:195], v[96:99]
	v_mfma_f32_16x16x32_bf16 v[84:87], v[168:171], v[200:203], v[84:87]
	v_mfma_f32_16x16x32_bf16 v[80:83], v[176:179], v[200:203], v[80:83]
	v_mfma_f32_16x16x32_bf16 v[68:71], v[168:171], v[208:211], v[68:71]
	v_mfma_f32_16x16x32_bf16 v[64:67], v[176:179], v[208:211], v[64:67]
	s_setprio 0
	s_barrier
	s_add_u32 s48, s48, s50
	s_addc_u32 s49, s49, s51
	s_add_i32 s23, s23, s33
	s_mov_b32 m0, s23
	ds_read_b128 v[180:183], v166 offset:49152
	ds_read_b128 v[184:187], v166 offset:50176
	ds_read_b128 v[188:191], v166 offset:51200
	ds_read_b128 v[192:195], v166 offset:52224
	ds_read_b128 v[196:199], v166 offset:53248
	ds_read_b128 v[200:203], v166 offset:54272
	ds_read_b128 v[204:207], v166 offset:55296
	ds_read_b128 v[208:211], v166 offset:56320
	global_load_lds_dwordx4 v142, s[48:49]
	s_add_i32 m0, s23, 0x2000
	v_lshl_add_u64 v[212:213], s[48:49], 0, v[146:147]
	s_add_u32 s48, s48, 0x80000
	s_addc_u32 s49, s49, 0
	s_add_i32 s23, s71, s33
	global_load_lds_dwordx4 v[212:213], off
	s_mov_b32 m0, s23
	s_nop 0
	global_load_lds_dwordx4 v142, s[48:49]
	s_add_i32 m0, s23, 0x2000
	s_nop 0
	global_load_lds_dwordx4 v146, s[48:49]
	s_mov_b32 m0, s60
	s_nop 0
	global_load_lds_dwordx4 v140, s[54:55]
	s_mov_b32 m0, s61
	s_nop 0
	global_load_lds_dwordx4 v144, s[54:55]
	s_waitcnt vmcnt(8)
	s_waitcnt lgkmcnt(0)
	s_barrier
	s_setprio 1
	s_waitcnt lgkmcnt(0)
	v_mfma_f32_16x16x32_bf16 v[60:63], v[128:131], v[180:183], v[60:63]
	v_mfma_f32_16x16x32_bf16 v[56:59], v[136:139], v[180:183], v[56:59]
	v_mfma_f32_16x16x32_bf16 v[44:47], v[128:131], v[188:191], v[44:47]
	v_mfma_f32_16x16x32_bf16 v[40:43], v[136:139], v[188:191], v[40:43]
	v_mfma_f32_16x16x32_bf16 v[28:31], v[128:131], v[196:199], v[28:31]
	v_mfma_f32_16x16x32_bf16 v[24:27], v[136:139], v[196:199], v[24:27]
	v_mfma_f32_16x16x32_bf16 v[12:15], v[128:131], v[204:207], v[12:15]
	v_mfma_f32_16x16x32_bf16 v[8:11], v[136:139], v[204:207], v[8:11]
	v_mfma_f32_16x16x32_bf16 v[60:63], v[132:135], v[184:187], v[60:63]
	v_mfma_f32_16x16x32_bf16 v[56:59], v[152:155], v[184:187], v[56:59]
	v_mfma_f32_16x16x32_bf16 v[44:47], v[132:135], v[192:195], v[44:47]
	v_mfma_f32_16x16x32_bf16 v[40:43], v[152:155], v[192:195], v[40:43]
	v_mfma_f32_16x16x32_bf16 v[28:31], v[132:135], v[200:203], v[28:31]
	v_mfma_f32_16x16x32_bf16 v[24:27], v[152:155], v[200:203], v[24:27]
	v_mfma_f32_16x16x32_bf16 v[12:15], v[132:135], v[208:211], v[12:15]
	v_mfma_f32_16x16x32_bf16 v[8:11], v[152:155], v[208:211], v[8:11]
	s_setprio 0
	s_setprio 1
	v_mfma_f32_16x16x32_bf16 v[52:55], v[156:159], v[180:183], v[52:55]
	v_mfma_f32_16x16x32_bf16 v[48:51], v[172:175], v[180:183], v[48:51]
	v_mfma_f32_16x16x32_bf16 v[36:39], v[156:159], v[188:191], v[36:39]
	v_mfma_f32_16x16x32_bf16 v[32:35], v[172:175], v[188:191], v[32:35]
	v_mfma_f32_16x16x32_bf16 v[20:23], v[156:159], v[196:199], v[20:23]
	v_mfma_f32_16x16x32_bf16 v[16:19], v[172:175], v[196:199], v[16:19]
	v_mfma_f32_16x16x32_bf16 v[4:7], v[156:159], v[204:207], v[4:7]
	v_mfma_f32_16x16x32_bf16 v[0:3], v[172:175], v[204:207], v[0:3]
	v_mfma_f32_16x16x32_bf16 v[52:55], v[168:171], v[184:187], v[52:55]
	v_mfma_f32_16x16x32_bf16 v[48:51], v[176:179], v[184:187], v[48:51]
	v_mfma_f32_16x16x32_bf16 v[36:39], v[168:171], v[192:195], v[36:39]
	v_mfma_f32_16x16x32_bf16 v[32:35], v[176:179], v[192:195], v[32:35]
	v_mfma_f32_16x16x32_bf16 v[20:23], v[168:171], v[200:203], v[20:23]
	v_mfma_f32_16x16x32_bf16 v[16:19], v[176:179], v[200:203], v[16:19]
	v_mfma_f32_16x16x32_bf16 v[4:7], v[168:171], v[208:211], v[4:7]
	v_mfma_f32_16x16x32_bf16 v[0:3], v[176:179], v[208:211], v[0:3]
	s_setprio 0
	s_barrier
	s_cmp_gt_u32 s31, 29
	s_mov_b32 s31, s21
	s_cbranch_scc1 .LBB0_1378

; #define PG8_STAGE(bufoff, gbase, voff) do { _Pragma("unroll") for (int _i = 0; _i < 2; ++_i) \
;         __builtin_amdgcn_global_load_lds((const unsigned*)((const char*)(gbase) + (voff)[_i]), (LAS unsigned*)(lds + (bufoff) + ldsw + _i * 8192), 16, 0, 0); } while (0)
; #define PG8_WAIT_V(n) asm volatile("s_waitcnt vmcnt(" #n ")" ::: "memory")
; #define PG8_BAR __builtin_amdgcn_s_barrier()
; template <class Epi>
; __device__ __forceinline__ void gemm_phase(LAS unsigned char* lds, const Gemm g, const StaticOrder S, const Epi E) {
;     ...
;     const int aoff = lds_byte(wr * 64 + fr, fq * 8), boff = lds_byte(wc * 32 + fr, fq * 8);
;     ...
;     PG8_STAGE(PG8_SB(0, 0), cB, voffB); PG8_STAGE(PG8_SB(0, 1), cB + hstepB, voffB); PG8_STAGE(PG8_SA(0, 0), cA, voffA); PG8_STAGE(PG8_SA(0, 1), cA + hstepA, voffA);
;     if (wr == 1) PG8_BAR;
;     PG8_WAIT_V(2); PG8_BAR;
;     PG8_STAGE(PG8_SB(1, 0), cB + ksc, voffB); PG8_STAGE(PG8_SA(1, 0), cA + ksc, voffA); PG8_STAGE(PG8_SB(1, 1), cB + hstepB + ksc, voffB);
;     PG8_WAIT_V(6); PG8_BAR;
.LBB0_1467:
	s_add_u32 s6, s82, 0x2a9d0000
	s_addc_u32 s7, s83, 0
	s_lshl_b32 s9, s9, 5
	s_mov_b64 s[26:27], 0x80
	s_and_b32 s14, s9, 0x60
	s_add_i32 m0, s21, 0x18000
	v_lshl_add_u64 v[6:7], v[6:7], 0, s[26:27]
	s_lshl_b32 s10, s8, 13
	s_lshl_b32 s9, s14, 7
	s_waitcnt vmcnt(2)
	s_barrier
	global_load_lds_dwordx4 v[6:7], off
	v_lshl_add_u64 v[4:5], v[4:5], 0, s[26:27]
	s_add_i32 m0, s21, 0x1a000
	s_add_i32 s51, s21, 0x8000
	s_add_i32 s52, s21, 0xa000
	global_load_lds_dwordx4 v[4:5], off
	v_lshl_add_u64 v[0:1], v[0:1], 0, s[26:27]
	s_mov_b32 m0, s51
	s_add_u32 s12, s22, 0x80080
	global_load_lds_dwordx4 v[0:1], off
	v_lshl_add_u64 v[0:1], v[2:3], 0, s[26:27]
	s_mov_b32 m0, s52
	s_addc_u32 s13, s23, 0
	global_load_lds_dwordx4 v[0:1], off
	s_add_i32 m0, s21, 0x1c000
	s_nop 0
	global_load_lds_dwordx4 v132, s[12:13]
	s_add_i32 m0, s21, 0x1e000
	v_lshlrev_b32_e32 v2, 2, v224
	global_load_lds_dwordx4 v128, s[12:13]
	v_and_b32_e32 v0, 15, v224
	v_lshlrev_b32_e32 v1, 1, v8
	s_sext_i32_i16 s59, s0
	v_lshl_or_b32 v142, s8, 6, v0
	v_lshl_or_b32 v0, v0, 6, v1
	v_and_b32_e32 v2, 32, v2
	v_lshlrev_b32_e32 v3, 6, v224
	s_movk_i32 s0, 0x3c0
	s_waitcnt vmcnt(6)
	s_ashr_i32 s53, s78, 31
	v_bitop3_b32 v0, v0, s10, v2 bitop3:0xde
	v_and_or_b32 v1, v3, s0, v1
	s_cmpk_lt_u32 s1, 0x100
	v_bitop3_b32 v143, s9, v1, v2 bitop3:0xf6
	s_cselect_b64 s[8:9], -1, 0
	v_or_b32_e32 v144, s14, v8
	v_mov_b64_e32 v[136:137], 0xb00
	v_mov_b64_e32 v[138:139], 0xaff
	s_movk_i32 s54, 0xff80
	s_add_i32 s55, 0, 0x10000
	s_add_i32 s56, 0, 0x14000
	v_add_u32_e32 v145, 0, v0
	s_movk_i32 s57, 0x2c00
	v_mov_b32_e32 v146, 0x358637bd
	s_barrier
	s_branch .LBB0_1470

; #define PG8_STAGE(bufoff, gbase, voff) do { _Pragma("unroll") for (int _i = 0; _i < 2; ++_i) \
;         __builtin_amdgcn_global_load_lds((const unsigned*)((const char*)(gbase) + (voff)[_i]), (LAS unsigned*)(lds + (bufoff) + ldsw + _i * 8192), 16, 0, 0); } while (0)
; #define PG8_LDA(dst, b, h) do { _Pragma("unroll") for (int m = 0; m < 4; ++m) _Pragma("unroll") for (int k = 0; k < 2; ++k) dst[m][k] = *(const LAS bf16x8*)(lds + PG8_SA(b, h) + aoff + m * 2048 + k * 1024); } while (0)
; #define PG8_LDB(dst, b, h) do { _Pragma("unroll") for (int n = 0; n < 2; ++n) _Pragma("unroll") for (int k = 0; k < 2; ++k) dst[n][k] = *(const LAS bf16x8*)(lds + PG8_SB(b, h) + boff + n * 2048 + k * 1024); } while (0)
; #define PG8_MMA(ai, bj, At, Bt) do { __builtin_amdgcn_s_setprio(1); _Pragma("unroll") for (int m = 0; m < 4; ++m) _Pragma("unroll") for (int n = 0; n < 2; ++n) _Pragma("unroll") for (int k = 0; k < 2; ++k) \
;         acc[ai][bj][m][n] = __builtin_amdgcn_mfma_f32_16x16x32_bf16(Bt[n][k], At[m][k], acc[ai][bj][m][n], 0, 0, 0); __builtin_amdgcn_s_setprio(0); } while (0)
; #define PG8_WAIT_V(n) asm volatile("s_waitcnt vmcnt(" #n ")" ::: "memory")
; #define PG8_WAIT_L(n) asm volatile("s_waitcnt lgkmcnt(" #n ")" ::: "memory")
; #define PG8_BAR __builtin_amdgcn_s_barrier()
; #define PG8_SCHED __builtin_amdgcn_sched_barrier(0)
; template <class Epi>
; __device__ __forceinline__ void gemm_phase(LAS unsigned char* lds, const Gemm g, const StaticOrder S, const Epi E) {
;     ...
;             const char* a1 = cA + (long)(t + 1) * ksc;
;             const char* a2 = last ? nA : cA + (long)(t + 2) * ksc; const char* b2 = last ? nB : cB + (long)(t + 2) * ksc;
;             const long ks3 = last ? ksn : ksc;
;             const char* a3 = a2 + ks3; const char* b3 = b2 + ks3;
;             PG8_LDB(B0, 0, 0); PG8_LDB(B1, 0, 1); PG8_SCHED; PG8_LDA(At, 0, 0); PG8_STAGE(PG8_SA(1, 1), a1 + hstepA, voffA);
;             PG8_WAIT_V(8); PG8_WAIT_L(0); PG8_BAR; PG8_MMA(0, 0, At, B0); PG8_MMA(0, 1, At, B1); PG8_BAR; PG8_SCHED;
;             PG8_LDA(At, 0, 1); PG8_STAGE(PG8_SB(0, 0), b2, voffB); PG8_STAGE(PG8_SB(0, 1), b2 + hstepB, voffB); PG8_STAGE(PG8_SA(0, 0), a2, voffA);
;             PG8_WAIT_V(8); PG8_WAIT_L(0); PG8_BAR; PG8_MMA(1, 0, At, B0); PG8_MMA(1, 1, At, B1); PG8_BAR; PG8_SCHED;
.LBB0_1473:
	v_add_u32_e32 v140, s55, v143
	ds_read_b128 v[148:151], v140
	ds_read_b128 v[152:155], v140 offset:1024
	ds_read_b128 v[156:159], v140 offset:2048
	ds_read_b128 v[160:163], v140 offset:3072
	v_add_u32_e32 v140, s56, v143
	ds_read_b128 v[164:167], v140
	ds_read_b128 v[168:171], v140 offset:1024
	ds_read_b128 v[172:175], v140 offset:2048
	ds_read_b128 v[176:179], v140 offset:3072
	s_or_b32 s13, s60, 1
	s_mul_i32 s42, s27, s13
	s_mul_hi_u32 s43, s26, s13
	s_add_i32 s43, s43, s42
	s_mul_i32 s13, s26, s13
	s_add_u32 s13, s24, s13
	s_addc_u32 s61, s25, s43
	s_add_u32 s42, s40, s38
	s_addc_u32 s43, s41, s39
	s_add_u32 s62, s13, 0x80000
	s_addc_u32 s63, s61, 0
	s_add_i32 m0, s21, 0xc000
	ds_read_b128 v[180:183], v145
	ds_read_b128 v[184:187], v145 offset:1024
	ds_read_b128 v[188:191], v145 offset:2048
	ds_read_b128 v[192:195], v145 offset:3072
	ds_read_b128 v[196:199], v145 offset:4096
	ds_read_b128 v[200:203], v145 offset:5120
	ds_read_b128 v[204:207], v145 offset:6144
	ds_read_b128 v[208:211], v145 offset:7168
	global_load_lds_dwordx4 v134, s[62:63]
	s_add_i32 m0, s21, 0xe000
	s_nop 0
	global_load_lds_dwordx4 v130, s[62:63]
	s_waitcnt vmcnt(8)
	s_waitcnt lgkmcnt(0)
	s_barrier
	s_setprio 1
	s_waitcnt lgkmcnt(0)
	v_mfma_f32_16x16x32_bf16 v[116:119], v[148:151], v[180:183], v[116:119]
	v_mfma_f32_16x16x32_bf16 v[112:115], v[156:159], v[180:183], v[112:115]
	v_mfma_f32_16x16x32_bf16 v[108:111], v[148:151], v[188:191], v[108:111]
	v_mfma_f32_16x16x32_bf16 v[104:107], v[156:159], v[188:191], v[104:107]
	v_mfma_f32_16x16x32_bf16 v[92:95], v[148:151], v[196:199], v[92:95]
	v_mfma_f32_16x16x32_bf16 v[88:91], v[156:159], v[196:199], v[88:91]
	v_mfma_f32_16x16x32_bf16 v[76:79], v[148:151], v[204:207], v[76:79]
	v_mfma_f32_16x16x32_bf16 v[72:75], v[156:159], v[204:207], v[72:75]
	v_mfma_f32_16x16x32_bf16 v[116:119], v[152:155], v[184:187], v[116:119]
	v_mfma_f32_16x16x32_bf16 v[112:115], v[160:163], v[184:187], v[112:115]
	v_mfma_f32_16x16x32_bf16 v[108:111], v[152:155], v[192:195], v[108:111]
	v_mfma_f32_16x16x32_bf16 v[104:107], v[160:163], v[192:195], v[104:107]
	v_mfma_f32_16x16x32_bf16 v[92:95], v[152:155], v[200:203], v[92:95]
	v_mfma_f32_16x16x32_bf16 v[88:91], v[160:163], v[200:203], v[88:91]
	v_mfma_f32_16x16x32_bf16 v[76:79], v[152:155], v[208:211], v[76:79]
	v_mfma_f32_16x16x32_bf16 v[72:75], v[160:163], v[208:211], v[72:75]
	s_setprio 0
	s_setprio 1
	v_mfma_f32_16x16x32_bf16 v[124:127], v[164:167], v[180:183], v[124:127]
	v_mfma_f32_16x16x32_bf16 v[120:123], v[172:175], v[180:183], v[120:123]
	v_mfma_f32_16x16x32_bf16 v[100:103], v[164:167], v[188:191], v[100:103]
	v_mfma_f32_16x16x32_bf16 v[96:99], v[172:175], v[188:191], v[96:99]
	v_mfma_f32_16x16x32_bf16 v[84:87], v[164:167], v[196:199], v[84:87]
	v_mfma_f32_16x16x32_bf16 v[80:83], v[172:175], v[196:199], v[80:83]
	v_mfma_f32_16x16x32_bf16 v[68:71], v[164:167], v[204:207], v[68:71]
	v_mfma_f32_16x16x32_bf16 v[64:67], v[172:175], v[204:207], v[64:67]
	v_mfma_f32_16x16x32_bf16 v[124:127], v[168:171], v[184:187], v[124:127]
	v_mfma_f32_16x16x32_bf16 v[120:123], v[176:179], v[184:187], v[120:123]
	v_mfma_f32_16x16x32_bf16 v[100:103], v[168:171], v[192:195], v[100:103]
	v_mfma_f32_16x16x32_bf16 v[96:99], v[176:179], v[192:195], v[96:99]
	v_mfma_f32_16x16x32_bf16 v[84:87], v[168:171], v[200:203], v[84:87]
	v_mfma_f32_16x16x32_bf16 v[80:83], v[176:179], v[200:203], v[80:83]
	v_mfma_f32_16x16x32_bf16 v[68:71], v[168:171], v[208:211], v[68:71]
	v_mfma_f32_16x16x32_bf16 v[64:67], v[176:179], v[208:211], v[64:67]
	s_setprio 0
	s_barrier
	s_add_i32 s13, s55, s45
	s_mov_b32 m0, s13
	ds_read_b128 v[180:183], v145 offset:16384
	ds_read_b128 v[184:187], v145 offset:17408
	ds_read_b128 v[188:191], v145 offset:18432
	ds_read_b128 v[192:195], v145 offset:19456
	ds_read_b128 v[196:199], v145 offset:20480
	ds_read_b128 v[200:203], v145 offset:21504
	ds_read_b128 v[204:207], v145 offset:22528
	ds_read_b128 v[208:211], v145 offset:23552
	global_load_lds_dwordx4 v132, s[36:37]
	s_add_i32 m0, s13, 0x2000
	s_add_u32 s62, s36, 0x80000
	s_addc_u32 s63, s37, 0
	s_add_i32 s13, s56, s45
	global_load_lds_dwordx4 v128, s[36:37]
	s_mov_b32 m0, s13
	s_nop 0
	global_load_lds_dwordx4 v132, s[62:63]
	s_add_i32 m0, s13, 0x2000
	s_nop 0
	global_load_lds_dwordx4 v128, s[62:63]
	s_mov_b32 m0, s21
	s_nop 0
	global_load_lds_dwordx4 v134, s[40:41]
	s_mov_b32 m0, s48
	s_nop 0
	global_load_lds_dwordx4 v130, s[40:41]
	s_waitcnt vmcnt(8)
	s_waitcnt lgkmcnt(0)
	s_barrier
	s_setprio 1
	s_waitcnt lgkmcnt(0)
	v_mfma_f32_16x16x32_bf16 v[60:63], v[148:151], v[180:183], v[60:63]
	v_mfma_f32_16x16x32_bf16 v[56:59], v[156:159], v[180:183], v[56:59]
	v_mfma_f32_16x16x32_bf16 v[44:47], v[148:151], v[188:191], v[44:47]
	v_mfma_f32_16x16x32_bf16 v[40:43], v[156:159], v[188:191], v[40:43]
	v_mfma_f32_16x16x32_bf16 v[28:31], v[148:151], v[196:199], v[28:31]
	v_mfma_f32_16x16x32_bf16 v[24:27], v[156:159], v[196:199], v[24:27]
	v_mfma_f32_16x16x32_bf16 v[12:15], v[148:151], v[204:207], v[12:15]
	v_mfma_f32_16x16x32_bf16 v[8:11], v[156:159], v[204:207], v[8:11]
	v_mfma_f32_16x16x32_bf16 v[60:63], v[152:155], v[184:187], v[60:63]
	v_mfma_f32_16x16x32_bf16 v[56:59], v[160:163], v[184:187], v[56:59]
	v_mfma_f32_16x16x32_bf16 v[44:47], v[152:155], v[192:195], v[44:47]
	v_mfma_f32_16x16x32_bf16 v[40:43], v[160:163], v[192:195], v[40:43]
	v_mfma_f32_16x16x32_bf16 v[28:31], v[152:155], v[200:203], v[28:31]
	v_mfma_f32_16x16x32_bf16 v[24:27], v[160:163], v[200:203], v[24:27]
	v_mfma_f32_16x16x32_bf16 v[12:15], v[152:155], v[208:211], v[12:15]
	v_mfma_f32_16x16x32_bf16 v[8:11], v[160:163], v[208:211], v[8:11]
	s_setprio 0
	s_setprio 1
	v_mfma_f32_16x16x32_bf16 v[52:55], v[164:167], v[180:183], v[52:55]
	v_mfma_f32_16x16x32_bf16 v[48:51], v[172:175], v[180:183], v[48:51]
	v_mfma_f32_16x16x32_bf16 v[36:39], v[164:167], v[188:191], v[36:39]
	v_mfma_f32_16x16x32_bf16 v[32:35], v[172:175], v[188:191], v[32:35]
	v_mfma_f32_16x16x32_bf16 v[20:23], v[164:167], v[196:199], v[20:23]
	v_mfma_f32_16x16x32_bf16 v[16:19], v[172:175], v[196:199], v[16:19]
	v_mfma_f32_16x16x32_bf16 v[4:7], v[164:167], v[204:207], v[4:7]
	v_mfma_f32_16x16x32_bf16 v[0:3], v[172:175], v[204:207], v[0:3]
	v_mfma_f32_16x16x32_bf16 v[52:55], v[168:171], v[184:187], v[52:55]
	v_mfma_f32_16x16x32_bf16 v[48:51], v[176:179], v[184:187], v[48:51]
	v_mfma_f32_16x16x32_bf16 v[36:39], v[168:171], v[192:195], v[36:39]
	v_mfma_f32_16x16x32_bf16 v[32:35], v[176:179], v[192:195], v[32:35]
	v_mfma_f32_16x16x32_bf16 v[20:23], v[168:171], v[200:203], v[20:23]
	v_mfma_f32_16x16x32_bf16 v[16:19], v[176:179], v[200:203], v[16:19]
	v_mfma_f32_16x16x32_bf16 v[4:7], v[168:171], v[208:211], v[4:7]
	v_mfma_f32_16x16x32_bf16 v[0:3], v[176:179], v[208:211], v[0:3]
	s_setprio 0
	s_barrier
; #define PG8_STAGE(bufoff, gbase, voff) do { _Pragma("unroll") for (int _i = 0; _i < 2; ++_i) \
;         __builtin_amdgcn_global_load_lds((const unsigned*)((const char*)(gbase) + (voff)[_i]), (LAS unsigned*)(lds + (bufoff) + ldsw + _i * 8192), 16, 0, 0); } while (0)
; #define PG8_LDA(dst, b, h) do { _Pragma("unroll") for (int m = 0; m < 4; ++m) _Pragma("unroll") for (int k = 0; k < 2; ++k) dst[m][k] = *(const LAS bf16x8*)(lds + PG8_SA(b, h) + aoff + m * 2048 + k * 1024); } while (0)
; #define PG8_LDB(dst, b, h) do { _Pragma("unroll") for (int n = 0; n < 2; ++n) _Pragma("unroll") for (int k = 0; k < 2; ++k) dst[n][k] = *(const LAS bf16x8*)(lds + PG8_SB(b, h) + boff + n * 2048 + k * 1024); } while (0)
; #define PG8_MMA(ai, bj, At, Bt) do { __builtin_amdgcn_s_setprio(1); _Pragma("unroll") for (int m = 0; m < 4; ++m) _Pragma("unroll") for (int n = 0; n < 2; ++n) _Pragma("unroll") for (int k = 0; k < 2; ++k) \
;         acc[ai][bj][m][n] = __builtin_amdgcn_mfma_f32_16x16x32_bf16(Bt[n][k], At[m][k], acc[ai][bj][m][n], 0, 0, 0); __builtin_amdgcn_s_setprio(0); } while (0)
; #define PG8_WAIT_V(n) asm volatile("s_waitcnt vmcnt(" #n ")" ::: "memory")
; #define PG8_WAIT_L(n) asm volatile("s_waitcnt lgkmcnt(" #n ")" ::: "memory")
; #define PG8_BAR __builtin_amdgcn_s_barrier()
; #define PG8_SCHED __builtin_amdgcn_sched_barrier(0)
; template <class Epi>
; __device__ __forceinline__ void gemm_phase(LAS unsigned char* lds, const Gemm g, const StaticOrder S, const Epi E) {
;     ...
;             PG8_LDB(B0, 1, 0); PG8_LDB(B1, 1, 1); PG8_SCHED; PG8_LDA(At, 1, 0); PG8_STAGE(PG8_SA(0, 1), a2 + hstepA, voffA);
;             PG8_WAIT_V(8); PG8_WAIT_L(0); PG8_BAR; PG8_MMA(0, 0, At, B0); PG8_MMA(0, 1, At, B1); PG8_BAR; PG8_SCHED;
;             PG8_LDA(At, 1, 1); PG8_STAGE(PG8_SB(1, 0), b3, voffB); PG8_STAGE(PG8_SB(1, 1), b3 + hstepB, voffB); PG8_STAGE(PG8_SA(1, 0), a3, voffA);
;             PG8_WAIT_V(8); PG8_WAIT_L(0); PG8_BAR; PG8_MMA(1, 0, At, B0); PG8_MMA(1, 1, At, B1); PG8_BAR; PG8_SCHED;
	s_add_i32 s13, 0, 0x18000
	v_add_u32_e32 v140, s13, v143
	s_add_i32 s61, 0, 0x1c000
	ds_read_b128 v[148:151], v140
	ds_read_b128 v[152:155], v140 offset:1024
	ds_read_b128 v[156:159], v140 offset:2048
	ds_read_b128 v[160:163], v140 offset:3072
	v_add_u32_e32 v140, s61, v143
	ds_read_b128 v[164:167], v140
	ds_read_b128 v[168:171], v140 offset:1024
	ds_read_b128 v[172:175], v140 offset:2048
	ds_read_b128 v[176:179], v140 offset:3072
	s_add_u32 s40, s40, 0x80000
	s_addc_u32 s41, s41, 0
	s_mov_b32 m0, s49
	ds_read_b128 v[180:183], v145 offset:32768
	ds_read_b128 v[184:187], v145 offset:33792
	ds_read_b128 v[188:191], v145 offset:34816
	ds_read_b128 v[192:195], v145 offset:35840
	ds_read_b128 v[196:199], v145 offset:36864
	ds_read_b128 v[200:203], v145 offset:37888
	ds_read_b128 v[204:207], v145 offset:38912
	ds_read_b128 v[208:211], v145 offset:39936
	global_load_lds_dwordx4 v134, s[40:41]
	s_mov_b32 m0, s50
	s_nop 0
	global_load_lds_dwordx4 v130, s[40:41]
	s_waitcnt vmcnt(8)
	s_waitcnt lgkmcnt(0)
	s_barrier
	s_setprio 1
	s_waitcnt lgkmcnt(0)
	v_mfma_f32_16x16x32_bf16 v[116:119], v[148:151], v[180:183], v[116:119]
	v_mfma_f32_16x16x32_bf16 v[112:115], v[156:159], v[180:183], v[112:115]
	v_mfma_f32_16x16x32_bf16 v[108:111], v[148:151], v[188:191], v[108:111]
	v_mfma_f32_16x16x32_bf16 v[104:107], v[156:159], v[188:191], v[104:107]
	v_mfma_f32_16x16x32_bf16 v[92:95], v[148:151], v[196:199], v[92:95]
	v_mfma_f32_16x16x32_bf16 v[88:91], v[156:159], v[196:199], v[88:91]
	v_mfma_f32_16x16x32_bf16 v[76:79], v[148:151], v[204:207], v[76:79]
	v_mfma_f32_16x16x32_bf16 v[72:75], v[156:159], v[204:207], v[72:75]
	v_mfma_f32_16x16x32_bf16 v[116:119], v[152:155], v[184:187], v[116:119]
	v_mfma_f32_16x16x32_bf16 v[112:115], v[160:163], v[184:187], v[112:115]
	v_mfma_f32_16x16x32_bf16 v[108:111], v[152:155], v[192:195], v[108:111]
	v_mfma_f32_16x16x32_bf16 v[104:107], v[160:163], v[192:195], v[104:107]
	v_mfma_f32_16x16x32_bf16 v[92:95], v[152:155], v[200:203], v[92:95]
	v_mfma_f32_16x16x32_bf16 v[88:91], v[160:163], v[200:203], v[88:91]
	v_mfma_f32_16x16x32_bf16 v[76:79], v[152:155], v[208:211], v[76:79]
	v_mfma_f32_16x16x32_bf16 v[72:75], v[160:163], v[208:211], v[72:75]
	s_setprio 0
	s_setprio 1
	v_mfma_f32_16x16x32_bf16 v[124:127], v[164:167], v[180:183], v[124:127]
	v_mfma_f32_16x16x32_bf16 v[120:123], v[172:175], v[180:183], v[120:123]
	v_mfma_f32_16x16x32_bf16 v[100:103], v[164:167], v[188:191], v[100:103]
	v_mfma_f32_16x16x32_bf16 v[96:99], v[172:175], v[188:191], v[96:99]
	v_mfma_f32_16x16x32_bf16 v[84:87], v[164:167], v[196:199], v[84:87]
	v_mfma_f32_16x16x32_bf16 v[80:83], v[172:175], v[196:199], v[80:83]
	v_mfma_f32_16x16x32_bf16 v[68:71], v[164:167], v[204:207], v[68:71]
	v_mfma_f32_16x16x32_bf16 v[64:67], v[172:175], v[204:207], v[64:67]
	v_mfma_f32_16x16x32_bf16 v[124:127], v[168:171], v[184:187], v[124:127]
	v_mfma_f32_16x16x32_bf16 v[120:123], v[176:179], v[184:187], v[120:123]
	v_mfma_f32_16x16x32_bf16 v[100:103], v[168:171], v[192:195], v[100:103]
	v_mfma_f32_16x16x32_bf16 v[96:99], v[176:179], v[192:195], v[96:99]
	v_mfma_f32_16x16x32_bf16 v[84:87], v[168:171], v[200:203], v[84:87]
	v_mfma_f32_16x16x32_bf16 v[80:83], v[176:179], v[200:203], v[80:83]
	v_mfma_f32_16x16x32_bf16 v[68:71], v[168:171], v[208:211], v[68:71]
	v_mfma_f32_16x16x32_bf16 v[64:67], v[176:179], v[208:211], v[64:67]
	s_setprio 0
	s_barrier
	s_add_u32 s36, s36, s38
	s_addc_u32 s37, s37, s39
	s_add_i32 s13, s13, s45
	s_mov_b32 m0, s13
	ds_read_b128 v[180:183], v145 offset:49152
	ds_read_b128 v[184:187], v145 offset:50176
	ds_read_b128 v[188:191], v145 offset:51200
	ds_read_b128 v[192:195], v145 offset:52224
	ds_read_b128 v[196:199], v145 offset:53248
	ds_read_b128 v[200:203], v145 offset:54272
	ds_read_b128 v[204:207], v145 offset:55296
	ds_read_b128 v[208:211], v145 offset:56320
	global_load_lds_dwordx4 v132, s[36:37]
	s_add_i32 m0, s13, 0x2000
	v_lshl_add_u64 v[140:141], s[36:37], 0, v[128:129]
	s_add_u32 s36, s36, 0x80000
	s_addc_u32 s37, s37, 0
	s_add_i32 s13, s61, s45
	global_load_lds_dwordx4 v[140:141], off
	s_mov_b32 m0, s13
	s_nop 0
	global_load_lds_dwordx4 v132, s[36:37]
	s_add_i32 m0, s13, 0x2000
	s_nop 0
	global_load_lds_dwordx4 v128, s[36:37]
	s_mov_b32 m0, s51
	s_nop 0
	global_load_lds_dwordx4 v134, s[42:43]
	s_mov_b32 m0, s52
	s_nop 0
	global_load_lds_dwordx4 v130, s[42:43]
	s_waitcnt vmcnt(8)
	s_waitcnt lgkmcnt(0)
	s_barrier
	s_setprio 1
	s_waitcnt lgkmcnt(0)
	v_mfma_f32_16x16x32_bf16 v[60:63], v[148:151], v[180:183], v[60:63]
	v_mfma_f32_16x16x32_bf16 v[56:59], v[156:159], v[180:183], v[56:59]
	v_mfma_f32_16x16x32_bf16 v[44:47], v[148:151], v[188:191], v[44:47]
	v_mfma_f32_16x16x32_bf16 v[40:43], v[156:159], v[188:191], v[40:43]
	v_mfma_f32_16x16x32_bf16 v[28:31], v[148:151], v[196:199], v[28:31]
	v_mfma_f32_16x16x32_bf16 v[24:27], v[156:159], v[196:199], v[24:27]
	v_mfma_f32_16x16x32_bf16 v[12:15], v[148:151], v[204:207], v[12:15]
	v_mfma_f32_16x16x32_bf16 v[8:11], v[156:159], v[204:207], v[8:11]
	v_mfma_f32_16x16x32_bf16 v[60:63], v[152:155], v[184:187], v[60:63]
	v_mfma_f32_16x16x32_bf16 v[56:59], v[160:163], v[184:187], v[56:59]
	v_mfma_f32_16x16x32_bf16 v[44:47], v[152:155], v[192:195], v[44:47]
	v_mfma_f32_16x16x32_bf16 v[40:43], v[160:163], v[192:195], v[40:43]
	v_mfma_f32_16x16x32_bf16 v[28:31], v[152:155], v[200:203], v[28:31]
	v_mfma_f32_16x16x32_bf16 v[24:27], v[160:163], v[200:203], v[24:27]
	v_mfma_f32_16x16x32_bf16 v[12:15], v[152:155], v[208:211], v[12:15]
	v_mfma_f32_16x16x32_bf16 v[8:11], v[160:163], v[208:211], v[8:11]
	s_setprio 0
	s_setprio 1
	v_mfma_f32_16x16x32_bf16 v[52:55], v[164:167], v[180:183], v[52:55]
	v_mfma_f32_16x16x32_bf16 v[48:51], v[172:175], v[180:183], v[48:51]
	v_mfma_f32_16x16x32_bf16 v[36:39], v[164:167], v[188:191], v[36:39]
	v_mfma_f32_16x16x32_bf16 v[32:35], v[172:175], v[188:191], v[32:35]
	v_mfma_f32_16x16x32_bf16 v[20:23], v[164:167], v[196:199], v[20:23]
	v_mfma_f32_16x16x32_bf16 v[16:19], v[172:175], v[196:199], v[16:19]
	v_mfma_f32_16x16x32_bf16 v[4:7], v[164:167], v[204:207], v[4:7]
	v_mfma_f32_16x16x32_bf16 v[0:3], v[172:175], v[204:207], v[0:3]
	v_mfma_f32_16x16x32_bf16 v[52:55], v[168:171], v[184:187], v[52:55]
	v_mfma_f32_16x16x32_bf16 v[48:51], v[176:179], v[184:187], v[48:51]
	v_mfma_f32_16x16x32_bf16 v[36:39], v[168:171], v[192:195], v[36:39]
	v_mfma_f32_16x16x32_bf16 v[32:35], v[176:179], v[192:195], v[32:35]
	v_mfma_f32_16x16x32_bf16 v[20:23], v[168:171], v[200:203], v[20:23]
	v_mfma_f32_16x16x32_bf16 v[16:19], v[176:179], v[200:203], v[16:19]
	v_mfma_f32_16x16x32_bf16 v[4:7], v[168:171], v[208:211], v[4:7]
	v_mfma_f32_16x16x32_bf16 v[0:3], v[176:179], v[208:211], v[0:3]
	s_setprio 0
	s_barrier
	s_cmp_gt_u32 s60, 29
	s_mov_b32 s60, s11
	s_cbranch_scc1 .LBB0_1478

; #define PG8_STAGE(bufoff, gbase, voff) do { _Pragma("unroll") for (int _i = 0; _i < 2; ++_i) \
;         __builtin_amdgcn_global_load_lds((const unsigned*)((const char*)(gbase) + (voff)[_i]), (LAS unsigned*)(lds + (bufoff) + ldsw + _i * 8192), 16, 0, 0); } while (0)
; #define PG8_WAIT_V(n) asm volatile("s_waitcnt vmcnt(" #n ")" ::: "memory")
; #define PG8_BAR __builtin_amdgcn_s_barrier()
; template <class Epi>
; __device__ __forceinline__ void gemm_phase(LAS unsigned char* lds, const Gemm g, const StaticOrder S, const Epi E) {
;     ...
;     const int aoff = lds_byte(wr * 64 + fr, fq * 8), boff = lds_byte(wc * 32 + fr, fq * 8);
;     ...
;     const long klast = (long)(nt - 1) * (long)kstep;
;     long ksc = g.rev0 ? -(long)kstep : (long)kstep, ksn = ksc;
;     const char* cA = (const char*)g.A + (size_t)cur.pm * tstepA + (size_t)cur.pn * g.a_pn_off + (g.rev0 ? klast : 0); const char* cB = (const char*)g.Bt + (size_t)cur.pn * tstepB + (g.rev0 ? klast : 0);
;     PG8_STAGE(PG8_SB(0, 0), cB, voffB); PG8_STAGE(PG8_SB(0, 1), cB + hstepB, voffB); PG8_STAGE(PG8_SA(0, 0), cA, voffA); PG8_STAGE(PG8_SA(0, 1), cA + hstepA, voffA);
;     if (wr == 1) PG8_BAR;
;     PG8_WAIT_V(2); PG8_BAR;
;     PG8_STAGE(PG8_SB(1, 0), cB + ksc, voffB); PG8_STAGE(PG8_SA(1, 0), cA + ksc, voffA); PG8_STAGE(PG8_SB(1, 1), cB + hstepB + ksc, voffB);
;     PG8_WAIT_V(6); PG8_BAR;
.LBB0_1544:
	s_lshl_b32 s3, s3, 5
	s_and_b32 s3, s3, 0x60
	s_lshl_b32 s14, s0, 13
	s_lshl_b32 s15, s3, 7
	s_ashr_i32 s50, s79, 31
	s_add_u32 s12, s1, 0x2b00
	s_addc_u32 s13, s2, 0
	s_add_i32 m0, s46, 0x18000
	s_waitcnt vmcnt(2)
	s_barrier
	global_load_lds_dwordx4 v142, s[12:13]
	s_add_i32 m0, s46, 0x1a000
	v_lshl_add_u64 v[0:1], s[12:13], 0, v[146:147]
	s_add_u32 s12, s5, 0x2b00
	s_addc_u32 s13, s10, 0
	s_add_i32 s51, s46, 0x8000
	s_add_i32 s52, s46, 0xa000
	global_load_lds_dwordx4 v[0:1], off
	s_mov_b32 m0, s51
	s_add_u32 s10, s1, 0x162b00
	global_load_lds_dwordx4 v140, s[12:13]
	s_mov_b32 m0, s52
	s_addc_u32 s11, s2, 0
	global_load_lds_dwordx4 v144, s[12:13]
	s_add_i32 m0, s46, 0x1c000
	s_nop 0
	global_load_lds_dwordx4 v142, s[10:11]
	s_add_i32 m0, s46, 0x1e000
	v_lshlrev_b32_e32 v3, 2, v224
	global_load_lds_dwordx4 v146, s[10:11]
	v_bfe_u32 v1, v224, 4, 2
	v_and_b32_e32 v0, 15, v224
	v_lshlrev_b32_e32 v2, 4, v1
	v_lshl_or_b32 v160, s0, 6, v0
	v_lshl_or_b32 v0, v0, 6, v2
	v_and_b32_e32 v3, 32, v3
	s_ashr_i32 s53, s78, 31
	v_bitop3_b32 v0, v0, s14, v3 bitop3:0xde
	v_lshlrev_b32_e32 v4, 6, v224
	s_movk_i32 s0, 0x3c0
	s_waitcnt vmcnt(6)
	s_cmpk_lt_u32 s4, 0x100
	v_and_or_b32 v2, v4, s0, v2
	s_cselect_b64 s[10:11], -1, 0
	s_add_u32 s12, s82, 0x2a9e0000
	s_movk_i32 s34, 0xff80
	v_add_u32_e32 v163, 0, v0
	v_mbcnt_lo_u32_b32 v0, -1, 0
	v_bitop3_b32 v161, s15, v2, v3 bitop3:0xf6
	s_addc_u32 s13, s83, 0
	v_cmp_eq_u32_e64 s[0:1], 0, v1
	v_lshl_or_b32 v162, v1, 3, s3
	s_mov_b32 s35, -1
	v_mov_b64_e32 v[148:149], 0x200
	v_mov_b64_e32 v[150:151], 0x1ff
	s_movk_i32 s54, 0x80
	s_add_i32 s55, 0, 0x10000
	s_add_i32 s56, 0, 0x14000
	s_mov_b64 s[14:15], 0x80000
	s_mov_b32 s57, 0x80000
	s_mov_b64 s[16:17], 0x90000
	s_mov_b32 s58, 0x90000
	s_mov_b64 s[18:19], 0xa0000
	s_mov_b32 s59, 0xa0000
	s_mov_b64 s[20:21], 0xb0000
	s_mov_b32 s60, 0xb0000
	v_mbcnt_hi_u32_b32 v164, -1, v0
	s_barrier
	s_branch .LBB0_1547

; #define PG8_STAGE(bufoff, gbase, voff) do { _Pragma("unroll") for (int _i = 0; _i < 2; ++_i) \
;         __builtin_amdgcn_global_load_lds((const unsigned*)((const char*)(gbase) + (voff)[_i]), (LAS unsigned*)(lds + (bufoff) + ldsw + _i * 8192), 16, 0, 0); } while (0)
; #define PG8_LDA(dst, b, h) do { _Pragma("unroll") for (int m = 0; m < 4; ++m) _Pragma("unroll") for (int k = 0; k < 2; ++k) dst[m][k] = *(const LAS bf16x8*)(lds + PG8_SA(b, h) + aoff + m * 2048 + k * 1024); } while (0)
; #define PG8_LDB(dst, b, h) do { _Pragma("unroll") for (int n = 0; n < 2; ++n) _Pragma("unroll") for (int k = 0; k < 2; ++k) dst[n][k] = *(const LAS bf16x8*)(lds + PG8_SB(b, h) + boff + n * 2048 + k * 1024); } while (0)
; #define PG8_MMA(ai, bj, At, Bt) do { __builtin_amdgcn_s_setprio(1); _Pragma("unroll") for (int m = 0; m < 4; ++m) _Pragma("unroll") for (int n = 0; n < 2; ++n) _Pragma("unroll") for (int k = 0; k < 2; ++k) \
;         acc[ai][bj][m][n] = __builtin_amdgcn_mfma_f32_16x16x32_bf16(Bt[n][k], At[m][k], acc[ai][bj][m][n], 0, 0, 0); __builtin_amdgcn_s_setprio(0); } while (0)
; #define PG8_WAIT_V(n) asm volatile("s_waitcnt vmcnt(" #n ")" ::: "memory")
; #define PG8_WAIT_L(n) asm volatile("s_waitcnt lgkmcnt(" #n ")" ::: "memory")
; #define PG8_BAR __builtin_amdgcn_s_barrier()
; #define PG8_SCHED __builtin_amdgcn_sched_barrier(0)
; template <class Epi>
; __device__ __forceinline__ void gemm_phase(LAS unsigned char* lds, const Gemm g, const StaticOrder S, const Epi E) {
;     ...
;             const char* a1 = cA + (long)(t + 1) * ksc;
;             const char* a2 = last ? nA : cA + (long)(t + 2) * ksc; const char* b2 = last ? nB : cB + (long)(t + 2) * ksc;
;             const long ks3 = last ? ksn : ksc;
;             const char* a3 = a2 + ks3; const char* b3 = b2 + ks3;
;             PG8_LDB(B0, 0, 0); PG8_LDB(B1, 0, 1); PG8_SCHED; PG8_LDA(At, 0, 0); PG8_STAGE(PG8_SA(1, 1), a1 + hstepA, voffA);
;             PG8_WAIT_V(8); PG8_WAIT_L(0); PG8_BAR; PG8_MMA(0, 0, At, B0); PG8_MMA(0, 1, At, B1); PG8_BAR; PG8_SCHED;
;             PG8_LDA(At, 0, 1); PG8_STAGE(PG8_SB(0, 0), b2, voffB); PG8_STAGE(PG8_SB(0, 1), b2 + hstepB, voffB); PG8_STAGE(PG8_SA(0, 0), a2, voffA);
;             PG8_WAIT_V(8); PG8_WAIT_L(0); PG8_BAR; PG8_MMA(1, 0, At, B0); PG8_MMA(1, 1, At, B1); PG8_BAR; PG8_SCHED;
.LBB0_1558:
	v_add_u32_e32 v152, s55, v161
	v_add_u32_e32 v165, s56, v161
	ds_read_b128 v[128:131], v152
	ds_read_b128 v[132:135], v152 offset:1024
	ds_read_b128 v[136:139], v152 offset:2048
	ds_read_b128 v[152:155], v152 offset:3072
	ds_read_b128 v[156:159], v165
	ds_read_b128 v[166:169], v165 offset:1024
	ds_read_b128 v[170:173], v165 offset:2048
	ds_read_b128 v[174:177], v165 offset:3072
	s_or_b32 s42, s66, 1
	s_mul_i32 s43, s35, s42
	s_mul_hi_u32 s68, s34, s42
	s_add_i32 s68, s68, s43
	s_mul_i32 s42, s34, s42
	s_add_u32 s69, s30, s42
	s_addc_u32 s70, s31, s68
	s_add_u32 s42, s40, s38
	s_addc_u32 s43, s41, s39
	s_add_u32 s68, s69, 0x160000
	s_addc_u32 s69, s70, 0
	s_add_i32 m0, s46, 0xc000
	ds_read_b128 v[178:181], v163
	ds_read_b128 v[182:185], v163 offset:1024
	ds_read_b128 v[186:189], v163 offset:2048
	ds_read_b128 v[190:193], v163 offset:3072
	ds_read_b128 v[194:197], v163 offset:4096
	ds_read_b128 v[198:201], v163 offset:5120
	ds_read_b128 v[202:205], v163 offset:6144
	ds_read_b128 v[206:209], v163 offset:7168
	global_load_lds_dwordx4 v140, s[68:69]
	s_add_i32 m0, s46, 0xe000
	s_nop 0
	global_load_lds_dwordx4 v144, s[68:69]
	s_waitcnt vmcnt(8)
	s_waitcnt lgkmcnt(0)
	s_barrier
	s_setprio 1
	s_waitcnt lgkmcnt(0)
	v_mfma_f32_16x16x32_bf16 v[124:127], v[128:131], v[178:181], v[124:127]
	v_mfma_f32_16x16x32_bf16 v[120:123], v[136:139], v[178:181], v[120:123]
	v_mfma_f32_16x16x32_bf16 v[108:111], v[128:131], v[186:189], v[108:111]
	v_mfma_f32_16x16x32_bf16 v[104:107], v[136:139], v[186:189], v[104:107]
	v_mfma_f32_16x16x32_bf16 v[92:95], v[128:131], v[194:197], v[92:95]
	v_mfma_f32_16x16x32_bf16 v[88:91], v[136:139], v[194:197], v[88:91]
	v_mfma_f32_16x16x32_bf16 v[76:79], v[128:131], v[202:205], v[76:79]
	v_mfma_f32_16x16x32_bf16 v[72:75], v[136:139], v[202:205], v[72:75]
	v_mfma_f32_16x16x32_bf16 v[124:127], v[132:135], v[182:185], v[124:127]
	v_mfma_f32_16x16x32_bf16 v[120:123], v[152:155], v[182:185], v[120:123]
	v_mfma_f32_16x16x32_bf16 v[108:111], v[132:135], v[190:193], v[108:111]
	v_mfma_f32_16x16x32_bf16 v[104:107], v[152:155], v[190:193], v[104:107]
	v_mfma_f32_16x16x32_bf16 v[92:95], v[132:135], v[198:201], v[92:95]
	v_mfma_f32_16x16x32_bf16 v[88:91], v[152:155], v[198:201], v[88:91]
	v_mfma_f32_16x16x32_bf16 v[76:79], v[132:135], v[206:209], v[76:79]
	v_mfma_f32_16x16x32_bf16 v[72:75], v[152:155], v[206:209], v[72:75]
	s_setprio 0
	s_setprio 1
	v_mfma_f32_16x16x32_bf16 v[116:119], v[156:159], v[178:181], v[116:119]
	v_mfma_f32_16x16x32_bf16 v[112:115], v[170:173], v[178:181], v[112:115]
	v_mfma_f32_16x16x32_bf16 v[100:103], v[156:159], v[186:189], v[100:103]
	v_mfma_f32_16x16x32_bf16 v[96:99], v[170:173], v[186:189], v[96:99]
	v_mfma_f32_16x16x32_bf16 v[84:87], v[156:159], v[194:197], v[84:87]
	v_mfma_f32_16x16x32_bf16 v[80:83], v[170:173], v[194:197], v[80:83]
	v_mfma_f32_16x16x32_bf16 v[68:71], v[156:159], v[202:205], v[68:71]
	v_mfma_f32_16x16x32_bf16 v[64:67], v[170:173], v[202:205], v[64:67]
	v_mfma_f32_16x16x32_bf16 v[116:119], v[166:169], v[182:185], v[116:119]
	v_mfma_f32_16x16x32_bf16 v[112:115], v[174:177], v[182:185], v[112:115]
	v_mfma_f32_16x16x32_bf16 v[100:103], v[166:169], v[190:193], v[100:103]
	v_mfma_f32_16x16x32_bf16 v[96:99], v[174:177], v[190:193], v[96:99]
	v_mfma_f32_16x16x32_bf16 v[84:87], v[166:169], v[198:201], v[84:87]
	v_mfma_f32_16x16x32_bf16 v[80:83], v[174:177], v[198:201], v[80:83]
	v_mfma_f32_16x16x32_bf16 v[68:71], v[166:169], v[206:209], v[68:71]
	v_mfma_f32_16x16x32_bf16 v[64:67], v[174:177], v[206:209], v[64:67]
	s_setprio 0
	s_barrier
	s_add_i32 s68, s55, s45
	s_mov_b32 m0, s68
	ds_read_b128 v[178:181], v163 offset:16384
	ds_read_b128 v[182:185], v163 offset:17408
	ds_read_b128 v[186:189], v163 offset:18432
	ds_read_b128 v[190:193], v163 offset:19456
	ds_read_b128 v[194:197], v163 offset:20480
	ds_read_b128 v[198:201], v163 offset:21504
	ds_read_b128 v[202:205], v163 offset:22528
	ds_read_b128 v[206:209], v163 offset:23552
	global_load_lds_dwordx4 v142, s[36:37]
	s_add_i32 m0, s68, 0x2000
	s_add_u32 s68, s36, 0x160000
	s_addc_u32 s69, s37, 0
	s_add_i32 s70, s56, s45
	global_load_lds_dwordx4 v146, s[36:37]
	s_mov_b32 m0, s70
	s_nop 0
	global_load_lds_dwordx4 v142, s[68:69]
	s_add_i32 m0, s70, 0x2000
	s_nop 0
	global_load_lds_dwordx4 v146, s[68:69]
	s_mov_b32 m0, s46
	s_nop 0
	global_load_lds_dwordx4 v140, s[40:41]
	s_mov_b32 m0, s47
	s_nop 0
	global_load_lds_dwordx4 v144, s[40:41]
	s_waitcnt vmcnt(8)
	s_waitcnt lgkmcnt(0)
	s_barrier
	s_setprio 1
	s_waitcnt lgkmcnt(0)
	v_mfma_f32_16x16x32_bf16 v[60:63], v[128:131], v[178:181], v[60:63]
	v_mfma_f32_16x16x32_bf16 v[56:59], v[136:139], v[178:181], v[56:59]
	v_mfma_f32_16x16x32_bf16 v[44:47], v[128:131], v[186:189], v[44:47]
	v_mfma_f32_16x16x32_bf16 v[40:43], v[136:139], v[186:189], v[40:43]
	v_mfma_f32_16x16x32_bf16 v[28:31], v[128:131], v[194:197], v[28:31]
	v_mfma_f32_16x16x32_bf16 v[24:27], v[136:139], v[194:197], v[24:27]
	v_mfma_f32_16x16x32_bf16 v[12:15], v[128:131], v[202:205], v[12:15]
	v_mfma_f32_16x16x32_bf16 v[8:11], v[136:139], v[202:205], v[8:11]
	v_mfma_f32_16x16x32_bf16 v[60:63], v[132:135], v[182:185], v[60:63]
	v_mfma_f32_16x16x32_bf16 v[56:59], v[152:155], v[182:185], v[56:59]
	v_mfma_f32_16x16x32_bf16 v[44:47], v[132:135], v[190:193], v[44:47]
	v_mfma_f32_16x16x32_bf16 v[40:43], v[152:155], v[190:193], v[40:43]
	v_mfma_f32_16x16x32_bf16 v[28:31], v[132:135], v[198:201], v[28:31]
	v_mfma_f32_16x16x32_bf16 v[24:27], v[152:155], v[198:201], v[24:27]
	v_mfma_f32_16x16x32_bf16 v[12:15], v[132:135], v[206:209], v[12:15]
	v_mfma_f32_16x16x32_bf16 v[8:11], v[152:155], v[206:209], v[8:11]
	s_setprio 0
	s_setprio 1
	v_mfma_f32_16x16x32_bf16 v[52:55], v[156:159], v[178:181], v[52:55]
	v_mfma_f32_16x16x32_bf16 v[48:51], v[170:173], v[178:181], v[48:51]
	v_mfma_f32_16x16x32_bf16 v[36:39], v[156:159], v[186:189], v[36:39]
	v_mfma_f32_16x16x32_bf16 v[32:35], v[170:173], v[186:189], v[32:35]
	v_mfma_f32_16x16x32_bf16 v[20:23], v[156:159], v[194:197], v[20:23]
	v_mfma_f32_16x16x32_bf16 v[16:19], v[170:173], v[194:197], v[16:19]
	v_mfma_f32_16x16x32_bf16 v[4:7], v[156:159], v[202:205], v[4:7]
	v_mfma_f32_16x16x32_bf16 v[0:3], v[170:173], v[202:205], v[0:3]
	v_mfma_f32_16x16x32_bf16 v[52:55], v[166:169], v[182:185], v[52:55]
	v_mfma_f32_16x16x32_bf16 v[48:51], v[174:177], v[182:185], v[48:51]
	v_mfma_f32_16x16x32_bf16 v[36:39], v[166:169], v[190:193], v[36:39]
	v_mfma_f32_16x16x32_bf16 v[32:35], v[174:177], v[190:193], v[32:35]
	v_mfma_f32_16x16x32_bf16 v[20:23], v[166:169], v[198:201], v[20:23]
	v_mfma_f32_16x16x32_bf16 v[16:19], v[174:177], v[198:201], v[16:19]
	v_mfma_f32_16x16x32_bf16 v[4:7], v[166:169], v[206:209], v[4:7]
	v_mfma_f32_16x16x32_bf16 v[0:3], v[174:177], v[206:209], v[0:3]
	s_setprio 0
	s_barrier
; #define PG8_STAGE(bufoff, gbase, voff) do { _Pragma("unroll") for (int _i = 0; _i < 2; ++_i) \
;         __builtin_amdgcn_global_load_lds((const unsigned*)((const char*)(gbase) + (voff)[_i]), (LAS unsigned*)(lds + (bufoff) + ldsw + _i * 8192), 16, 0, 0); } while (0)
; #define PG8_LDA(dst, b, h) do { _Pragma("unroll") for (int m = 0; m < 4; ++m) _Pragma("unroll") for (int k = 0; k < 2; ++k) dst[m][k] = *(const LAS bf16x8*)(lds + PG8_SA(b, h) + aoff + m * 2048 + k * 1024); } while (0)
; #define PG8_LDB(dst, b, h) do { _Pragma("unroll") for (int n = 0; n < 2; ++n) _Pragma("unroll") for (int k = 0; k < 2; ++k) dst[n][k] = *(const LAS bf16x8*)(lds + PG8_SB(b, h) + boff + n * 2048 + k * 1024); } while (0)
; #define PG8_MMA(ai, bj, At, Bt) do { __builtin_amdgcn_s_setprio(1); _Pragma("unroll") for (int m = 0; m < 4; ++m) _Pragma("unroll") for (int n = 0; n < 2; ++n) _Pragma("unroll") for (int k = 0; k < 2; ++k) \
;         acc[ai][bj][m][n] = __builtin_amdgcn_mfma_f32_16x16x32_bf16(Bt[n][k], At[m][k], acc[ai][bj][m][n], 0, 0, 0); __builtin_amdgcn_s_setprio(0); } while (0)
; #define PG8_WAIT_V(n) asm volatile("s_waitcnt vmcnt(" #n ")" ::: "memory")
; #define PG8_WAIT_L(n) asm volatile("s_waitcnt lgkmcnt(" #n ")" ::: "memory")
; #define PG8_BAR __builtin_amdgcn_s_barrier()
; #define PG8_SCHED __builtin_amdgcn_sched_barrier(0)
; template <class Epi>
; __device__ __forceinline__ void gemm_phase(LAS unsigned char* lds, const Gemm g, const StaticOrder S, const Epi E) {
;     ...
;             PG8_LDB(B0, 1, 0); PG8_LDB(B1, 1, 1); PG8_SCHED; PG8_LDA(At, 1, 0); PG8_STAGE(PG8_SA(0, 1), a2 + hstepA, voffA);
;             PG8_WAIT_V(8); PG8_WAIT_L(0); PG8_BAR; PG8_MMA(0, 0, At, B0); PG8_MMA(0, 1, At, B1); PG8_BAR; PG8_SCHED;
;             PG8_LDA(At, 1, 1); PG8_STAGE(PG8_SB(1, 0), b3, voffB); PG8_STAGE(PG8_SB(1, 1), b3 + hstepB, voffB); PG8_STAGE(PG8_SA(1, 0), a3, voffA);
;             PG8_WAIT_V(8); PG8_WAIT_L(0); PG8_BAR; PG8_MMA(1, 0, At, B0); PG8_MMA(1, 1, At, B1); PG8_BAR; PG8_SCHED;
	s_add_i32 s68, 0, 0x18000
	s_add_i32 s69, 0, 0x1c000
	v_add_u32_e32 v152, s68, v161
	v_add_u32_e32 v165, s69, v161
	ds_read_b128 v[128:131], v152
	ds_read_b128 v[132:135], v152 offset:1024
	ds_read_b128 v[136:139], v152 offset:2048
	ds_read_b128 v[152:155], v152 offset:3072
	ds_read_b128 v[156:159], v165
	ds_read_b128 v[166:169], v165 offset:1024
	ds_read_b128 v[170:173], v165 offset:2048
	ds_read_b128 v[174:177], v165 offset:3072
	s_add_u32 s40, s40, 0x160000
	s_addc_u32 s41, s41, 0
	s_mov_b32 m0, s48
	ds_read_b128 v[178:181], v163 offset:32768
	ds_read_b128 v[182:185], v163 offset:33792
	ds_read_b128 v[186:189], v163 offset:34816
	ds_read_b128 v[190:193], v163 offset:35840
	ds_read_b128 v[194:197], v163 offset:36864
	ds_read_b128 v[198:201], v163 offset:37888
	ds_read_b128 v[202:205], v163 offset:38912
	ds_read_b128 v[206:209], v163 offset:39936
	global_load_lds_dwordx4 v140, s[40:41]
	s_mov_b32 m0, s49
	s_nop 0
	global_load_lds_dwordx4 v144, s[40:41]
	s_waitcnt vmcnt(8)
	s_waitcnt lgkmcnt(0)
	s_barrier
	s_setprio 1
	s_waitcnt lgkmcnt(0)
	v_mfma_f32_16x16x32_bf16 v[124:127], v[128:131], v[178:181], v[124:127]
	v_mfma_f32_16x16x32_bf16 v[120:123], v[136:139], v[178:181], v[120:123]
	v_mfma_f32_16x16x32_bf16 v[108:111], v[128:131], v[186:189], v[108:111]
	v_mfma_f32_16x16x32_bf16 v[104:107], v[136:139], v[186:189], v[104:107]
	v_mfma_f32_16x16x32_bf16 v[92:95], v[128:131], v[194:197], v[92:95]
	v_mfma_f32_16x16x32_bf16 v[88:91], v[136:139], v[194:197], v[88:91]
	v_mfma_f32_16x16x32_bf16 v[76:79], v[128:131], v[202:205], v[76:79]
	v_mfma_f32_16x16x32_bf16 v[72:75], v[136:139], v[202:205], v[72:75]
	v_mfma_f32_16x16x32_bf16 v[124:127], v[132:135], v[182:185], v[124:127]
	v_mfma_f32_16x16x32_bf16 v[120:123], v[152:155], v[182:185], v[120:123]
	v_mfma_f32_16x16x32_bf16 v[108:111], v[132:135], v[190:193], v[108:111]
	v_mfma_f32_16x16x32_bf16 v[104:107], v[152:155], v[190:193], v[104:107]
	v_mfma_f32_16x16x32_bf16 v[92:95], v[132:135], v[198:201], v[92:95]
	v_mfma_f32_16x16x32_bf16 v[88:91], v[152:155], v[198:201], v[88:91]
	v_mfma_f32_16x16x32_bf16 v[76:79], v[132:135], v[206:209], v[76:79]
	v_mfma_f32_16x16x32_bf16 v[72:75], v[152:155], v[206:209], v[72:75]
	s_setprio 0
	s_setprio 1
	v_mfma_f32_16x16x32_bf16 v[116:119], v[156:159], v[178:181], v[116:119]
	v_mfma_f32_16x16x32_bf16 v[112:115], v[170:173], v[178:181], v[112:115]
	v_mfma_f32_16x16x32_bf16 v[100:103], v[156:159], v[186:189], v[100:103]
	v_mfma_f32_16x16x32_bf16 v[96:99], v[170:173], v[186:189], v[96:99]
	v_mfma_f32_16x16x32_bf16 v[84:87], v[156:159], v[194:197], v[84:87]
	v_mfma_f32_16x16x32_bf16 v[80:83], v[170:173], v[194:197], v[80:83]
	v_mfma_f32_16x16x32_bf16 v[68:71], v[156:159], v[202:205], v[68:71]
	v_mfma_f32_16x16x32_bf16 v[64:67], v[170:173], v[202:205], v[64:67]
	v_mfma_f32_16x16x32_bf16 v[116:119], v[166:169], v[182:185], v[116:119]
	v_mfma_f32_16x16x32_bf16 v[112:115], v[174:177], v[182:185], v[112:115]
	v_mfma_f32_16x16x32_bf16 v[100:103], v[166:169], v[190:193], v[100:103]
	v_mfma_f32_16x16x32_bf16 v[96:99], v[174:177], v[190:193], v[96:99]
	v_mfma_f32_16x16x32_bf16 v[84:87], v[166:169], v[198:201], v[84:87]
	v_mfma_f32_16x16x32_bf16 v[80:83], v[174:177], v[198:201], v[80:83]
	v_mfma_f32_16x16x32_bf16 v[68:71], v[166:169], v[206:209], v[68:71]
	v_mfma_f32_16x16x32_bf16 v[64:67], v[174:177], v[206:209], v[64:67]
	s_setprio 0
	s_barrier
	s_add_u32 s36, s36, s38
	s_addc_u32 s37, s37, s39
	s_add_i32 s38, s68, s45
	s_mov_b32 m0, s38
	ds_read_b128 v[178:181], v163 offset:49152
	ds_read_b128 v[182:185], v163 offset:50176
	ds_read_b128 v[186:189], v163 offset:51200
	ds_read_b128 v[190:193], v163 offset:52224
	ds_read_b128 v[194:197], v163 offset:53248
	ds_read_b128 v[198:201], v163 offset:54272
	ds_read_b128 v[202:205], v163 offset:55296
	ds_read_b128 v[206:209], v163 offset:56320
	global_load_lds_dwordx4 v142, s[36:37]
	s_add_i32 m0, s38, 0x2000
	v_lshl_add_u64 v[210:211], s[36:37], 0, v[146:147]
	s_add_u32 s36, s36, 0x160000
	s_addc_u32 s37, s37, 0
	s_add_i32 s38, s69, s45
	global_load_lds_dwordx4 v[210:211], off
	s_mov_b32 m0, s38
	s_nop 0
	global_load_lds_dwordx4 v142, s[36:37]
	s_add_i32 m0, s38, 0x2000
	s_nop 0
	global_load_lds_dwordx4 v146, s[36:37]
	s_mov_b32 m0, s51
	s_nop 0
	global_load_lds_dwordx4 v140, s[42:43]
	s_mov_b32 m0, s52
	s_nop 0
	global_load_lds_dwordx4 v144, s[42:43]
	s_waitcnt vmcnt(8)
	s_waitcnt lgkmcnt(0)
	s_barrier
	s_setprio 1
	s_waitcnt lgkmcnt(0)
	v_mfma_f32_16x16x32_bf16 v[60:63], v[128:131], v[178:181], v[60:63]
	v_mfma_f32_16x16x32_bf16 v[56:59], v[136:139], v[178:181], v[56:59]
	v_mfma_f32_16x16x32_bf16 v[44:47], v[128:131], v[186:189], v[44:47]
	v_mfma_f32_16x16x32_bf16 v[40:43], v[136:139], v[186:189], v[40:43]
	v_mfma_f32_16x16x32_bf16 v[28:31], v[128:131], v[194:197], v[28:31]
	v_mfma_f32_16x16x32_bf16 v[24:27], v[136:139], v[194:197], v[24:27]
	v_mfma_f32_16x16x32_bf16 v[12:15], v[128:131], v[202:205], v[12:15]
	v_mfma_f32_16x16x32_bf16 v[8:11], v[136:139], v[202:205], v[8:11]
	v_mfma_f32_16x16x32_bf16 v[60:63], v[132:135], v[182:185], v[60:63]
	v_mfma_f32_16x16x32_bf16 v[56:59], v[152:155], v[182:185], v[56:59]
	v_mfma_f32_16x16x32_bf16 v[44:47], v[132:135], v[190:193], v[44:47]
	v_mfma_f32_16x16x32_bf16 v[40:43], v[152:155], v[190:193], v[40:43]
	v_mfma_f32_16x16x32_bf16 v[28:31], v[132:135], v[198:201], v[28:31]
	v_mfma_f32_16x16x32_bf16 v[24:27], v[152:155], v[198:201], v[24:27]
	v_mfma_f32_16x16x32_bf16 v[12:15], v[132:135], v[206:209], v[12:15]
	v_mfma_f32_16x16x32_bf16 v[8:11], v[152:155], v[206:209], v[8:11]
	s_setprio 0
	s_setprio 1
	v_mfma_f32_16x16x32_bf16 v[52:55], v[156:159], v[178:181], v[52:55]
	v_mfma_f32_16x16x32_bf16 v[48:51], v[170:173], v[178:181], v[48:51]
	v_mfma_f32_16x16x32_bf16 v[36:39], v[156:159], v[186:189], v[36:39]
	v_mfma_f32_16x16x32_bf16 v[32:35], v[170:173], v[186:189], v[32:35]
	v_mfma_f32_16x16x32_bf16 v[20:23], v[156:159], v[194:197], v[20:23]
	v_mfma_f32_16x16x32_bf16 v[16:19], v[170:173], v[194:197], v[16:19]
	v_mfma_f32_16x16x32_bf16 v[4:7], v[156:159], v[202:205], v[4:7]
	v_mfma_f32_16x16x32_bf16 v[0:3], v[170:173], v[202:205], v[0:3]
	v_mfma_f32_16x16x32_bf16 v[52:55], v[166:169], v[182:185], v[52:55]
	v_mfma_f32_16x16x32_bf16 v[48:51], v[174:177], v[182:185], v[48:51]
	v_mfma_f32_16x16x32_bf16 v[36:39], v[166:169], v[190:193], v[36:39]
	v_mfma_f32_16x16x32_bf16 v[32:35], v[174:177], v[190:193], v[32:35]
	v_mfma_f32_16x16x32_bf16 v[20:23], v[166:169], v[198:201], v[20:23]
	v_mfma_f32_16x16x32_bf16 v[16:19], v[174:177], v[198:201], v[16:19]
	v_mfma_f32_16x16x32_bf16 v[4:7], v[166:169], v[206:209], v[4:7]
	v_mfma_f32_16x16x32_bf16 v[0:3], v[174:177], v[206:209], v[0:3]
	s_setprio 0
	s_barrier
	s_cmpk_gt_u32 s66, 0x55
	s_mov_b32 s66, s67
	s_cbranch_scc1 .LBB0_1563
